# v60 + phase-1 LOAD segment only: all 16 ds_read_b128 issued before the scalar address preparation
# baseline (speedup 1.0000x reference)
.LBB0_297:
	ds_read_b128 v[150:153], v146
	ds_read_b128 v[154:157], v146 offset:1024
	ds_read_b128 v[158:161], v146 offset:2048
	ds_read_b128 v[162:165], v146 offset:3072
	ds_read_b128 v[166:169], v147
	ds_read_b128 v[170:173], v147 offset:1024
	ds_read_b128 v[174:177], v147 offset:2048
	ds_read_b128 v[178:181], v147 offset:3072
	ds_read_b128 v[182:185], v148
	ds_read_b128 v[186:189], v148 offset:1024
	ds_read_b128 v[190:193], v148 offset:2048
	ds_read_b128 v[194:197], v148 offset:3072
	ds_read_b128 v[198:201], v148 offset:4096
	ds_read_b128 v[206:209], v148 offset:5120
	ds_read_b128 v[210:213], v148 offset:6144
	ds_read_b128 v[214:217], v148 offset:7168
	s_add_u32 s47, s38, s46
	s_addc_u32 s66, s39, 0
	s_add_u32 s64, s47, 0x100
	s_addc_u32 s65, s66, 0
	s_and_b64 s[48:49], s[44:45], exec
	s_cselect_b32 s49, s70, s65
	s_cselect_b32 s48, s71, s64
	s_add_u32 s46, s36, s46
	s_addc_u32 s64, s37, 0
	s_add_u32 s46, s46, 0x100
	s_addc_u32 s64, s64, 0
	s_and_b64 s[44:45], s[44:45], exec
	s_cselect_b32 s65, s72, s64
	s_cselect_b32 s64, s73, s46
	s_add_u32 s68, s47, 0x10080
	s_addc_u32 s69, s66, 0
	s_add_i32 s83, s30, s2
	s_add_i32 m0, s16, 0xc000
	s_add_i32 s84, s16, 0xe000
	s_add_i32 s80, s83, 0x2000
	s_add_u32 s66, s64, 0x40000
	s_addc_u32 s67, s65, 0
	s_add_i32 s82, s31, s2
	s_add_i32 s81, s82, 0x2000
	s_add_i32 s79, 0, 0x18000
	s_add_i32 s78, 0, 0x1c000
	s_add_u32 s46, s48, 0x10000
	s_addc_u32 s47, s49, 0
	s_add_i32 s77, s79, s2
	s_add_i32 s75, s77, 0x2000
	s_add_u32 s44, s64, 0x40080
	s_addc_u32 s45, s65, 0
	s_add_i32 s76, s78, s2
	s_add_i32 s74, s76, 0x2000
	v_lshl_add_u64 v[202:203], s[68:69], 0, v[130:131]
	global_load_lds_dwordx4 v[202:203], off
	v_lshl_add_u64 v[202:203], s[68:69], 0, v[132:133]
	s_mov_b32 m0, s84
	s_nop 0
	global_load_lds_dwordx4 v[202:203], off
	s_waitcnt vmcnt(8)
	s_waitcnt lgkmcnt(0)
	s_setprio 1
	s_barrier
	v_mfma_f32_16x16x32_bf16 v[126:129], v[150:153], v[182:185], v[126:129]
	v_mfma_f32_16x16x32_bf16 v[122:125], v[158:161], v[182:185], v[122:125]
	v_mfma_f32_16x16x32_bf16 v[118:121], v[150:153], v[190:193], v[118:121]
	v_mfma_f32_16x16x32_bf16 v[114:117], v[158:161], v[190:193], v[114:117]
	v_mfma_f32_16x16x32_bf16 v[102:105], v[150:153], v[198:201], v[102:105]
	v_mfma_f32_16x16x32_bf16 v[98:101], v[158:161], v[198:201], v[98:101]
	v_mfma_f32_16x16x32_bf16 v[86:89], v[150:153], v[210:213], v[86:89]
	v_mfma_f32_16x16x32_bf16 v[82:85], v[158:161], v[210:213], v[82:85]
	v_mfma_f32_16x16x32_bf16 v[126:129], v[154:157], v[186:189], v[126:129]
	v_mfma_f32_16x16x32_bf16 v[122:125], v[162:165], v[186:189], v[122:125]
	v_mfma_f32_16x16x32_bf16 v[118:121], v[154:157], v[194:197], v[118:121]
	v_mfma_f32_16x16x32_bf16 v[114:117], v[162:165], v[194:197], v[114:117]
	v_mfma_f32_16x16x32_bf16 v[102:105], v[154:157], v[206:209], v[102:105]
	v_mfma_f32_16x16x32_bf16 v[98:101], v[162:165], v[206:209], v[98:101]
	v_mfma_f32_16x16x32_bf16 v[86:89], v[154:157], v[214:217], v[86:89]
	v_mfma_f32_16x16x32_bf16 v[82:85], v[162:165], v[214:217], v[82:85]
	v_mfma_f32_16x16x32_bf16 v[110:113], v[166:169], v[182:185], v[110:113]
	v_mfma_f32_16x16x32_bf16 v[106:109], v[174:177], v[182:185], v[106:109]
	v_mfma_f32_16x16x32_bf16 v[94:97], v[166:169], v[190:193], v[94:97]
	v_mfma_f32_16x16x32_bf16 v[90:93], v[174:177], v[190:193], v[90:93]
	v_mfma_f32_16x16x32_bf16 v[78:81], v[166:169], v[198:201], v[78:81]
	v_mfma_f32_16x16x32_bf16 v[74:77], v[174:177], v[198:201], v[74:77]
	v_mfma_f32_16x16x32_bf16 v[70:73], v[166:169], v[210:213], v[70:73]
	v_mfma_f32_16x16x32_bf16 v[66:69], v[174:177], v[210:213], v[66:69]
	v_mfma_f32_16x16x32_bf16 v[110:113], v[170:173], v[186:189], v[110:113]
	v_mfma_f32_16x16x32_bf16 v[106:109], v[178:181], v[186:189], v[106:109]
	v_mfma_f32_16x16x32_bf16 v[94:97], v[170:173], v[194:197], v[94:97]
	v_mfma_f32_16x16x32_bf16 v[90:93], v[178:181], v[194:197], v[90:93]
	v_mfma_f32_16x16x32_bf16 v[78:81], v[170:173], v[206:209], v[78:81]
	v_mfma_f32_16x16x32_bf16 v[74:77], v[178:181], v[206:209], v[74:77]
	v_mfma_f32_16x16x32_bf16 v[70:73], v[170:173], v[214:217], v[70:73]
	v_mfma_f32_16x16x32_bf16 v[66:69], v[178:181], v[214:217], v[66:69]
	s_setprio 0
	s_barrier
	s_mov_b32 m0, s83
	v_lshl_add_u64 v[202:203], s[64:65], 0, v[136:137]
	ds_read_b128 v[182:185], v148 offset:16384
	ds_read_b128 v[186:189], v148 offset:17408
	ds_read_b128 v[190:193], v148 offset:18432
	ds_read_b128 v[194:197], v148 offset:19456
	ds_read_b128 v[198:201], v148 offset:20480
	ds_read_b128 v[206:209], v148 offset:21504
	ds_read_b128 v[210:213], v148 offset:22528
	ds_read_b128 v[214:217], v148 offset:23552
	global_load_lds_dwordx4 v[202:203], off
	v_lshl_add_u64 v[218:219], s[64:65], 0, v[134:135]
	s_mov_b32 m0, s80
	v_lshl_add_u64 v[220:221], s[66:67], 0, v[136:137]
	global_load_lds_dwordx4 v[218:219], off
	s_mov_b32 m0, s82
	v_lshl_add_u64 v[222:223], s[48:49], 0, v[132:133]
	global_load_lds_dwordx4 v[220:221], off
	v_lshl_add_u64 v[220:221], s[66:67], 0, v[134:135]
	s_mov_b32 m0, s81
	s_nop 0
	global_load_lds_dwordx4 v[220:221], off
	v_lshl_add_u64 v[220:221], s[48:49], 0, v[130:131]
	s_mov_b32 m0, s16
	s_nop 0
	global_load_lds_dwordx4 v[220:221], off
	s_mov_b32 m0, s17
	s_nop 0
	global_load_lds_dwordx4 v[222:223], off
	s_waitcnt vmcnt(8)
	s_waitcnt lgkmcnt(0)
	s_setprio 1
	s_barrier
	v_mfma_f32_16x16x32_bf16 v[62:65], v[150:153], v[182:185], v[62:65]
	v_mfma_f32_16x16x32_bf16 v[58:61], v[158:161], v[182:185], v[58:61]
	v_mfma_f32_16x16x32_bf16 v[54:57], v[150:153], v[190:193], v[54:57]
	v_mfma_f32_16x16x32_bf16 v[50:53], v[158:161], v[190:193], v[50:53]
	v_mfma_f32_16x16x32_bf16 v[38:41], v[150:153], v[198:201], v[38:41]
	v_mfma_f32_16x16x32_bf16 v[34:37], v[158:161], v[198:201], v[34:37]
	v_mfma_f32_16x16x32_bf16 v[22:25], v[150:153], v[210:213], v[22:25]
	v_mfma_f32_16x16x32_bf16 v[18:21], v[158:161], v[210:213], v[18:21]
	v_mfma_f32_16x16x32_bf16 v[62:65], v[154:157], v[186:189], v[62:65]
	v_mfma_f32_16x16x32_bf16 v[58:61], v[162:165], v[186:189], v[58:61]
	v_mfma_f32_16x16x32_bf16 v[54:57], v[154:157], v[194:197], v[54:57]
	v_mfma_f32_16x16x32_bf16 v[50:53], v[162:165], v[194:197], v[50:53]
	v_mfma_f32_16x16x32_bf16 v[38:41], v[154:157], v[206:209], v[38:41]
	v_mfma_f32_16x16x32_bf16 v[34:37], v[162:165], v[206:209], v[34:37]
	v_mfma_f32_16x16x32_bf16 v[22:25], v[154:157], v[214:217], v[22:25]
	v_mfma_f32_16x16x32_bf16 v[18:21], v[162:165], v[214:217], v[18:21]
	v_mfma_f32_16x16x32_bf16 v[46:49], v[166:169], v[182:185], v[46:49]
	v_mfma_f32_16x16x32_bf16 v[42:45], v[174:177], v[182:185], v[42:45]
	v_mfma_f32_16x16x32_bf16 v[30:33], v[166:169], v[190:193], v[30:33]
	v_mfma_f32_16x16x32_bf16 v[26:29], v[174:177], v[190:193], v[26:29]
	v_mfma_f32_16x16x32_bf16 v[14:17], v[166:169], v[198:201], v[14:17]
	v_mfma_f32_16x16x32_bf16 v[10:13], v[174:177], v[198:201], v[10:13]
	v_mfma_f32_16x16x32_bf16 v[6:9], v[166:169], v[210:213], v[6:9]
	v_mfma_f32_16x16x32_bf16 v[2:5], v[174:177], v[210:213], v[2:5]
	v_mfma_f32_16x16x32_bf16 v[46:49], v[170:173], v[186:189], v[46:49]
	v_mfma_f32_16x16x32_bf16 v[42:45], v[178:181], v[186:189], v[42:45]
	v_mfma_f32_16x16x32_bf16 v[30:33], v[170:173], v[194:197], v[30:33]
	v_mfma_f32_16x16x32_bf16 v[26:29], v[178:181], v[194:197], v[26:29]
	v_mfma_f32_16x16x32_bf16 v[14:17], v[170:173], v[206:209], v[14:17]
	v_mfma_f32_16x16x32_bf16 v[10:13], v[178:181], v[206:209], v[10:13]
	v_mfma_f32_16x16x32_bf16 v[6:9], v[170:173], v[214:217], v[6:9]
	v_mfma_f32_16x16x32_bf16 v[2:5], v[178:181], v[214:217], v[2:5]
	s_setprio 0
	s_barrier
	v_add_u32_e32 v149, s79, v145
	ds_read_b128 v[150:153], v149
	ds_read_b128 v[154:157], v149 offset:1024
	ds_read_b128 v[158:161], v149 offset:2048
	ds_read_b128 v[162:165], v149 offset:3072
	v_add_u32_e32 v149, s78, v145
	ds_read_b128 v[166:169], v149
	ds_read_b128 v[170:173], v149 offset:1024
	ds_read_b128 v[174:177], v149 offset:2048
	ds_read_b128 v[178:181], v149 offset:3072
	s_mov_b32 m0, s18
	v_lshl_add_u64 v[224:225], s[46:47], 0, v[130:131]
	ds_read_b128 v[182:185], v148 offset:32768
	ds_read_b128 v[186:189], v148 offset:33792
	ds_read_b128 v[190:193], v148 offset:34816
	ds_read_b128 v[194:197], v148 offset:35840
	ds_read_b128 v[198:201], v148 offset:36864
	ds_read_b128 v[206:209], v148 offset:37888
	ds_read_b128 v[210:213], v148 offset:38912
	ds_read_b128 v[214:217], v148 offset:39936
	global_load_lds_dwordx4 v[224:225], off
	v_lshl_add_u64 v[224:225], s[46:47], 0, v[132:133]
	s_mov_b32 m0, s19
	s_nop 0
	global_load_lds_dwordx4 v[224:225], off
	s_waitcnt vmcnt(8)
	s_waitcnt lgkmcnt(0)
	s_setprio 1
	s_barrier
	v_mfma_f32_16x16x32_bf16 v[126:129], v[150:153], v[182:185], v[126:129]
	v_mfma_f32_16x16x32_bf16 v[122:125], v[158:161], v[182:185], v[122:125]
	v_mfma_f32_16x16x32_bf16 v[118:121], v[150:153], v[190:193], v[118:121]
	v_mfma_f32_16x16x32_bf16 v[114:117], v[158:161], v[190:193], v[114:117]
	v_mfma_f32_16x16x32_bf16 v[102:105], v[150:153], v[198:201], v[102:105]
	v_mfma_f32_16x16x32_bf16 v[98:101], v[158:161], v[198:201], v[98:101]
	v_mfma_f32_16x16x32_bf16 v[86:89], v[150:153], v[210:213], v[86:89]
	v_mfma_f32_16x16x32_bf16 v[82:85], v[158:161], v[210:213], v[82:85]
	v_mfma_f32_16x16x32_bf16 v[126:129], v[154:157], v[186:189], v[126:129]
	v_mfma_f32_16x16x32_bf16 v[122:125], v[162:165], v[186:189], v[122:125]
	v_mfma_f32_16x16x32_bf16 v[118:121], v[154:157], v[194:197], v[118:121]
	v_mfma_f32_16x16x32_bf16 v[114:117], v[162:165], v[194:197], v[114:117]
	v_mfma_f32_16x16x32_bf16 v[102:105], v[154:157], v[206:209], v[102:105]
	v_mfma_f32_16x16x32_bf16 v[98:101], v[162:165], v[206:209], v[98:101]
	v_mfma_f32_16x16x32_bf16 v[86:89], v[154:157], v[214:217], v[86:89]
	v_mfma_f32_16x16x32_bf16 v[82:85], v[162:165], v[214:217], v[82:85]
	v_mfma_f32_16x16x32_bf16 v[110:113], v[166:169], v[182:185], v[110:113]
	v_mfma_f32_16x16x32_bf16 v[106:109], v[174:177], v[182:185], v[106:109]
	v_mfma_f32_16x16x32_bf16 v[94:97], v[166:169], v[190:193], v[94:97]
	v_mfma_f32_16x16x32_bf16 v[90:93], v[174:177], v[190:193], v[90:93]
	v_mfma_f32_16x16x32_bf16 v[78:81], v[166:169], v[198:201], v[78:81]
	v_mfma_f32_16x16x32_bf16 v[74:77], v[174:177], v[198:201], v[74:77]
	v_mfma_f32_16x16x32_bf16 v[70:73], v[166:169], v[210:213], v[70:73]
	v_mfma_f32_16x16x32_bf16 v[66:69], v[174:177], v[210:213], v[66:69]
	v_mfma_f32_16x16x32_bf16 v[110:113], v[170:173], v[186:189], v[110:113]
	v_mfma_f32_16x16x32_bf16 v[106:109], v[178:181], v[186:189], v[106:109]
	v_mfma_f32_16x16x32_bf16 v[94:97], v[170:173], v[194:197], v[94:97]
	v_mfma_f32_16x16x32_bf16 v[90:93], v[178:181], v[194:197], v[90:93]
	v_mfma_f32_16x16x32_bf16 v[78:81], v[170:173], v[206:209], v[78:81]
	v_mfma_f32_16x16x32_bf16 v[74:77], v[178:181], v[206:209], v[74:77]
	v_mfma_f32_16x16x32_bf16 v[70:73], v[170:173], v[214:217], v[70:73]
	v_mfma_f32_16x16x32_bf16 v[66:69], v[178:181], v[214:217], v[66:69]
	s_setprio 0
	s_barrier
	s_mov_b32 m0, s77
	v_lshl_add_u64 v[202:203], v[202:203], 0, s[8:9]
	ds_read_b128 v[182:185], v148 offset:49152
	ds_read_b128 v[186:189], v148 offset:50176
	ds_read_b128 v[190:193], v148 offset:51200
	ds_read_b128 v[194:197], v148 offset:52224
	ds_read_b128 v[198:201], v148 offset:53248
	ds_read_b128 v[206:209], v148 offset:54272
	ds_read_b128 v[210:213], v148 offset:55296
	ds_read_b128 v[214:217], v148 offset:56320
	global_load_lds_dwordx4 v[202:203], off
	v_lshl_add_u64 v[202:203], v[218:219], 0, s[8:9]
	s_mov_b32 m0, s75
	s_nop 0
	global_load_lds_dwordx4 v[202:203], off
	v_lshl_add_u64 v[202:203], s[44:45], 0, v[136:137]
	s_mov_b32 m0, s76
	s_nop 0
	global_load_lds_dwordx4 v[202:203], off
	v_lshl_add_u64 v[202:203], s[44:45], 0, v[134:135]
	s_mov_b32 m0, s74
	s_nop 0
	global_load_lds_dwordx4 v[202:203], off
	v_lshl_add_u64 v[202:203], v[220:221], 0, s[8:9]
	s_mov_b32 m0, s28
	s_nop 0
	global_load_lds_dwordx4 v[202:203], off
	v_lshl_add_u64 v[202:203], v[222:223], 0, s[8:9]
	s_mov_b32 m0, s29
	s_nop 0
	global_load_lds_dwordx4 v[202:203], off
	s_waitcnt vmcnt(8)
	s_waitcnt lgkmcnt(0)
	s_setprio 1
	s_barrier
	v_mfma_f32_16x16x32_bf16 v[62:65], v[150:153], v[182:185], v[62:65]
	v_mfma_f32_16x16x32_bf16 v[58:61], v[158:161], v[182:185], v[58:61]
	v_mfma_f32_16x16x32_bf16 v[54:57], v[150:153], v[190:193], v[54:57]
	v_mfma_f32_16x16x32_bf16 v[50:53], v[158:161], v[190:193], v[50:53]
	v_mfma_f32_16x16x32_bf16 v[38:41], v[150:153], v[198:201], v[38:41]
	v_mfma_f32_16x16x32_bf16 v[34:37], v[158:161], v[198:201], v[34:37]
	v_mfma_f32_16x16x32_bf16 v[22:25], v[150:153], v[210:213], v[22:25]
	v_mfma_f32_16x16x32_bf16 v[18:21], v[158:161], v[210:213], v[18:21]
	v_mfma_f32_16x16x32_bf16 v[62:65], v[154:157], v[186:189], v[62:65]
	v_mfma_f32_16x16x32_bf16 v[58:61], v[162:165], v[186:189], v[58:61]
	v_mfma_f32_16x16x32_bf16 v[54:57], v[154:157], v[194:197], v[54:57]
	v_mfma_f32_16x16x32_bf16 v[50:53], v[162:165], v[194:197], v[50:53]
	v_mfma_f32_16x16x32_bf16 v[38:41], v[154:157], v[206:209], v[38:41]
	v_mfma_f32_16x16x32_bf16 v[34:37], v[162:165], v[206:209], v[34:37]
	v_mfma_f32_16x16x32_bf16 v[22:25], v[154:157], v[214:217], v[22:25]
	v_mfma_f32_16x16x32_bf16 v[18:21], v[162:165], v[214:217], v[18:21]
	v_mfma_f32_16x16x32_bf16 v[46:49], v[166:169], v[182:185], v[46:49]
	v_mfma_f32_16x16x32_bf16 v[42:45], v[174:177], v[182:185], v[42:45]
	v_mfma_f32_16x16x32_bf16 v[30:33], v[166:169], v[190:193], v[30:33]
	v_mfma_f32_16x16x32_bf16 v[26:29], v[174:177], v[190:193], v[26:29]
	v_mfma_f32_16x16x32_bf16 v[14:17], v[166:169], v[198:201], v[14:17]
	v_mfma_f32_16x16x32_bf16 v[10:13], v[174:177], v[198:201], v[10:13]
	v_mfma_f32_16x16x32_bf16 v[6:9], v[166:169], v[210:213], v[6:9]
	v_mfma_f32_16x16x32_bf16 v[2:5], v[174:177], v[210:213], v[2:5]
	v_mfma_f32_16x16x32_bf16 v[46:49], v[170:173], v[186:189], v[46:49]
	v_mfma_f32_16x16x32_bf16 v[42:45], v[178:181], v[186:189], v[42:45]
	v_mfma_f32_16x16x32_bf16 v[30:33], v[170:173], v[194:197], v[30:33]
	v_mfma_f32_16x16x32_bf16 v[26:29], v[178:181], v[194:197], v[26:29]
	v_mfma_f32_16x16x32_bf16 v[14:17], v[170:173], v[206:209], v[14:17]
	v_mfma_f32_16x16x32_bf16 v[10:13], v[178:181], v[206:209], v[10:13]
	v_mfma_f32_16x16x32_bf16 v[6:9], v[170:173], v[214:217], v[6:9]
	v_mfma_f32_16x16x32_bf16 v[2:5], v[178:181], v[214:217], v[2:5]
	s_setprio 0
	s_barrier
	s_movk_i32 s46, 0x100
	s_andn2_b64 vcc, exec, s[42:43]
	s_mov_b64 s[44:45], -1
	s_mov_b64 s[42:43], 0
	s_cbranch_vccz .LBB0_297
	s_and_b64 vcc, exec, s[10:11]
	s_cbranch_vccz .LBB0_300
	s_barrier

.LBB0_313:
	ds_read_b128 v[144:147], v140
	ds_read_b128 v[148:151], v140 offset:1024
	ds_read_b128 v[152:155], v140 offset:2048
	ds_read_b128 v[156:159], v140 offset:3072
	ds_read_b128 v[160:163], v141
	ds_read_b128 v[164:167], v141 offset:1024
	ds_read_b128 v[168:171], v141 offset:2048
	ds_read_b128 v[172:175], v141 offset:3072
	ds_read_b128 v[176:179], v142
	ds_read_b128 v[180:183], v142 offset:1024
	ds_read_b128 v[184:187], v142 offset:2048
	ds_read_b128 v[188:191], v142 offset:3072
	ds_read_b128 v[192:195], v142 offset:4096
	ds_read_b128 v[196:199], v142 offset:5120
	ds_read_b128 v[200:203], v142 offset:6144
	ds_read_b128 v[206:209], v142 offset:7168
	s_add_u32 s49, s38, s48
	s_addc_u32 s68, s39, 0
	s_add_u32 s66, s49, 0x100
	s_addc_u32 s67, s68, 0
	s_and_b64 s[64:65], s[46:47], exec
	s_cselect_b32 s65, s43, s67
	s_cselect_b32 s64, s75, s66
	s_add_u32 s48, s36, s48
	s_addc_u32 s66, s37, 0
	s_add_u32 s48, s48, 0x100
	s_addc_u32 s66, s66, 0
	s_and_b64 s[46:47], s[46:47], exec
	s_cselect_b32 s67, s76, s66
	s_cselect_b32 s66, s77, s48
	s_add_u32 s70, s49, 0x10080
	s_addc_u32 s71, s68, 0
	s_add_i32 s87, s33, s2
	s_add_i32 m0, s16, 0xc000
	s_add_i32 s88, s16, 0xe000
	s_add_i32 s84, s87, 0x2000
	s_add_u32 s68, s66, 0x1000
	s_addc_u32 s69, s67, 0
	s_add_i32 s86, s34, s2
	s_add_i32 s85, s86, 0x2000
	s_add_i32 s83, 0, 0x18000
	s_add_i32 s82, 0, 0x1c000
	s_add_u32 s48, s64, 0x10000
	s_addc_u32 s49, s65, 0
	s_add_i32 s81, s83, s2
	s_add_i32 s79, s81, 0x2000
	s_add_u32 s46, s66, 0x1080
	s_addc_u32 s47, s67, 0
	s_add_i32 s80, s82, s2
	s_add_i32 s78, s80, 0x2000
	v_lshl_add_u64 v[210:211], s[70:71], 0, v[130:131]
	global_load_lds_dwordx4 v[210:211], off
	v_lshl_add_u64 v[210:211], s[70:71], 0, v[132:133]
	s_mov_b32 m0, s88
	s_nop 0
	global_load_lds_dwordx4 v[210:211], off
	s_waitcnt vmcnt(8)
	s_waitcnt lgkmcnt(0)
	s_setprio 1
	s_barrier
	v_mfma_f32_16x16x32_bf16 v[126:129], v[144:147], v[176:179], v[126:129]
	v_mfma_f32_16x16x32_bf16 v[122:125], v[152:155], v[176:179], v[122:125]
	v_mfma_f32_16x16x32_bf16 v[118:121], v[144:147], v[184:187], v[118:121]
	v_mfma_f32_16x16x32_bf16 v[114:117], v[152:155], v[184:187], v[114:117]
	v_mfma_f32_16x16x32_bf16 v[102:105], v[144:147], v[192:195], v[102:105]
	v_mfma_f32_16x16x32_bf16 v[98:101], v[152:155], v[192:195], v[98:101]
	v_mfma_f32_16x16x32_bf16 v[86:89], v[144:147], v[200:203], v[86:89]
	v_mfma_f32_16x16x32_bf16 v[82:85], v[152:155], v[200:203], v[82:85]
	v_mfma_f32_16x16x32_bf16 v[126:129], v[148:151], v[180:183], v[126:129]
	v_mfma_f32_16x16x32_bf16 v[122:125], v[156:159], v[180:183], v[122:125]
	v_mfma_f32_16x16x32_bf16 v[118:121], v[148:151], v[188:191], v[118:121]
	v_mfma_f32_16x16x32_bf16 v[114:117], v[156:159], v[188:191], v[114:117]
	v_mfma_f32_16x16x32_bf16 v[102:105], v[148:151], v[196:199], v[102:105]
	v_mfma_f32_16x16x32_bf16 v[98:101], v[156:159], v[196:199], v[98:101]
	v_mfma_f32_16x16x32_bf16 v[86:89], v[148:151], v[206:209], v[86:89]
	v_mfma_f32_16x16x32_bf16 v[82:85], v[156:159], v[206:209], v[82:85]
	v_mfma_f32_16x16x32_bf16 v[110:113], v[160:163], v[176:179], v[110:113]
	v_mfma_f32_16x16x32_bf16 v[106:109], v[168:171], v[176:179], v[106:109]
	v_mfma_f32_16x16x32_bf16 v[94:97], v[160:163], v[184:187], v[94:97]
	v_mfma_f32_16x16x32_bf16 v[90:93], v[168:171], v[184:187], v[90:93]
	v_mfma_f32_16x16x32_bf16 v[78:81], v[160:163], v[192:195], v[78:81]
	v_mfma_f32_16x16x32_bf16 v[74:77], v[168:171], v[192:195], v[74:77]
	v_mfma_f32_16x16x32_bf16 v[70:73], v[160:163], v[200:203], v[70:73]
	v_mfma_f32_16x16x32_bf16 v[66:69], v[168:171], v[200:203], v[66:69]
	v_mfma_f32_16x16x32_bf16 v[110:113], v[164:167], v[180:183], v[110:113]
	v_mfma_f32_16x16x32_bf16 v[106:109], v[172:175], v[180:183], v[106:109]
	v_mfma_f32_16x16x32_bf16 v[94:97], v[164:167], v[188:191], v[94:97]
	v_mfma_f32_16x16x32_bf16 v[90:93], v[172:175], v[188:191], v[90:93]
	v_mfma_f32_16x16x32_bf16 v[78:81], v[164:167], v[196:199], v[78:81]
	v_mfma_f32_16x16x32_bf16 v[74:77], v[172:175], v[196:199], v[74:77]
	v_mfma_f32_16x16x32_bf16 v[70:73], v[164:167], v[206:209], v[70:73]
	v_mfma_f32_16x16x32_bf16 v[66:69], v[172:175], v[206:209], v[66:69]
	s_setprio 0
	s_barrier
	s_mov_b32 m0, s87
	v_lshl_add_u64 v[210:211], s[66:67], 0, v[136:137]
	ds_read_b128 v[176:179], v142 offset:16384
	ds_read_b128 v[180:183], v142 offset:17408
	ds_read_b128 v[184:187], v142 offset:18432
	ds_read_b128 v[188:191], v142 offset:19456
	ds_read_b128 v[192:195], v142 offset:20480
	ds_read_b128 v[196:199], v142 offset:21504
	ds_read_b128 v[200:203], v142 offset:22528
	ds_read_b128 v[206:209], v142 offset:23552
	global_load_lds_dwordx4 v[210:211], off
	v_lshl_add_u64 v[212:213], s[66:67], 0, v[134:135]
	s_mov_b32 m0, s84
	v_lshl_add_u64 v[214:215], s[68:69], 0, v[136:137]
	global_load_lds_dwordx4 v[212:213], off
	s_mov_b32 m0, s86
	v_lshl_add_u64 v[216:217], s[64:65], 0, v[132:133]
	global_load_lds_dwordx4 v[214:215], off
	v_lshl_add_u64 v[214:215], s[68:69], 0, v[134:135]
	s_mov_b32 m0, s85
	s_nop 0
	global_load_lds_dwordx4 v[214:215], off
	v_lshl_add_u64 v[214:215], s[64:65], 0, v[130:131]
	s_mov_b32 m0, s16
	s_nop 0
	global_load_lds_dwordx4 v[214:215], off
	s_mov_b32 m0, s17
	s_nop 0
	global_load_lds_dwordx4 v[216:217], off
	s_waitcnt vmcnt(8)
	s_waitcnt lgkmcnt(0)
	s_setprio 1
	s_barrier
	v_mfma_f32_16x16x32_bf16 v[62:65], v[144:147], v[176:179], v[62:65]
	v_mfma_f32_16x16x32_bf16 v[58:61], v[152:155], v[176:179], v[58:61]
	v_mfma_f32_16x16x32_bf16 v[54:57], v[144:147], v[184:187], v[54:57]
	v_mfma_f32_16x16x32_bf16 v[50:53], v[152:155], v[184:187], v[50:53]
	v_mfma_f32_16x16x32_bf16 v[38:41], v[144:147], v[192:195], v[38:41]
	v_mfma_f32_16x16x32_bf16 v[34:37], v[152:155], v[192:195], v[34:37]
	v_mfma_f32_16x16x32_bf16 v[22:25], v[144:147], v[200:203], v[22:25]
	v_mfma_f32_16x16x32_bf16 v[18:21], v[152:155], v[200:203], v[18:21]
	v_mfma_f32_16x16x32_bf16 v[62:65], v[148:151], v[180:183], v[62:65]
	v_mfma_f32_16x16x32_bf16 v[58:61], v[156:159], v[180:183], v[58:61]
	v_mfma_f32_16x16x32_bf16 v[54:57], v[148:151], v[188:191], v[54:57]
	v_mfma_f32_16x16x32_bf16 v[50:53], v[156:159], v[188:191], v[50:53]
	v_mfma_f32_16x16x32_bf16 v[38:41], v[148:151], v[196:199], v[38:41]
	v_mfma_f32_16x16x32_bf16 v[34:37], v[156:159], v[196:199], v[34:37]
	v_mfma_f32_16x16x32_bf16 v[22:25], v[148:151], v[206:209], v[22:25]
	v_mfma_f32_16x16x32_bf16 v[18:21], v[156:159], v[206:209], v[18:21]
	v_mfma_f32_16x16x32_bf16 v[46:49], v[160:163], v[176:179], v[46:49]
	v_mfma_f32_16x16x32_bf16 v[42:45], v[168:171], v[176:179], v[42:45]
	v_mfma_f32_16x16x32_bf16 v[30:33], v[160:163], v[184:187], v[30:33]
	v_mfma_f32_16x16x32_bf16 v[26:29], v[168:171], v[184:187], v[26:29]
	v_mfma_f32_16x16x32_bf16 v[14:17], v[160:163], v[192:195], v[14:17]
	v_mfma_f32_16x16x32_bf16 v[10:13], v[168:171], v[192:195], v[10:13]
	v_mfma_f32_16x16x32_bf16 v[6:9], v[160:163], v[200:203], v[6:9]
	v_mfma_f32_16x16x32_bf16 v[2:5], v[168:171], v[200:203], v[2:5]
	v_mfma_f32_16x16x32_bf16 v[46:49], v[164:167], v[180:183], v[46:49]
	v_mfma_f32_16x16x32_bf16 v[42:45], v[172:175], v[180:183], v[42:45]
	v_mfma_f32_16x16x32_bf16 v[30:33], v[164:167], v[188:191], v[30:33]
	v_mfma_f32_16x16x32_bf16 v[26:29], v[172:175], v[188:191], v[26:29]
	v_mfma_f32_16x16x32_bf16 v[14:17], v[164:167], v[196:199], v[14:17]
	v_mfma_f32_16x16x32_bf16 v[10:13], v[172:175], v[196:199], v[10:13]
	v_mfma_f32_16x16x32_bf16 v[6:9], v[164:167], v[206:209], v[6:9]
	v_mfma_f32_16x16x32_bf16 v[2:5], v[172:175], v[206:209], v[2:5]
	s_setprio 0
	s_barrier
	v_add_u32_e32 v143, s83, v139
	ds_read_b128 v[144:147], v143
	ds_read_b128 v[148:151], v143 offset:1024
	ds_read_b128 v[152:155], v143 offset:2048
	ds_read_b128 v[156:159], v143 offset:3072
	v_add_u32_e32 v143, s82, v139
	ds_read_b128 v[160:163], v143
	ds_read_b128 v[164:167], v143 offset:1024
	ds_read_b128 v[168:171], v143 offset:2048
	ds_read_b128 v[172:175], v143 offset:3072
	s_mov_b32 m0, s18
	v_lshl_add_u64 v[218:219], s[48:49], 0, v[130:131]
	ds_read_b128 v[176:179], v142 offset:32768
	ds_read_b128 v[180:183], v142 offset:33792
	ds_read_b128 v[184:187], v142 offset:34816
	ds_read_b128 v[188:191], v142 offset:35840
	ds_read_b128 v[192:195], v142 offset:36864
	ds_read_b128 v[196:199], v142 offset:37888
	ds_read_b128 v[200:203], v142 offset:38912
	ds_read_b128 v[206:209], v142 offset:39936
	global_load_lds_dwordx4 v[218:219], off
	v_lshl_add_u64 v[218:219], s[48:49], 0, v[132:133]
	s_mov_b32 m0, s19
	s_nop 0
	global_load_lds_dwordx4 v[218:219], off
	s_waitcnt vmcnt(8)
	s_waitcnt lgkmcnt(0)
	s_setprio 1
	s_barrier
	v_mfma_f32_16x16x32_bf16 v[126:129], v[144:147], v[176:179], v[126:129]
	v_mfma_f32_16x16x32_bf16 v[122:125], v[152:155], v[176:179], v[122:125]
	v_mfma_f32_16x16x32_bf16 v[118:121], v[144:147], v[184:187], v[118:121]
	v_mfma_f32_16x16x32_bf16 v[114:117], v[152:155], v[184:187], v[114:117]
	v_mfma_f32_16x16x32_bf16 v[102:105], v[144:147], v[192:195], v[102:105]
	v_mfma_f32_16x16x32_bf16 v[98:101], v[152:155], v[192:195], v[98:101]
	v_mfma_f32_16x16x32_bf16 v[86:89], v[144:147], v[200:203], v[86:89]
	v_mfma_f32_16x16x32_bf16 v[82:85], v[152:155], v[200:203], v[82:85]
	v_mfma_f32_16x16x32_bf16 v[126:129], v[148:151], v[180:183], v[126:129]
	v_mfma_f32_16x16x32_bf16 v[122:125], v[156:159], v[180:183], v[122:125]
	v_mfma_f32_16x16x32_bf16 v[118:121], v[148:151], v[188:191], v[118:121]
	v_mfma_f32_16x16x32_bf16 v[114:117], v[156:159], v[188:191], v[114:117]
	v_mfma_f32_16x16x32_bf16 v[102:105], v[148:151], v[196:199], v[102:105]
	v_mfma_f32_16x16x32_bf16 v[98:101], v[156:159], v[196:199], v[98:101]
	v_mfma_f32_16x16x32_bf16 v[86:89], v[148:151], v[206:209], v[86:89]
	v_mfma_f32_16x16x32_bf16 v[82:85], v[156:159], v[206:209], v[82:85]
	v_mfma_f32_16x16x32_bf16 v[110:113], v[160:163], v[176:179], v[110:113]
	v_mfma_f32_16x16x32_bf16 v[106:109], v[168:171], v[176:179], v[106:109]
	v_mfma_f32_16x16x32_bf16 v[94:97], v[160:163], v[184:187], v[94:97]
	v_mfma_f32_16x16x32_bf16 v[90:93], v[168:171], v[184:187], v[90:93]
	v_mfma_f32_16x16x32_bf16 v[78:81], v[160:163], v[192:195], v[78:81]
	v_mfma_f32_16x16x32_bf16 v[74:77], v[168:171], v[192:195], v[74:77]
	v_mfma_f32_16x16x32_bf16 v[70:73], v[160:163], v[200:203], v[70:73]
	v_mfma_f32_16x16x32_bf16 v[66:69], v[168:171], v[200:203], v[66:69]
	v_mfma_f32_16x16x32_bf16 v[110:113], v[164:167], v[180:183], v[110:113]
	v_mfma_f32_16x16x32_bf16 v[106:109], v[172:175], v[180:183], v[106:109]
	v_mfma_f32_16x16x32_bf16 v[94:97], v[164:167], v[188:191], v[94:97]
	v_mfma_f32_16x16x32_bf16 v[90:93], v[172:175], v[188:191], v[90:93]
	v_mfma_f32_16x16x32_bf16 v[78:81], v[164:167], v[196:199], v[78:81]
	v_mfma_f32_16x16x32_bf16 v[74:77], v[172:175], v[196:199], v[74:77]
	v_mfma_f32_16x16x32_bf16 v[70:73], v[164:167], v[206:209], v[70:73]
	v_mfma_f32_16x16x32_bf16 v[66:69], v[172:175], v[206:209], v[66:69]
	s_setprio 0
	s_barrier
	s_mov_b32 m0, s81
	v_lshl_add_u64 v[210:211], v[210:211], 0, s[8:9]
	ds_read_b128 v[176:179], v142 offset:49152
	ds_read_b128 v[180:183], v142 offset:50176
	ds_read_b128 v[184:187], v142 offset:51200
	ds_read_b128 v[188:191], v142 offset:52224
	ds_read_b128 v[192:195], v142 offset:53248
	ds_read_b128 v[196:199], v142 offset:54272
	ds_read_b128 v[200:203], v142 offset:55296
	ds_read_b128 v[206:209], v142 offset:56320
	global_load_lds_dwordx4 v[210:211], off
	v_lshl_add_u64 v[210:211], v[212:213], 0, s[8:9]
	s_mov_b32 m0, s79
	s_nop 0
	global_load_lds_dwordx4 v[210:211], off
	v_lshl_add_u64 v[210:211], s[46:47], 0, v[136:137]
	s_mov_b32 m0, s80
	s_nop 0
	global_load_lds_dwordx4 v[210:211], off
	v_lshl_add_u64 v[210:211], s[46:47], 0, v[134:135]
	s_mov_b32 m0, s78
	s_nop 0
	global_load_lds_dwordx4 v[210:211], off
	v_lshl_add_u64 v[210:211], v[214:215], 0, s[8:9]
	s_mov_b32 m0, s30
	s_nop 0
	global_load_lds_dwordx4 v[210:211], off
	v_lshl_add_u64 v[210:211], v[216:217], 0, s[8:9]
	s_mov_b32 m0, s31
	s_nop 0
	global_load_lds_dwordx4 v[210:211], off
	s_waitcnt vmcnt(8)
	s_waitcnt lgkmcnt(0)
	s_setprio 1
	s_barrier
	v_mfma_f32_16x16x32_bf16 v[62:65], v[144:147], v[176:179], v[62:65]
	v_mfma_f32_16x16x32_bf16 v[58:61], v[152:155], v[176:179], v[58:61]
	v_mfma_f32_16x16x32_bf16 v[54:57], v[144:147], v[184:187], v[54:57]
	v_mfma_f32_16x16x32_bf16 v[50:53], v[152:155], v[184:187], v[50:53]
	v_mfma_f32_16x16x32_bf16 v[38:41], v[144:147], v[192:195], v[38:41]
	v_mfma_f32_16x16x32_bf16 v[34:37], v[152:155], v[192:195], v[34:37]
	v_mfma_f32_16x16x32_bf16 v[22:25], v[144:147], v[200:203], v[22:25]
	v_mfma_f32_16x16x32_bf16 v[18:21], v[152:155], v[200:203], v[18:21]
	v_mfma_f32_16x16x32_bf16 v[62:65], v[148:151], v[180:183], v[62:65]
	v_mfma_f32_16x16x32_bf16 v[58:61], v[156:159], v[180:183], v[58:61]
	v_mfma_f32_16x16x32_bf16 v[54:57], v[148:151], v[188:191], v[54:57]
	v_mfma_f32_16x16x32_bf16 v[50:53], v[156:159], v[188:191], v[50:53]
	v_mfma_f32_16x16x32_bf16 v[38:41], v[148:151], v[196:199], v[38:41]
	v_mfma_f32_16x16x32_bf16 v[34:37], v[156:159], v[196:199], v[34:37]
	v_mfma_f32_16x16x32_bf16 v[22:25], v[148:151], v[206:209], v[22:25]
	v_mfma_f32_16x16x32_bf16 v[18:21], v[156:159], v[206:209], v[18:21]
	v_mfma_f32_16x16x32_bf16 v[46:49], v[160:163], v[176:179], v[46:49]
	v_mfma_f32_16x16x32_bf16 v[42:45], v[168:171], v[176:179], v[42:45]
	v_mfma_f32_16x16x32_bf16 v[30:33], v[160:163], v[184:187], v[30:33]
	v_mfma_f32_16x16x32_bf16 v[26:29], v[168:171], v[184:187], v[26:29]
	v_mfma_f32_16x16x32_bf16 v[14:17], v[160:163], v[192:195], v[14:17]
	v_mfma_f32_16x16x32_bf16 v[10:13], v[168:171], v[192:195], v[10:13]
	v_mfma_f32_16x16x32_bf16 v[6:9], v[160:163], v[200:203], v[6:9]
	v_mfma_f32_16x16x32_bf16 v[2:5], v[168:171], v[200:203], v[2:5]
	v_mfma_f32_16x16x32_bf16 v[46:49], v[164:167], v[180:183], v[46:49]
	v_mfma_f32_16x16x32_bf16 v[42:45], v[172:175], v[180:183], v[42:45]
	v_mfma_f32_16x16x32_bf16 v[30:33], v[164:167], v[188:191], v[30:33]
	v_mfma_f32_16x16x32_bf16 v[26:29], v[172:175], v[188:191], v[26:29]
	v_mfma_f32_16x16x32_bf16 v[14:17], v[164:167], v[196:199], v[14:17]
	v_mfma_f32_16x16x32_bf16 v[10:13], v[172:175], v[196:199], v[10:13]
	v_mfma_f32_16x16x32_bf16 v[6:9], v[164:167], v[206:209], v[6:9]
	v_mfma_f32_16x16x32_bf16 v[2:5], v[172:175], v[206:209], v[2:5]
	s_setprio 0
	s_barrier
	s_movk_i32 s48, 0x100
	s_andn2_b64 vcc, exec, s[44:45]
	s_mov_b64 s[46:47], -1
	s_mov_b64 s[44:45], 0
	s_cbranch_vccz .LBB0_313
	s_and_b64 vcc, exec, s[10:11]
	s_cbranch_vccz .LBB0_316
	s_barrier

.LBB0_383:
	s_add_u32 s26, s0, s22
	s_addc_u32 s27, s1, s23
	s_and_b64 s[44:45], s[36:37], exec
	s_cselect_b32 s15, s27, s43
	s_cselect_b32 s39, s26, s42
	s_add_u32 s66, s42, 0x100
	s_addc_u32 s67, s43, 0
	s_mov_b32 s68, -2
	s_mov_b64 s[42:43], 0
	ds_read_b128 v[152:155], v146
	ds_read_b128 v[156:159], v146 offset:1024
	ds_read_b128 v[160:163], v146 offset:2048
	ds_read_b128 v[164:167], v146 offset:3072
	ds_read_b128 v[168:171], v147
	ds_read_b128 v[172:175], v147 offset:1024
	ds_read_b128 v[176:179], v147 offset:2048
	ds_read_b128 v[180:183], v147 offset:3072
	ds_read_b128 v[184:187], v148
	ds_read_b128 v[188:191], v148 offset:1024
	ds_read_b128 v[192:195], v148 offset:2048
	ds_read_b128 v[196:199], v148 offset:3072
	ds_read_b128 v[200:203], v148 offset:4096
	ds_read_b128 v[206:209], v148 offset:5120
	ds_read_b128 v[210:213], v148 offset:6144
	ds_read_b128 v[214:217], v148 offset:7168
	s_add_u32 s44, s42, 0x100
	s_addc_u32 s45, s43, 0
	s_add_u32 s46, s66, s42
	s_addc_u32 s47, s67, s43
	s_cmp_eq_u32 s68, 4
	s_cselect_b32 s48, 0, s44
	s_cselect_b32 s49, 0, s45
	s_cselect_b32 s46, s39, s46
	s_cselect_b32 s47, s15, s47
	s_add_u32 s48, s6, s48
	s_addc_u32 s49, s7, s49
	s_mov_b32 m0, s29
	v_lshl_add_u64 v[218:219], v[138:139], 0, s[42:43]
	global_load_lds_dwordx4 v[218:219], off
	v_lshl_add_u64 v[218:219], v[140:141], 0, s[42:43]
	s_mov_b32 m0, s30
	s_nop 0
	global_load_lds_dwordx4 v[218:219], off
	s_waitcnt vmcnt(8)
	s_waitcnt lgkmcnt(0)
	s_setprio 1
	s_barrier
	v_mfma_f32_16x16x32_bf16 v[126:129], v[152:155], v[184:187], 0
	v_mfma_f32_16x16x32_bf16 v[122:125], v[160:163], v[184:187], 0
	v_mfma_f32_16x16x32_bf16 v[118:121], v[152:155], v[192:195], 0
	v_mfma_f32_16x16x32_bf16 v[114:117], v[160:163], v[192:195], 0
	v_mfma_f32_16x16x32_bf16 v[102:105], v[152:155], v[200:203], 0
	v_mfma_f32_16x16x32_bf16 v[98:101], v[160:163], v[200:203], 0
	v_mfma_f32_16x16x32_bf16 v[86:89], v[152:155], v[210:213], 0
	v_mfma_f32_16x16x32_bf16 v[82:85], v[160:163], v[210:213], 0
	v_mfma_f32_16x16x32_bf16 v[126:129], v[156:159], v[188:191], v[126:129]
	v_mfma_f32_16x16x32_bf16 v[122:125], v[164:167], v[188:191], v[122:125]
	v_mfma_f32_16x16x32_bf16 v[118:121], v[156:159], v[196:199], v[118:121]
	v_mfma_f32_16x16x32_bf16 v[114:117], v[164:167], v[196:199], v[114:117]
	v_mfma_f32_16x16x32_bf16 v[102:105], v[156:159], v[206:209], v[102:105]
	v_mfma_f32_16x16x32_bf16 v[98:101], v[164:167], v[206:209], v[98:101]
	v_mfma_f32_16x16x32_bf16 v[86:89], v[156:159], v[214:217], v[86:89]
	v_mfma_f32_16x16x32_bf16 v[82:85], v[164:167], v[214:217], v[82:85]
	v_mfma_f32_16x16x32_bf16 v[110:113], v[168:171], v[184:187], 0
	v_mfma_f32_16x16x32_bf16 v[106:109], v[176:179], v[184:187], 0
	v_mfma_f32_16x16x32_bf16 v[94:97], v[168:171], v[192:195], 0
	v_mfma_f32_16x16x32_bf16 v[90:93], v[176:179], v[192:195], 0
	v_mfma_f32_16x16x32_bf16 v[78:81], v[168:171], v[200:203], 0
	v_mfma_f32_16x16x32_bf16 v[74:77], v[176:179], v[200:203], 0
	v_mfma_f32_16x16x32_bf16 v[70:73], v[168:171], v[210:213], 0
	v_mfma_f32_16x16x32_bf16 v[66:69], v[176:179], v[210:213], 0
	v_mfma_f32_16x16x32_bf16 v[110:113], v[172:175], v[188:191], v[110:113]
	v_mfma_f32_16x16x32_bf16 v[106:109], v[180:183], v[188:191], v[106:109]
	v_mfma_f32_16x16x32_bf16 v[94:97], v[172:175], v[196:199], v[94:97]
	v_mfma_f32_16x16x32_bf16 v[90:93], v[180:183], v[196:199], v[90:93]
	v_mfma_f32_16x16x32_bf16 v[78:81], v[172:175], v[206:209], v[78:81]
	v_mfma_f32_16x16x32_bf16 v[74:77], v[180:183], v[206:209], v[74:77]
	v_mfma_f32_16x16x32_bf16 v[70:73], v[172:175], v[214:217], v[70:73]
	v_mfma_f32_16x16x32_bf16 v[66:69], v[180:183], v[214:217], v[66:69]
	s_setprio 0
	s_barrier
	s_mov_b32 m0, s31
	v_lshl_add_u64 v[218:219], s[46:47], 0, v[134:135]
	s_add_u32 s42, s46, 0x20000
	ds_read_b128 v[184:187], v148 offset:16384
	ds_read_b128 v[188:191], v148 offset:17408
	ds_read_b128 v[192:195], v148 offset:18432
	ds_read_b128 v[196:199], v148 offset:19456
	ds_read_b128 v[200:203], v148 offset:20480
	ds_read_b128 v[206:209], v148 offset:21504
	ds_read_b128 v[210:213], v148 offset:22528
	ds_read_b128 v[214:217], v148 offset:23552
	global_load_lds_dwordx4 v[218:219], off
	v_lshl_add_u64 v[220:221], s[46:47], 0, v[130:131]
	s_mov_b32 m0, s33
	s_addc_u32 s43, s47, 0
	global_load_lds_dwordx4 v[220:221], off
	v_lshl_add_u64 v[222:223], s[42:43], 0, v[134:135]
	s_mov_b32 m0, s34
	v_lshl_add_u64 v[224:225], s[48:49], 0, v[132:133]
	global_load_lds_dwordx4 v[222:223], off
	v_lshl_add_u64 v[222:223], s[42:43], 0, v[130:131]
	s_mov_b32 m0, s35
	s_nop 0
	global_load_lds_dwordx4 v[222:223], off
	v_lshl_add_u64 v[222:223], s[48:49], 0, v[136:137]
	s_mov_b32 m0, s2
	s_nop 0
	global_load_lds_dwordx4 v[222:223], off
	s_mov_b32 m0, s3
	s_nop 0
	global_load_lds_dwordx4 v[224:225], off
	s_waitcnt vmcnt(8)
	s_waitcnt lgkmcnt(0)
	s_setprio 1
	s_barrier
	v_mfma_f32_16x16x32_bf16 v[62:65], v[152:155], v[184:187], 0
	v_mfma_f32_16x16x32_bf16 v[58:61], v[160:163], v[184:187], 0
	v_mfma_f32_16x16x32_bf16 v[54:57], v[152:155], v[192:195], 0
	v_mfma_f32_16x16x32_bf16 v[50:53], v[160:163], v[192:195], 0
	v_mfma_f32_16x16x32_bf16 v[38:41], v[152:155], v[200:203], 0
	v_mfma_f32_16x16x32_bf16 v[34:37], v[160:163], v[200:203], 0
	v_mfma_f32_16x16x32_bf16 v[22:25], v[152:155], v[210:213], 0
	v_mfma_f32_16x16x32_bf16 v[18:21], v[160:163], v[210:213], 0
	v_mfma_f32_16x16x32_bf16 v[62:65], v[156:159], v[188:191], v[62:65]
	v_mfma_f32_16x16x32_bf16 v[58:61], v[164:167], v[188:191], v[58:61]
	v_mfma_f32_16x16x32_bf16 v[54:57], v[156:159], v[196:199], v[54:57]
	v_mfma_f32_16x16x32_bf16 v[50:53], v[164:167], v[196:199], v[50:53]
	v_mfma_f32_16x16x32_bf16 v[38:41], v[156:159], v[206:209], v[38:41]
	v_mfma_f32_16x16x32_bf16 v[34:37], v[164:167], v[206:209], v[34:37]
	v_mfma_f32_16x16x32_bf16 v[22:25], v[156:159], v[214:217], v[22:25]
	v_mfma_f32_16x16x32_bf16 v[18:21], v[164:167], v[214:217], v[18:21]
	v_mfma_f32_16x16x32_bf16 v[46:49], v[168:171], v[184:187], 0
	v_mfma_f32_16x16x32_bf16 v[42:45], v[176:179], v[184:187], 0
	v_mfma_f32_16x16x32_bf16 v[30:33], v[168:171], v[192:195], 0
	v_mfma_f32_16x16x32_bf16 v[26:29], v[176:179], v[192:195], 0
	v_mfma_f32_16x16x32_bf16 v[14:17], v[168:171], v[200:203], 0
	v_mfma_f32_16x16x32_bf16 v[10:13], v[176:179], v[200:203], 0
	v_mfma_f32_16x16x32_bf16 v[6:9], v[168:171], v[210:213], 0
	v_mfma_f32_16x16x32_bf16 v[2:5], v[176:179], v[210:213], 0
	v_mfma_f32_16x16x32_bf16 v[46:49], v[172:175], v[188:191], v[46:49]
	v_mfma_f32_16x16x32_bf16 v[42:45], v[180:183], v[188:191], v[42:45]
	v_mfma_f32_16x16x32_bf16 v[30:33], v[172:175], v[196:199], v[30:33]
	v_mfma_f32_16x16x32_bf16 v[26:29], v[180:183], v[196:199], v[26:29]
	v_mfma_f32_16x16x32_bf16 v[14:17], v[172:175], v[206:209], v[14:17]
	v_mfma_f32_16x16x32_bf16 v[10:13], v[180:183], v[206:209], v[10:13]
	v_mfma_f32_16x16x32_bf16 v[6:9], v[172:175], v[214:217], v[6:9]
	v_mfma_f32_16x16x32_bf16 v[2:5], v[180:183], v[214:217], v[2:5]
	s_setprio 0
	s_barrier
	ds_read_b128 v[152:155], v149
	ds_read_b128 v[156:159], v149 offset:1024
	ds_read_b128 v[160:163], v149 offset:2048
	ds_read_b128 v[164:167], v149 offset:3072
	ds_read_b128 v[168:171], v150
	ds_read_b128 v[172:175], v150 offset:1024
	ds_read_b128 v[176:179], v150 offset:2048
	ds_read_b128 v[180:183], v150 offset:3072
	s_add_u32 s42, s48, 0x20000
	s_addc_u32 s43, s49, 0
	s_mov_b32 m0, s16
	v_lshl_add_u64 v[226:227], s[42:43], 0, v[136:137]
	ds_read_b128 v[184:187], v148 offset:32768
	ds_read_b128 v[188:191], v148 offset:33792
	ds_read_b128 v[192:195], v148 offset:34816
	ds_read_b128 v[196:199], v148 offset:35840
	ds_read_b128 v[200:203], v148 offset:36864
	ds_read_b128 v[206:209], v148 offset:37888
	ds_read_b128 v[210:213], v148 offset:38912
	ds_read_b128 v[214:217], v148 offset:39936
	global_load_lds_dwordx4 v[226:227], off
	v_lshl_add_u64 v[226:227], s[42:43], 0, v[132:133]
	s_mov_b32 m0, s17
	s_nop 0
	global_load_lds_dwordx4 v[226:227], off
	s_waitcnt vmcnt(8)
	s_waitcnt lgkmcnt(0)
	s_setprio 1
	s_barrier
	v_mfma_f32_16x16x32_bf16 v[126:129], v[152:155], v[184:187], v[126:129]
	v_mfma_f32_16x16x32_bf16 v[122:125], v[160:163], v[184:187], v[122:125]
	v_mfma_f32_16x16x32_bf16 v[118:121], v[152:155], v[192:195], v[118:121]
	v_mfma_f32_16x16x32_bf16 v[114:117], v[160:163], v[192:195], v[114:117]
	v_mfma_f32_16x16x32_bf16 v[102:105], v[152:155], v[200:203], v[102:105]
	v_mfma_f32_16x16x32_bf16 v[98:101], v[160:163], v[200:203], v[98:101]
	v_mfma_f32_16x16x32_bf16 v[86:89], v[152:155], v[210:213], v[86:89]
	v_mfma_f32_16x16x32_bf16 v[82:85], v[160:163], v[210:213], v[82:85]
	v_mfma_f32_16x16x32_bf16 v[126:129], v[156:159], v[188:191], v[126:129]
	v_mfma_f32_16x16x32_bf16 v[122:125], v[164:167], v[188:191], v[122:125]
	v_mfma_f32_16x16x32_bf16 v[118:121], v[156:159], v[196:199], v[118:121]
	v_mfma_f32_16x16x32_bf16 v[114:117], v[164:167], v[196:199], v[114:117]
	v_mfma_f32_16x16x32_bf16 v[102:105], v[156:159], v[206:209], v[102:105]
	v_mfma_f32_16x16x32_bf16 v[98:101], v[164:167], v[206:209], v[98:101]
	v_mfma_f32_16x16x32_bf16 v[86:89], v[156:159], v[214:217], v[86:89]
	v_mfma_f32_16x16x32_bf16 v[82:85], v[164:167], v[214:217], v[82:85]
	v_mfma_f32_16x16x32_bf16 v[110:113], v[168:171], v[184:187], v[110:113]
	v_mfma_f32_16x16x32_bf16 v[106:109], v[176:179], v[184:187], v[106:109]
	v_mfma_f32_16x16x32_bf16 v[94:97], v[168:171], v[192:195], v[94:97]
	v_mfma_f32_16x16x32_bf16 v[90:93], v[176:179], v[192:195], v[90:93]
	v_mfma_f32_16x16x32_bf16 v[78:81], v[168:171], v[200:203], v[78:81]
	v_mfma_f32_16x16x32_bf16 v[74:77], v[176:179], v[200:203], v[74:77]
	v_mfma_f32_16x16x32_bf16 v[70:73], v[168:171], v[210:213], v[70:73]
	v_mfma_f32_16x16x32_bf16 v[66:69], v[176:179], v[210:213], v[66:69]
	v_mfma_f32_16x16x32_bf16 v[110:113], v[172:175], v[188:191], v[110:113]
	v_mfma_f32_16x16x32_bf16 v[106:109], v[180:183], v[188:191], v[106:109]
	v_mfma_f32_16x16x32_bf16 v[94:97], v[172:175], v[196:199], v[94:97]
	v_mfma_f32_16x16x32_bf16 v[90:93], v[180:183], v[196:199], v[90:93]
	v_mfma_f32_16x16x32_bf16 v[78:81], v[172:175], v[206:209], v[78:81]
	v_mfma_f32_16x16x32_bf16 v[74:77], v[180:183], v[206:209], v[74:77]
	v_mfma_f32_16x16x32_bf16 v[70:73], v[172:175], v[214:217], v[70:73]
	v_mfma_f32_16x16x32_bf16 v[66:69], v[180:183], v[214:217], v[66:69]
	s_setprio 0
	s_barrier
	s_mov_b32 m0, s62
	v_lshl_add_u64 v[218:219], v[218:219], 0, s[10:11]
	s_add_u32 s42, s46, 0x20080
	ds_read_b128 v[184:187], v148 offset:49152
	ds_read_b128 v[188:191], v148 offset:50176
	ds_read_b128 v[192:195], v148 offset:51200
	ds_read_b128 v[196:199], v148 offset:52224
	ds_read_b128 v[200:203], v148 offset:53248
	ds_read_b128 v[206:209], v148 offset:54272
	ds_read_b128 v[210:213], v148 offset:55296
	ds_read_b128 v[214:217], v148 offset:56320
	global_load_lds_dwordx4 v[218:219], off
	v_lshl_add_u64 v[218:219], v[220:221], 0, s[10:11]
	s_mov_b32 m0, s63
	s_addc_u32 s43, s47, 0
	global_load_lds_dwordx4 v[218:219], off
	v_lshl_add_u64 v[218:219], s[42:43], 0, v[134:135]
	s_mov_b32 m0, s64
	s_nop 0
	global_load_lds_dwordx4 v[218:219], off
	v_lshl_add_u64 v[218:219], s[42:43], 0, v[130:131]
	s_mov_b32 m0, s65
	s_nop 0
	global_load_lds_dwordx4 v[218:219], off
	v_lshl_add_u64 v[218:219], v[222:223], 0, s[10:11]
	s_mov_b32 m0, s25
	s_nop 0
	global_load_lds_dwordx4 v[218:219], off
	v_lshl_add_u64 v[218:219], v[224:225], 0, s[10:11]
	s_mov_b32 m0, s28
	s_nop 0
	global_load_lds_dwordx4 v[218:219], off
	s_waitcnt vmcnt(8)
	s_waitcnt lgkmcnt(0)
	s_setprio 1
	s_barrier
	v_mfma_f32_16x16x32_bf16 v[62:65], v[152:155], v[184:187], v[62:65]
	v_mfma_f32_16x16x32_bf16 v[58:61], v[160:163], v[184:187], v[58:61]
	v_mfma_f32_16x16x32_bf16 v[54:57], v[152:155], v[192:195], v[54:57]
	v_mfma_f32_16x16x32_bf16 v[50:53], v[160:163], v[192:195], v[50:53]
	v_mfma_f32_16x16x32_bf16 v[38:41], v[152:155], v[200:203], v[38:41]
	v_mfma_f32_16x16x32_bf16 v[34:37], v[160:163], v[200:203], v[34:37]
	v_mfma_f32_16x16x32_bf16 v[22:25], v[152:155], v[210:213], v[22:25]
	v_mfma_f32_16x16x32_bf16 v[18:21], v[160:163], v[210:213], v[18:21]
	v_mfma_f32_16x16x32_bf16 v[62:65], v[156:159], v[188:191], v[62:65]
	v_mfma_f32_16x16x32_bf16 v[58:61], v[164:167], v[188:191], v[58:61]
	v_mfma_f32_16x16x32_bf16 v[54:57], v[156:159], v[196:199], v[54:57]
	v_mfma_f32_16x16x32_bf16 v[50:53], v[164:167], v[196:199], v[50:53]
	v_mfma_f32_16x16x32_bf16 v[38:41], v[156:159], v[206:209], v[38:41]
	v_mfma_f32_16x16x32_bf16 v[34:37], v[164:167], v[206:209], v[34:37]
	v_mfma_f32_16x16x32_bf16 v[22:25], v[156:159], v[214:217], v[22:25]
	v_mfma_f32_16x16x32_bf16 v[18:21], v[164:167], v[214:217], v[18:21]
	v_mfma_f32_16x16x32_bf16 v[46:49], v[168:171], v[184:187], v[46:49]
	v_mfma_f32_16x16x32_bf16 v[42:45], v[176:179], v[184:187], v[42:45]
	v_mfma_f32_16x16x32_bf16 v[30:33], v[168:171], v[192:195], v[30:33]
	v_mfma_f32_16x16x32_bf16 v[26:29], v[176:179], v[192:195], v[26:29]
	v_mfma_f32_16x16x32_bf16 v[14:17], v[168:171], v[200:203], v[14:17]
	v_mfma_f32_16x16x32_bf16 v[10:13], v[176:179], v[200:203], v[10:13]
	v_mfma_f32_16x16x32_bf16 v[6:9], v[168:171], v[210:213], v[6:9]
	v_mfma_f32_16x16x32_bf16 v[2:5], v[176:179], v[210:213], v[2:5]
	v_mfma_f32_16x16x32_bf16 v[46:49], v[172:175], v[188:191], v[46:49]
	v_mfma_f32_16x16x32_bf16 v[42:45], v[180:183], v[188:191], v[42:45]
	v_mfma_f32_16x16x32_bf16 v[30:33], v[172:175], v[196:199], v[30:33]
	v_mfma_f32_16x16x32_bf16 v[26:29], v[180:183], v[196:199], v[26:29]
	v_mfma_f32_16x16x32_bf16 v[14:17], v[172:175], v[206:209], v[14:17]
	v_mfma_f32_16x16x32_bf16 v[10:13], v[180:183], v[206:209], v[10:13]
	v_mfma_f32_16x16x32_bf16 v[6:9], v[172:175], v[214:217], v[6:9]
	v_mfma_f32_16x16x32_bf16 v[2:5], v[180:183], v[214:217], v[2:5]
	s_setprio 0
	s_barrier
	s_add_i32 s68, s68, 2
	s_cmp_gt_u32 s68, 5
	s_mov_b64 s[42:43], s[44:45]
.LBB0_384:
	ds_read_b128 v[152:155], v146
	ds_read_b128 v[156:159], v146 offset:1024
	ds_read_b128 v[160:163], v146 offset:2048
	ds_read_b128 v[164:167], v146 offset:3072
	ds_read_b128 v[168:171], v147
	ds_read_b128 v[172:175], v147 offset:1024
	ds_read_b128 v[176:179], v147 offset:2048
	ds_read_b128 v[180:183], v147 offset:3072
	ds_read_b128 v[184:187], v148
	ds_read_b128 v[188:191], v148 offset:1024
	ds_read_b128 v[192:195], v148 offset:2048
	ds_read_b128 v[196:199], v148 offset:3072
	ds_read_b128 v[200:203], v148 offset:4096
	ds_read_b128 v[206:209], v148 offset:5120
	ds_read_b128 v[210:213], v148 offset:6144
	ds_read_b128 v[214:217], v148 offset:7168
	s_add_u32 s44, s42, 0x100
	s_addc_u32 s45, s43, 0
	s_add_u32 s46, s66, s42
	s_addc_u32 s47, s67, s43
	s_cmp_eq_u32 s68, 4
	s_cselect_b32 s48, 0, s44
	s_cselect_b32 s49, 0, s45
	s_cselect_b32 s46, s39, s46
	s_cselect_b32 s47, s15, s47
	s_add_u32 s48, s6, s48
	s_addc_u32 s49, s7, s49
	s_mov_b32 m0, s29
	v_lshl_add_u64 v[218:219], v[138:139], 0, s[42:43]
	global_load_lds_dwordx4 v[218:219], off
	v_lshl_add_u64 v[218:219], v[140:141], 0, s[42:43]
	s_mov_b32 m0, s30
	s_nop 0
	global_load_lds_dwordx4 v[218:219], off
	s_waitcnt vmcnt(8)
	s_waitcnt lgkmcnt(0)
	s_setprio 1
	s_barrier
	v_mfma_f32_16x16x32_bf16 v[126:129], v[152:155], v[184:187], v[126:129]
	v_mfma_f32_16x16x32_bf16 v[122:125], v[160:163], v[184:187], v[122:125]
	v_mfma_f32_16x16x32_bf16 v[118:121], v[152:155], v[192:195], v[118:121]
	v_mfma_f32_16x16x32_bf16 v[114:117], v[160:163], v[192:195], v[114:117]
	v_mfma_f32_16x16x32_bf16 v[102:105], v[152:155], v[200:203], v[102:105]
	v_mfma_f32_16x16x32_bf16 v[98:101], v[160:163], v[200:203], v[98:101]
	v_mfma_f32_16x16x32_bf16 v[86:89], v[152:155], v[210:213], v[86:89]
	v_mfma_f32_16x16x32_bf16 v[82:85], v[160:163], v[210:213], v[82:85]
	v_mfma_f32_16x16x32_bf16 v[126:129], v[156:159], v[188:191], v[126:129]
	v_mfma_f32_16x16x32_bf16 v[122:125], v[164:167], v[188:191], v[122:125]
	v_mfma_f32_16x16x32_bf16 v[118:121], v[156:159], v[196:199], v[118:121]
	v_mfma_f32_16x16x32_bf16 v[114:117], v[164:167], v[196:199], v[114:117]
	v_mfma_f32_16x16x32_bf16 v[102:105], v[156:159], v[206:209], v[102:105]
	v_mfma_f32_16x16x32_bf16 v[98:101], v[164:167], v[206:209], v[98:101]
	v_mfma_f32_16x16x32_bf16 v[86:89], v[156:159], v[214:217], v[86:89]
	v_mfma_f32_16x16x32_bf16 v[82:85], v[164:167], v[214:217], v[82:85]
	v_mfma_f32_16x16x32_bf16 v[110:113], v[168:171], v[184:187], v[110:113]
	v_mfma_f32_16x16x32_bf16 v[106:109], v[176:179], v[184:187], v[106:109]
	v_mfma_f32_16x16x32_bf16 v[94:97], v[168:171], v[192:195], v[94:97]
	v_mfma_f32_16x16x32_bf16 v[90:93], v[176:179], v[192:195], v[90:93]
	v_mfma_f32_16x16x32_bf16 v[78:81], v[168:171], v[200:203], v[78:81]
	v_mfma_f32_16x16x32_bf16 v[74:77], v[176:179], v[200:203], v[74:77]
	v_mfma_f32_16x16x32_bf16 v[70:73], v[168:171], v[210:213], v[70:73]
	v_mfma_f32_16x16x32_bf16 v[66:69], v[176:179], v[210:213], v[66:69]
	v_mfma_f32_16x16x32_bf16 v[110:113], v[172:175], v[188:191], v[110:113]
	v_mfma_f32_16x16x32_bf16 v[106:109], v[180:183], v[188:191], v[106:109]
	v_mfma_f32_16x16x32_bf16 v[94:97], v[172:175], v[196:199], v[94:97]
	v_mfma_f32_16x16x32_bf16 v[90:93], v[180:183], v[196:199], v[90:93]
	v_mfma_f32_16x16x32_bf16 v[78:81], v[172:175], v[206:209], v[78:81]
	v_mfma_f32_16x16x32_bf16 v[74:77], v[180:183], v[206:209], v[74:77]
	v_mfma_f32_16x16x32_bf16 v[70:73], v[172:175], v[214:217], v[70:73]
	v_mfma_f32_16x16x32_bf16 v[66:69], v[180:183], v[214:217], v[66:69]
	s_setprio 0
	s_barrier
	s_mov_b32 m0, s31
	v_lshl_add_u64 v[218:219], s[46:47], 0, v[134:135]
	s_add_u32 s42, s46, 0x20000
	ds_read_b128 v[184:187], v148 offset:16384
	ds_read_b128 v[188:191], v148 offset:17408
	ds_read_b128 v[192:195], v148 offset:18432
	ds_read_b128 v[196:199], v148 offset:19456
	ds_read_b128 v[200:203], v148 offset:20480
	ds_read_b128 v[206:209], v148 offset:21504
	ds_read_b128 v[210:213], v148 offset:22528
	ds_read_b128 v[214:217], v148 offset:23552
	global_load_lds_dwordx4 v[218:219], off
	v_lshl_add_u64 v[220:221], s[46:47], 0, v[130:131]
	s_mov_b32 m0, s33
	s_addc_u32 s43, s47, 0
	global_load_lds_dwordx4 v[220:221], off
	v_lshl_add_u64 v[222:223], s[42:43], 0, v[134:135]
	s_mov_b32 m0, s34
	v_lshl_add_u64 v[224:225], s[48:49], 0, v[132:133]
	global_load_lds_dwordx4 v[222:223], off
	v_lshl_add_u64 v[222:223], s[42:43], 0, v[130:131]
	s_mov_b32 m0, s35
	s_nop 0
	global_load_lds_dwordx4 v[222:223], off
	v_lshl_add_u64 v[222:223], s[48:49], 0, v[136:137]
	s_mov_b32 m0, s2
	s_nop 0
	global_load_lds_dwordx4 v[222:223], off
	s_mov_b32 m0, s3
	s_nop 0
	global_load_lds_dwordx4 v[224:225], off
	s_waitcnt vmcnt(8)
	s_waitcnt lgkmcnt(0)
	s_setprio 1
	s_barrier
	v_mfma_f32_16x16x32_bf16 v[62:65], v[152:155], v[184:187], v[62:65]
	v_mfma_f32_16x16x32_bf16 v[58:61], v[160:163], v[184:187], v[58:61]
	v_mfma_f32_16x16x32_bf16 v[54:57], v[152:155], v[192:195], v[54:57]
	v_mfma_f32_16x16x32_bf16 v[50:53], v[160:163], v[192:195], v[50:53]
	v_mfma_f32_16x16x32_bf16 v[38:41], v[152:155], v[200:203], v[38:41]
	v_mfma_f32_16x16x32_bf16 v[34:37], v[160:163], v[200:203], v[34:37]
	v_mfma_f32_16x16x32_bf16 v[22:25], v[152:155], v[210:213], v[22:25]
	v_mfma_f32_16x16x32_bf16 v[18:21], v[160:163], v[210:213], v[18:21]
	v_mfma_f32_16x16x32_bf16 v[62:65], v[156:159], v[188:191], v[62:65]
	v_mfma_f32_16x16x32_bf16 v[58:61], v[164:167], v[188:191], v[58:61]
	v_mfma_f32_16x16x32_bf16 v[54:57], v[156:159], v[196:199], v[54:57]
	v_mfma_f32_16x16x32_bf16 v[50:53], v[164:167], v[196:199], v[50:53]
	v_mfma_f32_16x16x32_bf16 v[38:41], v[156:159], v[206:209], v[38:41]
	v_mfma_f32_16x16x32_bf16 v[34:37], v[164:167], v[206:209], v[34:37]
	v_mfma_f32_16x16x32_bf16 v[22:25], v[156:159], v[214:217], v[22:25]
	v_mfma_f32_16x16x32_bf16 v[18:21], v[164:167], v[214:217], v[18:21]
	v_mfma_f32_16x16x32_bf16 v[46:49], v[168:171], v[184:187], v[46:49]
	v_mfma_f32_16x16x32_bf16 v[42:45], v[176:179], v[184:187], v[42:45]
	v_mfma_f32_16x16x32_bf16 v[30:33], v[168:171], v[192:195], v[30:33]
	v_mfma_f32_16x16x32_bf16 v[26:29], v[176:179], v[192:195], v[26:29]
	v_mfma_f32_16x16x32_bf16 v[14:17], v[168:171], v[200:203], v[14:17]
	v_mfma_f32_16x16x32_bf16 v[10:13], v[176:179], v[200:203], v[10:13]
	v_mfma_f32_16x16x32_bf16 v[6:9], v[168:171], v[210:213], v[6:9]
	v_mfma_f32_16x16x32_bf16 v[2:5], v[176:179], v[210:213], v[2:5]
	v_mfma_f32_16x16x32_bf16 v[46:49], v[172:175], v[188:191], v[46:49]
	v_mfma_f32_16x16x32_bf16 v[42:45], v[180:183], v[188:191], v[42:45]
	v_mfma_f32_16x16x32_bf16 v[30:33], v[172:175], v[196:199], v[30:33]
	v_mfma_f32_16x16x32_bf16 v[26:29], v[180:183], v[196:199], v[26:29]
	v_mfma_f32_16x16x32_bf16 v[14:17], v[172:175], v[206:209], v[14:17]
	v_mfma_f32_16x16x32_bf16 v[10:13], v[180:183], v[206:209], v[10:13]
	v_mfma_f32_16x16x32_bf16 v[6:9], v[172:175], v[214:217], v[6:9]
	v_mfma_f32_16x16x32_bf16 v[2:5], v[180:183], v[214:217], v[2:5]
	s_setprio 0
	s_barrier
	ds_read_b128 v[152:155], v149
	ds_read_b128 v[156:159], v149 offset:1024
	ds_read_b128 v[160:163], v149 offset:2048
	ds_read_b128 v[164:167], v149 offset:3072
	ds_read_b128 v[168:171], v150
	ds_read_b128 v[172:175], v150 offset:1024
	ds_read_b128 v[176:179], v150 offset:2048
	ds_read_b128 v[180:183], v150 offset:3072
	s_add_u32 s42, s48, 0x20000
	s_addc_u32 s43, s49, 0
	s_mov_b32 m0, s16
	v_lshl_add_u64 v[226:227], s[42:43], 0, v[136:137]
	ds_read_b128 v[184:187], v148 offset:32768
	ds_read_b128 v[188:191], v148 offset:33792
	ds_read_b128 v[192:195], v148 offset:34816
	ds_read_b128 v[196:199], v148 offset:35840
	ds_read_b128 v[200:203], v148 offset:36864
	ds_read_b128 v[206:209], v148 offset:37888
	ds_read_b128 v[210:213], v148 offset:38912
	ds_read_b128 v[214:217], v148 offset:39936
	global_load_lds_dwordx4 v[226:227], off
	v_lshl_add_u64 v[226:227], s[42:43], 0, v[132:133]
	s_mov_b32 m0, s17
	s_nop 0
	global_load_lds_dwordx4 v[226:227], off
	s_waitcnt vmcnt(8)
	s_waitcnt lgkmcnt(0)
	s_setprio 1
	s_barrier
	v_mfma_f32_16x16x32_bf16 v[126:129], v[152:155], v[184:187], v[126:129]
	v_mfma_f32_16x16x32_bf16 v[122:125], v[160:163], v[184:187], v[122:125]
	v_mfma_f32_16x16x32_bf16 v[118:121], v[152:155], v[192:195], v[118:121]
	v_mfma_f32_16x16x32_bf16 v[114:117], v[160:163], v[192:195], v[114:117]
	v_mfma_f32_16x16x32_bf16 v[102:105], v[152:155], v[200:203], v[102:105]
	v_mfma_f32_16x16x32_bf16 v[98:101], v[160:163], v[200:203], v[98:101]
	v_mfma_f32_16x16x32_bf16 v[86:89], v[152:155], v[210:213], v[86:89]
	v_mfma_f32_16x16x32_bf16 v[82:85], v[160:163], v[210:213], v[82:85]
	v_mfma_f32_16x16x32_bf16 v[126:129], v[156:159], v[188:191], v[126:129]
	v_mfma_f32_16x16x32_bf16 v[122:125], v[164:167], v[188:191], v[122:125]
	v_mfma_f32_16x16x32_bf16 v[118:121], v[156:159], v[196:199], v[118:121]
	v_mfma_f32_16x16x32_bf16 v[114:117], v[164:167], v[196:199], v[114:117]
	v_mfma_f32_16x16x32_bf16 v[102:105], v[156:159], v[206:209], v[102:105]
	v_mfma_f32_16x16x32_bf16 v[98:101], v[164:167], v[206:209], v[98:101]
	v_mfma_f32_16x16x32_bf16 v[86:89], v[156:159], v[214:217], v[86:89]
	v_mfma_f32_16x16x32_bf16 v[82:85], v[164:167], v[214:217], v[82:85]
	v_mfma_f32_16x16x32_bf16 v[110:113], v[168:171], v[184:187], v[110:113]
	v_mfma_f32_16x16x32_bf16 v[106:109], v[176:179], v[184:187], v[106:109]
	v_mfma_f32_16x16x32_bf16 v[94:97], v[168:171], v[192:195], v[94:97]
	v_mfma_f32_16x16x32_bf16 v[90:93], v[176:179], v[192:195], v[90:93]
	v_mfma_f32_16x16x32_bf16 v[78:81], v[168:171], v[200:203], v[78:81]
	v_mfma_f32_16x16x32_bf16 v[74:77], v[176:179], v[200:203], v[74:77]
	v_mfma_f32_16x16x32_bf16 v[70:73], v[168:171], v[210:213], v[70:73]
	v_mfma_f32_16x16x32_bf16 v[66:69], v[176:179], v[210:213], v[66:69]
	v_mfma_f32_16x16x32_bf16 v[110:113], v[172:175], v[188:191], v[110:113]
	v_mfma_f32_16x16x32_bf16 v[106:109], v[180:183], v[188:191], v[106:109]
	v_mfma_f32_16x16x32_bf16 v[94:97], v[172:175], v[196:199], v[94:97]
	v_mfma_f32_16x16x32_bf16 v[90:93], v[180:183], v[196:199], v[90:93]
	v_mfma_f32_16x16x32_bf16 v[78:81], v[172:175], v[206:209], v[78:81]
	v_mfma_f32_16x16x32_bf16 v[74:77], v[180:183], v[206:209], v[74:77]
	v_mfma_f32_16x16x32_bf16 v[70:73], v[172:175], v[214:217], v[70:73]
	v_mfma_f32_16x16x32_bf16 v[66:69], v[180:183], v[214:217], v[66:69]
	s_setprio 0
	s_barrier
	s_mov_b32 m0, s62
	v_lshl_add_u64 v[218:219], v[218:219], 0, s[10:11]
	s_add_u32 s42, s46, 0x20080
	ds_read_b128 v[184:187], v148 offset:49152
	ds_read_b128 v[188:191], v148 offset:50176
	ds_read_b128 v[192:195], v148 offset:51200
	ds_read_b128 v[196:199], v148 offset:52224
	ds_read_b128 v[200:203], v148 offset:53248
	ds_read_b128 v[206:209], v148 offset:54272
	ds_read_b128 v[210:213], v148 offset:55296
	ds_read_b128 v[214:217], v148 offset:56320
	global_load_lds_dwordx4 v[218:219], off
	v_lshl_add_u64 v[218:219], v[220:221], 0, s[10:11]
	s_mov_b32 m0, s63
	s_addc_u32 s43, s47, 0
	global_load_lds_dwordx4 v[218:219], off
	v_lshl_add_u64 v[218:219], s[42:43], 0, v[134:135]
	s_mov_b32 m0, s64
	s_nop 0
	global_load_lds_dwordx4 v[218:219], off
	v_lshl_add_u64 v[218:219], s[42:43], 0, v[130:131]
	s_mov_b32 m0, s65
	s_nop 0
	global_load_lds_dwordx4 v[218:219], off
	v_lshl_add_u64 v[218:219], v[222:223], 0, s[10:11]
	s_mov_b32 m0, s25
	s_nop 0
	global_load_lds_dwordx4 v[218:219], off
	v_lshl_add_u64 v[218:219], v[224:225], 0, s[10:11]
	s_mov_b32 m0, s28
	s_nop 0
	global_load_lds_dwordx4 v[218:219], off
	s_waitcnt vmcnt(8)
	s_waitcnt lgkmcnt(0)
	s_setprio 1
	s_barrier
	v_mfma_f32_16x16x32_bf16 v[62:65], v[152:155], v[184:187], v[62:65]
	v_mfma_f32_16x16x32_bf16 v[58:61], v[160:163], v[184:187], v[58:61]
	v_mfma_f32_16x16x32_bf16 v[54:57], v[152:155], v[192:195], v[54:57]
	v_mfma_f32_16x16x32_bf16 v[50:53], v[160:163], v[192:195], v[50:53]
	v_mfma_f32_16x16x32_bf16 v[38:41], v[152:155], v[200:203], v[38:41]
	v_mfma_f32_16x16x32_bf16 v[34:37], v[160:163], v[200:203], v[34:37]
	v_mfma_f32_16x16x32_bf16 v[22:25], v[152:155], v[210:213], v[22:25]
	v_mfma_f32_16x16x32_bf16 v[18:21], v[160:163], v[210:213], v[18:21]
	v_mfma_f32_16x16x32_bf16 v[62:65], v[156:159], v[188:191], v[62:65]
	v_mfma_f32_16x16x32_bf16 v[58:61], v[164:167], v[188:191], v[58:61]
	v_mfma_f32_16x16x32_bf16 v[54:57], v[156:159], v[196:199], v[54:57]
	v_mfma_f32_16x16x32_bf16 v[50:53], v[164:167], v[196:199], v[50:53]
	v_mfma_f32_16x16x32_bf16 v[38:41], v[156:159], v[206:209], v[38:41]
	v_mfma_f32_16x16x32_bf16 v[34:37], v[164:167], v[206:209], v[34:37]
	v_mfma_f32_16x16x32_bf16 v[22:25], v[156:159], v[214:217], v[22:25]
	v_mfma_f32_16x16x32_bf16 v[18:21], v[164:167], v[214:217], v[18:21]
	v_mfma_f32_16x16x32_bf16 v[46:49], v[168:171], v[184:187], v[46:49]
	v_mfma_f32_16x16x32_bf16 v[42:45], v[176:179], v[184:187], v[42:45]
	v_mfma_f32_16x16x32_bf16 v[30:33], v[168:171], v[192:195], v[30:33]
	v_mfma_f32_16x16x32_bf16 v[26:29], v[176:179], v[192:195], v[26:29]
	v_mfma_f32_16x16x32_bf16 v[14:17], v[168:171], v[200:203], v[14:17]
	v_mfma_f32_16x16x32_bf16 v[10:13], v[176:179], v[200:203], v[10:13]
	v_mfma_f32_16x16x32_bf16 v[6:9], v[168:171], v[210:213], v[6:9]
	v_mfma_f32_16x16x32_bf16 v[2:5], v[176:179], v[210:213], v[2:5]
	v_mfma_f32_16x16x32_bf16 v[46:49], v[172:175], v[188:191], v[46:49]
	v_mfma_f32_16x16x32_bf16 v[42:45], v[180:183], v[188:191], v[42:45]
	v_mfma_f32_16x16x32_bf16 v[30:33], v[172:175], v[196:199], v[30:33]
	v_mfma_f32_16x16x32_bf16 v[26:29], v[180:183], v[196:199], v[26:29]
	v_mfma_f32_16x16x32_bf16 v[14:17], v[172:175], v[206:209], v[14:17]
	v_mfma_f32_16x16x32_bf16 v[10:13], v[180:183], v[206:209], v[10:13]
	v_mfma_f32_16x16x32_bf16 v[6:9], v[172:175], v[214:217], v[6:9]
	v_mfma_f32_16x16x32_bf16 v[2:5], v[180:183], v[214:217], v[2:5]
	s_setprio 0
	s_barrier
	s_add_i32 s68, s68, 2
	s_cmp_gt_u32 s68, 5
	s_mov_b64 s[42:43], s[44:45]
	s_cbranch_scc0 .LBB0_384
	s_and_b64 vcc, exec, s[12:13]
	s_cbranch_vccz .LBB0_387
	s_barrier

.LBB0_406:
	ds_read_b128 v[146:149], v141
	ds_read_b128 v[150:153], v141 offset:1024
	ds_read_b128 v[154:157], v141 offset:2048
	ds_read_b128 v[158:161], v141 offset:3072
	ds_read_b128 v[162:165], v143
	ds_read_b128 v[166:169], v143 offset:1024
	ds_read_b128 v[170:173], v143 offset:2048
	ds_read_b128 v[174:177], v143 offset:3072
	ds_read_b128 v[178:181], v144
	ds_read_b128 v[182:185], v144 offset:1024
	ds_read_b128 v[186:189], v144 offset:2048
	ds_read_b128 v[190:193], v144 offset:3072
	ds_read_b128 v[194:197], v144 offset:4096
	ds_read_b128 v[198:201], v144 offset:5120
	ds_read_b128 v[206:209], v144 offset:6144
	ds_read_b128 v[210:213], v144 offset:7168
	s_lshl_b32 s74, s12, 7
	s_add_i32 s12, s12, 2
	v_cndmask_b32_e64 v138, 0, 1, s[66:67]
	s_lshl_b64 s[66:67], s[12:13], 7
	s_and_b64 s[68:69], s[64:65], exec
	s_cselect_b32 s66, 0, s66
	s_cselect_b32 s67, 0, s67
	s_add_u32 s70, s8, s66
	s_addc_u32 s71, s9, s67
	s_lshl_b64 s[66:67], s[12:13], 12
	s_add_u32 s12, s48, s66
	s_addc_u32 s66, s49, s67
	s_and_b64 s[64:65], s[64:65], exec
	s_cselect_b32 s73, s14, s66
	s_cselect_b32 s72, s15, s12
	s_add_u32 s76, s10, s74
	s_addc_u32 s77, s11, 0
	s_add_i32 s91, s62, s16
	s_add_i32 m0, s17, 0xc000
	s_add_i32 s92, s17, 0xe000
	s_add_i32 s88, s91, 0x2000
	s_add_u32 s74, s72, 0x10000
	s_addc_u32 s75, s73, 0
	s_add_i32 s90, s63, s16
	s_add_i32 s89, s90, 0x2000
	s_add_i32 s87, 0, 0x18000
	s_add_i32 s86, 0, 0x1c000
	s_add_u32 s68, s70, 0x10000
	s_addc_u32 s69, s71, 0
	s_add_u32 s64, s72, 0x1000
	s_addc_u32 s65, s73, 0
	s_add_i32 s85, s87, s16
	s_add_i32 s83, s85, 0x2000
	s_add_u32 s66, s72, 0x11000
	s_addc_u32 s67, s73, 0
	s_add_i32 s84, s86, s16
	s_add_i32 s12, s84, 0x2000
	v_cmp_ne_u32_e32 vcc, 1, v138
	v_lshl_add_u64 v[202:203], s[76:77], 0, v[136:137]
	v_lshl_add_u64 v[202:203], v[202:203], 0, s[36:37]
	global_load_lds_dwordx4 v[202:203], off
	v_lshl_add_u64 v[202:203], s[76:77], 0, v[132:133]
	v_lshl_add_u64 v[202:203], v[202:203], 0, s[36:37]
	s_mov_b32 m0, s92
	s_nop 0
	global_load_lds_dwordx4 v[202:203], off
	s_waitcnt vmcnt(8)
	s_waitcnt lgkmcnt(0)
	s_setprio 1
	s_barrier
	v_mfma_f32_16x16x32_bf16 v[126:129], v[146:149], v[178:181], v[126:129]
	v_mfma_f32_16x16x32_bf16 v[122:125], v[154:157], v[178:181], v[122:125]
	v_mfma_f32_16x16x32_bf16 v[118:121], v[146:149], v[186:189], v[118:121]
	v_mfma_f32_16x16x32_bf16 v[110:113], v[154:157], v[186:189], v[110:113]
	v_mfma_f32_16x16x32_bf16 v[102:105], v[146:149], v[194:197], v[102:105]
	v_mfma_f32_16x16x32_bf16 v[98:101], v[154:157], v[194:197], v[98:101]
	v_mfma_f32_16x16x32_bf16 v[86:89], v[146:149], v[206:209], v[86:89]
	v_mfma_f32_16x16x32_bf16 v[82:85], v[154:157], v[206:209], v[82:85]
	v_mfma_f32_16x16x32_bf16 v[126:129], v[150:153], v[182:185], v[126:129]
	v_mfma_f32_16x16x32_bf16 v[122:125], v[158:161], v[182:185], v[122:125]
	v_mfma_f32_16x16x32_bf16 v[118:121], v[150:153], v[190:193], v[118:121]
	v_mfma_f32_16x16x32_bf16 v[110:113], v[158:161], v[190:193], v[110:113]
	v_mfma_f32_16x16x32_bf16 v[102:105], v[150:153], v[198:201], v[102:105]
	v_mfma_f32_16x16x32_bf16 v[98:101], v[158:161], v[198:201], v[98:101]
	v_mfma_f32_16x16x32_bf16 v[86:89], v[150:153], v[210:213], v[86:89]
	v_mfma_f32_16x16x32_bf16 v[82:85], v[158:161], v[210:213], v[82:85]
	v_mfma_f32_16x16x32_bf16 v[114:117], v[162:165], v[178:181], v[114:117]
	v_mfma_f32_16x16x32_bf16 v[106:109], v[170:173], v[178:181], v[106:109]
	v_mfma_f32_16x16x32_bf16 v[94:97], v[162:165], v[186:189], v[94:97]
	v_mfma_f32_16x16x32_bf16 v[90:93], v[170:173], v[186:189], v[90:93]
	v_mfma_f32_16x16x32_bf16 v[78:81], v[162:165], v[194:197], v[78:81]
	v_mfma_f32_16x16x32_bf16 v[74:77], v[170:173], v[194:197], v[74:77]
	v_mfma_f32_16x16x32_bf16 v[70:73], v[162:165], v[206:209], v[70:73]
	v_mfma_f32_16x16x32_bf16 v[66:69], v[170:173], v[206:209], v[66:69]
	v_mfma_f32_16x16x32_bf16 v[114:117], v[166:169], v[182:185], v[114:117]
	v_mfma_f32_16x16x32_bf16 v[106:109], v[174:177], v[182:185], v[106:109]
	v_mfma_f32_16x16x32_bf16 v[94:97], v[166:169], v[190:193], v[94:97]
	v_mfma_f32_16x16x32_bf16 v[90:93], v[174:177], v[190:193], v[90:93]
	v_mfma_f32_16x16x32_bf16 v[78:81], v[166:169], v[198:201], v[78:81]
	v_mfma_f32_16x16x32_bf16 v[74:77], v[174:177], v[198:201], v[74:77]
	v_mfma_f32_16x16x32_bf16 v[70:73], v[166:169], v[210:213], v[70:73]
	v_mfma_f32_16x16x32_bf16 v[66:69], v[174:177], v[210:213], v[66:69]
	s_setprio 0
	s_barrier
	s_mov_b32 m0, s91
	v_lshl_add_u64 v[202:203], s[72:73], 0, v[134:135]
	ds_read_b128 v[178:181], v144 offset:16384
	ds_read_b128 v[182:185], v144 offset:17408
	ds_read_b128 v[186:189], v144 offset:18432
	ds_read_b128 v[190:193], v144 offset:19456
	ds_read_b128 v[194:197], v144 offset:20480
	ds_read_b128 v[198:201], v144 offset:21504
	ds_read_b128 v[206:209], v144 offset:22528
	ds_read_b128 v[210:213], v144 offset:23552
	global_load_lds_dwordx4 v[202:203], off
	v_lshl_add_u64 v[202:203], s[72:73], 0, v[130:131]
	s_mov_b32 m0, s88
	v_lshl_add_u64 v[214:215], s[70:71], 0, v[132:133]
	global_load_lds_dwordx4 v[202:203], off
	v_lshl_add_u64 v[202:203], s[74:75], 0, v[134:135]
	s_mov_b32 m0, s90
	s_nop 0
	global_load_lds_dwordx4 v[202:203], off
	v_lshl_add_u64 v[202:203], s[74:75], 0, v[130:131]
	s_mov_b32 m0, s89
	s_nop 0
	global_load_lds_dwordx4 v[202:203], off
	v_lshl_add_u64 v[202:203], s[70:71], 0, v[136:137]
	s_mov_b32 m0, s17
	s_nop 0
	global_load_lds_dwordx4 v[202:203], off
	s_mov_b32 m0, s18
	s_nop 0
	global_load_lds_dwordx4 v[214:215], off
	s_waitcnt vmcnt(8)
	s_waitcnt lgkmcnt(0)
	s_setprio 1
	s_barrier
	v_mfma_f32_16x16x32_bf16 v[62:65], v[146:149], v[178:181], v[62:65]
	v_mfma_f32_16x16x32_bf16 v[58:61], v[154:157], v[178:181], v[58:61]
	v_mfma_f32_16x16x32_bf16 v[54:57], v[146:149], v[186:189], v[54:57]
	v_mfma_f32_16x16x32_bf16 v[50:53], v[154:157], v[186:189], v[50:53]
	v_mfma_f32_16x16x32_bf16 v[38:41], v[146:149], v[194:197], v[38:41]
	v_mfma_f32_16x16x32_bf16 v[34:37], v[154:157], v[194:197], v[34:37]
	v_mfma_f32_16x16x32_bf16 v[22:25], v[146:149], v[206:209], v[22:25]
	v_mfma_f32_16x16x32_bf16 v[18:21], v[154:157], v[206:209], v[18:21]
	v_mfma_f32_16x16x32_bf16 v[62:65], v[150:153], v[182:185], v[62:65]
	v_mfma_f32_16x16x32_bf16 v[58:61], v[158:161], v[182:185], v[58:61]
	v_mfma_f32_16x16x32_bf16 v[54:57], v[150:153], v[190:193], v[54:57]
	v_mfma_f32_16x16x32_bf16 v[50:53], v[158:161], v[190:193], v[50:53]
	v_mfma_f32_16x16x32_bf16 v[38:41], v[150:153], v[198:201], v[38:41]
	v_mfma_f32_16x16x32_bf16 v[34:37], v[158:161], v[198:201], v[34:37]
	v_mfma_f32_16x16x32_bf16 v[22:25], v[150:153], v[210:213], v[22:25]
	v_mfma_f32_16x16x32_bf16 v[18:21], v[158:161], v[210:213], v[18:21]
	v_mfma_f32_16x16x32_bf16 v[46:49], v[162:165], v[178:181], v[46:49]
	v_mfma_f32_16x16x32_bf16 v[42:45], v[170:173], v[178:181], v[42:45]
	v_mfma_f32_16x16x32_bf16 v[30:33], v[162:165], v[186:189], v[30:33]
	v_mfma_f32_16x16x32_bf16 v[26:29], v[170:173], v[186:189], v[26:29]
	v_mfma_f32_16x16x32_bf16 v[14:17], v[162:165], v[194:197], v[14:17]
	v_mfma_f32_16x16x32_bf16 v[10:13], v[170:173], v[194:197], v[10:13]
	v_mfma_f32_16x16x32_bf16 v[6:9], v[162:165], v[206:209], v[6:9]
	v_mfma_f32_16x16x32_bf16 v[2:5], v[170:173], v[206:209], v[2:5]
	v_mfma_f32_16x16x32_bf16 v[46:49], v[166:169], v[182:185], v[46:49]
	v_mfma_f32_16x16x32_bf16 v[42:45], v[174:177], v[182:185], v[42:45]
	v_mfma_f32_16x16x32_bf16 v[30:33], v[166:169], v[190:193], v[30:33]
	v_mfma_f32_16x16x32_bf16 v[26:29], v[174:177], v[190:193], v[26:29]
	v_mfma_f32_16x16x32_bf16 v[14:17], v[166:169], v[198:201], v[14:17]
	v_mfma_f32_16x16x32_bf16 v[10:13], v[174:177], v[198:201], v[10:13]
	v_mfma_f32_16x16x32_bf16 v[6:9], v[166:169], v[210:213], v[6:9]
	v_mfma_f32_16x16x32_bf16 v[2:5], v[174:177], v[210:213], v[2:5]
	s_setprio 0
	s_barrier
	v_add_u32_e32 v138, s87, v140
	ds_read_b128 v[146:149], v138
	ds_read_b128 v[150:153], v138 offset:1024
	ds_read_b128 v[154:157], v138 offset:2048
	ds_read_b128 v[158:161], v138 offset:3072
	v_add_u32_e32 v138, s86, v140
	ds_read_b128 v[162:165], v138
	ds_read_b128 v[166:169], v138 offset:1024
	ds_read_b128 v[170:173], v138 offset:2048
	ds_read_b128 v[174:177], v138 offset:3072
	s_mov_b32 m0, s19
	v_lshl_add_u64 v[216:217], s[68:69], 0, v[136:137]
	ds_read_b128 v[178:181], v144 offset:32768
	ds_read_b128 v[182:185], v144 offset:33792
	ds_read_b128 v[186:189], v144 offset:34816
	ds_read_b128 v[190:193], v144 offset:35840
	ds_read_b128 v[194:197], v144 offset:36864
	ds_read_b128 v[198:201], v144 offset:37888
	ds_read_b128 v[206:209], v144 offset:38912
	ds_read_b128 v[210:213], v144 offset:39936
	global_load_lds_dwordx4 v[216:217], off
	v_lshl_add_u64 v[216:217], s[68:69], 0, v[132:133]
	s_mov_b32 m0, s24
	s_nop 0
	global_load_lds_dwordx4 v[216:217], off
	s_waitcnt vmcnt(8)
	s_waitcnt lgkmcnt(0)
	s_setprio 1
	s_barrier
	v_mfma_f32_16x16x32_bf16 v[126:129], v[146:149], v[178:181], v[126:129]
	v_mfma_f32_16x16x32_bf16 v[122:125], v[154:157], v[178:181], v[122:125]
	v_mfma_f32_16x16x32_bf16 v[118:121], v[146:149], v[186:189], v[118:121]
	v_mfma_f32_16x16x32_bf16 v[110:113], v[154:157], v[186:189], v[110:113]
	v_mfma_f32_16x16x32_bf16 v[102:105], v[146:149], v[194:197], v[102:105]
	v_mfma_f32_16x16x32_bf16 v[98:101], v[154:157], v[194:197], v[98:101]
	v_mfma_f32_16x16x32_bf16 v[86:89], v[146:149], v[206:209], v[86:89]
	v_mfma_f32_16x16x32_bf16 v[82:85], v[154:157], v[206:209], v[82:85]
	v_mfma_f32_16x16x32_bf16 v[126:129], v[150:153], v[182:185], v[126:129]
	v_mfma_f32_16x16x32_bf16 v[122:125], v[158:161], v[182:185], v[122:125]
	v_mfma_f32_16x16x32_bf16 v[118:121], v[150:153], v[190:193], v[118:121]
	v_mfma_f32_16x16x32_bf16 v[110:113], v[158:161], v[190:193], v[110:113]
	v_mfma_f32_16x16x32_bf16 v[102:105], v[150:153], v[198:201], v[102:105]
	v_mfma_f32_16x16x32_bf16 v[98:101], v[158:161], v[198:201], v[98:101]
	v_mfma_f32_16x16x32_bf16 v[86:89], v[150:153], v[210:213], v[86:89]
	v_mfma_f32_16x16x32_bf16 v[82:85], v[158:161], v[210:213], v[82:85]
	v_mfma_f32_16x16x32_bf16 v[114:117], v[162:165], v[178:181], v[114:117]
	v_mfma_f32_16x16x32_bf16 v[106:109], v[170:173], v[178:181], v[106:109]
	v_mfma_f32_16x16x32_bf16 v[94:97], v[162:165], v[186:189], v[94:97]
	v_mfma_f32_16x16x32_bf16 v[90:93], v[170:173], v[186:189], v[90:93]
	v_mfma_f32_16x16x32_bf16 v[78:81], v[162:165], v[194:197], v[78:81]
	v_mfma_f32_16x16x32_bf16 v[74:77], v[170:173], v[194:197], v[74:77]
	v_mfma_f32_16x16x32_bf16 v[70:73], v[162:165], v[206:209], v[70:73]
	v_mfma_f32_16x16x32_bf16 v[66:69], v[170:173], v[206:209], v[66:69]
	v_mfma_f32_16x16x32_bf16 v[114:117], v[166:169], v[182:185], v[114:117]
	v_mfma_f32_16x16x32_bf16 v[106:109], v[174:177], v[182:185], v[106:109]
	v_mfma_f32_16x16x32_bf16 v[94:97], v[166:169], v[190:193], v[94:97]
	v_mfma_f32_16x16x32_bf16 v[90:93], v[174:177], v[190:193], v[90:93]
	v_mfma_f32_16x16x32_bf16 v[78:81], v[166:169], v[198:201], v[78:81]
	v_mfma_f32_16x16x32_bf16 v[74:77], v[174:177], v[198:201], v[74:77]
	v_mfma_f32_16x16x32_bf16 v[70:73], v[166:169], v[210:213], v[70:73]
	v_mfma_f32_16x16x32_bf16 v[66:69], v[174:177], v[210:213], v[66:69]
	s_setprio 0
	s_barrier
	s_mov_b32 m0, s85
	v_lshl_add_u64 v[216:217], s[64:65], 0, v[134:135]
	ds_read_b128 v[178:181], v144 offset:49152
	ds_read_b128 v[182:185], v144 offset:50176
	ds_read_b128 v[186:189], v144 offset:51200
	ds_read_b128 v[190:193], v144 offset:52224
	ds_read_b128 v[194:197], v144 offset:53248
	ds_read_b128 v[198:201], v144 offset:54272
	ds_read_b128 v[206:209], v144 offset:55296
	ds_read_b128 v[210:213], v144 offset:56320
	global_load_lds_dwordx4 v[216:217], off
	v_lshl_add_u64 v[216:217], s[64:65], 0, v[130:131]
	s_mov_b32 m0, s83
	v_lshl_add_u64 v[202:203], v[202:203], 0, s[36:37]
	global_load_lds_dwordx4 v[216:217], off
	v_lshl_add_u64 v[216:217], s[66:67], 0, v[134:135]
	s_mov_b32 m0, s84
	s_nop 0
	global_load_lds_dwordx4 v[216:217], off
	v_lshl_add_u64 v[216:217], s[66:67], 0, v[130:131]
	s_mov_b32 m0, s12
	s_nop 0
	global_load_lds_dwordx4 v[216:217], off
	s_mov_b32 m0, s31
	s_nop 0
	global_load_lds_dwordx4 v[202:203], off
	v_lshl_add_u64 v[202:203], v[214:215], 0, s[36:37]
	s_mov_b32 m0, s33
	s_nop 0
	global_load_lds_dwordx4 v[202:203], off
	s_waitcnt vmcnt(8)
	s_waitcnt lgkmcnt(0)
	s_setprio 1
	s_barrier
	v_mfma_f32_16x16x32_bf16 v[62:65], v[146:149], v[178:181], v[62:65]
	v_mfma_f32_16x16x32_bf16 v[58:61], v[154:157], v[178:181], v[58:61]
	v_mfma_f32_16x16x32_bf16 v[54:57], v[146:149], v[186:189], v[54:57]
	v_mfma_f32_16x16x32_bf16 v[50:53], v[154:157], v[186:189], v[50:53]
	v_mfma_f32_16x16x32_bf16 v[38:41], v[146:149], v[194:197], v[38:41]
	v_mfma_f32_16x16x32_bf16 v[34:37], v[154:157], v[194:197], v[34:37]
	v_mfma_f32_16x16x32_bf16 v[22:25], v[146:149], v[206:209], v[22:25]
	v_mfma_f32_16x16x32_bf16 v[18:21], v[154:157], v[206:209], v[18:21]
	v_mfma_f32_16x16x32_bf16 v[62:65], v[150:153], v[182:185], v[62:65]
	v_mfma_f32_16x16x32_bf16 v[58:61], v[158:161], v[182:185], v[58:61]
	v_mfma_f32_16x16x32_bf16 v[54:57], v[150:153], v[190:193], v[54:57]
	v_mfma_f32_16x16x32_bf16 v[50:53], v[158:161], v[190:193], v[50:53]
	v_mfma_f32_16x16x32_bf16 v[38:41], v[150:153], v[198:201], v[38:41]
	v_mfma_f32_16x16x32_bf16 v[34:37], v[158:161], v[198:201], v[34:37]
	v_mfma_f32_16x16x32_bf16 v[22:25], v[150:153], v[210:213], v[22:25]
	v_mfma_f32_16x16x32_bf16 v[18:21], v[158:161], v[210:213], v[18:21]
	v_mfma_f32_16x16x32_bf16 v[46:49], v[162:165], v[178:181], v[46:49]
	v_mfma_f32_16x16x32_bf16 v[42:45], v[170:173], v[178:181], v[42:45]
	v_mfma_f32_16x16x32_bf16 v[30:33], v[162:165], v[186:189], v[30:33]
	v_mfma_f32_16x16x32_bf16 v[26:29], v[170:173], v[186:189], v[26:29]
	v_mfma_f32_16x16x32_bf16 v[14:17], v[162:165], v[194:197], v[14:17]
	v_mfma_f32_16x16x32_bf16 v[10:13], v[170:173], v[194:197], v[10:13]
	v_mfma_f32_16x16x32_bf16 v[6:9], v[162:165], v[206:209], v[6:9]
	v_mfma_f32_16x16x32_bf16 v[2:5], v[170:173], v[206:209], v[2:5]
	v_mfma_f32_16x16x32_bf16 v[46:49], v[166:169], v[182:185], v[46:49]
	v_mfma_f32_16x16x32_bf16 v[42:45], v[174:177], v[182:185], v[42:45]
	v_mfma_f32_16x16x32_bf16 v[30:33], v[166:169], v[190:193], v[30:33]
	v_mfma_f32_16x16x32_bf16 v[26:29], v[174:177], v[190:193], v[26:29]
	v_mfma_f32_16x16x32_bf16 v[14:17], v[166:169], v[198:201], v[14:17]
	v_mfma_f32_16x16x32_bf16 v[10:13], v[174:177], v[198:201], v[10:13]
	v_mfma_f32_16x16x32_bf16 v[6:9], v[166:169], v[210:213], v[6:9]
	v_mfma_f32_16x16x32_bf16 v[2:5], v[174:177], v[210:213], v[2:5]
	s_setprio 0
	s_barrier
	s_mov_b64 s[66:67], 0
	s_mov_b64 s[64:65], -1
	s_mov_b32 s12, 2
	s_cbranch_vccz .LBB0_406
	s_and_b64 vcc, exec, s[22:23]
	s_cbranch_vccz .LBB0_409
	s_barrier

.LBB0_476:
	s_add_u32 s22, s2, s49
	s_addc_u32 s23, s3, s29
	s_and_b64 s[26:27], s[20:21], exec
	s_cselect_b32 s63, s23, s37
	s_cselect_b32 s64, s22, s36
	s_add_u32 s26, s16, s12
	s_addc_u32 s27, s17, s13
	s_and_b64 s[42:43], s[20:21], exec
	s_cselect_b32 s65, s27, s39
	s_cselect_b32 s66, s26, s38
	s_add_u32 s36, s36, 0x20080
	s_addc_u32 s37, s37, 0
	s_add_u32 s67, s38, 0x100
	s_addc_u32 s68, s39, 0
	s_mov_b32 s69, -2
	ds_read_b128 v[148:151], v144
	ds_read_b128 v[152:155], v144 offset:1024
	ds_read_b128 v[156:159], v144 offset:2048
	ds_read_b128 v[160:163], v144 offset:3072
	ds_read_b128 v[164:167], v145
	ds_read_b128 v[168:171], v145 offset:1024
	ds_read_b128 v[172:175], v145 offset:2048
	ds_read_b128 v[176:179], v145 offset:3072
	ds_read_b128 v[180:183], v146
	ds_read_b128 v[184:187], v146 offset:1024
	ds_read_b128 v[188:191], v146 offset:2048
	ds_read_b128 v[192:195], v146 offset:3072
	ds_read_b128 v[196:199], v146 offset:4096
	ds_read_b128 v[200:203], v146 offset:5120
	ds_read_b128 v[206:209], v146 offset:6144
	ds_read_b128 v[210:213], v146 offset:7168
	s_add_u32 s38, s36, 0xfffe0080
	s_addc_u32 s39, s37, -1
	s_cmp_eq_u32 s69, 4
	s_cselect_b32 s43, s63, s39
	s_cselect_b32 s42, s64, s38
	s_cselect_b32 s39, s65, s68
	s_cselect_b32 s38, s66, s67
	s_add_i32 m0, s19, 0xc000
	v_lshl_add_u64 v[214:215], s[36:37], 0, v[138:139]
	global_load_lds_dwordx4 v[214:215], off
	v_lshl_add_u64 v[214:215], s[36:37], 0, v[140:141]
	s_add_i32 m0, s19, 0xe000
	s_nop 0
	global_load_lds_dwordx4 v[214:215], off
	s_waitcnt vmcnt(8)
	s_waitcnt lgkmcnt(0)
	s_setprio 1
	s_barrier
	v_mfma_f32_16x16x32_bf16 v[126:129], v[148:151], v[180:183], 0
	v_mfma_f32_16x16x32_bf16 v[122:125], v[156:159], v[180:183], 0
	v_mfma_f32_16x16x32_bf16 v[118:121], v[148:151], v[188:191], 0
	v_mfma_f32_16x16x32_bf16 v[114:117], v[156:159], v[188:191], 0
	v_mfma_f32_16x16x32_bf16 v[102:105], v[148:151], v[196:199], 0
	v_mfma_f32_16x16x32_bf16 v[98:101], v[156:159], v[196:199], 0
	v_mfma_f32_16x16x32_bf16 v[86:89], v[148:151], v[206:209], 0
	v_mfma_f32_16x16x32_bf16 v[82:85], v[156:159], v[206:209], 0
	v_mfma_f32_16x16x32_bf16 v[126:129], v[152:155], v[184:187], v[126:129]
	v_mfma_f32_16x16x32_bf16 v[122:125], v[160:163], v[184:187], v[122:125]
	v_mfma_f32_16x16x32_bf16 v[118:121], v[152:155], v[192:195], v[118:121]
	v_mfma_f32_16x16x32_bf16 v[114:117], v[160:163], v[192:195], v[114:117]
	v_mfma_f32_16x16x32_bf16 v[102:105], v[152:155], v[200:203], v[102:105]
	v_mfma_f32_16x16x32_bf16 v[98:101], v[160:163], v[200:203], v[98:101]
	v_mfma_f32_16x16x32_bf16 v[86:89], v[152:155], v[210:213], v[86:89]
	v_mfma_f32_16x16x32_bf16 v[82:85], v[160:163], v[210:213], v[82:85]
	v_mfma_f32_16x16x32_bf16 v[110:113], v[164:167], v[180:183], 0
	v_mfma_f32_16x16x32_bf16 v[106:109], v[172:175], v[180:183], 0
	v_mfma_f32_16x16x32_bf16 v[94:97], v[164:167], v[188:191], 0
	v_mfma_f32_16x16x32_bf16 v[90:93], v[172:175], v[188:191], 0
	v_mfma_f32_16x16x32_bf16 v[78:81], v[164:167], v[196:199], 0
	v_mfma_f32_16x16x32_bf16 v[74:77], v[172:175], v[196:199], 0
	v_mfma_f32_16x16x32_bf16 v[70:73], v[164:167], v[206:209], 0
	v_mfma_f32_16x16x32_bf16 v[66:69], v[172:175], v[206:209], 0
	v_mfma_f32_16x16x32_bf16 v[110:113], v[168:171], v[184:187], v[110:113]
	v_mfma_f32_16x16x32_bf16 v[106:109], v[176:179], v[184:187], v[106:109]
	v_mfma_f32_16x16x32_bf16 v[94:97], v[168:171], v[192:195], v[94:97]
	v_mfma_f32_16x16x32_bf16 v[90:93], v[176:179], v[192:195], v[90:93]
	v_mfma_f32_16x16x32_bf16 v[78:81], v[168:171], v[200:203], v[78:81]
	v_mfma_f32_16x16x32_bf16 v[74:77], v[176:179], v[200:203], v[74:77]
	v_mfma_f32_16x16x32_bf16 v[70:73], v[168:171], v[210:213], v[70:73]
	v_mfma_f32_16x16x32_bf16 v[66:69], v[176:179], v[210:213], v[66:69]
	s_setprio 0
	s_barrier
	s_add_i32 s70, s35, s18
	v_lshl_add_u64 v[214:215], s[38:39], 0, v[134:135]
	s_mov_b32 m0, s70
	ds_read_b128 v[180:183], v146 offset:16384
	ds_read_b128 v[184:187], v146 offset:17408
	ds_read_b128 v[188:191], v146 offset:18432
	ds_read_b128 v[192:195], v146 offset:19456
	ds_read_b128 v[196:199], v146 offset:20480
	ds_read_b128 v[200:203], v146 offset:21504
	ds_read_b128 v[206:209], v146 offset:22528
	ds_read_b128 v[210:213], v146 offset:23552
	global_load_lds_dwordx4 v[214:215], off
	s_add_i32 m0, s70, 0x2000
	s_add_u32 s70, s38, 0x200000
	v_lshl_add_u64 v[216:217], s[38:39], 0, v[130:131]
	s_addc_u32 s71, s39, 0
	s_add_i32 s72, s44, s18
	global_load_lds_dwordx4 v[216:217], off
	v_lshl_add_u64 v[218:219], s[70:71], 0, v[134:135]
	s_mov_b32 m0, s72
	v_lshl_add_u64 v[220:221], s[42:43], 0, v[132:133]
	global_load_lds_dwordx4 v[218:219], off
	v_lshl_add_u64 v[218:219], s[70:71], 0, v[130:131]
	s_add_i32 m0, s72, 0x2000
	s_nop 0
	global_load_lds_dwordx4 v[218:219], off
	v_lshl_add_u64 v[218:219], s[42:43], 0, v[136:137]
	s_mov_b32 m0, s19
	s_nop 0
	global_load_lds_dwordx4 v[218:219], off
	s_mov_b32 m0, s24
	s_nop 0
	global_load_lds_dwordx4 v[220:221], off
	s_waitcnt vmcnt(8)
	s_waitcnt lgkmcnt(0)
	s_setprio 1
	s_barrier
	v_mfma_f32_16x16x32_bf16 v[62:65], v[148:151], v[180:183], 0
	v_mfma_f32_16x16x32_bf16 v[58:61], v[156:159], v[180:183], 0
	v_mfma_f32_16x16x32_bf16 v[54:57], v[148:151], v[188:191], 0
	v_mfma_f32_16x16x32_bf16 v[50:53], v[156:159], v[188:191], 0
	v_mfma_f32_16x16x32_bf16 v[38:41], v[148:151], v[196:199], 0
	v_mfma_f32_16x16x32_bf16 v[34:37], v[156:159], v[196:199], 0
	v_mfma_f32_16x16x32_bf16 v[22:25], v[148:151], v[206:209], 0
	v_mfma_f32_16x16x32_bf16 v[18:21], v[156:159], v[206:209], 0
	v_mfma_f32_16x16x32_bf16 v[62:65], v[152:155], v[184:187], v[62:65]
	v_mfma_f32_16x16x32_bf16 v[58:61], v[160:163], v[184:187], v[58:61]
	v_mfma_f32_16x16x32_bf16 v[54:57], v[152:155], v[192:195], v[54:57]
	v_mfma_f32_16x16x32_bf16 v[50:53], v[160:163], v[192:195], v[50:53]
	v_mfma_f32_16x16x32_bf16 v[38:41], v[152:155], v[200:203], v[38:41]
	v_mfma_f32_16x16x32_bf16 v[34:37], v[160:163], v[200:203], v[34:37]
	v_mfma_f32_16x16x32_bf16 v[22:25], v[152:155], v[210:213], v[22:25]
	v_mfma_f32_16x16x32_bf16 v[18:21], v[160:163], v[210:213], v[18:21]
	v_mfma_f32_16x16x32_bf16 v[46:49], v[164:167], v[180:183], 0
	v_mfma_f32_16x16x32_bf16 v[42:45], v[172:175], v[180:183], 0
	v_mfma_f32_16x16x32_bf16 v[30:33], v[164:167], v[188:191], 0
	v_mfma_f32_16x16x32_bf16 v[26:29], v[172:175], v[188:191], 0
	v_mfma_f32_16x16x32_bf16 v[14:17], v[164:167], v[196:199], 0
	v_mfma_f32_16x16x32_bf16 v[10:13], v[172:175], v[196:199], 0
	v_mfma_f32_16x16x32_bf16 v[6:9], v[164:167], v[206:209], 0
	v_mfma_f32_16x16x32_bf16 v[2:5], v[172:175], v[206:209], 0
	v_mfma_f32_16x16x32_bf16 v[46:49], v[168:171], v[184:187], v[46:49]
	v_mfma_f32_16x16x32_bf16 v[42:45], v[176:179], v[184:187], v[42:45]
	v_mfma_f32_16x16x32_bf16 v[30:33], v[168:171], v[192:195], v[30:33]
	v_mfma_f32_16x16x32_bf16 v[26:29], v[176:179], v[192:195], v[26:29]
	v_mfma_f32_16x16x32_bf16 v[14:17], v[168:171], v[200:203], v[14:17]
	v_mfma_f32_16x16x32_bf16 v[10:13], v[176:179], v[200:203], v[10:13]
	v_mfma_f32_16x16x32_bf16 v[6:9], v[168:171], v[210:213], v[6:9]
	v_mfma_f32_16x16x32_bf16 v[2:5], v[176:179], v[210:213], v[2:5]
	s_setprio 0
	s_barrier
	s_add_i32 s70, 0, 0x18000
	v_add_u32_e32 v147, s70, v143
	s_add_i32 s71, 0, 0x1c000
	ds_read_b128 v[148:151], v147
	ds_read_b128 v[152:155], v147 offset:1024
	ds_read_b128 v[156:159], v147 offset:2048
	ds_read_b128 v[160:163], v147 offset:3072
	v_add_u32_e32 v147, s71, v143
	ds_read_b128 v[164:167], v147
	ds_read_b128 v[168:171], v147 offset:1024
	ds_read_b128 v[172:175], v147 offset:2048
	ds_read_b128 v[176:179], v147 offset:3072
	s_add_u32 s42, s42, 0x20000
	s_addc_u32 s43, s43, 0
	s_mov_b32 m0, s25
	v_lshl_add_u64 v[222:223], s[42:43], 0, v[136:137]
	ds_read_b128 v[180:183], v146 offset:32768
	ds_read_b128 v[184:187], v146 offset:33792
	ds_read_b128 v[188:191], v146 offset:34816
	ds_read_b128 v[192:195], v146 offset:35840
	ds_read_b128 v[196:199], v146 offset:36864
	ds_read_b128 v[200:203], v146 offset:37888
	ds_read_b128 v[206:209], v146 offset:38912
	ds_read_b128 v[210:213], v146 offset:39936
	global_load_lds_dwordx4 v[222:223], off
	v_lshl_add_u64 v[222:223], s[42:43], 0, v[132:133]
	s_mov_b32 m0, s28
	s_nop 0
	global_load_lds_dwordx4 v[222:223], off
	s_waitcnt vmcnt(8)
	s_waitcnt lgkmcnt(0)
	s_setprio 1
	s_barrier
	v_mfma_f32_16x16x32_bf16 v[126:129], v[148:151], v[180:183], v[126:129]
	v_mfma_f32_16x16x32_bf16 v[122:125], v[156:159], v[180:183], v[122:125]
	v_mfma_f32_16x16x32_bf16 v[118:121], v[148:151], v[188:191], v[118:121]
	v_mfma_f32_16x16x32_bf16 v[114:117], v[156:159], v[188:191], v[114:117]
	v_mfma_f32_16x16x32_bf16 v[102:105], v[148:151], v[196:199], v[102:105]
	v_mfma_f32_16x16x32_bf16 v[98:101], v[156:159], v[196:199], v[98:101]
	v_mfma_f32_16x16x32_bf16 v[86:89], v[148:151], v[206:209], v[86:89]
	v_mfma_f32_16x16x32_bf16 v[82:85], v[156:159], v[206:209], v[82:85]
	v_mfma_f32_16x16x32_bf16 v[126:129], v[152:155], v[184:187], v[126:129]
	v_mfma_f32_16x16x32_bf16 v[122:125], v[160:163], v[184:187], v[122:125]
	v_mfma_f32_16x16x32_bf16 v[118:121], v[152:155], v[192:195], v[118:121]
	v_mfma_f32_16x16x32_bf16 v[114:117], v[160:163], v[192:195], v[114:117]
	v_mfma_f32_16x16x32_bf16 v[102:105], v[152:155], v[200:203], v[102:105]
	v_mfma_f32_16x16x32_bf16 v[98:101], v[160:163], v[200:203], v[98:101]
	v_mfma_f32_16x16x32_bf16 v[86:89], v[152:155], v[210:213], v[86:89]
	v_mfma_f32_16x16x32_bf16 v[82:85], v[160:163], v[210:213], v[82:85]
	v_mfma_f32_16x16x32_bf16 v[110:113], v[164:167], v[180:183], v[110:113]
	v_mfma_f32_16x16x32_bf16 v[106:109], v[172:175], v[180:183], v[106:109]
	v_mfma_f32_16x16x32_bf16 v[94:97], v[164:167], v[188:191], v[94:97]
	v_mfma_f32_16x16x32_bf16 v[90:93], v[172:175], v[188:191], v[90:93]
	v_mfma_f32_16x16x32_bf16 v[78:81], v[164:167], v[196:199], v[78:81]
	v_mfma_f32_16x16x32_bf16 v[74:77], v[172:175], v[196:199], v[74:77]
	v_mfma_f32_16x16x32_bf16 v[70:73], v[164:167], v[206:209], v[70:73]
	v_mfma_f32_16x16x32_bf16 v[66:69], v[172:175], v[206:209], v[66:69]
	v_mfma_f32_16x16x32_bf16 v[110:113], v[168:171], v[184:187], v[110:113]
	v_mfma_f32_16x16x32_bf16 v[106:109], v[176:179], v[184:187], v[106:109]
	v_mfma_f32_16x16x32_bf16 v[94:97], v[168:171], v[192:195], v[94:97]
	v_mfma_f32_16x16x32_bf16 v[90:93], v[176:179], v[192:195], v[90:93]
	v_mfma_f32_16x16x32_bf16 v[78:81], v[168:171], v[200:203], v[78:81]
	v_mfma_f32_16x16x32_bf16 v[74:77], v[176:179], v[200:203], v[74:77]
	v_mfma_f32_16x16x32_bf16 v[70:73], v[168:171], v[210:213], v[70:73]
	v_mfma_f32_16x16x32_bf16 v[66:69], v[176:179], v[210:213], v[66:69]
	s_setprio 0
	s_barrier
	s_add_i32 s42, s70, s18
	v_lshl_add_u64 v[214:215], v[214:215], 0, s[8:9]
	s_mov_b32 m0, s42
	ds_read_b128 v[180:183], v146 offset:49152
	ds_read_b128 v[184:187], v146 offset:50176
	ds_read_b128 v[188:191], v146 offset:51200
	ds_read_b128 v[192:195], v146 offset:52224
	ds_read_b128 v[196:199], v146 offset:53248
	ds_read_b128 v[200:203], v146 offset:54272
	ds_read_b128 v[206:209], v146 offset:55296
	ds_read_b128 v[210:213], v146 offset:56320
	global_load_lds_dwordx4 v[214:215], off
	s_add_i32 m0, s42, 0x2000
	s_add_u32 s38, s38, 0x200080
	v_lshl_add_u64 v[214:215], v[216:217], 0, s[8:9]
	s_addc_u32 s39, s39, 0
	s_add_i32 s42, s71, s18
	global_load_lds_dwordx4 v[214:215], off
	v_lshl_add_u64 v[214:215], s[38:39], 0, v[134:135]
	s_mov_b32 m0, s42
	s_nop 0
	global_load_lds_dwordx4 v[214:215], off
	v_lshl_add_u64 v[214:215], s[38:39], 0, v[130:131]
	s_add_i32 m0, s42, 0x2000
	s_nop 0
	global_load_lds_dwordx4 v[214:215], off
	v_lshl_add_u64 v[214:215], v[218:219], 0, s[8:9]
	s_mov_b32 m0, s33
	s_nop 0
	global_load_lds_dwordx4 v[214:215], off
	v_lshl_add_u64 v[214:215], v[220:221], 0, s[8:9]
	s_mov_b32 m0, s34
	s_nop 0
	global_load_lds_dwordx4 v[214:215], off
	s_waitcnt vmcnt(8)
	s_waitcnt lgkmcnt(0)
	s_setprio 1
	s_barrier
	v_mfma_f32_16x16x32_bf16 v[62:65], v[148:151], v[180:183], v[62:65]
	v_mfma_f32_16x16x32_bf16 v[58:61], v[156:159], v[180:183], v[58:61]
	v_mfma_f32_16x16x32_bf16 v[54:57], v[148:151], v[188:191], v[54:57]
	v_mfma_f32_16x16x32_bf16 v[50:53], v[156:159], v[188:191], v[50:53]
	v_mfma_f32_16x16x32_bf16 v[38:41], v[148:151], v[196:199], v[38:41]
	v_mfma_f32_16x16x32_bf16 v[34:37], v[156:159], v[196:199], v[34:37]
	v_mfma_f32_16x16x32_bf16 v[22:25], v[148:151], v[206:209], v[22:25]
	v_mfma_f32_16x16x32_bf16 v[18:21], v[156:159], v[206:209], v[18:21]
	v_mfma_f32_16x16x32_bf16 v[62:65], v[152:155], v[184:187], v[62:65]
	v_mfma_f32_16x16x32_bf16 v[58:61], v[160:163], v[184:187], v[58:61]
	v_mfma_f32_16x16x32_bf16 v[54:57], v[152:155], v[192:195], v[54:57]
	v_mfma_f32_16x16x32_bf16 v[50:53], v[160:163], v[192:195], v[50:53]
	v_mfma_f32_16x16x32_bf16 v[38:41], v[152:155], v[200:203], v[38:41]
	v_mfma_f32_16x16x32_bf16 v[34:37], v[160:163], v[200:203], v[34:37]
	v_mfma_f32_16x16x32_bf16 v[22:25], v[152:155], v[210:213], v[22:25]
	v_mfma_f32_16x16x32_bf16 v[18:21], v[160:163], v[210:213], v[18:21]
	v_mfma_f32_16x16x32_bf16 v[46:49], v[164:167], v[180:183], v[46:49]
	v_mfma_f32_16x16x32_bf16 v[42:45], v[172:175], v[180:183], v[42:45]
	v_mfma_f32_16x16x32_bf16 v[30:33], v[164:167], v[188:191], v[30:33]
	v_mfma_f32_16x16x32_bf16 v[26:29], v[172:175], v[188:191], v[26:29]
	v_mfma_f32_16x16x32_bf16 v[14:17], v[164:167], v[196:199], v[14:17]
	v_mfma_f32_16x16x32_bf16 v[10:13], v[172:175], v[196:199], v[10:13]
	v_mfma_f32_16x16x32_bf16 v[6:9], v[164:167], v[206:209], v[6:9]
	v_mfma_f32_16x16x32_bf16 v[2:5], v[172:175], v[206:209], v[2:5]
	v_mfma_f32_16x16x32_bf16 v[46:49], v[168:171], v[184:187], v[46:49]
	v_mfma_f32_16x16x32_bf16 v[42:45], v[176:179], v[184:187], v[42:45]
	v_mfma_f32_16x16x32_bf16 v[30:33], v[168:171], v[192:195], v[30:33]
	v_mfma_f32_16x16x32_bf16 v[26:29], v[176:179], v[192:195], v[26:29]
	v_mfma_f32_16x16x32_bf16 v[14:17], v[168:171], v[200:203], v[14:17]
	v_mfma_f32_16x16x32_bf16 v[10:13], v[176:179], v[200:203], v[10:13]
	v_mfma_f32_16x16x32_bf16 v[6:9], v[168:171], v[210:213], v[6:9]
	v_mfma_f32_16x16x32_bf16 v[2:5], v[176:179], v[210:213], v[2:5]
	s_setprio 0
	s_barrier
	s_add_i32 s69, s69, 2
	s_add_u32 s36, s36, 0x100
	s_addc_u32 s37, s37, 0
	s_add_u32 s67, s67, 0x100
	s_addc_u32 s68, s68, 0
	s_cmp_gt_u32 s69, 5
.LBB0_477:
	ds_read_b128 v[148:151], v144
	ds_read_b128 v[152:155], v144 offset:1024
	ds_read_b128 v[156:159], v144 offset:2048
	ds_read_b128 v[160:163], v144 offset:3072
	ds_read_b128 v[164:167], v145
	ds_read_b128 v[168:171], v145 offset:1024
	ds_read_b128 v[172:175], v145 offset:2048
	ds_read_b128 v[176:179], v145 offset:3072
	ds_read_b128 v[180:183], v146
	ds_read_b128 v[184:187], v146 offset:1024
	ds_read_b128 v[188:191], v146 offset:2048
	ds_read_b128 v[192:195], v146 offset:3072
	ds_read_b128 v[196:199], v146 offset:4096
	ds_read_b128 v[200:203], v146 offset:5120
	ds_read_b128 v[206:209], v146 offset:6144
	ds_read_b128 v[210:213], v146 offset:7168
	s_add_u32 s38, s36, 0xfffe0080
	s_addc_u32 s39, s37, -1
	s_cmp_eq_u32 s69, 4
	s_cselect_b32 s43, s63, s39
	s_cselect_b32 s42, s64, s38
	s_cselect_b32 s39, s65, s68
	s_cselect_b32 s38, s66, s67
	s_add_i32 m0, s19, 0xc000
	v_lshl_add_u64 v[214:215], s[36:37], 0, v[138:139]
	global_load_lds_dwordx4 v[214:215], off
	v_lshl_add_u64 v[214:215], s[36:37], 0, v[140:141]
	s_add_i32 m0, s19, 0xe000
	s_nop 0
	global_load_lds_dwordx4 v[214:215], off
	s_waitcnt vmcnt(8)
	s_waitcnt lgkmcnt(0)
	s_setprio 1
	s_barrier
	v_mfma_f32_16x16x32_bf16 v[126:129], v[148:151], v[180:183], v[126:129]
	v_mfma_f32_16x16x32_bf16 v[122:125], v[156:159], v[180:183], v[122:125]
	v_mfma_f32_16x16x32_bf16 v[118:121], v[148:151], v[188:191], v[118:121]
	v_mfma_f32_16x16x32_bf16 v[114:117], v[156:159], v[188:191], v[114:117]
	v_mfma_f32_16x16x32_bf16 v[102:105], v[148:151], v[196:199], v[102:105]
	v_mfma_f32_16x16x32_bf16 v[98:101], v[156:159], v[196:199], v[98:101]
	v_mfma_f32_16x16x32_bf16 v[86:89], v[148:151], v[206:209], v[86:89]
	v_mfma_f32_16x16x32_bf16 v[82:85], v[156:159], v[206:209], v[82:85]
	v_mfma_f32_16x16x32_bf16 v[126:129], v[152:155], v[184:187], v[126:129]
	v_mfma_f32_16x16x32_bf16 v[122:125], v[160:163], v[184:187], v[122:125]
	v_mfma_f32_16x16x32_bf16 v[118:121], v[152:155], v[192:195], v[118:121]
	v_mfma_f32_16x16x32_bf16 v[114:117], v[160:163], v[192:195], v[114:117]
	v_mfma_f32_16x16x32_bf16 v[102:105], v[152:155], v[200:203], v[102:105]
	v_mfma_f32_16x16x32_bf16 v[98:101], v[160:163], v[200:203], v[98:101]
	v_mfma_f32_16x16x32_bf16 v[86:89], v[152:155], v[210:213], v[86:89]
	v_mfma_f32_16x16x32_bf16 v[82:85], v[160:163], v[210:213], v[82:85]
	v_mfma_f32_16x16x32_bf16 v[110:113], v[164:167], v[180:183], v[110:113]
	v_mfma_f32_16x16x32_bf16 v[106:109], v[172:175], v[180:183], v[106:109]
	v_mfma_f32_16x16x32_bf16 v[94:97], v[164:167], v[188:191], v[94:97]
	v_mfma_f32_16x16x32_bf16 v[90:93], v[172:175], v[188:191], v[90:93]
	v_mfma_f32_16x16x32_bf16 v[78:81], v[164:167], v[196:199], v[78:81]
	v_mfma_f32_16x16x32_bf16 v[74:77], v[172:175], v[196:199], v[74:77]
	v_mfma_f32_16x16x32_bf16 v[70:73], v[164:167], v[206:209], v[70:73]
	v_mfma_f32_16x16x32_bf16 v[66:69], v[172:175], v[206:209], v[66:69]
	v_mfma_f32_16x16x32_bf16 v[110:113], v[168:171], v[184:187], v[110:113]
	v_mfma_f32_16x16x32_bf16 v[106:109], v[176:179], v[184:187], v[106:109]
	v_mfma_f32_16x16x32_bf16 v[94:97], v[168:171], v[192:195], v[94:97]
	v_mfma_f32_16x16x32_bf16 v[90:93], v[176:179], v[192:195], v[90:93]
	v_mfma_f32_16x16x32_bf16 v[78:81], v[168:171], v[200:203], v[78:81]
	v_mfma_f32_16x16x32_bf16 v[74:77], v[176:179], v[200:203], v[74:77]
	v_mfma_f32_16x16x32_bf16 v[70:73], v[168:171], v[210:213], v[70:73]
	v_mfma_f32_16x16x32_bf16 v[66:69], v[176:179], v[210:213], v[66:69]
	s_setprio 0
	s_barrier
	s_add_i32 s70, s35, s18
	v_lshl_add_u64 v[214:215], s[38:39], 0, v[134:135]
	s_mov_b32 m0, s70
	ds_read_b128 v[180:183], v146 offset:16384
	ds_read_b128 v[184:187], v146 offset:17408
	ds_read_b128 v[188:191], v146 offset:18432
	ds_read_b128 v[192:195], v146 offset:19456
	ds_read_b128 v[196:199], v146 offset:20480
	ds_read_b128 v[200:203], v146 offset:21504
	ds_read_b128 v[206:209], v146 offset:22528
	ds_read_b128 v[210:213], v146 offset:23552
	global_load_lds_dwordx4 v[214:215], off
	s_add_i32 m0, s70, 0x2000
	s_add_u32 s70, s38, 0x200000
	v_lshl_add_u64 v[216:217], s[38:39], 0, v[130:131]
	s_addc_u32 s71, s39, 0
	s_add_i32 s72, s44, s18
	global_load_lds_dwordx4 v[216:217], off
	v_lshl_add_u64 v[218:219], s[70:71], 0, v[134:135]
	s_mov_b32 m0, s72
	v_lshl_add_u64 v[220:221], s[42:43], 0, v[132:133]
	global_load_lds_dwordx4 v[218:219], off
	v_lshl_add_u64 v[218:219], s[70:71], 0, v[130:131]
	s_add_i32 m0, s72, 0x2000
	s_nop 0
	global_load_lds_dwordx4 v[218:219], off
	v_lshl_add_u64 v[218:219], s[42:43], 0, v[136:137]
	s_mov_b32 m0, s19
	s_nop 0
	global_load_lds_dwordx4 v[218:219], off
	s_mov_b32 m0, s24
	s_nop 0
	global_load_lds_dwordx4 v[220:221], off
	s_waitcnt vmcnt(8)
	s_waitcnt lgkmcnt(0)
	s_setprio 1
	s_barrier
	v_mfma_f32_16x16x32_bf16 v[62:65], v[148:151], v[180:183], v[62:65]
	v_mfma_f32_16x16x32_bf16 v[58:61], v[156:159], v[180:183], v[58:61]
	v_mfma_f32_16x16x32_bf16 v[54:57], v[148:151], v[188:191], v[54:57]
	v_mfma_f32_16x16x32_bf16 v[50:53], v[156:159], v[188:191], v[50:53]
	v_mfma_f32_16x16x32_bf16 v[38:41], v[148:151], v[196:199], v[38:41]
	v_mfma_f32_16x16x32_bf16 v[34:37], v[156:159], v[196:199], v[34:37]
	v_mfma_f32_16x16x32_bf16 v[22:25], v[148:151], v[206:209], v[22:25]
	v_mfma_f32_16x16x32_bf16 v[18:21], v[156:159], v[206:209], v[18:21]
	v_mfma_f32_16x16x32_bf16 v[62:65], v[152:155], v[184:187], v[62:65]
	v_mfma_f32_16x16x32_bf16 v[58:61], v[160:163], v[184:187], v[58:61]
	v_mfma_f32_16x16x32_bf16 v[54:57], v[152:155], v[192:195], v[54:57]
	v_mfma_f32_16x16x32_bf16 v[50:53], v[160:163], v[192:195], v[50:53]
	v_mfma_f32_16x16x32_bf16 v[38:41], v[152:155], v[200:203], v[38:41]
	v_mfma_f32_16x16x32_bf16 v[34:37], v[160:163], v[200:203], v[34:37]
	v_mfma_f32_16x16x32_bf16 v[22:25], v[152:155], v[210:213], v[22:25]
	v_mfma_f32_16x16x32_bf16 v[18:21], v[160:163], v[210:213], v[18:21]
	v_mfma_f32_16x16x32_bf16 v[46:49], v[164:167], v[180:183], v[46:49]
	v_mfma_f32_16x16x32_bf16 v[42:45], v[172:175], v[180:183], v[42:45]
	v_mfma_f32_16x16x32_bf16 v[30:33], v[164:167], v[188:191], v[30:33]
	v_mfma_f32_16x16x32_bf16 v[26:29], v[172:175], v[188:191], v[26:29]
	v_mfma_f32_16x16x32_bf16 v[14:17], v[164:167], v[196:199], v[14:17]
	v_mfma_f32_16x16x32_bf16 v[10:13], v[172:175], v[196:199], v[10:13]
	v_mfma_f32_16x16x32_bf16 v[6:9], v[164:167], v[206:209], v[6:9]
	v_mfma_f32_16x16x32_bf16 v[2:5], v[172:175], v[206:209], v[2:5]
	v_mfma_f32_16x16x32_bf16 v[46:49], v[168:171], v[184:187], v[46:49]
	v_mfma_f32_16x16x32_bf16 v[42:45], v[176:179], v[184:187], v[42:45]
	v_mfma_f32_16x16x32_bf16 v[30:33], v[168:171], v[192:195], v[30:33]
	v_mfma_f32_16x16x32_bf16 v[26:29], v[176:179], v[192:195], v[26:29]
	v_mfma_f32_16x16x32_bf16 v[14:17], v[168:171], v[200:203], v[14:17]
	v_mfma_f32_16x16x32_bf16 v[10:13], v[176:179], v[200:203], v[10:13]
	v_mfma_f32_16x16x32_bf16 v[6:9], v[168:171], v[210:213], v[6:9]
	v_mfma_f32_16x16x32_bf16 v[2:5], v[176:179], v[210:213], v[2:5]
	s_setprio 0
	s_barrier
	s_add_i32 s70, 0, 0x18000
	v_add_u32_e32 v147, s70, v143
	s_add_i32 s71, 0, 0x1c000
	ds_read_b128 v[148:151], v147
	ds_read_b128 v[152:155], v147 offset:1024
	ds_read_b128 v[156:159], v147 offset:2048
	ds_read_b128 v[160:163], v147 offset:3072
	v_add_u32_e32 v147, s71, v143
	ds_read_b128 v[164:167], v147
	ds_read_b128 v[168:171], v147 offset:1024
	ds_read_b128 v[172:175], v147 offset:2048
	ds_read_b128 v[176:179], v147 offset:3072
	s_add_u32 s42, s42, 0x20000
	s_addc_u32 s43, s43, 0
	s_mov_b32 m0, s25
	v_lshl_add_u64 v[222:223], s[42:43], 0, v[136:137]
	ds_read_b128 v[180:183], v146 offset:32768
	ds_read_b128 v[184:187], v146 offset:33792
	ds_read_b128 v[188:191], v146 offset:34816
	ds_read_b128 v[192:195], v146 offset:35840
	ds_read_b128 v[196:199], v146 offset:36864
	ds_read_b128 v[200:203], v146 offset:37888
	ds_read_b128 v[206:209], v146 offset:38912
	ds_read_b128 v[210:213], v146 offset:39936
	global_load_lds_dwordx4 v[222:223], off
	v_lshl_add_u64 v[222:223], s[42:43], 0, v[132:133]
	s_mov_b32 m0, s28
	s_nop 0
	global_load_lds_dwordx4 v[222:223], off
	s_waitcnt vmcnt(8)
	s_waitcnt lgkmcnt(0)
	s_setprio 1
	s_barrier
	v_mfma_f32_16x16x32_bf16 v[126:129], v[148:151], v[180:183], v[126:129]
	v_mfma_f32_16x16x32_bf16 v[122:125], v[156:159], v[180:183], v[122:125]
	v_mfma_f32_16x16x32_bf16 v[118:121], v[148:151], v[188:191], v[118:121]
	v_mfma_f32_16x16x32_bf16 v[114:117], v[156:159], v[188:191], v[114:117]
	v_mfma_f32_16x16x32_bf16 v[102:105], v[148:151], v[196:199], v[102:105]
	v_mfma_f32_16x16x32_bf16 v[98:101], v[156:159], v[196:199], v[98:101]
	v_mfma_f32_16x16x32_bf16 v[86:89], v[148:151], v[206:209], v[86:89]
	v_mfma_f32_16x16x32_bf16 v[82:85], v[156:159], v[206:209], v[82:85]
	v_mfma_f32_16x16x32_bf16 v[126:129], v[152:155], v[184:187], v[126:129]
	v_mfma_f32_16x16x32_bf16 v[122:125], v[160:163], v[184:187], v[122:125]
	v_mfma_f32_16x16x32_bf16 v[118:121], v[152:155], v[192:195], v[118:121]
	v_mfma_f32_16x16x32_bf16 v[114:117], v[160:163], v[192:195], v[114:117]
	v_mfma_f32_16x16x32_bf16 v[102:105], v[152:155], v[200:203], v[102:105]
	v_mfma_f32_16x16x32_bf16 v[98:101], v[160:163], v[200:203], v[98:101]
	v_mfma_f32_16x16x32_bf16 v[86:89], v[152:155], v[210:213], v[86:89]
	v_mfma_f32_16x16x32_bf16 v[82:85], v[160:163], v[210:213], v[82:85]
	v_mfma_f32_16x16x32_bf16 v[110:113], v[164:167], v[180:183], v[110:113]
	v_mfma_f32_16x16x32_bf16 v[106:109], v[172:175], v[180:183], v[106:109]
	v_mfma_f32_16x16x32_bf16 v[94:97], v[164:167], v[188:191], v[94:97]
	v_mfma_f32_16x16x32_bf16 v[90:93], v[172:175], v[188:191], v[90:93]
	v_mfma_f32_16x16x32_bf16 v[78:81], v[164:167], v[196:199], v[78:81]
	v_mfma_f32_16x16x32_bf16 v[74:77], v[172:175], v[196:199], v[74:77]
	v_mfma_f32_16x16x32_bf16 v[70:73], v[164:167], v[206:209], v[70:73]
	v_mfma_f32_16x16x32_bf16 v[66:69], v[172:175], v[206:209], v[66:69]
	v_mfma_f32_16x16x32_bf16 v[110:113], v[168:171], v[184:187], v[110:113]
	v_mfma_f32_16x16x32_bf16 v[106:109], v[176:179], v[184:187], v[106:109]
	v_mfma_f32_16x16x32_bf16 v[94:97], v[168:171], v[192:195], v[94:97]
	v_mfma_f32_16x16x32_bf16 v[90:93], v[176:179], v[192:195], v[90:93]
	v_mfma_f32_16x16x32_bf16 v[78:81], v[168:171], v[200:203], v[78:81]
	v_mfma_f32_16x16x32_bf16 v[74:77], v[176:179], v[200:203], v[74:77]
	v_mfma_f32_16x16x32_bf16 v[70:73], v[168:171], v[210:213], v[70:73]
	v_mfma_f32_16x16x32_bf16 v[66:69], v[176:179], v[210:213], v[66:69]
	s_setprio 0
	s_barrier
	s_add_i32 s42, s70, s18
	v_lshl_add_u64 v[214:215], v[214:215], 0, s[8:9]
	s_mov_b32 m0, s42
	ds_read_b128 v[180:183], v146 offset:49152
	ds_read_b128 v[184:187], v146 offset:50176
	ds_read_b128 v[188:191], v146 offset:51200
	ds_read_b128 v[192:195], v146 offset:52224
	ds_read_b128 v[196:199], v146 offset:53248
	ds_read_b128 v[200:203], v146 offset:54272
	ds_read_b128 v[206:209], v146 offset:55296
	ds_read_b128 v[210:213], v146 offset:56320
	global_load_lds_dwordx4 v[214:215], off
	s_add_i32 m0, s42, 0x2000
	s_add_u32 s38, s38, 0x200080
	v_lshl_add_u64 v[214:215], v[216:217], 0, s[8:9]
	s_addc_u32 s39, s39, 0
	s_add_i32 s42, s71, s18
	global_load_lds_dwordx4 v[214:215], off
	v_lshl_add_u64 v[214:215], s[38:39], 0, v[134:135]
	s_mov_b32 m0, s42
	s_nop 0
	global_load_lds_dwordx4 v[214:215], off
	v_lshl_add_u64 v[214:215], s[38:39], 0, v[130:131]
	s_add_i32 m0, s42, 0x2000
	s_nop 0
	global_load_lds_dwordx4 v[214:215], off
	v_lshl_add_u64 v[214:215], v[218:219], 0, s[8:9]
	s_mov_b32 m0, s33
	s_nop 0
	global_load_lds_dwordx4 v[214:215], off
	v_lshl_add_u64 v[214:215], v[220:221], 0, s[8:9]
	s_mov_b32 m0, s34
	s_nop 0
	global_load_lds_dwordx4 v[214:215], off
	s_waitcnt vmcnt(8)
	s_waitcnt lgkmcnt(0)
	s_setprio 1
	s_barrier
	v_mfma_f32_16x16x32_bf16 v[62:65], v[148:151], v[180:183], v[62:65]
	v_mfma_f32_16x16x32_bf16 v[58:61], v[156:159], v[180:183], v[58:61]
	v_mfma_f32_16x16x32_bf16 v[54:57], v[148:151], v[188:191], v[54:57]
	v_mfma_f32_16x16x32_bf16 v[50:53], v[156:159], v[188:191], v[50:53]
	v_mfma_f32_16x16x32_bf16 v[38:41], v[148:151], v[196:199], v[38:41]
	v_mfma_f32_16x16x32_bf16 v[34:37], v[156:159], v[196:199], v[34:37]
	v_mfma_f32_16x16x32_bf16 v[22:25], v[148:151], v[206:209], v[22:25]
	v_mfma_f32_16x16x32_bf16 v[18:21], v[156:159], v[206:209], v[18:21]
	v_mfma_f32_16x16x32_bf16 v[62:65], v[152:155], v[184:187], v[62:65]
	v_mfma_f32_16x16x32_bf16 v[58:61], v[160:163], v[184:187], v[58:61]
	v_mfma_f32_16x16x32_bf16 v[54:57], v[152:155], v[192:195], v[54:57]
	v_mfma_f32_16x16x32_bf16 v[50:53], v[160:163], v[192:195], v[50:53]
	v_mfma_f32_16x16x32_bf16 v[38:41], v[152:155], v[200:203], v[38:41]
	v_mfma_f32_16x16x32_bf16 v[34:37], v[160:163], v[200:203], v[34:37]
	v_mfma_f32_16x16x32_bf16 v[22:25], v[152:155], v[210:213], v[22:25]
	v_mfma_f32_16x16x32_bf16 v[18:21], v[160:163], v[210:213], v[18:21]
	v_mfma_f32_16x16x32_bf16 v[46:49], v[164:167], v[180:183], v[46:49]
	v_mfma_f32_16x16x32_bf16 v[42:45], v[172:175], v[180:183], v[42:45]
	v_mfma_f32_16x16x32_bf16 v[30:33], v[164:167], v[188:191], v[30:33]
	v_mfma_f32_16x16x32_bf16 v[26:29], v[172:175], v[188:191], v[26:29]
	v_mfma_f32_16x16x32_bf16 v[14:17], v[164:167], v[196:199], v[14:17]
	v_mfma_f32_16x16x32_bf16 v[10:13], v[172:175], v[196:199], v[10:13]
	v_mfma_f32_16x16x32_bf16 v[6:9], v[164:167], v[206:209], v[6:9]
	v_mfma_f32_16x16x32_bf16 v[2:5], v[172:175], v[206:209], v[2:5]
	v_mfma_f32_16x16x32_bf16 v[46:49], v[168:171], v[184:187], v[46:49]
	v_mfma_f32_16x16x32_bf16 v[42:45], v[176:179], v[184:187], v[42:45]
	v_mfma_f32_16x16x32_bf16 v[30:33], v[168:171], v[192:195], v[30:33]
	v_mfma_f32_16x16x32_bf16 v[26:29], v[176:179], v[192:195], v[26:29]
	v_mfma_f32_16x16x32_bf16 v[14:17], v[168:171], v[200:203], v[14:17]
	v_mfma_f32_16x16x32_bf16 v[10:13], v[176:179], v[200:203], v[10:13]
	v_mfma_f32_16x16x32_bf16 v[6:9], v[168:171], v[210:213], v[6:9]
	v_mfma_f32_16x16x32_bf16 v[2:5], v[176:179], v[210:213], v[2:5]
	s_setprio 0
	s_barrier
	s_add_i32 s69, s69, 2
	s_add_u32 s36, s36, 0x100
	s_addc_u32 s37, s37, 0
	s_add_u32 s67, s67, 0x100
	s_addc_u32 s68, s68, 0
	s_cmp_gt_u32 s69, 5
	s_cbranch_scc0 .LBB0_477
	s_and_b64 vcc, exec, s[10:11]
	s_cbranch_vccz .LBB0_480
	s_barrier

.LBB0_565:
	v_readlane_b32 s62, v249, 27
	v_readlane_b32 s63, v249, 28
	s_add_u32 s72, s62, s68
	s_addc_u32 s73, s63, s69
	s_and_b64 s[62:63], s[70:71], exec
	s_cselect_b32 s31, s73, s77
	s_cselect_b32 s33, s72, s76
	s_add_u32 s74, s35, s66
	s_addc_u32 s75, s85, s67
	s_and_b64 s[62:63], s[70:71], exec
	s_cselect_b32 s34, s75, s79
	s_cselect_b32 s39, s74, s78
	s_add_i32 s45, s7, -2
	s_add_u32 s76, s76, 0x40080
	s_addc_u32 s77, s77, 0
	s_add_u32 s47, s78, 0x100
	s_addc_u32 s62, s79, 0
	s_mov_b32 s63, 0
	ds_read_b128 v[114:117], v190
	ds_read_b128 v[118:121], v190 offset:1024
	ds_read_b128 v[122:125], v190 offset:2048
	ds_read_b128 v[126:129], v190 offset:3072
	ds_read_b128 v[146:149], v191
	ds_read_b128 v[150:153], v191 offset:1024
	ds_read_b128 v[154:157], v191 offset:2048
	ds_read_b128 v[158:161], v191 offset:3072
	ds_read_b128 v[162:165], v192
	ds_read_b128 v[166:169], v192 offset:1024
	ds_read_b128 v[194:197], v192 offset:2048
	ds_read_b128 v[198:201], v192 offset:3072
	ds_read_b128 v[206:209], v192 offset:4096
	ds_read_b128 v[210:213], v192 offset:5120
	ds_read_b128 v[214:217], v192 offset:6144
	ds_read_b128 v[218:221], v192 offset:7168
	s_waitcnt vmcnt(0)
	s_add_i32 s82, s63, 2
	s_add_u32 s78, s76, 0xfffc0080
	s_addc_u32 s79, s77, -1
	s_cmp_eq_u32 s45, s63
	s_cselect_b32 s81, s31, s79
	s_cselect_b32 s80, s33, s78
	s_cselect_b32 s79, s34, s62
	s_cselect_b32 s78, s39, s47
	s_add_i32 m0, s87, 0xc000
	v_lshl_add_u64 v[186:187], s[76:77], 0, v[180:181]
	global_load_lds_dwordx4 v[186:187], off
	v_lshl_add_u64 v[186:187], s[76:77], 0, v[182:183]
	s_add_i32 m0, s87, 0xe000
	s_nop 0
	global_load_lds_dwordx4 v[186:187], off
	s_waitcnt vmcnt(8)
	s_waitcnt lgkmcnt(0)
	s_setprio 1
	s_barrier
	v_mfma_f32_16x16x32_bf16 v[142:145], v[114:117], v[162:165], 0
	v_mfma_f32_16x16x32_bf16 v[138:141], v[122:125], v[162:165], 0
	v_mfma_f32_16x16x32_bf16 v[110:113], v[114:117], v[194:197], 0
	v_mfma_f32_16x16x32_bf16 v[106:109], v[122:125], v[194:197], 0
	v_mfma_f32_16x16x32_bf16 v[98:101], v[114:117], v[206:209], 0
	v_mfma_f32_16x16x32_bf16 v[90:93], v[122:125], v[206:209], 0
	v_mfma_f32_16x16x32_bf16 v[82:85], v[114:117], v[214:217], 0
	v_mfma_f32_16x16x32_bf16 v[74:77], v[122:125], v[214:217], 0
	v_mfma_f32_16x16x32_bf16 v[142:145], v[118:121], v[166:169], v[142:145]
	v_mfma_f32_16x16x32_bf16 v[138:141], v[126:129], v[166:169], v[138:141]
	v_mfma_f32_16x16x32_bf16 v[110:113], v[118:121], v[198:201], v[110:113]
	v_mfma_f32_16x16x32_bf16 v[106:109], v[126:129], v[198:201], v[106:109]
	v_mfma_f32_16x16x32_bf16 v[98:101], v[118:121], v[210:213], v[98:101]
	v_mfma_f32_16x16x32_bf16 v[90:93], v[126:129], v[210:213], v[90:93]
	v_mfma_f32_16x16x32_bf16 v[82:85], v[118:121], v[218:221], v[82:85]
	v_mfma_f32_16x16x32_bf16 v[74:77], v[126:129], v[218:221], v[74:77]
	v_mfma_f32_16x16x32_bf16 v[134:137], v[146:149], v[162:165], 0
	v_mfma_f32_16x16x32_bf16 v[130:133], v[154:157], v[162:165], 0
	v_mfma_f32_16x16x32_bf16 v[102:105], v[146:149], v[194:197], 0
	v_mfma_f32_16x16x32_bf16 v[94:97], v[154:157], v[194:197], 0
	v_mfma_f32_16x16x32_bf16 v[86:89], v[146:149], v[206:209], 0
	v_mfma_f32_16x16x32_bf16 v[78:81], v[154:157], v[206:209], 0
	v_mfma_f32_16x16x32_bf16 v[70:73], v[146:149], v[214:217], 0
	v_mfma_f32_16x16x32_bf16 v[66:69], v[154:157], v[214:217], 0
	v_mfma_f32_16x16x32_bf16 v[134:137], v[150:153], v[166:169], v[134:137]
	v_mfma_f32_16x16x32_bf16 v[130:133], v[158:161], v[166:169], v[130:133]
	v_mfma_f32_16x16x32_bf16 v[102:105], v[150:153], v[198:201], v[102:105]
	v_mfma_f32_16x16x32_bf16 v[94:97], v[158:161], v[198:201], v[94:97]
	v_mfma_f32_16x16x32_bf16 v[86:89], v[150:153], v[210:213], v[86:89]
	v_mfma_f32_16x16x32_bf16 v[78:81], v[158:161], v[210:213], v[78:81]
	v_mfma_f32_16x16x32_bf16 v[70:73], v[150:153], v[218:221], v[70:73]
	v_mfma_f32_16x16x32_bf16 v[66:69], v[158:161], v[218:221], v[66:69]
	s_setprio 0
	s_barrier
	s_add_i32 s63, s24, s86
	v_lshl_add_u64 v[186:187], s[78:79], 0, v[172:173]
	s_mov_b32 m0, s63
	ds_read_b128 v[162:165], v192 offset:16384
	ds_read_b128 v[166:169], v192 offset:17408
	ds_read_b128 v[194:197], v192 offset:18432
	ds_read_b128 v[198:201], v192 offset:19456
	ds_read_b128 v[206:209], v192 offset:20480
	ds_read_b128 v[210:213], v192 offset:21504
	ds_read_b128 v[214:217], v192 offset:22528
	ds_read_b128 v[218:221], v192 offset:23552
	global_load_lds_dwordx4 v[186:187], off
	s_add_i32 m0, s63, 0x2000
	s_add_u32 vcc_lo, s78, 0x40000
	v_lshl_add_u64 v[202:203], s[78:79], 0, v[176:177]
	s_addc_u32 vcc_hi, s79, 0
	s_add_i32 s63, s25, s86
	global_load_lds_dwordx4 v[202:203], off
	v_lshl_add_u64 v[222:223], vcc, 0, v[172:173]
	s_mov_b32 m0, s63
	v_lshl_add_u64 v[224:225], s[80:81], 0, v[174:175]
	global_load_lds_dwordx4 v[222:223], off
	v_lshl_add_u64 v[222:223], vcc, 0, v[176:177]
	s_add_i32 m0, s63, 0x2000
	s_nop 0
	global_load_lds_dwordx4 v[222:223], off
	v_lshl_add_u64 v[222:223], s[80:81], 0, v[170:171]
	s_mov_b32 m0, s87
	s_nop 0
	global_load_lds_dwordx4 v[222:223], off
	s_mov_b32 m0, s88
	s_nop 0
	global_load_lds_dwordx4 v[224:225], off
	s_waitcnt vmcnt(8)
	s_waitcnt lgkmcnt(0)
	s_setprio 1
	s_barrier
	v_mfma_f32_16x16x32_bf16 v[62:65], v[114:117], v[162:165], 0
	v_mfma_f32_16x16x32_bf16 v[58:61], v[122:125], v[162:165], 0
	v_mfma_f32_16x16x32_bf16 v[50:53], v[114:117], v[194:197], 0
	v_mfma_f32_16x16x32_bf16 v[42:45], v[122:125], v[194:197], 0
	v_mfma_f32_16x16x32_bf16 v[34:37], v[114:117], v[206:209], 0
	v_mfma_f32_16x16x32_bf16 v[26:29], v[122:125], v[206:209], 0
	v_mfma_f32_16x16x32_bf16 v[18:21], v[114:117], v[214:217], 0
	v_mfma_f32_16x16x32_bf16 v[10:13], v[122:125], v[214:217], 0
	v_mfma_f32_16x16x32_bf16 v[62:65], v[118:121], v[166:169], v[62:65]
	v_mfma_f32_16x16x32_bf16 v[58:61], v[126:129], v[166:169], v[58:61]
	v_mfma_f32_16x16x32_bf16 v[50:53], v[118:121], v[198:201], v[50:53]
	v_mfma_f32_16x16x32_bf16 v[42:45], v[126:129], v[198:201], v[42:45]
	v_mfma_f32_16x16x32_bf16 v[34:37], v[118:121], v[210:213], v[34:37]
	v_mfma_f32_16x16x32_bf16 v[26:29], v[126:129], v[210:213], v[26:29]
	v_mfma_f32_16x16x32_bf16 v[18:21], v[118:121], v[218:221], v[18:21]
	v_mfma_f32_16x16x32_bf16 v[10:13], v[126:129], v[218:221], v[10:13]
	v_mfma_f32_16x16x32_bf16 v[54:57], v[146:149], v[162:165], 0
	v_mfma_f32_16x16x32_bf16 v[46:49], v[154:157], v[162:165], 0
	v_mfma_f32_16x16x32_bf16 v[38:41], v[146:149], v[194:197], 0
	v_mfma_f32_16x16x32_bf16 v[30:33], v[154:157], v[194:197], 0
	v_mfma_f32_16x16x32_bf16 v[22:25], v[146:149], v[206:209], 0
	v_mfma_f32_16x16x32_bf16 v[14:17], v[154:157], v[206:209], 0
	v_mfma_f32_16x16x32_bf16 v[6:9], v[146:149], v[214:217], 0
	v_mfma_f32_16x16x32_bf16 v[2:5], v[154:157], v[214:217], 0
	v_mfma_f32_16x16x32_bf16 v[54:57], v[150:153], v[166:169], v[54:57]
	v_mfma_f32_16x16x32_bf16 v[46:49], v[158:161], v[166:169], v[46:49]
	v_mfma_f32_16x16x32_bf16 v[38:41], v[150:153], v[198:201], v[38:41]
	v_mfma_f32_16x16x32_bf16 v[30:33], v[158:161], v[198:201], v[30:33]
	v_mfma_f32_16x16x32_bf16 v[22:25], v[150:153], v[210:213], v[22:25]
	v_mfma_f32_16x16x32_bf16 v[14:17], v[158:161], v[210:213], v[14:17]
	v_mfma_f32_16x16x32_bf16 v[6:9], v[150:153], v[218:221], v[6:9]
	v_mfma_f32_16x16x32_bf16 v[2:5], v[158:161], v[218:221], v[2:5]
	s_setprio 0
	s_barrier
	s_add_i32 s63, 0, 0x18000
	s_add_i32 s83, 0, 0x1c000
	v_add_u32_e32 v126, s63, v189
	v_add_u32_e32 v158, s83, v189
	ds_read_b128 v[114:117], v126
	ds_read_b128 v[118:121], v126 offset:1024
	ds_read_b128 v[122:125], v126 offset:2048
	ds_read_b128 v[126:129], v126 offset:3072
	ds_read_b128 v[146:149], v158
	ds_read_b128 v[150:153], v158 offset:1024
	ds_read_b128 v[154:157], v158 offset:2048
	ds_read_b128 v[158:161], v158 offset:3072
	s_add_u32 s80, s80, 0x40000
	s_addc_u32 s81, s81, 0
	s_mov_b32 m0, s89
	v_lshl_add_u64 v[226:227], s[80:81], 0, v[170:171]
	ds_read_b128 v[162:165], v192 offset:32768
	ds_read_b128 v[166:169], v192 offset:33792
	ds_read_b128 v[194:197], v192 offset:34816
	ds_read_b128 v[198:201], v192 offset:35840
	ds_read_b128 v[206:209], v192 offset:36864
	ds_read_b128 v[210:213], v192 offset:37888
	ds_read_b128 v[214:217], v192 offset:38912
	ds_read_b128 v[218:221], v192 offset:39936
	global_load_lds_dwordx4 v[226:227], off
	v_lshl_add_u64 v[226:227], s[80:81], 0, v[174:175]
	s_mov_b32 m0, s90
	s_nop 0
	global_load_lds_dwordx4 v[226:227], off
	s_waitcnt vmcnt(8)
	s_waitcnt lgkmcnt(0)
	s_setprio 1
	s_barrier
	v_mfma_f32_16x16x32_bf16 v[142:145], v[114:117], v[162:165], v[142:145]
	v_mfma_f32_16x16x32_bf16 v[138:141], v[122:125], v[162:165], v[138:141]
	v_mfma_f32_16x16x32_bf16 v[110:113], v[114:117], v[194:197], v[110:113]
	v_mfma_f32_16x16x32_bf16 v[106:109], v[122:125], v[194:197], v[106:109]
	v_mfma_f32_16x16x32_bf16 v[98:101], v[114:117], v[206:209], v[98:101]
	v_mfma_f32_16x16x32_bf16 v[90:93], v[122:125], v[206:209], v[90:93]
	v_mfma_f32_16x16x32_bf16 v[82:85], v[114:117], v[214:217], v[82:85]
	v_mfma_f32_16x16x32_bf16 v[74:77], v[122:125], v[214:217], v[74:77]
	v_mfma_f32_16x16x32_bf16 v[142:145], v[118:121], v[166:169], v[142:145]
	v_mfma_f32_16x16x32_bf16 v[138:141], v[126:129], v[166:169], v[138:141]
	v_mfma_f32_16x16x32_bf16 v[110:113], v[118:121], v[198:201], v[110:113]
	v_mfma_f32_16x16x32_bf16 v[106:109], v[126:129], v[198:201], v[106:109]
	v_mfma_f32_16x16x32_bf16 v[98:101], v[118:121], v[210:213], v[98:101]
	v_mfma_f32_16x16x32_bf16 v[90:93], v[126:129], v[210:213], v[90:93]
	v_mfma_f32_16x16x32_bf16 v[82:85], v[118:121], v[218:221], v[82:85]
	v_mfma_f32_16x16x32_bf16 v[74:77], v[126:129], v[218:221], v[74:77]
	v_mfma_f32_16x16x32_bf16 v[134:137], v[146:149], v[162:165], v[134:137]
	v_mfma_f32_16x16x32_bf16 v[130:133], v[154:157], v[162:165], v[130:133]
	v_mfma_f32_16x16x32_bf16 v[102:105], v[146:149], v[194:197], v[102:105]
	v_mfma_f32_16x16x32_bf16 v[94:97], v[154:157], v[194:197], v[94:97]
	v_mfma_f32_16x16x32_bf16 v[86:89], v[146:149], v[206:209], v[86:89]
	v_mfma_f32_16x16x32_bf16 v[78:81], v[154:157], v[206:209], v[78:81]
	v_mfma_f32_16x16x32_bf16 v[70:73], v[146:149], v[214:217], v[70:73]
	v_mfma_f32_16x16x32_bf16 v[66:69], v[154:157], v[214:217], v[66:69]
	v_mfma_f32_16x16x32_bf16 v[134:137], v[150:153], v[166:169], v[134:137]
	v_mfma_f32_16x16x32_bf16 v[130:133], v[158:161], v[166:169], v[130:133]
	v_mfma_f32_16x16x32_bf16 v[102:105], v[150:153], v[198:201], v[102:105]
	v_mfma_f32_16x16x32_bf16 v[94:97], v[158:161], v[198:201], v[94:97]
	v_mfma_f32_16x16x32_bf16 v[86:89], v[150:153], v[210:213], v[86:89]
	v_mfma_f32_16x16x32_bf16 v[78:81], v[158:161], v[210:213], v[78:81]
	v_mfma_f32_16x16x32_bf16 v[70:73], v[150:153], v[218:221], v[70:73]
	v_mfma_f32_16x16x32_bf16 v[66:69], v[158:161], v[218:221], v[66:69]
	s_setprio 0
	s_barrier
	s_add_i32 s63, s63, s86
	v_lshl_add_u64 v[186:187], v[186:187], 0, s[22:23]
	s_mov_b32 m0, s63
	ds_read_b128 v[162:165], v192 offset:49152
	ds_read_b128 v[166:169], v192 offset:50176
	ds_read_b128 v[194:197], v192 offset:51200
	ds_read_b128 v[198:201], v192 offset:52224
	ds_read_b128 v[206:209], v192 offset:53248
	ds_read_b128 v[210:213], v192 offset:54272
	ds_read_b128 v[214:217], v192 offset:55296
	ds_read_b128 v[218:221], v192 offset:56320
	global_load_lds_dwordx4 v[186:187], off
	s_add_i32 m0, s63, 0x2000
	s_add_u32 s78, s78, 0x40080
	v_lshl_add_u64 v[186:187], v[202:203], 0, s[22:23]
	s_addc_u32 s79, s79, 0
	s_add_i32 s63, s83, s86
	global_load_lds_dwordx4 v[186:187], off
	v_lshl_add_u64 v[186:187], s[78:79], 0, v[172:173]
	s_mov_b32 m0, s63
	s_nop 0
	global_load_lds_dwordx4 v[186:187], off
	v_lshl_add_u64 v[186:187], s[78:79], 0, v[176:177]
	s_add_i32 m0, s63, 0x2000
	s_nop 0
	global_load_lds_dwordx4 v[186:187], off
	v_lshl_add_u64 v[186:187], v[222:223], 0, s[22:23]
	s_mov_b32 m0, s95
	s_nop 0
	global_load_lds_dwordx4 v[186:187], off
	v_lshl_add_u64 v[186:187], v[224:225], 0, s[22:23]
	s_mov_b32 m0, s96
	s_nop 0
	global_load_lds_dwordx4 v[186:187], off
	s_waitcnt vmcnt(8)
	s_waitcnt lgkmcnt(0)
	s_setprio 1
	s_barrier
	v_mfma_f32_16x16x32_bf16 v[62:65], v[114:117], v[162:165], v[62:65]
	v_mfma_f32_16x16x32_bf16 v[58:61], v[122:125], v[162:165], v[58:61]
	v_mfma_f32_16x16x32_bf16 v[50:53], v[114:117], v[194:197], v[50:53]
	v_mfma_f32_16x16x32_bf16 v[42:45], v[122:125], v[194:197], v[42:45]
	v_mfma_f32_16x16x32_bf16 v[34:37], v[114:117], v[206:209], v[34:37]
	v_mfma_f32_16x16x32_bf16 v[26:29], v[122:125], v[206:209], v[26:29]
	v_mfma_f32_16x16x32_bf16 v[18:21], v[114:117], v[214:217], v[18:21]
	v_mfma_f32_16x16x32_bf16 v[10:13], v[122:125], v[214:217], v[10:13]
	v_mfma_f32_16x16x32_bf16 v[62:65], v[118:121], v[166:169], v[62:65]
	v_mfma_f32_16x16x32_bf16 v[58:61], v[126:129], v[166:169], v[58:61]
	v_mfma_f32_16x16x32_bf16 v[50:53], v[118:121], v[198:201], v[50:53]
	v_mfma_f32_16x16x32_bf16 v[42:45], v[126:129], v[198:201], v[42:45]
	v_mfma_f32_16x16x32_bf16 v[34:37], v[118:121], v[210:213], v[34:37]
	v_mfma_f32_16x16x32_bf16 v[26:29], v[126:129], v[210:213], v[26:29]
	v_mfma_f32_16x16x32_bf16 v[18:21], v[118:121], v[218:221], v[18:21]
	v_mfma_f32_16x16x32_bf16 v[10:13], v[126:129], v[218:221], v[10:13]
	v_mfma_f32_16x16x32_bf16 v[54:57], v[146:149], v[162:165], v[54:57]
	v_mfma_f32_16x16x32_bf16 v[46:49], v[154:157], v[162:165], v[46:49]
	v_mfma_f32_16x16x32_bf16 v[38:41], v[146:149], v[194:197], v[38:41]
	v_mfma_f32_16x16x32_bf16 v[30:33], v[154:157], v[194:197], v[30:33]
	v_mfma_f32_16x16x32_bf16 v[22:25], v[146:149], v[206:209], v[22:25]
	v_mfma_f32_16x16x32_bf16 v[14:17], v[154:157], v[206:209], v[14:17]
	v_mfma_f32_16x16x32_bf16 v[6:9], v[146:149], v[214:217], v[6:9]
	v_mfma_f32_16x16x32_bf16 v[2:5], v[154:157], v[214:217], v[2:5]
	v_mfma_f32_16x16x32_bf16 v[54:57], v[150:153], v[166:169], v[54:57]
	v_mfma_f32_16x16x32_bf16 v[46:49], v[158:161], v[166:169], v[46:49]
	v_mfma_f32_16x16x32_bf16 v[38:41], v[150:153], v[198:201], v[38:41]
	v_mfma_f32_16x16x32_bf16 v[30:33], v[158:161], v[198:201], v[30:33]
	v_mfma_f32_16x16x32_bf16 v[22:25], v[150:153], v[210:213], v[22:25]
	v_mfma_f32_16x16x32_bf16 v[14:17], v[158:161], v[210:213], v[14:17]
	v_mfma_f32_16x16x32_bf16 v[6:9], v[150:153], v[218:221], v[6:9]
	v_mfma_f32_16x16x32_bf16 v[2:5], v[158:161], v[218:221], v[2:5]
	s_setprio 0
	s_barrier
	s_add_u32 s76, s76, 0x100
	s_addc_u32 s77, s77, 0
	s_add_u32 s47, s47, 0x100
	s_addc_u32 s62, s62, 0
	s_cmp_ge_i32 s82, s7
	s_mov_b32 s63, s82
.LBB0_566:
	ds_read_b128 v[114:117], v190
	ds_read_b128 v[118:121], v190 offset:1024
	ds_read_b128 v[122:125], v190 offset:2048
	ds_read_b128 v[126:129], v190 offset:3072
	ds_read_b128 v[146:149], v191
	ds_read_b128 v[150:153], v191 offset:1024
	ds_read_b128 v[154:157], v191 offset:2048
	ds_read_b128 v[158:161], v191 offset:3072
	ds_read_b128 v[162:165], v192
	ds_read_b128 v[166:169], v192 offset:1024
	ds_read_b128 v[194:197], v192 offset:2048
	ds_read_b128 v[198:201], v192 offset:3072
	ds_read_b128 v[206:209], v192 offset:4096
	ds_read_b128 v[210:213], v192 offset:5120
	ds_read_b128 v[214:217], v192 offset:6144
	ds_read_b128 v[218:221], v192 offset:7168
	s_waitcnt vmcnt(0)
	s_add_i32 s82, s63, 2
	s_add_u32 s78, s76, 0xfffc0080
	s_addc_u32 s79, s77, -1
	s_cmp_eq_u32 s45, s63
	s_cselect_b32 s81, s31, s79
	s_cselect_b32 s80, s33, s78
	s_cselect_b32 s79, s34, s62
	s_cselect_b32 s78, s39, s47
	s_add_i32 m0, s87, 0xc000
	v_lshl_add_u64 v[186:187], s[76:77], 0, v[180:181]
	global_load_lds_dwordx4 v[186:187], off
	v_lshl_add_u64 v[186:187], s[76:77], 0, v[182:183]
	s_add_i32 m0, s87, 0xe000
	s_nop 0
	global_load_lds_dwordx4 v[186:187], off
	s_waitcnt vmcnt(8)
	s_waitcnt lgkmcnt(0)
	s_setprio 1
	s_barrier
	v_mfma_f32_16x16x32_bf16 v[142:145], v[114:117], v[162:165], v[142:145]
	v_mfma_f32_16x16x32_bf16 v[138:141], v[122:125], v[162:165], v[138:141]
	v_mfma_f32_16x16x32_bf16 v[110:113], v[114:117], v[194:197], v[110:113]
	v_mfma_f32_16x16x32_bf16 v[106:109], v[122:125], v[194:197], v[106:109]
	v_mfma_f32_16x16x32_bf16 v[98:101], v[114:117], v[206:209], v[98:101]
	v_mfma_f32_16x16x32_bf16 v[90:93], v[122:125], v[206:209], v[90:93]
	v_mfma_f32_16x16x32_bf16 v[82:85], v[114:117], v[214:217], v[82:85]
	v_mfma_f32_16x16x32_bf16 v[74:77], v[122:125], v[214:217], v[74:77]
	v_mfma_f32_16x16x32_bf16 v[142:145], v[118:121], v[166:169], v[142:145]
	v_mfma_f32_16x16x32_bf16 v[138:141], v[126:129], v[166:169], v[138:141]
	v_mfma_f32_16x16x32_bf16 v[110:113], v[118:121], v[198:201], v[110:113]
	v_mfma_f32_16x16x32_bf16 v[106:109], v[126:129], v[198:201], v[106:109]
	v_mfma_f32_16x16x32_bf16 v[98:101], v[118:121], v[210:213], v[98:101]
	v_mfma_f32_16x16x32_bf16 v[90:93], v[126:129], v[210:213], v[90:93]
	v_mfma_f32_16x16x32_bf16 v[82:85], v[118:121], v[218:221], v[82:85]
	v_mfma_f32_16x16x32_bf16 v[74:77], v[126:129], v[218:221], v[74:77]
	v_mfma_f32_16x16x32_bf16 v[134:137], v[146:149], v[162:165], v[134:137]
	v_mfma_f32_16x16x32_bf16 v[130:133], v[154:157], v[162:165], v[130:133]
	v_mfma_f32_16x16x32_bf16 v[102:105], v[146:149], v[194:197], v[102:105]
	v_mfma_f32_16x16x32_bf16 v[94:97], v[154:157], v[194:197], v[94:97]
	v_mfma_f32_16x16x32_bf16 v[86:89], v[146:149], v[206:209], v[86:89]
	v_mfma_f32_16x16x32_bf16 v[78:81], v[154:157], v[206:209], v[78:81]
	v_mfma_f32_16x16x32_bf16 v[70:73], v[146:149], v[214:217], v[70:73]
	v_mfma_f32_16x16x32_bf16 v[66:69], v[154:157], v[214:217], v[66:69]
	v_mfma_f32_16x16x32_bf16 v[134:137], v[150:153], v[166:169], v[134:137]
	v_mfma_f32_16x16x32_bf16 v[130:133], v[158:161], v[166:169], v[130:133]
	v_mfma_f32_16x16x32_bf16 v[102:105], v[150:153], v[198:201], v[102:105]
	v_mfma_f32_16x16x32_bf16 v[94:97], v[158:161], v[198:201], v[94:97]
	v_mfma_f32_16x16x32_bf16 v[86:89], v[150:153], v[210:213], v[86:89]
	v_mfma_f32_16x16x32_bf16 v[78:81], v[158:161], v[210:213], v[78:81]
	v_mfma_f32_16x16x32_bf16 v[70:73], v[150:153], v[218:221], v[70:73]
	v_mfma_f32_16x16x32_bf16 v[66:69], v[158:161], v[218:221], v[66:69]
	s_setprio 0
	s_barrier
	s_add_i32 s63, s24, s86
	v_lshl_add_u64 v[186:187], s[78:79], 0, v[172:173]
	s_mov_b32 m0, s63
	ds_read_b128 v[162:165], v192 offset:16384
	ds_read_b128 v[166:169], v192 offset:17408
	ds_read_b128 v[194:197], v192 offset:18432
	ds_read_b128 v[198:201], v192 offset:19456
	ds_read_b128 v[206:209], v192 offset:20480
	ds_read_b128 v[210:213], v192 offset:21504
	ds_read_b128 v[214:217], v192 offset:22528
	ds_read_b128 v[218:221], v192 offset:23552
	global_load_lds_dwordx4 v[186:187], off
	s_add_i32 m0, s63, 0x2000
	s_add_u32 vcc_lo, s78, 0x40000
	v_lshl_add_u64 v[202:203], s[78:79], 0, v[176:177]
	s_addc_u32 vcc_hi, s79, 0
	s_add_i32 s63, s25, s86
	global_load_lds_dwordx4 v[202:203], off
	v_lshl_add_u64 v[222:223], vcc, 0, v[172:173]
	s_mov_b32 m0, s63
	v_lshl_add_u64 v[224:225], s[80:81], 0, v[174:175]
	global_load_lds_dwordx4 v[222:223], off
	v_lshl_add_u64 v[222:223], vcc, 0, v[176:177]
	s_add_i32 m0, s63, 0x2000
	s_nop 0
	global_load_lds_dwordx4 v[222:223], off
	v_lshl_add_u64 v[222:223], s[80:81], 0, v[170:171]
	s_mov_b32 m0, s87
	s_nop 0
	global_load_lds_dwordx4 v[222:223], off
	s_mov_b32 m0, s88
	s_nop 0
	global_load_lds_dwordx4 v[224:225], off
	s_waitcnt vmcnt(8)
	s_waitcnt lgkmcnt(0)
	s_setprio 1
	s_barrier
	v_mfma_f32_16x16x32_bf16 v[62:65], v[114:117], v[162:165], v[62:65]
	v_mfma_f32_16x16x32_bf16 v[58:61], v[122:125], v[162:165], v[58:61]
	v_mfma_f32_16x16x32_bf16 v[50:53], v[114:117], v[194:197], v[50:53]
	v_mfma_f32_16x16x32_bf16 v[42:45], v[122:125], v[194:197], v[42:45]
	v_mfma_f32_16x16x32_bf16 v[34:37], v[114:117], v[206:209], v[34:37]
	v_mfma_f32_16x16x32_bf16 v[26:29], v[122:125], v[206:209], v[26:29]
	v_mfma_f32_16x16x32_bf16 v[18:21], v[114:117], v[214:217], v[18:21]
	v_mfma_f32_16x16x32_bf16 v[10:13], v[122:125], v[214:217], v[10:13]
	v_mfma_f32_16x16x32_bf16 v[62:65], v[118:121], v[166:169], v[62:65]
	v_mfma_f32_16x16x32_bf16 v[58:61], v[126:129], v[166:169], v[58:61]
	v_mfma_f32_16x16x32_bf16 v[50:53], v[118:121], v[198:201], v[50:53]
	v_mfma_f32_16x16x32_bf16 v[42:45], v[126:129], v[198:201], v[42:45]
	v_mfma_f32_16x16x32_bf16 v[34:37], v[118:121], v[210:213], v[34:37]
	v_mfma_f32_16x16x32_bf16 v[26:29], v[126:129], v[210:213], v[26:29]
	v_mfma_f32_16x16x32_bf16 v[18:21], v[118:121], v[218:221], v[18:21]
	v_mfma_f32_16x16x32_bf16 v[10:13], v[126:129], v[218:221], v[10:13]
	v_mfma_f32_16x16x32_bf16 v[54:57], v[146:149], v[162:165], v[54:57]
	v_mfma_f32_16x16x32_bf16 v[46:49], v[154:157], v[162:165], v[46:49]
	v_mfma_f32_16x16x32_bf16 v[38:41], v[146:149], v[194:197], v[38:41]
	v_mfma_f32_16x16x32_bf16 v[30:33], v[154:157], v[194:197], v[30:33]
	v_mfma_f32_16x16x32_bf16 v[22:25], v[146:149], v[206:209], v[22:25]
	v_mfma_f32_16x16x32_bf16 v[14:17], v[154:157], v[206:209], v[14:17]
	v_mfma_f32_16x16x32_bf16 v[6:9], v[146:149], v[214:217], v[6:9]
	v_mfma_f32_16x16x32_bf16 v[2:5], v[154:157], v[214:217], v[2:5]
	v_mfma_f32_16x16x32_bf16 v[54:57], v[150:153], v[166:169], v[54:57]
	v_mfma_f32_16x16x32_bf16 v[46:49], v[158:161], v[166:169], v[46:49]
	v_mfma_f32_16x16x32_bf16 v[38:41], v[150:153], v[198:201], v[38:41]
	v_mfma_f32_16x16x32_bf16 v[30:33], v[158:161], v[198:201], v[30:33]
	v_mfma_f32_16x16x32_bf16 v[22:25], v[150:153], v[210:213], v[22:25]
	v_mfma_f32_16x16x32_bf16 v[14:17], v[158:161], v[210:213], v[14:17]
	v_mfma_f32_16x16x32_bf16 v[6:9], v[150:153], v[218:221], v[6:9]
	v_mfma_f32_16x16x32_bf16 v[2:5], v[158:161], v[218:221], v[2:5]
	s_setprio 0
	s_barrier
	s_add_i32 s63, 0, 0x18000
	s_add_i32 s83, 0, 0x1c000
	v_add_u32_e32 v126, s63, v189
	v_add_u32_e32 v158, s83, v189
	ds_read_b128 v[114:117], v126
	ds_read_b128 v[118:121], v126 offset:1024
	ds_read_b128 v[122:125], v126 offset:2048
	ds_read_b128 v[126:129], v126 offset:3072
	ds_read_b128 v[146:149], v158
	ds_read_b128 v[150:153], v158 offset:1024
	ds_read_b128 v[154:157], v158 offset:2048
	ds_read_b128 v[158:161], v158 offset:3072
	s_add_u32 s80, s80, 0x40000
	s_addc_u32 s81, s81, 0
	s_mov_b32 m0, s89
	v_lshl_add_u64 v[226:227], s[80:81], 0, v[170:171]
	ds_read_b128 v[162:165], v192 offset:32768
	ds_read_b128 v[166:169], v192 offset:33792
	ds_read_b128 v[194:197], v192 offset:34816
	ds_read_b128 v[198:201], v192 offset:35840
	ds_read_b128 v[206:209], v192 offset:36864
	ds_read_b128 v[210:213], v192 offset:37888
	ds_read_b128 v[214:217], v192 offset:38912
	ds_read_b128 v[218:221], v192 offset:39936
	global_load_lds_dwordx4 v[226:227], off
	v_lshl_add_u64 v[226:227], s[80:81], 0, v[174:175]
	s_mov_b32 m0, s90
	s_nop 0
	global_load_lds_dwordx4 v[226:227], off
	s_waitcnt vmcnt(8)
	s_waitcnt lgkmcnt(0)
	s_setprio 1
	s_barrier
	v_mfma_f32_16x16x32_bf16 v[142:145], v[114:117], v[162:165], v[142:145]
	v_mfma_f32_16x16x32_bf16 v[138:141], v[122:125], v[162:165], v[138:141]
	v_mfma_f32_16x16x32_bf16 v[110:113], v[114:117], v[194:197], v[110:113]
	v_mfma_f32_16x16x32_bf16 v[106:109], v[122:125], v[194:197], v[106:109]
	v_mfma_f32_16x16x32_bf16 v[98:101], v[114:117], v[206:209], v[98:101]
	v_mfma_f32_16x16x32_bf16 v[90:93], v[122:125], v[206:209], v[90:93]
	v_mfma_f32_16x16x32_bf16 v[82:85], v[114:117], v[214:217], v[82:85]
	v_mfma_f32_16x16x32_bf16 v[74:77], v[122:125], v[214:217], v[74:77]
	v_mfma_f32_16x16x32_bf16 v[142:145], v[118:121], v[166:169], v[142:145]
	v_mfma_f32_16x16x32_bf16 v[138:141], v[126:129], v[166:169], v[138:141]
	v_mfma_f32_16x16x32_bf16 v[110:113], v[118:121], v[198:201], v[110:113]
	v_mfma_f32_16x16x32_bf16 v[106:109], v[126:129], v[198:201], v[106:109]
	v_mfma_f32_16x16x32_bf16 v[98:101], v[118:121], v[210:213], v[98:101]
	v_mfma_f32_16x16x32_bf16 v[90:93], v[126:129], v[210:213], v[90:93]
	v_mfma_f32_16x16x32_bf16 v[82:85], v[118:121], v[218:221], v[82:85]
	v_mfma_f32_16x16x32_bf16 v[74:77], v[126:129], v[218:221], v[74:77]
	v_mfma_f32_16x16x32_bf16 v[134:137], v[146:149], v[162:165], v[134:137]
	v_mfma_f32_16x16x32_bf16 v[130:133], v[154:157], v[162:165], v[130:133]
	v_mfma_f32_16x16x32_bf16 v[102:105], v[146:149], v[194:197], v[102:105]
	v_mfma_f32_16x16x32_bf16 v[94:97], v[154:157], v[194:197], v[94:97]
	v_mfma_f32_16x16x32_bf16 v[86:89], v[146:149], v[206:209], v[86:89]
	v_mfma_f32_16x16x32_bf16 v[78:81], v[154:157], v[206:209], v[78:81]
	v_mfma_f32_16x16x32_bf16 v[70:73], v[146:149], v[214:217], v[70:73]
	v_mfma_f32_16x16x32_bf16 v[66:69], v[154:157], v[214:217], v[66:69]
	v_mfma_f32_16x16x32_bf16 v[134:137], v[150:153], v[166:169], v[134:137]
	v_mfma_f32_16x16x32_bf16 v[130:133], v[158:161], v[166:169], v[130:133]
	v_mfma_f32_16x16x32_bf16 v[102:105], v[150:153], v[198:201], v[102:105]
	v_mfma_f32_16x16x32_bf16 v[94:97], v[158:161], v[198:201], v[94:97]
	v_mfma_f32_16x16x32_bf16 v[86:89], v[150:153], v[210:213], v[86:89]
	v_mfma_f32_16x16x32_bf16 v[78:81], v[158:161], v[210:213], v[78:81]
	v_mfma_f32_16x16x32_bf16 v[70:73], v[150:153], v[218:221], v[70:73]
	v_mfma_f32_16x16x32_bf16 v[66:69], v[158:161], v[218:221], v[66:69]
	s_setprio 0
	s_barrier
	s_add_i32 s63, s63, s86
	v_lshl_add_u64 v[186:187], v[186:187], 0, s[22:23]
	s_mov_b32 m0, s63
	ds_read_b128 v[162:165], v192 offset:49152
	ds_read_b128 v[166:169], v192 offset:50176
	ds_read_b128 v[194:197], v192 offset:51200
	ds_read_b128 v[198:201], v192 offset:52224
	ds_read_b128 v[206:209], v192 offset:53248
	ds_read_b128 v[210:213], v192 offset:54272
	ds_read_b128 v[214:217], v192 offset:55296
	ds_read_b128 v[218:221], v192 offset:56320
	global_load_lds_dwordx4 v[186:187], off
	s_add_i32 m0, s63, 0x2000
	s_add_u32 s78, s78, 0x40080
	v_lshl_add_u64 v[186:187], v[202:203], 0, s[22:23]
	s_addc_u32 s79, s79, 0
	s_add_i32 s63, s83, s86
	global_load_lds_dwordx4 v[186:187], off
	v_lshl_add_u64 v[186:187], s[78:79], 0, v[172:173]
	s_mov_b32 m0, s63
	s_nop 0
	global_load_lds_dwordx4 v[186:187], off
	v_lshl_add_u64 v[186:187], s[78:79], 0, v[176:177]
	s_add_i32 m0, s63, 0x2000
	s_nop 0
	global_load_lds_dwordx4 v[186:187], off
	v_lshl_add_u64 v[186:187], v[222:223], 0, s[22:23]
	s_mov_b32 m0, s95
	s_nop 0
	global_load_lds_dwordx4 v[186:187], off
	v_lshl_add_u64 v[186:187], v[224:225], 0, s[22:23]
	s_mov_b32 m0, s96
	s_nop 0
	global_load_lds_dwordx4 v[186:187], off
	s_waitcnt vmcnt(8)
	s_waitcnt lgkmcnt(0)
	s_setprio 1
	s_barrier
	v_mfma_f32_16x16x32_bf16 v[62:65], v[114:117], v[162:165], v[62:65]
	v_mfma_f32_16x16x32_bf16 v[58:61], v[122:125], v[162:165], v[58:61]
	v_mfma_f32_16x16x32_bf16 v[50:53], v[114:117], v[194:197], v[50:53]
	v_mfma_f32_16x16x32_bf16 v[42:45], v[122:125], v[194:197], v[42:45]
	v_mfma_f32_16x16x32_bf16 v[34:37], v[114:117], v[206:209], v[34:37]
	v_mfma_f32_16x16x32_bf16 v[26:29], v[122:125], v[206:209], v[26:29]
	v_mfma_f32_16x16x32_bf16 v[18:21], v[114:117], v[214:217], v[18:21]
	v_mfma_f32_16x16x32_bf16 v[10:13], v[122:125], v[214:217], v[10:13]
	v_mfma_f32_16x16x32_bf16 v[62:65], v[118:121], v[166:169], v[62:65]
	v_mfma_f32_16x16x32_bf16 v[58:61], v[126:129], v[166:169], v[58:61]
	v_mfma_f32_16x16x32_bf16 v[50:53], v[118:121], v[198:201], v[50:53]
	v_mfma_f32_16x16x32_bf16 v[42:45], v[126:129], v[198:201], v[42:45]
	v_mfma_f32_16x16x32_bf16 v[34:37], v[118:121], v[210:213], v[34:37]
	v_mfma_f32_16x16x32_bf16 v[26:29], v[126:129], v[210:213], v[26:29]
	v_mfma_f32_16x16x32_bf16 v[18:21], v[118:121], v[218:221], v[18:21]
	v_mfma_f32_16x16x32_bf16 v[10:13], v[126:129], v[218:221], v[10:13]
	v_mfma_f32_16x16x32_bf16 v[54:57], v[146:149], v[162:165], v[54:57]
	v_mfma_f32_16x16x32_bf16 v[46:49], v[154:157], v[162:165], v[46:49]
	v_mfma_f32_16x16x32_bf16 v[38:41], v[146:149], v[194:197], v[38:41]
	v_mfma_f32_16x16x32_bf16 v[30:33], v[154:157], v[194:197], v[30:33]
	v_mfma_f32_16x16x32_bf16 v[22:25], v[146:149], v[206:209], v[22:25]
	v_mfma_f32_16x16x32_bf16 v[14:17], v[154:157], v[206:209], v[14:17]
	v_mfma_f32_16x16x32_bf16 v[6:9], v[146:149], v[214:217], v[6:9]
	v_mfma_f32_16x16x32_bf16 v[2:5], v[154:157], v[214:217], v[2:5]
	v_mfma_f32_16x16x32_bf16 v[54:57], v[150:153], v[166:169], v[54:57]
	v_mfma_f32_16x16x32_bf16 v[46:49], v[158:161], v[166:169], v[46:49]
	v_mfma_f32_16x16x32_bf16 v[38:41], v[150:153], v[198:201], v[38:41]
	v_mfma_f32_16x16x32_bf16 v[30:33], v[158:161], v[198:201], v[30:33]
	v_mfma_f32_16x16x32_bf16 v[22:25], v[150:153], v[210:213], v[22:25]
	v_mfma_f32_16x16x32_bf16 v[14:17], v[158:161], v[210:213], v[14:17]
	v_mfma_f32_16x16x32_bf16 v[6:9], v[150:153], v[218:221], v[6:9]
	v_mfma_f32_16x16x32_bf16 v[2:5], v[158:161], v[218:221], v[2:5]
	s_setprio 0
	s_barrier
	s_add_u32 s76, s76, 0x100
	s_addc_u32 s77, s77, 0
	s_add_u32 s47, s47, 0x100
	s_addc_u32 s62, s62, 0
	s_cmp_ge_i32 s82, s7
	s_mov_b32 s63, s82
	s_cbranch_scc0 .LBB0_566
	s_and_b64 vcc, exec, s[26:27]
	s_cbranch_vccz .LBB0_569
	s_barrier

.LBB0_744:
	s_add_u32 s36, s96, s22
	s_addc_u32 s37, s97, s23
	s_and_b64 s[14:15], s[4:5], exec
	s_cselect_b32 s14, s37, s43
	s_cselect_b32 s15, s36, s42
	s_add_u32 s38, s2, s26
	s_addc_u32 s39, s3, s27
	s_and_b64 s[46:47], s[4:5], exec
	s_cselect_b32 s21, s39, s45
	s_cselect_b32 s65, s38, s44
	s_add_u32 s42, s42, 0x40080
	s_addc_u32 s43, s43, 0
	s_add_u32 s66, s44, 0x100
	s_addc_u32 s67, s45, 0
	s_mov_b32 s68, -2
	ds_read_b128 v[154:157], v150
	ds_read_b128 v[158:161], v150 offset:1024
	ds_read_b128 v[162:165], v150 offset:2048
	ds_read_b128 v[166:169], v150 offset:3072
	ds_read_b128 v[170:173], v151
	ds_read_b128 v[174:177], v151 offset:1024
	ds_read_b128 v[178:181], v151 offset:2048
	ds_read_b128 v[182:185], v151 offset:3072
	ds_read_b128 v[186:189], v152
	ds_read_b128 v[190:193], v152 offset:1024
	ds_read_b128 v[194:197], v152 offset:2048
	ds_read_b128 v[198:201], v152 offset:3072
	ds_read_b128 v[206:209], v152 offset:4096
	ds_read_b128 v[210:213], v152 offset:5120
	ds_read_b128 v[214:217], v152 offset:6144
	ds_read_b128 v[218:221], v152 offset:7168
	s_add_u32 s44, s42, 0xfffc0080
	s_addc_u32 s45, s43, -1
	s_cmp_eq_u32 s68, 12
	s_cselect_b32 s47, s14, s45
	s_cselect_b32 s46, s15, s44
	s_cselect_b32 s45, s21, s67
	s_cselect_b32 s44, s65, s66
	s_add_i32 m0, s19, 0xc000
	v_lshl_add_u64 v[146:147], s[42:43], 0, v[138:139]
	global_load_lds_dwordx4 v[146:147], off
	v_lshl_add_u64 v[146:147], s[42:43], 0, v[140:141]
	s_add_i32 m0, s19, 0xe000
	s_nop 0
	global_load_lds_dwordx4 v[146:147], off
	s_waitcnt vmcnt(8)
	s_waitcnt lgkmcnt(0)
	s_setprio 1
	s_barrier
	v_mfma_f32_16x16x32_bf16 v[126:129], v[154:157], v[186:189], 0
	v_mfma_f32_16x16x32_bf16 v[122:125], v[162:165], v[186:189], 0
	v_mfma_f32_16x16x32_bf16 v[110:113], v[154:157], v[194:197], 0
	v_mfma_f32_16x16x32_bf16 v[106:109], v[162:165], v[194:197], 0
	v_mfma_f32_16x16x32_bf16 v[94:97], v[154:157], v[206:209], 0
	v_mfma_f32_16x16x32_bf16 v[90:93], v[162:165], v[206:209], 0
	v_mfma_f32_16x16x32_bf16 v[78:81], v[154:157], v[214:217], 0
	v_mfma_f32_16x16x32_bf16 v[74:77], v[162:165], v[214:217], 0
	v_mfma_f32_16x16x32_bf16 v[126:129], v[158:161], v[190:193], v[126:129]
	v_mfma_f32_16x16x32_bf16 v[122:125], v[166:169], v[190:193], v[122:125]
	v_mfma_f32_16x16x32_bf16 v[110:113], v[158:161], v[198:201], v[110:113]
	v_mfma_f32_16x16x32_bf16 v[106:109], v[166:169], v[198:201], v[106:109]
	v_mfma_f32_16x16x32_bf16 v[94:97], v[158:161], v[210:213], v[94:97]
	v_mfma_f32_16x16x32_bf16 v[90:93], v[166:169], v[210:213], v[90:93]
	v_mfma_f32_16x16x32_bf16 v[78:81], v[158:161], v[218:221], v[78:81]
	v_mfma_f32_16x16x32_bf16 v[74:77], v[166:169], v[218:221], v[74:77]
	v_mfma_f32_16x16x32_bf16 v[118:121], v[170:173], v[186:189], 0
	v_mfma_f32_16x16x32_bf16 v[114:117], v[178:181], v[186:189], 0
	v_mfma_f32_16x16x32_bf16 v[102:105], v[170:173], v[194:197], 0
	v_mfma_f32_16x16x32_bf16 v[98:101], v[178:181], v[194:197], 0
	v_mfma_f32_16x16x32_bf16 v[86:89], v[170:173], v[206:209], 0
	v_mfma_f32_16x16x32_bf16 v[82:85], v[178:181], v[206:209], 0
	v_mfma_f32_16x16x32_bf16 v[70:73], v[170:173], v[214:217], 0
	v_mfma_f32_16x16x32_bf16 v[66:69], v[178:181], v[214:217], 0
	v_mfma_f32_16x16x32_bf16 v[118:121], v[174:177], v[190:193], v[118:121]
	v_mfma_f32_16x16x32_bf16 v[114:117], v[182:185], v[190:193], v[114:117]
	v_mfma_f32_16x16x32_bf16 v[102:105], v[174:177], v[198:201], v[102:105]
	v_mfma_f32_16x16x32_bf16 v[98:101], v[182:185], v[198:201], v[98:101]
	v_mfma_f32_16x16x32_bf16 v[86:89], v[174:177], v[210:213], v[86:89]
	v_mfma_f32_16x16x32_bf16 v[82:85], v[182:185], v[210:213], v[82:85]
	v_mfma_f32_16x16x32_bf16 v[70:73], v[174:177], v[218:221], v[70:73]
	v_mfma_f32_16x16x32_bf16 v[66:69], v[182:185], v[218:221], v[66:69]
	s_setprio 0
	s_barrier
	s_add_i32 s69, s49, s16
	v_lshl_add_u64 v[146:147], s[44:45], 0, v[134:135]
	s_mov_b32 m0, s69
	ds_read_b128 v[186:189], v152 offset:16384
	ds_read_b128 v[190:193], v152 offset:17408
	ds_read_b128 v[194:197], v152 offset:18432
	ds_read_b128 v[198:201], v152 offset:19456
	ds_read_b128 v[206:209], v152 offset:20480
	ds_read_b128 v[210:213], v152 offset:21504
	ds_read_b128 v[214:217], v152 offset:22528
	ds_read_b128 v[218:221], v152 offset:23552
	global_load_lds_dwordx4 v[146:147], off
	s_add_i32 m0, s69, 0x2000
	s_add_u32 s70, s44, 0x40000
	v_lshl_add_u64 v[202:203], s[44:45], 0, v[130:131]
	s_addc_u32 s71, s45, 0
	s_add_i32 s69, s62, s16
	global_load_lds_dwordx4 v[202:203], off
	v_lshl_add_u64 v[222:223], s[70:71], 0, v[134:135]
	s_mov_b32 m0, s69
	v_lshl_add_u64 v[224:225], s[46:47], 0, v[132:133]
	global_load_lds_dwordx4 v[222:223], off
	v_lshl_add_u64 v[222:223], s[70:71], 0, v[130:131]
	s_add_i32 m0, s69, 0x2000
	s_nop 0
	global_load_lds_dwordx4 v[222:223], off
	v_lshl_add_u64 v[222:223], s[46:47], 0, v[136:137]
	s_mov_b32 m0, s19
	s_nop 0
	global_load_lds_dwordx4 v[222:223], off
	s_mov_b32 m0, s24
	s_nop 0
	global_load_lds_dwordx4 v[224:225], off
	s_waitcnt vmcnt(8)
	s_waitcnt lgkmcnt(0)
	s_setprio 1
	s_barrier
	v_mfma_f32_16x16x32_bf16 v[62:65], v[154:157], v[186:189], 0
	v_mfma_f32_16x16x32_bf16 v[58:61], v[162:165], v[186:189], 0
	v_mfma_f32_16x16x32_bf16 v[46:49], v[154:157], v[194:197], 0
	v_mfma_f32_16x16x32_bf16 v[42:45], v[162:165], v[194:197], 0
	v_mfma_f32_16x16x32_bf16 v[30:33], v[154:157], v[206:209], 0
	v_mfma_f32_16x16x32_bf16 v[26:29], v[162:165], v[206:209], 0
	v_mfma_f32_16x16x32_bf16 v[14:17], v[154:157], v[214:217], 0
	v_mfma_f32_16x16x32_bf16 v[10:13], v[162:165], v[214:217], 0
	v_mfma_f32_16x16x32_bf16 v[62:65], v[158:161], v[190:193], v[62:65]
	v_mfma_f32_16x16x32_bf16 v[58:61], v[166:169], v[190:193], v[58:61]
	v_mfma_f32_16x16x32_bf16 v[46:49], v[158:161], v[198:201], v[46:49]
	v_mfma_f32_16x16x32_bf16 v[42:45], v[166:169], v[198:201], v[42:45]
	v_mfma_f32_16x16x32_bf16 v[30:33], v[158:161], v[210:213], v[30:33]
	v_mfma_f32_16x16x32_bf16 v[26:29], v[166:169], v[210:213], v[26:29]
	v_mfma_f32_16x16x32_bf16 v[14:17], v[158:161], v[218:221], v[14:17]
	v_mfma_f32_16x16x32_bf16 v[10:13], v[166:169], v[218:221], v[10:13]
	v_mfma_f32_16x16x32_bf16 v[54:57], v[170:173], v[186:189], 0
	v_mfma_f32_16x16x32_bf16 v[50:53], v[178:181], v[186:189], 0
	v_mfma_f32_16x16x32_bf16 v[38:41], v[170:173], v[194:197], 0
	v_mfma_f32_16x16x32_bf16 v[34:37], v[178:181], v[194:197], 0
	v_mfma_f32_16x16x32_bf16 v[22:25], v[170:173], v[206:209], 0
	v_mfma_f32_16x16x32_bf16 v[18:21], v[178:181], v[206:209], 0
	v_mfma_f32_16x16x32_bf16 v[6:9], v[170:173], v[214:217], 0
	v_mfma_f32_16x16x32_bf16 v[2:5], v[178:181], v[214:217], 0
	v_mfma_f32_16x16x32_bf16 v[54:57], v[174:177], v[190:193], v[54:57]
	v_mfma_f32_16x16x32_bf16 v[50:53], v[182:185], v[190:193], v[50:53]
	v_mfma_f32_16x16x32_bf16 v[38:41], v[174:177], v[198:201], v[38:41]
	v_mfma_f32_16x16x32_bf16 v[34:37], v[182:185], v[198:201], v[34:37]
	v_mfma_f32_16x16x32_bf16 v[22:25], v[174:177], v[210:213], v[22:25]
	v_mfma_f32_16x16x32_bf16 v[18:21], v[182:185], v[210:213], v[18:21]
	v_mfma_f32_16x16x32_bf16 v[6:9], v[174:177], v[218:221], v[6:9]
	v_mfma_f32_16x16x32_bf16 v[2:5], v[182:185], v[218:221], v[2:5]
	s_setprio 0
	s_barrier
	s_add_i32 s69, 0, 0x18000
	v_add_u32_e32 v153, s69, v149
	s_add_i32 s70, 0, 0x1c000
	ds_read_b128 v[154:157], v153
	ds_read_b128 v[158:161], v153 offset:1024
	ds_read_b128 v[162:165], v153 offset:2048
	ds_read_b128 v[166:169], v153 offset:3072
	v_add_u32_e32 v153, s70, v149
	ds_read_b128 v[170:173], v153
	ds_read_b128 v[174:177], v153 offset:1024
	ds_read_b128 v[178:181], v153 offset:2048
	ds_read_b128 v[182:185], v153 offset:3072
	s_add_u32 s46, s46, 0x40000
	s_addc_u32 s47, s47, 0
	s_mov_b32 m0, s25
	v_lshl_add_u64 v[226:227], s[46:47], 0, v[136:137]
	ds_read_b128 v[186:189], v152 offset:32768
	ds_read_b128 v[190:193], v152 offset:33792
	ds_read_b128 v[194:197], v152 offset:34816
	ds_read_b128 v[198:201], v152 offset:35840
	ds_read_b128 v[206:209], v152 offset:36864
	ds_read_b128 v[210:213], v152 offset:37888
	ds_read_b128 v[214:217], v152 offset:38912
	ds_read_b128 v[218:221], v152 offset:39936
	global_load_lds_dwordx4 v[226:227], off
	v_lshl_add_u64 v[226:227], s[46:47], 0, v[132:133]
	s_mov_b32 m0, s28
	s_nop 0
	global_load_lds_dwordx4 v[226:227], off
	s_waitcnt vmcnt(8)
	s_waitcnt lgkmcnt(0)
	s_setprio 1
	s_barrier
	v_mfma_f32_16x16x32_bf16 v[126:129], v[154:157], v[186:189], v[126:129]
	v_mfma_f32_16x16x32_bf16 v[122:125], v[162:165], v[186:189], v[122:125]
	v_mfma_f32_16x16x32_bf16 v[110:113], v[154:157], v[194:197], v[110:113]
	v_mfma_f32_16x16x32_bf16 v[106:109], v[162:165], v[194:197], v[106:109]
	v_mfma_f32_16x16x32_bf16 v[94:97], v[154:157], v[206:209], v[94:97]
	v_mfma_f32_16x16x32_bf16 v[90:93], v[162:165], v[206:209], v[90:93]
	v_mfma_f32_16x16x32_bf16 v[78:81], v[154:157], v[214:217], v[78:81]
	v_mfma_f32_16x16x32_bf16 v[74:77], v[162:165], v[214:217], v[74:77]
	v_mfma_f32_16x16x32_bf16 v[126:129], v[158:161], v[190:193], v[126:129]
	v_mfma_f32_16x16x32_bf16 v[122:125], v[166:169], v[190:193], v[122:125]
	v_mfma_f32_16x16x32_bf16 v[110:113], v[158:161], v[198:201], v[110:113]
	v_mfma_f32_16x16x32_bf16 v[106:109], v[166:169], v[198:201], v[106:109]
	v_mfma_f32_16x16x32_bf16 v[94:97], v[158:161], v[210:213], v[94:97]
	v_mfma_f32_16x16x32_bf16 v[90:93], v[166:169], v[210:213], v[90:93]
	v_mfma_f32_16x16x32_bf16 v[78:81], v[158:161], v[218:221], v[78:81]
	v_mfma_f32_16x16x32_bf16 v[74:77], v[166:169], v[218:221], v[74:77]
	v_mfma_f32_16x16x32_bf16 v[118:121], v[170:173], v[186:189], v[118:121]
	v_mfma_f32_16x16x32_bf16 v[114:117], v[178:181], v[186:189], v[114:117]
	v_mfma_f32_16x16x32_bf16 v[102:105], v[170:173], v[194:197], v[102:105]
	v_mfma_f32_16x16x32_bf16 v[98:101], v[178:181], v[194:197], v[98:101]
	v_mfma_f32_16x16x32_bf16 v[86:89], v[170:173], v[206:209], v[86:89]
	v_mfma_f32_16x16x32_bf16 v[82:85], v[178:181], v[206:209], v[82:85]
	v_mfma_f32_16x16x32_bf16 v[70:73], v[170:173], v[214:217], v[70:73]
	v_mfma_f32_16x16x32_bf16 v[66:69], v[178:181], v[214:217], v[66:69]
	v_mfma_f32_16x16x32_bf16 v[118:121], v[174:177], v[190:193], v[118:121]
	v_mfma_f32_16x16x32_bf16 v[114:117], v[182:185], v[190:193], v[114:117]
	v_mfma_f32_16x16x32_bf16 v[102:105], v[174:177], v[198:201], v[102:105]
	v_mfma_f32_16x16x32_bf16 v[98:101], v[182:185], v[198:201], v[98:101]
	v_mfma_f32_16x16x32_bf16 v[86:89], v[174:177], v[210:213], v[86:89]
	v_mfma_f32_16x16x32_bf16 v[82:85], v[182:185], v[210:213], v[82:85]
	v_mfma_f32_16x16x32_bf16 v[70:73], v[174:177], v[218:221], v[70:73]
	v_mfma_f32_16x16x32_bf16 v[66:69], v[182:185], v[218:221], v[66:69]
	s_setprio 0
	s_barrier
	s_add_i32 s46, s69, s16
	v_lshl_add_u64 v[146:147], v[146:147], 0, s[10:11]
	s_mov_b32 m0, s46
	ds_read_b128 v[186:189], v152 offset:49152
	ds_read_b128 v[190:193], v152 offset:50176
	ds_read_b128 v[194:197], v152 offset:51200
	ds_read_b128 v[198:201], v152 offset:52224
	ds_read_b128 v[206:209], v152 offset:53248
	ds_read_b128 v[210:213], v152 offset:54272
	ds_read_b128 v[214:217], v152 offset:55296
	ds_read_b128 v[218:221], v152 offset:56320
	global_load_lds_dwordx4 v[146:147], off
	s_add_i32 m0, s46, 0x2000
	s_add_u32 s44, s44, 0x40080
	v_lshl_add_u64 v[146:147], v[202:203], 0, s[10:11]
	s_addc_u32 s45, s45, 0
	s_add_i32 s46, s70, s16
	global_load_lds_dwordx4 v[146:147], off
	v_lshl_add_u64 v[146:147], s[44:45], 0, v[134:135]
	s_mov_b32 m0, s46
	s_nop 0
	global_load_lds_dwordx4 v[146:147], off
	v_lshl_add_u64 v[146:147], s[44:45], 0, v[130:131]
	s_add_i32 m0, s46, 0x2000
	s_nop 0
	global_load_lds_dwordx4 v[146:147], off
	v_lshl_add_u64 v[146:147], v[222:223], 0, s[10:11]
	s_mov_b32 m0, s33
	s_nop 0
	global_load_lds_dwordx4 v[146:147], off
	v_lshl_add_u64 v[146:147], v[224:225], 0, s[10:11]
	s_mov_b32 m0, s35
	s_nop 0
	global_load_lds_dwordx4 v[146:147], off
	s_waitcnt vmcnt(8)
	s_waitcnt lgkmcnt(0)
	s_setprio 1
	s_barrier
	v_mfma_f32_16x16x32_bf16 v[62:65], v[154:157], v[186:189], v[62:65]
	v_mfma_f32_16x16x32_bf16 v[58:61], v[162:165], v[186:189], v[58:61]
	v_mfma_f32_16x16x32_bf16 v[46:49], v[154:157], v[194:197], v[46:49]
	v_mfma_f32_16x16x32_bf16 v[42:45], v[162:165], v[194:197], v[42:45]
	v_mfma_f32_16x16x32_bf16 v[30:33], v[154:157], v[206:209], v[30:33]
	v_mfma_f32_16x16x32_bf16 v[26:29], v[162:165], v[206:209], v[26:29]
	v_mfma_f32_16x16x32_bf16 v[14:17], v[154:157], v[214:217], v[14:17]
	v_mfma_f32_16x16x32_bf16 v[10:13], v[162:165], v[214:217], v[10:13]
	v_mfma_f32_16x16x32_bf16 v[62:65], v[158:161], v[190:193], v[62:65]
	v_mfma_f32_16x16x32_bf16 v[58:61], v[166:169], v[190:193], v[58:61]
	v_mfma_f32_16x16x32_bf16 v[46:49], v[158:161], v[198:201], v[46:49]
	v_mfma_f32_16x16x32_bf16 v[42:45], v[166:169], v[198:201], v[42:45]
	v_mfma_f32_16x16x32_bf16 v[30:33], v[158:161], v[210:213], v[30:33]
	v_mfma_f32_16x16x32_bf16 v[26:29], v[166:169], v[210:213], v[26:29]
	v_mfma_f32_16x16x32_bf16 v[14:17], v[158:161], v[218:221], v[14:17]
	v_mfma_f32_16x16x32_bf16 v[10:13], v[166:169], v[218:221], v[10:13]
	v_mfma_f32_16x16x32_bf16 v[54:57], v[170:173], v[186:189], v[54:57]
	v_mfma_f32_16x16x32_bf16 v[50:53], v[178:181], v[186:189], v[50:53]
	v_mfma_f32_16x16x32_bf16 v[38:41], v[170:173], v[194:197], v[38:41]
	v_mfma_f32_16x16x32_bf16 v[34:37], v[178:181], v[194:197], v[34:37]
	v_mfma_f32_16x16x32_bf16 v[22:25], v[170:173], v[206:209], v[22:25]
	v_mfma_f32_16x16x32_bf16 v[18:21], v[178:181], v[206:209], v[18:21]
	v_mfma_f32_16x16x32_bf16 v[6:9], v[170:173], v[214:217], v[6:9]
	v_mfma_f32_16x16x32_bf16 v[2:5], v[178:181], v[214:217], v[2:5]
	v_mfma_f32_16x16x32_bf16 v[54:57], v[174:177], v[190:193], v[54:57]
	v_mfma_f32_16x16x32_bf16 v[50:53], v[182:185], v[190:193], v[50:53]
	v_mfma_f32_16x16x32_bf16 v[38:41], v[174:177], v[198:201], v[38:41]
	v_mfma_f32_16x16x32_bf16 v[34:37], v[182:185], v[198:201], v[34:37]
	v_mfma_f32_16x16x32_bf16 v[22:25], v[174:177], v[210:213], v[22:25]
	v_mfma_f32_16x16x32_bf16 v[18:21], v[182:185], v[210:213], v[18:21]
	v_mfma_f32_16x16x32_bf16 v[6:9], v[174:177], v[218:221], v[6:9]
	v_mfma_f32_16x16x32_bf16 v[2:5], v[182:185], v[218:221], v[2:5]
	s_setprio 0
	s_barrier
	s_add_i32 s68, s68, 2
	s_add_u32 s42, s42, 0x100
	s_addc_u32 s43, s43, 0
	s_add_u32 s66, s66, 0x100
	s_addc_u32 s67, s67, 0
	s_cmp_gt_u32 s68, 13
.LBB0_745:
	ds_read_b128 v[154:157], v150
	ds_read_b128 v[158:161], v150 offset:1024
	ds_read_b128 v[162:165], v150 offset:2048
	ds_read_b128 v[166:169], v150 offset:3072
	ds_read_b128 v[170:173], v151
	ds_read_b128 v[174:177], v151 offset:1024
	ds_read_b128 v[178:181], v151 offset:2048
	ds_read_b128 v[182:185], v151 offset:3072
	ds_read_b128 v[186:189], v152
	ds_read_b128 v[190:193], v152 offset:1024
	ds_read_b128 v[194:197], v152 offset:2048
	ds_read_b128 v[198:201], v152 offset:3072
	ds_read_b128 v[206:209], v152 offset:4096
	ds_read_b128 v[210:213], v152 offset:5120
	ds_read_b128 v[214:217], v152 offset:6144
	ds_read_b128 v[218:221], v152 offset:7168
	s_add_u32 s44, s42, 0xfffc0080
	s_addc_u32 s45, s43, -1
	s_cmp_eq_u32 s68, 12
	s_cselect_b32 s47, s14, s45
	s_cselect_b32 s46, s15, s44
	s_cselect_b32 s45, s21, s67
	s_cselect_b32 s44, s65, s66
	s_add_i32 m0, s19, 0xc000
	v_lshl_add_u64 v[146:147], s[42:43], 0, v[138:139]
	global_load_lds_dwordx4 v[146:147], off
	v_lshl_add_u64 v[146:147], s[42:43], 0, v[140:141]
	s_add_i32 m0, s19, 0xe000
	s_nop 0
	global_load_lds_dwordx4 v[146:147], off
	s_waitcnt vmcnt(8)
	s_waitcnt lgkmcnt(0)
	s_setprio 1
	s_barrier
	v_mfma_f32_16x16x32_bf16 v[126:129], v[154:157], v[186:189], v[126:129]
	v_mfma_f32_16x16x32_bf16 v[122:125], v[162:165], v[186:189], v[122:125]
	v_mfma_f32_16x16x32_bf16 v[110:113], v[154:157], v[194:197], v[110:113]
	v_mfma_f32_16x16x32_bf16 v[106:109], v[162:165], v[194:197], v[106:109]
	v_mfma_f32_16x16x32_bf16 v[94:97], v[154:157], v[206:209], v[94:97]
	v_mfma_f32_16x16x32_bf16 v[90:93], v[162:165], v[206:209], v[90:93]
	v_mfma_f32_16x16x32_bf16 v[78:81], v[154:157], v[214:217], v[78:81]
	v_mfma_f32_16x16x32_bf16 v[74:77], v[162:165], v[214:217], v[74:77]
	v_mfma_f32_16x16x32_bf16 v[126:129], v[158:161], v[190:193], v[126:129]
	v_mfma_f32_16x16x32_bf16 v[122:125], v[166:169], v[190:193], v[122:125]
	v_mfma_f32_16x16x32_bf16 v[110:113], v[158:161], v[198:201], v[110:113]
	v_mfma_f32_16x16x32_bf16 v[106:109], v[166:169], v[198:201], v[106:109]
	v_mfma_f32_16x16x32_bf16 v[94:97], v[158:161], v[210:213], v[94:97]
	v_mfma_f32_16x16x32_bf16 v[90:93], v[166:169], v[210:213], v[90:93]
	v_mfma_f32_16x16x32_bf16 v[78:81], v[158:161], v[218:221], v[78:81]
	v_mfma_f32_16x16x32_bf16 v[74:77], v[166:169], v[218:221], v[74:77]
	v_mfma_f32_16x16x32_bf16 v[118:121], v[170:173], v[186:189], v[118:121]
	v_mfma_f32_16x16x32_bf16 v[114:117], v[178:181], v[186:189], v[114:117]
	v_mfma_f32_16x16x32_bf16 v[102:105], v[170:173], v[194:197], v[102:105]
	v_mfma_f32_16x16x32_bf16 v[98:101], v[178:181], v[194:197], v[98:101]
	v_mfma_f32_16x16x32_bf16 v[86:89], v[170:173], v[206:209], v[86:89]
	v_mfma_f32_16x16x32_bf16 v[82:85], v[178:181], v[206:209], v[82:85]
	v_mfma_f32_16x16x32_bf16 v[70:73], v[170:173], v[214:217], v[70:73]
	v_mfma_f32_16x16x32_bf16 v[66:69], v[178:181], v[214:217], v[66:69]
	v_mfma_f32_16x16x32_bf16 v[118:121], v[174:177], v[190:193], v[118:121]
	v_mfma_f32_16x16x32_bf16 v[114:117], v[182:185], v[190:193], v[114:117]
	v_mfma_f32_16x16x32_bf16 v[102:105], v[174:177], v[198:201], v[102:105]
	v_mfma_f32_16x16x32_bf16 v[98:101], v[182:185], v[198:201], v[98:101]
	v_mfma_f32_16x16x32_bf16 v[86:89], v[174:177], v[210:213], v[86:89]
	v_mfma_f32_16x16x32_bf16 v[82:85], v[182:185], v[210:213], v[82:85]
	v_mfma_f32_16x16x32_bf16 v[70:73], v[174:177], v[218:221], v[70:73]
	v_mfma_f32_16x16x32_bf16 v[66:69], v[182:185], v[218:221], v[66:69]
	s_setprio 0
	s_barrier
	s_add_i32 s69, s49, s16
	v_lshl_add_u64 v[146:147], s[44:45], 0, v[134:135]
	s_mov_b32 m0, s69
	ds_read_b128 v[186:189], v152 offset:16384
	ds_read_b128 v[190:193], v152 offset:17408
	ds_read_b128 v[194:197], v152 offset:18432
	ds_read_b128 v[198:201], v152 offset:19456
	ds_read_b128 v[206:209], v152 offset:20480
	ds_read_b128 v[210:213], v152 offset:21504
	ds_read_b128 v[214:217], v152 offset:22528
	ds_read_b128 v[218:221], v152 offset:23552
	global_load_lds_dwordx4 v[146:147], off
	s_add_i32 m0, s69, 0x2000
	s_add_u32 s70, s44, 0x40000
	v_lshl_add_u64 v[202:203], s[44:45], 0, v[130:131]
	s_addc_u32 s71, s45, 0
	s_add_i32 s69, s62, s16
	global_load_lds_dwordx4 v[202:203], off
	v_lshl_add_u64 v[222:223], s[70:71], 0, v[134:135]
	s_mov_b32 m0, s69
	v_lshl_add_u64 v[224:225], s[46:47], 0, v[132:133]
	global_load_lds_dwordx4 v[222:223], off
	v_lshl_add_u64 v[222:223], s[70:71], 0, v[130:131]
	s_add_i32 m0, s69, 0x2000
	s_nop 0
	global_load_lds_dwordx4 v[222:223], off
	v_lshl_add_u64 v[222:223], s[46:47], 0, v[136:137]
	s_mov_b32 m0, s19
	s_nop 0
	global_load_lds_dwordx4 v[222:223], off
	s_mov_b32 m0, s24
	s_nop 0
	global_load_lds_dwordx4 v[224:225], off
	s_waitcnt vmcnt(8)
	s_waitcnt lgkmcnt(0)
	s_setprio 1
	s_barrier
	v_mfma_f32_16x16x32_bf16 v[62:65], v[154:157], v[186:189], v[62:65]
	v_mfma_f32_16x16x32_bf16 v[58:61], v[162:165], v[186:189], v[58:61]
	v_mfma_f32_16x16x32_bf16 v[46:49], v[154:157], v[194:197], v[46:49]
	v_mfma_f32_16x16x32_bf16 v[42:45], v[162:165], v[194:197], v[42:45]
	v_mfma_f32_16x16x32_bf16 v[30:33], v[154:157], v[206:209], v[30:33]
	v_mfma_f32_16x16x32_bf16 v[26:29], v[162:165], v[206:209], v[26:29]
	v_mfma_f32_16x16x32_bf16 v[14:17], v[154:157], v[214:217], v[14:17]
	v_mfma_f32_16x16x32_bf16 v[10:13], v[162:165], v[214:217], v[10:13]
	v_mfma_f32_16x16x32_bf16 v[62:65], v[158:161], v[190:193], v[62:65]
	v_mfma_f32_16x16x32_bf16 v[58:61], v[166:169], v[190:193], v[58:61]
	v_mfma_f32_16x16x32_bf16 v[46:49], v[158:161], v[198:201], v[46:49]
	v_mfma_f32_16x16x32_bf16 v[42:45], v[166:169], v[198:201], v[42:45]
	v_mfma_f32_16x16x32_bf16 v[30:33], v[158:161], v[210:213], v[30:33]
	v_mfma_f32_16x16x32_bf16 v[26:29], v[166:169], v[210:213], v[26:29]
	v_mfma_f32_16x16x32_bf16 v[14:17], v[158:161], v[218:221], v[14:17]
	v_mfma_f32_16x16x32_bf16 v[10:13], v[166:169], v[218:221], v[10:13]
	v_mfma_f32_16x16x32_bf16 v[54:57], v[170:173], v[186:189], v[54:57]
	v_mfma_f32_16x16x32_bf16 v[50:53], v[178:181], v[186:189], v[50:53]
	v_mfma_f32_16x16x32_bf16 v[38:41], v[170:173], v[194:197], v[38:41]
	v_mfma_f32_16x16x32_bf16 v[34:37], v[178:181], v[194:197], v[34:37]
	v_mfma_f32_16x16x32_bf16 v[22:25], v[170:173], v[206:209], v[22:25]
	v_mfma_f32_16x16x32_bf16 v[18:21], v[178:181], v[206:209], v[18:21]
	v_mfma_f32_16x16x32_bf16 v[6:9], v[170:173], v[214:217], v[6:9]
	v_mfma_f32_16x16x32_bf16 v[2:5], v[178:181], v[214:217], v[2:5]
	v_mfma_f32_16x16x32_bf16 v[54:57], v[174:177], v[190:193], v[54:57]
	v_mfma_f32_16x16x32_bf16 v[50:53], v[182:185], v[190:193], v[50:53]
	v_mfma_f32_16x16x32_bf16 v[38:41], v[174:177], v[198:201], v[38:41]
	v_mfma_f32_16x16x32_bf16 v[34:37], v[182:185], v[198:201], v[34:37]
	v_mfma_f32_16x16x32_bf16 v[22:25], v[174:177], v[210:213], v[22:25]
	v_mfma_f32_16x16x32_bf16 v[18:21], v[182:185], v[210:213], v[18:21]
	v_mfma_f32_16x16x32_bf16 v[6:9], v[174:177], v[218:221], v[6:9]
	v_mfma_f32_16x16x32_bf16 v[2:5], v[182:185], v[218:221], v[2:5]
	s_setprio 0
	s_barrier
	s_add_i32 s69, 0, 0x18000
	v_add_u32_e32 v153, s69, v149
	s_add_i32 s70, 0, 0x1c000
	ds_read_b128 v[154:157], v153
	ds_read_b128 v[158:161], v153 offset:1024
	ds_read_b128 v[162:165], v153 offset:2048
	ds_read_b128 v[166:169], v153 offset:3072
	v_add_u32_e32 v153, s70, v149
	ds_read_b128 v[170:173], v153
	ds_read_b128 v[174:177], v153 offset:1024
	ds_read_b128 v[178:181], v153 offset:2048
	ds_read_b128 v[182:185], v153 offset:3072
	s_add_u32 s46, s46, 0x40000
	s_addc_u32 s47, s47, 0
	s_mov_b32 m0, s25
	v_lshl_add_u64 v[226:227], s[46:47], 0, v[136:137]
	ds_read_b128 v[186:189], v152 offset:32768
	ds_read_b128 v[190:193], v152 offset:33792
	ds_read_b128 v[194:197], v152 offset:34816
	ds_read_b128 v[198:201], v152 offset:35840
	ds_read_b128 v[206:209], v152 offset:36864
	ds_read_b128 v[210:213], v152 offset:37888
	ds_read_b128 v[214:217], v152 offset:38912
	ds_read_b128 v[218:221], v152 offset:39936
	global_load_lds_dwordx4 v[226:227], off
	v_lshl_add_u64 v[226:227], s[46:47], 0, v[132:133]
	s_mov_b32 m0, s28
	s_nop 0
	global_load_lds_dwordx4 v[226:227], off
	s_waitcnt vmcnt(8)
	s_waitcnt lgkmcnt(0)
	s_setprio 1
	s_barrier
	v_mfma_f32_16x16x32_bf16 v[126:129], v[154:157], v[186:189], v[126:129]
	v_mfma_f32_16x16x32_bf16 v[122:125], v[162:165], v[186:189], v[122:125]
	v_mfma_f32_16x16x32_bf16 v[110:113], v[154:157], v[194:197], v[110:113]
	v_mfma_f32_16x16x32_bf16 v[106:109], v[162:165], v[194:197], v[106:109]
	v_mfma_f32_16x16x32_bf16 v[94:97], v[154:157], v[206:209], v[94:97]
	v_mfma_f32_16x16x32_bf16 v[90:93], v[162:165], v[206:209], v[90:93]
	v_mfma_f32_16x16x32_bf16 v[78:81], v[154:157], v[214:217], v[78:81]
	v_mfma_f32_16x16x32_bf16 v[74:77], v[162:165], v[214:217], v[74:77]
	v_mfma_f32_16x16x32_bf16 v[126:129], v[158:161], v[190:193], v[126:129]
	v_mfma_f32_16x16x32_bf16 v[122:125], v[166:169], v[190:193], v[122:125]
	v_mfma_f32_16x16x32_bf16 v[110:113], v[158:161], v[198:201], v[110:113]
	v_mfma_f32_16x16x32_bf16 v[106:109], v[166:169], v[198:201], v[106:109]
	v_mfma_f32_16x16x32_bf16 v[94:97], v[158:161], v[210:213], v[94:97]
	v_mfma_f32_16x16x32_bf16 v[90:93], v[166:169], v[210:213], v[90:93]
	v_mfma_f32_16x16x32_bf16 v[78:81], v[158:161], v[218:221], v[78:81]
	v_mfma_f32_16x16x32_bf16 v[74:77], v[166:169], v[218:221], v[74:77]
	v_mfma_f32_16x16x32_bf16 v[118:121], v[170:173], v[186:189], v[118:121]
	v_mfma_f32_16x16x32_bf16 v[114:117], v[178:181], v[186:189], v[114:117]
	v_mfma_f32_16x16x32_bf16 v[102:105], v[170:173], v[194:197], v[102:105]
	v_mfma_f32_16x16x32_bf16 v[98:101], v[178:181], v[194:197], v[98:101]
	v_mfma_f32_16x16x32_bf16 v[86:89], v[170:173], v[206:209], v[86:89]
	v_mfma_f32_16x16x32_bf16 v[82:85], v[178:181], v[206:209], v[82:85]
	v_mfma_f32_16x16x32_bf16 v[70:73], v[170:173], v[214:217], v[70:73]
	v_mfma_f32_16x16x32_bf16 v[66:69], v[178:181], v[214:217], v[66:69]
	v_mfma_f32_16x16x32_bf16 v[118:121], v[174:177], v[190:193], v[118:121]
	v_mfma_f32_16x16x32_bf16 v[114:117], v[182:185], v[190:193], v[114:117]
	v_mfma_f32_16x16x32_bf16 v[102:105], v[174:177], v[198:201], v[102:105]
	v_mfma_f32_16x16x32_bf16 v[98:101], v[182:185], v[198:201], v[98:101]
	v_mfma_f32_16x16x32_bf16 v[86:89], v[174:177], v[210:213], v[86:89]
	v_mfma_f32_16x16x32_bf16 v[82:85], v[182:185], v[210:213], v[82:85]
	v_mfma_f32_16x16x32_bf16 v[70:73], v[174:177], v[218:221], v[70:73]
	v_mfma_f32_16x16x32_bf16 v[66:69], v[182:185], v[218:221], v[66:69]
	s_setprio 0
	s_barrier
	s_add_i32 s46, s69, s16
	v_lshl_add_u64 v[146:147], v[146:147], 0, s[10:11]
	s_mov_b32 m0, s46
	ds_read_b128 v[186:189], v152 offset:49152
	ds_read_b128 v[190:193], v152 offset:50176
	ds_read_b128 v[194:197], v152 offset:51200
	ds_read_b128 v[198:201], v152 offset:52224
	ds_read_b128 v[206:209], v152 offset:53248
	ds_read_b128 v[210:213], v152 offset:54272
	ds_read_b128 v[214:217], v152 offset:55296
	ds_read_b128 v[218:221], v152 offset:56320
	global_load_lds_dwordx4 v[146:147], off
	s_add_i32 m0, s46, 0x2000
	s_add_u32 s44, s44, 0x40080
	v_lshl_add_u64 v[146:147], v[202:203], 0, s[10:11]
	s_addc_u32 s45, s45, 0
	s_add_i32 s46, s70, s16
	global_load_lds_dwordx4 v[146:147], off
	v_lshl_add_u64 v[146:147], s[44:45], 0, v[134:135]
	s_mov_b32 m0, s46
	s_nop 0
	global_load_lds_dwordx4 v[146:147], off
	v_lshl_add_u64 v[146:147], s[44:45], 0, v[130:131]
	s_add_i32 m0, s46, 0x2000
	s_nop 0
	global_load_lds_dwordx4 v[146:147], off
	v_lshl_add_u64 v[146:147], v[222:223], 0, s[10:11]
	s_mov_b32 m0, s33
	s_nop 0
	global_load_lds_dwordx4 v[146:147], off
	v_lshl_add_u64 v[146:147], v[224:225], 0, s[10:11]
	s_mov_b32 m0, s35
	s_nop 0
	global_load_lds_dwordx4 v[146:147], off
	s_waitcnt vmcnt(8)
	s_waitcnt lgkmcnt(0)
	s_setprio 1
	s_barrier
	v_mfma_f32_16x16x32_bf16 v[62:65], v[154:157], v[186:189], v[62:65]
	v_mfma_f32_16x16x32_bf16 v[58:61], v[162:165], v[186:189], v[58:61]
	v_mfma_f32_16x16x32_bf16 v[46:49], v[154:157], v[194:197], v[46:49]
	v_mfma_f32_16x16x32_bf16 v[42:45], v[162:165], v[194:197], v[42:45]
	v_mfma_f32_16x16x32_bf16 v[30:33], v[154:157], v[206:209], v[30:33]
	v_mfma_f32_16x16x32_bf16 v[26:29], v[162:165], v[206:209], v[26:29]
	v_mfma_f32_16x16x32_bf16 v[14:17], v[154:157], v[214:217], v[14:17]
	v_mfma_f32_16x16x32_bf16 v[10:13], v[162:165], v[214:217], v[10:13]
	v_mfma_f32_16x16x32_bf16 v[62:65], v[158:161], v[190:193], v[62:65]
	v_mfma_f32_16x16x32_bf16 v[58:61], v[166:169], v[190:193], v[58:61]
	v_mfma_f32_16x16x32_bf16 v[46:49], v[158:161], v[198:201], v[46:49]
	v_mfma_f32_16x16x32_bf16 v[42:45], v[166:169], v[198:201], v[42:45]
	v_mfma_f32_16x16x32_bf16 v[30:33], v[158:161], v[210:213], v[30:33]
	v_mfma_f32_16x16x32_bf16 v[26:29], v[166:169], v[210:213], v[26:29]
	v_mfma_f32_16x16x32_bf16 v[14:17], v[158:161], v[218:221], v[14:17]
	v_mfma_f32_16x16x32_bf16 v[10:13], v[166:169], v[218:221], v[10:13]
	v_mfma_f32_16x16x32_bf16 v[54:57], v[170:173], v[186:189], v[54:57]
	v_mfma_f32_16x16x32_bf16 v[50:53], v[178:181], v[186:189], v[50:53]
	v_mfma_f32_16x16x32_bf16 v[38:41], v[170:173], v[194:197], v[38:41]
	v_mfma_f32_16x16x32_bf16 v[34:37], v[178:181], v[194:197], v[34:37]
	v_mfma_f32_16x16x32_bf16 v[22:25], v[170:173], v[206:209], v[22:25]
	v_mfma_f32_16x16x32_bf16 v[18:21], v[178:181], v[206:209], v[18:21]
	v_mfma_f32_16x16x32_bf16 v[6:9], v[170:173], v[214:217], v[6:9]
	v_mfma_f32_16x16x32_bf16 v[2:5], v[178:181], v[214:217], v[2:5]
	v_mfma_f32_16x16x32_bf16 v[54:57], v[174:177], v[190:193], v[54:57]
	v_mfma_f32_16x16x32_bf16 v[50:53], v[182:185], v[190:193], v[50:53]
	v_mfma_f32_16x16x32_bf16 v[38:41], v[174:177], v[198:201], v[38:41]
	v_mfma_f32_16x16x32_bf16 v[34:37], v[182:185], v[198:201], v[34:37]
	v_mfma_f32_16x16x32_bf16 v[22:25], v[174:177], v[210:213], v[22:25]
	v_mfma_f32_16x16x32_bf16 v[18:21], v[182:185], v[210:213], v[18:21]
	v_mfma_f32_16x16x32_bf16 v[6:9], v[174:177], v[218:221], v[6:9]
	v_mfma_f32_16x16x32_bf16 v[2:5], v[182:185], v[218:221], v[2:5]
	s_setprio 0
	s_barrier
	s_add_i32 s68, s68, 2
	s_add_u32 s42, s42, 0x100
	s_addc_u32 s43, s43, 0
	s_add_u32 s66, s66, 0x100
	s_addc_u32 s67, s67, 0
	s_cmp_gt_u32 s68, 13
	s_cbranch_scc0 .LBB0_745
	s_and_b64 vcc, exec, s[12:13]
	s_cbranch_vccz .LBB0_748
	s_barrier

.LBB0_833:
	s_add_u32 s72, s0, s68
	s_addc_u32 s73, s1, s69
	s_and_b64 s[62:63], s[70:71], exec
	s_cselect_b32 s15, s73, s77
	s_cselect_b32 s33, s72, s76
	s_add_u32 s74, s35, s66
	s_addc_u32 s75, s85, s67
	s_and_b64 s[62:63], s[70:71], exec
	s_cselect_b32 s34, s75, s79
	s_cselect_b32 s39, s74, s78
	s_add_i32 s45, s7, -2
	s_add_u32 s76, s76, 0x100080
	s_addc_u32 s77, s77, 0
	s_add_u32 s47, s78, 0x100
	s_addc_u32 s62, s79, 0
	s_mov_b32 s63, 0
	s_waitcnt vmcnt(0)
	ds_read_b128 v[114:117], v190
	ds_read_b128 v[118:121], v190 offset:1024
	ds_read_b128 v[122:125], v190 offset:2048
	ds_read_b128 v[126:129], v190 offset:3072
	ds_read_b128 v[146:149], v191
	ds_read_b128 v[150:153], v191 offset:1024
	ds_read_b128 v[154:157], v191 offset:2048
	ds_read_b128 v[158:161], v191 offset:3072
	ds_read_b128 v[162:165], v192
	ds_read_b128 v[166:169], v192 offset:1024
	ds_read_b128 v[194:197], v192 offset:2048
	ds_read_b128 v[198:201], v192 offset:3072
	ds_read_b128 v[206:209], v192 offset:4096
	ds_read_b128 v[210:213], v192 offset:5120
	ds_read_b128 v[214:217], v192 offset:6144
	ds_read_b128 v[218:221], v192 offset:7168
	s_add_i32 s82, s63, 2
	s_add_u32 s78, s76, 0xfff00080
	s_addc_u32 s79, s77, -1
	s_cmp_eq_u32 s45, s63
	s_cselect_b32 s81, s15, s79
	s_cselect_b32 s80, s33, s78
	s_cselect_b32 s79, s34, s62
	s_cselect_b32 s78, s39, s47
	s_add_i32 m0, s87, 0xc000
	v_lshl_add_u64 v[186:187], s[76:77], 0, v[180:181]
	global_load_lds_dwordx4 v[186:187], off
	v_lshl_add_u64 v[186:187], s[76:77], 0, v[182:183]
	s_add_i32 m0, s87, 0xe000
	s_nop 0
	global_load_lds_dwordx4 v[186:187], off
	s_waitcnt vmcnt(8)
	s_waitcnt lgkmcnt(0)
	s_setprio 1
	s_barrier
	v_mfma_f32_16x16x32_bf16 v[142:145], v[114:117], v[162:165], 0
	v_mfma_f32_16x16x32_bf16 v[138:141], v[122:125], v[162:165], 0
	v_mfma_f32_16x16x32_bf16 v[110:113], v[114:117], v[194:197], 0
	v_mfma_f32_16x16x32_bf16 v[106:109], v[122:125], v[194:197], 0
	v_mfma_f32_16x16x32_bf16 v[98:101], v[114:117], v[206:209], 0
	v_mfma_f32_16x16x32_bf16 v[90:93], v[122:125], v[206:209], 0
	v_mfma_f32_16x16x32_bf16 v[82:85], v[114:117], v[214:217], 0
	v_mfma_f32_16x16x32_bf16 v[74:77], v[122:125], v[214:217], 0
	v_mfma_f32_16x16x32_bf16 v[142:145], v[118:121], v[166:169], v[142:145]
	v_mfma_f32_16x16x32_bf16 v[138:141], v[126:129], v[166:169], v[138:141]
	v_mfma_f32_16x16x32_bf16 v[110:113], v[118:121], v[198:201], v[110:113]
	v_mfma_f32_16x16x32_bf16 v[106:109], v[126:129], v[198:201], v[106:109]
	v_mfma_f32_16x16x32_bf16 v[98:101], v[118:121], v[210:213], v[98:101]
	v_mfma_f32_16x16x32_bf16 v[90:93], v[126:129], v[210:213], v[90:93]
	v_mfma_f32_16x16x32_bf16 v[82:85], v[118:121], v[218:221], v[82:85]
	v_mfma_f32_16x16x32_bf16 v[74:77], v[126:129], v[218:221], v[74:77]
	v_mfma_f32_16x16x32_bf16 v[134:137], v[146:149], v[162:165], 0
	v_mfma_f32_16x16x32_bf16 v[130:133], v[154:157], v[162:165], 0
	v_mfma_f32_16x16x32_bf16 v[102:105], v[146:149], v[194:197], 0
	v_mfma_f32_16x16x32_bf16 v[94:97], v[154:157], v[194:197], 0
	v_mfma_f32_16x16x32_bf16 v[86:89], v[146:149], v[206:209], 0
	v_mfma_f32_16x16x32_bf16 v[78:81], v[154:157], v[206:209], 0
	v_mfma_f32_16x16x32_bf16 v[70:73], v[146:149], v[214:217], 0
	v_mfma_f32_16x16x32_bf16 v[66:69], v[154:157], v[214:217], 0
	v_mfma_f32_16x16x32_bf16 v[134:137], v[150:153], v[166:169], v[134:137]
	v_mfma_f32_16x16x32_bf16 v[130:133], v[158:161], v[166:169], v[130:133]
	v_mfma_f32_16x16x32_bf16 v[102:105], v[150:153], v[198:201], v[102:105]
	v_mfma_f32_16x16x32_bf16 v[94:97], v[158:161], v[198:201], v[94:97]
	v_mfma_f32_16x16x32_bf16 v[86:89], v[150:153], v[210:213], v[86:89]
	v_mfma_f32_16x16x32_bf16 v[78:81], v[158:161], v[210:213], v[78:81]
	v_mfma_f32_16x16x32_bf16 v[70:73], v[150:153], v[218:221], v[70:73]
	v_mfma_f32_16x16x32_bf16 v[66:69], v[158:161], v[218:221], v[66:69]
	s_setprio 0
	s_barrier
	s_add_i32 s63, s24, s86
	v_lshl_add_u64 v[186:187], s[78:79], 0, v[172:173]
	s_mov_b32 m0, s63
	ds_read_b128 v[162:165], v192 offset:16384
	ds_read_b128 v[166:169], v192 offset:17408
	ds_read_b128 v[194:197], v192 offset:18432
	ds_read_b128 v[198:201], v192 offset:19456
	ds_read_b128 v[206:209], v192 offset:20480
	ds_read_b128 v[210:213], v192 offset:21504
	ds_read_b128 v[214:217], v192 offset:22528
	ds_read_b128 v[218:221], v192 offset:23552
	global_load_lds_dwordx4 v[186:187], off
	s_add_i32 m0, s63, 0x2000
	s_add_u32 vcc_lo, s78, 0x100000
	v_lshl_add_u64 v[202:203], s[78:79], 0, v[176:177]
	s_addc_u32 vcc_hi, s79, 0
	s_add_i32 s63, s25, s86
	global_load_lds_dwordx4 v[202:203], off
	v_lshl_add_u64 v[222:223], vcc, 0, v[172:173]
	s_mov_b32 m0, s63
	v_lshl_add_u64 v[224:225], s[80:81], 0, v[174:175]
	global_load_lds_dwordx4 v[222:223], off
	v_lshl_add_u64 v[222:223], vcc, 0, v[176:177]
	s_add_i32 m0, s63, 0x2000
	s_nop 0
	global_load_lds_dwordx4 v[222:223], off
	v_lshl_add_u64 v[222:223], s[80:81], 0, v[170:171]
	s_mov_b32 m0, s87
	s_nop 0
	global_load_lds_dwordx4 v[222:223], off
	s_mov_b32 m0, s88
	s_nop 0
	global_load_lds_dwordx4 v[224:225], off
	s_waitcnt vmcnt(8)
	s_waitcnt lgkmcnt(0)
	s_setprio 1
	s_barrier
	v_mfma_f32_16x16x32_bf16 v[62:65], v[114:117], v[162:165], 0
	v_mfma_f32_16x16x32_bf16 v[58:61], v[122:125], v[162:165], 0
	v_mfma_f32_16x16x32_bf16 v[50:53], v[114:117], v[194:197], 0
	v_mfma_f32_16x16x32_bf16 v[42:45], v[122:125], v[194:197], 0
	v_mfma_f32_16x16x32_bf16 v[34:37], v[114:117], v[206:209], 0
	v_mfma_f32_16x16x32_bf16 v[26:29], v[122:125], v[206:209], 0
	v_mfma_f32_16x16x32_bf16 v[18:21], v[114:117], v[214:217], 0
	v_mfma_f32_16x16x32_bf16 v[10:13], v[122:125], v[214:217], 0
	v_mfma_f32_16x16x32_bf16 v[62:65], v[118:121], v[166:169], v[62:65]
	v_mfma_f32_16x16x32_bf16 v[58:61], v[126:129], v[166:169], v[58:61]
	v_mfma_f32_16x16x32_bf16 v[50:53], v[118:121], v[198:201], v[50:53]
	v_mfma_f32_16x16x32_bf16 v[42:45], v[126:129], v[198:201], v[42:45]
	v_mfma_f32_16x16x32_bf16 v[34:37], v[118:121], v[210:213], v[34:37]
	v_mfma_f32_16x16x32_bf16 v[26:29], v[126:129], v[210:213], v[26:29]
	v_mfma_f32_16x16x32_bf16 v[18:21], v[118:121], v[218:221], v[18:21]
	v_mfma_f32_16x16x32_bf16 v[10:13], v[126:129], v[218:221], v[10:13]
	v_mfma_f32_16x16x32_bf16 v[54:57], v[146:149], v[162:165], 0
	v_mfma_f32_16x16x32_bf16 v[46:49], v[154:157], v[162:165], 0
	v_mfma_f32_16x16x32_bf16 v[38:41], v[146:149], v[194:197], 0
	v_mfma_f32_16x16x32_bf16 v[30:33], v[154:157], v[194:197], 0
	v_mfma_f32_16x16x32_bf16 v[22:25], v[146:149], v[206:209], 0
	v_mfma_f32_16x16x32_bf16 v[14:17], v[154:157], v[206:209], 0
	v_mfma_f32_16x16x32_bf16 v[6:9], v[146:149], v[214:217], 0
	v_mfma_f32_16x16x32_bf16 v[2:5], v[154:157], v[214:217], 0
	v_mfma_f32_16x16x32_bf16 v[54:57], v[150:153], v[166:169], v[54:57]
	v_mfma_f32_16x16x32_bf16 v[46:49], v[158:161], v[166:169], v[46:49]
	v_mfma_f32_16x16x32_bf16 v[38:41], v[150:153], v[198:201], v[38:41]
	v_mfma_f32_16x16x32_bf16 v[30:33], v[158:161], v[198:201], v[30:33]
	v_mfma_f32_16x16x32_bf16 v[22:25], v[150:153], v[210:213], v[22:25]
	v_mfma_f32_16x16x32_bf16 v[14:17], v[158:161], v[210:213], v[14:17]
	v_mfma_f32_16x16x32_bf16 v[6:9], v[150:153], v[218:221], v[6:9]
	v_mfma_f32_16x16x32_bf16 v[2:5], v[158:161], v[218:221], v[2:5]
	s_setprio 0
	s_barrier
	s_add_i32 s63, 0, 0x18000
	s_add_i32 s83, 0, 0x1c000
	v_add_u32_e32 v126, s63, v189
	v_add_u32_e32 v158, s83, v189
	ds_read_b128 v[114:117], v126
	ds_read_b128 v[118:121], v126 offset:1024
	ds_read_b128 v[122:125], v126 offset:2048
	ds_read_b128 v[126:129], v126 offset:3072
	ds_read_b128 v[146:149], v158
	ds_read_b128 v[150:153], v158 offset:1024
	ds_read_b128 v[154:157], v158 offset:2048
	ds_read_b128 v[158:161], v158 offset:3072
	s_add_u32 s80, s80, 0x100000
	s_addc_u32 s81, s81, 0
	s_mov_b32 m0, s89
	v_lshl_add_u64 v[226:227], s[80:81], 0, v[170:171]
	ds_read_b128 v[162:165], v192 offset:32768
	ds_read_b128 v[166:169], v192 offset:33792
	ds_read_b128 v[194:197], v192 offset:34816
	ds_read_b128 v[198:201], v192 offset:35840
	ds_read_b128 v[206:209], v192 offset:36864
	ds_read_b128 v[210:213], v192 offset:37888
	ds_read_b128 v[214:217], v192 offset:38912
	ds_read_b128 v[218:221], v192 offset:39936
	global_load_lds_dwordx4 v[226:227], off
	v_lshl_add_u64 v[226:227], s[80:81], 0, v[174:175]
	s_mov_b32 m0, s90
	s_nop 0
	global_load_lds_dwordx4 v[226:227], off
	s_waitcnt vmcnt(8)
	s_waitcnt lgkmcnt(0)
	s_setprio 1
	s_barrier
	v_mfma_f32_16x16x32_bf16 v[142:145], v[114:117], v[162:165], v[142:145]
	v_mfma_f32_16x16x32_bf16 v[138:141], v[122:125], v[162:165], v[138:141]
	v_mfma_f32_16x16x32_bf16 v[110:113], v[114:117], v[194:197], v[110:113]
	v_mfma_f32_16x16x32_bf16 v[106:109], v[122:125], v[194:197], v[106:109]
	v_mfma_f32_16x16x32_bf16 v[98:101], v[114:117], v[206:209], v[98:101]
	v_mfma_f32_16x16x32_bf16 v[90:93], v[122:125], v[206:209], v[90:93]
	v_mfma_f32_16x16x32_bf16 v[82:85], v[114:117], v[214:217], v[82:85]
	v_mfma_f32_16x16x32_bf16 v[74:77], v[122:125], v[214:217], v[74:77]
	v_mfma_f32_16x16x32_bf16 v[142:145], v[118:121], v[166:169], v[142:145]
	v_mfma_f32_16x16x32_bf16 v[138:141], v[126:129], v[166:169], v[138:141]
	v_mfma_f32_16x16x32_bf16 v[110:113], v[118:121], v[198:201], v[110:113]
	v_mfma_f32_16x16x32_bf16 v[106:109], v[126:129], v[198:201], v[106:109]
	v_mfma_f32_16x16x32_bf16 v[98:101], v[118:121], v[210:213], v[98:101]
	v_mfma_f32_16x16x32_bf16 v[90:93], v[126:129], v[210:213], v[90:93]
	v_mfma_f32_16x16x32_bf16 v[82:85], v[118:121], v[218:221], v[82:85]
	v_mfma_f32_16x16x32_bf16 v[74:77], v[126:129], v[218:221], v[74:77]
	v_mfma_f32_16x16x32_bf16 v[134:137], v[146:149], v[162:165], v[134:137]
	v_mfma_f32_16x16x32_bf16 v[130:133], v[154:157], v[162:165], v[130:133]
	v_mfma_f32_16x16x32_bf16 v[102:105], v[146:149], v[194:197], v[102:105]
	v_mfma_f32_16x16x32_bf16 v[94:97], v[154:157], v[194:197], v[94:97]
	v_mfma_f32_16x16x32_bf16 v[86:89], v[146:149], v[206:209], v[86:89]
	v_mfma_f32_16x16x32_bf16 v[78:81], v[154:157], v[206:209], v[78:81]
	v_mfma_f32_16x16x32_bf16 v[70:73], v[146:149], v[214:217], v[70:73]
	v_mfma_f32_16x16x32_bf16 v[66:69], v[154:157], v[214:217], v[66:69]
	v_mfma_f32_16x16x32_bf16 v[134:137], v[150:153], v[166:169], v[134:137]
	v_mfma_f32_16x16x32_bf16 v[130:133], v[158:161], v[166:169], v[130:133]
	v_mfma_f32_16x16x32_bf16 v[102:105], v[150:153], v[198:201], v[102:105]
	v_mfma_f32_16x16x32_bf16 v[94:97], v[158:161], v[198:201], v[94:97]
	v_mfma_f32_16x16x32_bf16 v[86:89], v[150:153], v[210:213], v[86:89]
	v_mfma_f32_16x16x32_bf16 v[78:81], v[158:161], v[210:213], v[78:81]
	v_mfma_f32_16x16x32_bf16 v[70:73], v[150:153], v[218:221], v[70:73]
	v_mfma_f32_16x16x32_bf16 v[66:69], v[158:161], v[218:221], v[66:69]
	s_setprio 0
	s_barrier
	s_add_i32 s63, s63, s86
	v_lshl_add_u64 v[186:187], v[186:187], 0, s[22:23]
	s_mov_b32 m0, s63
	ds_read_b128 v[162:165], v192 offset:49152
	ds_read_b128 v[166:169], v192 offset:50176
	ds_read_b128 v[194:197], v192 offset:51200
	ds_read_b128 v[198:201], v192 offset:52224
	ds_read_b128 v[206:209], v192 offset:53248
	ds_read_b128 v[210:213], v192 offset:54272
	ds_read_b128 v[214:217], v192 offset:55296
	ds_read_b128 v[218:221], v192 offset:56320
	global_load_lds_dwordx4 v[186:187], off
	s_add_i32 m0, s63, 0x2000
	s_add_u32 s78, s78, 0x100080
	v_lshl_add_u64 v[186:187], v[202:203], 0, s[22:23]
	s_addc_u32 s79, s79, 0
	s_add_i32 s63, s83, s86
	global_load_lds_dwordx4 v[186:187], off
	v_lshl_add_u64 v[186:187], s[78:79], 0, v[172:173]
	s_mov_b32 m0, s63
	s_nop 0
	global_load_lds_dwordx4 v[186:187], off
	v_lshl_add_u64 v[186:187], s[78:79], 0, v[176:177]
	s_add_i32 m0, s63, 0x2000
	s_nop 0
	global_load_lds_dwordx4 v[186:187], off
	v_lshl_add_u64 v[186:187], v[222:223], 0, s[22:23]
	s_mov_b32 m0, s95
	s_nop 0
	global_load_lds_dwordx4 v[186:187], off
	v_lshl_add_u64 v[186:187], v[224:225], 0, s[22:23]
	s_mov_b32 m0, s96
	s_nop 0
	global_load_lds_dwordx4 v[186:187], off
	s_waitcnt vmcnt(8)
	s_waitcnt lgkmcnt(0)
	s_setprio 1
	s_barrier
	v_mfma_f32_16x16x32_bf16 v[62:65], v[114:117], v[162:165], v[62:65]
	v_mfma_f32_16x16x32_bf16 v[58:61], v[122:125], v[162:165], v[58:61]
	v_mfma_f32_16x16x32_bf16 v[50:53], v[114:117], v[194:197], v[50:53]
	v_mfma_f32_16x16x32_bf16 v[42:45], v[122:125], v[194:197], v[42:45]
	v_mfma_f32_16x16x32_bf16 v[34:37], v[114:117], v[206:209], v[34:37]
	v_mfma_f32_16x16x32_bf16 v[26:29], v[122:125], v[206:209], v[26:29]
	v_mfma_f32_16x16x32_bf16 v[18:21], v[114:117], v[214:217], v[18:21]
	v_mfma_f32_16x16x32_bf16 v[10:13], v[122:125], v[214:217], v[10:13]
	v_mfma_f32_16x16x32_bf16 v[62:65], v[118:121], v[166:169], v[62:65]
	v_mfma_f32_16x16x32_bf16 v[58:61], v[126:129], v[166:169], v[58:61]
	v_mfma_f32_16x16x32_bf16 v[50:53], v[118:121], v[198:201], v[50:53]
	v_mfma_f32_16x16x32_bf16 v[42:45], v[126:129], v[198:201], v[42:45]
	v_mfma_f32_16x16x32_bf16 v[34:37], v[118:121], v[210:213], v[34:37]
	v_mfma_f32_16x16x32_bf16 v[26:29], v[126:129], v[210:213], v[26:29]
	v_mfma_f32_16x16x32_bf16 v[18:21], v[118:121], v[218:221], v[18:21]
	v_mfma_f32_16x16x32_bf16 v[10:13], v[126:129], v[218:221], v[10:13]
	v_mfma_f32_16x16x32_bf16 v[54:57], v[146:149], v[162:165], v[54:57]
	v_mfma_f32_16x16x32_bf16 v[46:49], v[154:157], v[162:165], v[46:49]
	v_mfma_f32_16x16x32_bf16 v[38:41], v[146:149], v[194:197], v[38:41]
	v_mfma_f32_16x16x32_bf16 v[30:33], v[154:157], v[194:197], v[30:33]
	v_mfma_f32_16x16x32_bf16 v[22:25], v[146:149], v[206:209], v[22:25]
	v_mfma_f32_16x16x32_bf16 v[14:17], v[154:157], v[206:209], v[14:17]
	v_mfma_f32_16x16x32_bf16 v[6:9], v[146:149], v[214:217], v[6:9]
	v_mfma_f32_16x16x32_bf16 v[2:5], v[154:157], v[214:217], v[2:5]
	v_mfma_f32_16x16x32_bf16 v[54:57], v[150:153], v[166:169], v[54:57]
	v_mfma_f32_16x16x32_bf16 v[46:49], v[158:161], v[166:169], v[46:49]
	v_mfma_f32_16x16x32_bf16 v[38:41], v[150:153], v[198:201], v[38:41]
	v_mfma_f32_16x16x32_bf16 v[30:33], v[158:161], v[198:201], v[30:33]
	v_mfma_f32_16x16x32_bf16 v[22:25], v[150:153], v[210:213], v[22:25]
	v_mfma_f32_16x16x32_bf16 v[14:17], v[158:161], v[210:213], v[14:17]
	v_mfma_f32_16x16x32_bf16 v[6:9], v[150:153], v[218:221], v[6:9]
	v_mfma_f32_16x16x32_bf16 v[2:5], v[158:161], v[218:221], v[2:5]
	s_setprio 0
	s_barrier
	s_add_u32 s76, s76, 0x100
	s_addc_u32 s77, s77, 0
	s_add_u32 s47, s47, 0x100
	s_addc_u32 s62, s62, 0
	s_cmp_ge_i32 s82, s7
	s_mov_b32 s63, s82
.LBB0_834:
	ds_read_b128 v[114:117], v190
	ds_read_b128 v[118:121], v190 offset:1024
	ds_read_b128 v[122:125], v190 offset:2048
	ds_read_b128 v[126:129], v190 offset:3072
	ds_read_b128 v[146:149], v191
	ds_read_b128 v[150:153], v191 offset:1024
	ds_read_b128 v[154:157], v191 offset:2048
	ds_read_b128 v[158:161], v191 offset:3072
	ds_read_b128 v[162:165], v192
	ds_read_b128 v[166:169], v192 offset:1024
	ds_read_b128 v[194:197], v192 offset:2048
	ds_read_b128 v[198:201], v192 offset:3072
	ds_read_b128 v[206:209], v192 offset:4096
	ds_read_b128 v[210:213], v192 offset:5120
	ds_read_b128 v[214:217], v192 offset:6144
	ds_read_b128 v[218:221], v192 offset:7168
	s_add_i32 s82, s63, 2
	s_add_u32 s78, s76, 0xfff00080
	s_addc_u32 s79, s77, -1
	s_cmp_eq_u32 s45, s63
	s_cselect_b32 s81, s15, s79
	s_cselect_b32 s80, s33, s78
	s_cselect_b32 s79, s34, s62
	s_cselect_b32 s78, s39, s47
	s_add_i32 m0, s87, 0xc000
	v_lshl_add_u64 v[186:187], s[76:77], 0, v[180:181]
	global_load_lds_dwordx4 v[186:187], off
	v_lshl_add_u64 v[186:187], s[76:77], 0, v[182:183]
	s_add_i32 m0, s87, 0xe000
	s_nop 0
	global_load_lds_dwordx4 v[186:187], off
	s_waitcnt vmcnt(8)
	s_waitcnt lgkmcnt(0)
	s_setprio 1
	s_barrier
	v_mfma_f32_16x16x32_bf16 v[142:145], v[114:117], v[162:165], v[142:145]
	v_mfma_f32_16x16x32_bf16 v[138:141], v[122:125], v[162:165], v[138:141]
	v_mfma_f32_16x16x32_bf16 v[110:113], v[114:117], v[194:197], v[110:113]
	v_mfma_f32_16x16x32_bf16 v[106:109], v[122:125], v[194:197], v[106:109]
	v_mfma_f32_16x16x32_bf16 v[98:101], v[114:117], v[206:209], v[98:101]
	v_mfma_f32_16x16x32_bf16 v[90:93], v[122:125], v[206:209], v[90:93]
	v_mfma_f32_16x16x32_bf16 v[82:85], v[114:117], v[214:217], v[82:85]
	v_mfma_f32_16x16x32_bf16 v[74:77], v[122:125], v[214:217], v[74:77]
	v_mfma_f32_16x16x32_bf16 v[142:145], v[118:121], v[166:169], v[142:145]
	v_mfma_f32_16x16x32_bf16 v[138:141], v[126:129], v[166:169], v[138:141]
	v_mfma_f32_16x16x32_bf16 v[110:113], v[118:121], v[198:201], v[110:113]
	v_mfma_f32_16x16x32_bf16 v[106:109], v[126:129], v[198:201], v[106:109]
	v_mfma_f32_16x16x32_bf16 v[98:101], v[118:121], v[210:213], v[98:101]
	v_mfma_f32_16x16x32_bf16 v[90:93], v[126:129], v[210:213], v[90:93]
	v_mfma_f32_16x16x32_bf16 v[82:85], v[118:121], v[218:221], v[82:85]
	v_mfma_f32_16x16x32_bf16 v[74:77], v[126:129], v[218:221], v[74:77]
	v_mfma_f32_16x16x32_bf16 v[134:137], v[146:149], v[162:165], v[134:137]
	v_mfma_f32_16x16x32_bf16 v[130:133], v[154:157], v[162:165], v[130:133]
	v_mfma_f32_16x16x32_bf16 v[102:105], v[146:149], v[194:197], v[102:105]
	v_mfma_f32_16x16x32_bf16 v[94:97], v[154:157], v[194:197], v[94:97]
	v_mfma_f32_16x16x32_bf16 v[86:89], v[146:149], v[206:209], v[86:89]
	v_mfma_f32_16x16x32_bf16 v[78:81], v[154:157], v[206:209], v[78:81]
	v_mfma_f32_16x16x32_bf16 v[70:73], v[146:149], v[214:217], v[70:73]
	v_mfma_f32_16x16x32_bf16 v[66:69], v[154:157], v[214:217], v[66:69]
	v_mfma_f32_16x16x32_bf16 v[134:137], v[150:153], v[166:169], v[134:137]
	v_mfma_f32_16x16x32_bf16 v[130:133], v[158:161], v[166:169], v[130:133]
	v_mfma_f32_16x16x32_bf16 v[102:105], v[150:153], v[198:201], v[102:105]
	v_mfma_f32_16x16x32_bf16 v[94:97], v[158:161], v[198:201], v[94:97]
	v_mfma_f32_16x16x32_bf16 v[86:89], v[150:153], v[210:213], v[86:89]
	v_mfma_f32_16x16x32_bf16 v[78:81], v[158:161], v[210:213], v[78:81]
	v_mfma_f32_16x16x32_bf16 v[70:73], v[150:153], v[218:221], v[70:73]
	v_mfma_f32_16x16x32_bf16 v[66:69], v[158:161], v[218:221], v[66:69]
	s_setprio 0
	s_barrier
	s_add_i32 s63, s24, s86
	v_lshl_add_u64 v[186:187], s[78:79], 0, v[172:173]
	s_mov_b32 m0, s63
	ds_read_b128 v[162:165], v192 offset:16384
	ds_read_b128 v[166:169], v192 offset:17408
	ds_read_b128 v[194:197], v192 offset:18432
	ds_read_b128 v[198:201], v192 offset:19456
	ds_read_b128 v[206:209], v192 offset:20480
	ds_read_b128 v[210:213], v192 offset:21504
	ds_read_b128 v[214:217], v192 offset:22528
	ds_read_b128 v[218:221], v192 offset:23552
	global_load_lds_dwordx4 v[186:187], off
	s_add_i32 m0, s63, 0x2000
	s_add_u32 vcc_lo, s78, 0x100000
	v_lshl_add_u64 v[202:203], s[78:79], 0, v[176:177]
	s_addc_u32 vcc_hi, s79, 0
	s_add_i32 s63, s25, s86
	global_load_lds_dwordx4 v[202:203], off
	v_lshl_add_u64 v[222:223], vcc, 0, v[172:173]
	s_mov_b32 m0, s63
	v_lshl_add_u64 v[224:225], s[80:81], 0, v[174:175]
	global_load_lds_dwordx4 v[222:223], off
	v_lshl_add_u64 v[222:223], vcc, 0, v[176:177]
	s_add_i32 m0, s63, 0x2000
	s_nop 0
	global_load_lds_dwordx4 v[222:223], off
	v_lshl_add_u64 v[222:223], s[80:81], 0, v[170:171]
	s_mov_b32 m0, s87
	s_nop 0
	global_load_lds_dwordx4 v[222:223], off
	s_mov_b32 m0, s88
	s_nop 0
	global_load_lds_dwordx4 v[224:225], off
	s_waitcnt vmcnt(8)
	s_waitcnt lgkmcnt(0)
	s_setprio 1
	s_barrier
	v_mfma_f32_16x16x32_bf16 v[62:65], v[114:117], v[162:165], v[62:65]
	v_mfma_f32_16x16x32_bf16 v[58:61], v[122:125], v[162:165], v[58:61]
	v_mfma_f32_16x16x32_bf16 v[50:53], v[114:117], v[194:197], v[50:53]
	v_mfma_f32_16x16x32_bf16 v[42:45], v[122:125], v[194:197], v[42:45]
	v_mfma_f32_16x16x32_bf16 v[34:37], v[114:117], v[206:209], v[34:37]
	v_mfma_f32_16x16x32_bf16 v[26:29], v[122:125], v[206:209], v[26:29]
	v_mfma_f32_16x16x32_bf16 v[18:21], v[114:117], v[214:217], v[18:21]
	v_mfma_f32_16x16x32_bf16 v[10:13], v[122:125], v[214:217], v[10:13]
	v_mfma_f32_16x16x32_bf16 v[62:65], v[118:121], v[166:169], v[62:65]
	v_mfma_f32_16x16x32_bf16 v[58:61], v[126:129], v[166:169], v[58:61]
	v_mfma_f32_16x16x32_bf16 v[50:53], v[118:121], v[198:201], v[50:53]
	v_mfma_f32_16x16x32_bf16 v[42:45], v[126:129], v[198:201], v[42:45]
	v_mfma_f32_16x16x32_bf16 v[34:37], v[118:121], v[210:213], v[34:37]
	v_mfma_f32_16x16x32_bf16 v[26:29], v[126:129], v[210:213], v[26:29]
	v_mfma_f32_16x16x32_bf16 v[18:21], v[118:121], v[218:221], v[18:21]
	v_mfma_f32_16x16x32_bf16 v[10:13], v[126:129], v[218:221], v[10:13]
	v_mfma_f32_16x16x32_bf16 v[54:57], v[146:149], v[162:165], v[54:57]
	v_mfma_f32_16x16x32_bf16 v[46:49], v[154:157], v[162:165], v[46:49]
	v_mfma_f32_16x16x32_bf16 v[38:41], v[146:149], v[194:197], v[38:41]
	v_mfma_f32_16x16x32_bf16 v[30:33], v[154:157], v[194:197], v[30:33]
	v_mfma_f32_16x16x32_bf16 v[22:25], v[146:149], v[206:209], v[22:25]
	v_mfma_f32_16x16x32_bf16 v[14:17], v[154:157], v[206:209], v[14:17]
	v_mfma_f32_16x16x32_bf16 v[6:9], v[146:149], v[214:217], v[6:9]
	v_mfma_f32_16x16x32_bf16 v[2:5], v[154:157], v[214:217], v[2:5]
	v_mfma_f32_16x16x32_bf16 v[54:57], v[150:153], v[166:169], v[54:57]
	v_mfma_f32_16x16x32_bf16 v[46:49], v[158:161], v[166:169], v[46:49]
	v_mfma_f32_16x16x32_bf16 v[38:41], v[150:153], v[198:201], v[38:41]
	v_mfma_f32_16x16x32_bf16 v[30:33], v[158:161], v[198:201], v[30:33]
	v_mfma_f32_16x16x32_bf16 v[22:25], v[150:153], v[210:213], v[22:25]
	v_mfma_f32_16x16x32_bf16 v[14:17], v[158:161], v[210:213], v[14:17]
	v_mfma_f32_16x16x32_bf16 v[6:9], v[150:153], v[218:221], v[6:9]
	v_mfma_f32_16x16x32_bf16 v[2:5], v[158:161], v[218:221], v[2:5]
	s_setprio 0
	s_barrier
	s_add_i32 s63, 0, 0x18000
	s_add_i32 s83, 0, 0x1c000
	v_add_u32_e32 v126, s63, v189
	v_add_u32_e32 v158, s83, v189
	ds_read_b128 v[114:117], v126
	ds_read_b128 v[118:121], v126 offset:1024
	ds_read_b128 v[122:125], v126 offset:2048
	ds_read_b128 v[126:129], v126 offset:3072
	ds_read_b128 v[146:149], v158
	ds_read_b128 v[150:153], v158 offset:1024
	ds_read_b128 v[154:157], v158 offset:2048
	ds_read_b128 v[158:161], v158 offset:3072
	s_add_u32 s80, s80, 0x100000
	s_addc_u32 s81, s81, 0
	s_mov_b32 m0, s89
	v_lshl_add_u64 v[226:227], s[80:81], 0, v[170:171]
	ds_read_b128 v[162:165], v192 offset:32768
	ds_read_b128 v[166:169], v192 offset:33792
	ds_read_b128 v[194:197], v192 offset:34816
	ds_read_b128 v[198:201], v192 offset:35840
	ds_read_b128 v[206:209], v192 offset:36864
	ds_read_b128 v[210:213], v192 offset:37888
	ds_read_b128 v[214:217], v192 offset:38912
	ds_read_b128 v[218:221], v192 offset:39936
	global_load_lds_dwordx4 v[226:227], off
	v_lshl_add_u64 v[226:227], s[80:81], 0, v[174:175]
	s_mov_b32 m0, s90
	s_nop 0
	global_load_lds_dwordx4 v[226:227], off
	s_waitcnt vmcnt(8)
	s_waitcnt lgkmcnt(0)
	s_setprio 1
	s_barrier
	v_mfma_f32_16x16x32_bf16 v[142:145], v[114:117], v[162:165], v[142:145]
	v_mfma_f32_16x16x32_bf16 v[138:141], v[122:125], v[162:165], v[138:141]
	v_mfma_f32_16x16x32_bf16 v[110:113], v[114:117], v[194:197], v[110:113]
	v_mfma_f32_16x16x32_bf16 v[106:109], v[122:125], v[194:197], v[106:109]
	v_mfma_f32_16x16x32_bf16 v[98:101], v[114:117], v[206:209], v[98:101]
	v_mfma_f32_16x16x32_bf16 v[90:93], v[122:125], v[206:209], v[90:93]
	v_mfma_f32_16x16x32_bf16 v[82:85], v[114:117], v[214:217], v[82:85]
	v_mfma_f32_16x16x32_bf16 v[74:77], v[122:125], v[214:217], v[74:77]
	v_mfma_f32_16x16x32_bf16 v[142:145], v[118:121], v[166:169], v[142:145]
	v_mfma_f32_16x16x32_bf16 v[138:141], v[126:129], v[166:169], v[138:141]
	v_mfma_f32_16x16x32_bf16 v[110:113], v[118:121], v[198:201], v[110:113]
	v_mfma_f32_16x16x32_bf16 v[106:109], v[126:129], v[198:201], v[106:109]
	v_mfma_f32_16x16x32_bf16 v[98:101], v[118:121], v[210:213], v[98:101]
	v_mfma_f32_16x16x32_bf16 v[90:93], v[126:129], v[210:213], v[90:93]
	v_mfma_f32_16x16x32_bf16 v[82:85], v[118:121], v[218:221], v[82:85]
	v_mfma_f32_16x16x32_bf16 v[74:77], v[126:129], v[218:221], v[74:77]
	v_mfma_f32_16x16x32_bf16 v[134:137], v[146:149], v[162:165], v[134:137]
	v_mfma_f32_16x16x32_bf16 v[130:133], v[154:157], v[162:165], v[130:133]
	v_mfma_f32_16x16x32_bf16 v[102:105], v[146:149], v[194:197], v[102:105]
	v_mfma_f32_16x16x32_bf16 v[94:97], v[154:157], v[194:197], v[94:97]
	v_mfma_f32_16x16x32_bf16 v[86:89], v[146:149], v[206:209], v[86:89]
	v_mfma_f32_16x16x32_bf16 v[78:81], v[154:157], v[206:209], v[78:81]
	v_mfma_f32_16x16x32_bf16 v[70:73], v[146:149], v[214:217], v[70:73]
	v_mfma_f32_16x16x32_bf16 v[66:69], v[154:157], v[214:217], v[66:69]
	v_mfma_f32_16x16x32_bf16 v[134:137], v[150:153], v[166:169], v[134:137]
	v_mfma_f32_16x16x32_bf16 v[130:133], v[158:161], v[166:169], v[130:133]
	v_mfma_f32_16x16x32_bf16 v[102:105], v[150:153], v[198:201], v[102:105]
	v_mfma_f32_16x16x32_bf16 v[94:97], v[158:161], v[198:201], v[94:97]
	v_mfma_f32_16x16x32_bf16 v[86:89], v[150:153], v[210:213], v[86:89]
	v_mfma_f32_16x16x32_bf16 v[78:81], v[158:161], v[210:213], v[78:81]
	v_mfma_f32_16x16x32_bf16 v[70:73], v[150:153], v[218:221], v[70:73]
	v_mfma_f32_16x16x32_bf16 v[66:69], v[158:161], v[218:221], v[66:69]
	s_setprio 0
	s_barrier
	s_add_i32 s63, s63, s86
	v_lshl_add_u64 v[186:187], v[186:187], 0, s[22:23]
	s_mov_b32 m0, s63
	ds_read_b128 v[162:165], v192 offset:49152
	ds_read_b128 v[166:169], v192 offset:50176
	ds_read_b128 v[194:197], v192 offset:51200
	ds_read_b128 v[198:201], v192 offset:52224
	ds_read_b128 v[206:209], v192 offset:53248
	ds_read_b128 v[210:213], v192 offset:54272
	ds_read_b128 v[214:217], v192 offset:55296
	ds_read_b128 v[218:221], v192 offset:56320
	global_load_lds_dwordx4 v[186:187], off
	s_add_i32 m0, s63, 0x2000
	s_add_u32 s78, s78, 0x100080
	v_lshl_add_u64 v[186:187], v[202:203], 0, s[22:23]
	s_addc_u32 s79, s79, 0
	s_add_i32 s63, s83, s86
	global_load_lds_dwordx4 v[186:187], off
	v_lshl_add_u64 v[186:187], s[78:79], 0, v[172:173]
	s_mov_b32 m0, s63
	s_nop 0
	global_load_lds_dwordx4 v[186:187], off
	v_lshl_add_u64 v[186:187], s[78:79], 0, v[176:177]
	s_add_i32 m0, s63, 0x2000
	s_nop 0
	global_load_lds_dwordx4 v[186:187], off
	v_lshl_add_u64 v[186:187], v[222:223], 0, s[22:23]
	s_mov_b32 m0, s95
	s_nop 0
	global_load_lds_dwordx4 v[186:187], off
	v_lshl_add_u64 v[186:187], v[224:225], 0, s[22:23]
	s_mov_b32 m0, s96
	s_nop 0
	global_load_lds_dwordx4 v[186:187], off
	s_waitcnt vmcnt(8)
	s_waitcnt lgkmcnt(0)
	s_setprio 1
	s_barrier
	v_mfma_f32_16x16x32_bf16 v[62:65], v[114:117], v[162:165], v[62:65]
	v_mfma_f32_16x16x32_bf16 v[58:61], v[122:125], v[162:165], v[58:61]
	v_mfma_f32_16x16x32_bf16 v[50:53], v[114:117], v[194:197], v[50:53]
	v_mfma_f32_16x16x32_bf16 v[42:45], v[122:125], v[194:197], v[42:45]
	v_mfma_f32_16x16x32_bf16 v[34:37], v[114:117], v[206:209], v[34:37]
	v_mfma_f32_16x16x32_bf16 v[26:29], v[122:125], v[206:209], v[26:29]
	v_mfma_f32_16x16x32_bf16 v[18:21], v[114:117], v[214:217], v[18:21]
	v_mfma_f32_16x16x32_bf16 v[10:13], v[122:125], v[214:217], v[10:13]
	v_mfma_f32_16x16x32_bf16 v[62:65], v[118:121], v[166:169], v[62:65]
	v_mfma_f32_16x16x32_bf16 v[58:61], v[126:129], v[166:169], v[58:61]
	v_mfma_f32_16x16x32_bf16 v[50:53], v[118:121], v[198:201], v[50:53]
	v_mfma_f32_16x16x32_bf16 v[42:45], v[126:129], v[198:201], v[42:45]
	v_mfma_f32_16x16x32_bf16 v[34:37], v[118:121], v[210:213], v[34:37]
	v_mfma_f32_16x16x32_bf16 v[26:29], v[126:129], v[210:213], v[26:29]
	v_mfma_f32_16x16x32_bf16 v[18:21], v[118:121], v[218:221], v[18:21]
	v_mfma_f32_16x16x32_bf16 v[10:13], v[126:129], v[218:221], v[10:13]
	v_mfma_f32_16x16x32_bf16 v[54:57], v[146:149], v[162:165], v[54:57]
	v_mfma_f32_16x16x32_bf16 v[46:49], v[154:157], v[162:165], v[46:49]
	v_mfma_f32_16x16x32_bf16 v[38:41], v[146:149], v[194:197], v[38:41]
	v_mfma_f32_16x16x32_bf16 v[30:33], v[154:157], v[194:197], v[30:33]
	v_mfma_f32_16x16x32_bf16 v[22:25], v[146:149], v[206:209], v[22:25]
	v_mfma_f32_16x16x32_bf16 v[14:17], v[154:157], v[206:209], v[14:17]
	v_mfma_f32_16x16x32_bf16 v[6:9], v[146:149], v[214:217], v[6:9]
	v_mfma_f32_16x16x32_bf16 v[2:5], v[154:157], v[214:217], v[2:5]
	v_mfma_f32_16x16x32_bf16 v[54:57], v[150:153], v[166:169], v[54:57]
	v_mfma_f32_16x16x32_bf16 v[46:49], v[158:161], v[166:169], v[46:49]
	v_mfma_f32_16x16x32_bf16 v[38:41], v[150:153], v[198:201], v[38:41]
	v_mfma_f32_16x16x32_bf16 v[30:33], v[158:161], v[198:201], v[30:33]
	v_mfma_f32_16x16x32_bf16 v[22:25], v[150:153], v[210:213], v[22:25]
	v_mfma_f32_16x16x32_bf16 v[14:17], v[158:161], v[210:213], v[14:17]
	v_mfma_f32_16x16x32_bf16 v[6:9], v[150:153], v[218:221], v[6:9]
	v_mfma_f32_16x16x32_bf16 v[2:5], v[158:161], v[218:221], v[2:5]
	s_setprio 0
	s_barrier
	s_add_u32 s76, s76, 0x100
	s_addc_u32 s77, s77, 0
	s_add_u32 s47, s47, 0x100
	s_addc_u32 s62, s62, 0
	s_cmp_ge_i32 s82, s7
	s_mov_b32 s63, s82
	s_cbranch_scc0 .LBB0_834
	s_and_b64 vcc, exec, s[26:27]
	s_cbranch_vccz .LBB0_837
	s_barrier

.LBB0_1012:
	s_add_u32 s48, s96, s44
	s_addc_u32 s49, s97, s45
	s_and_b64 s[14:15], s[4:5], exec
	s_cselect_b32 s6, s49, s65
	s_cselect_b32 s14, s48, s64
	s_add_u32 s50, s3, s46
	s_addc_u32 s51, s35, s47
	s_and_b64 s[18:19], s[4:5], exec
	s_cselect_b32 s15, s51, s67
	s_cselect_b32 s17, s50, s66
	s_add_u32 s64, s64, 0x40080
	s_addc_u32 s65, s65, 0
	s_add_u32 s18, s66, 0x100
	s_addc_u32 s19, s67, 0
	s_mov_b32 s24, -2
	s_waitcnt vmcnt(0)
	ds_read_b128 v[130:133], v172
	ds_read_b128 v[134:137], v172 offset:1024
	ds_read_b128 v[138:141], v172 offset:2048
	ds_read_b128 v[142:145], v172 offset:3072
	ds_read_b128 v[164:167], v173
	ds_read_b128 v[176:179], v173 offset:1024
	ds_read_b128 v[180:183], v173 offset:2048
	ds_read_b128 v[184:187], v173 offset:3072
	ds_read_b128 v[188:191], v174
	ds_read_b128 v[192:195], v174 offset:1024
	ds_read_b128 v[196:199], v174 offset:2048
	ds_read_b128 v[200:203], v174 offset:3072
	ds_read_b128 v[206:209], v174 offset:4096
	ds_read_b128 v[210:213], v174 offset:5120
	ds_read_b128 v[214:217], v174 offset:6144
	ds_read_b128 v[218:221], v174 offset:7168
	s_add_u32 s25, s64, 0xfffc0080
	s_addc_u32 s28, s65, -1
	s_cmp_eq_u32 s24, 12
	s_cselect_b32 s69, s6, s28
	s_cselect_b32 s68, s14, s25
	s_cselect_b32 s67, s15, s19
	s_cselect_b32 s66, s17, s18
	s_add_i32 m0, s73, 0xc000
	v_lshl_add_u64 v[168:169], s[64:65], 0, v[156:157]
	global_load_lds_dwordx4 v[168:169], off
	v_lshl_add_u64 v[168:169], s[64:65], 0, v[158:159]
	s_add_i32 m0, s73, 0xe000
	s_nop 0
	global_load_lds_dwordx4 v[168:169], off
	s_waitcnt vmcnt(8)
	s_waitcnt lgkmcnt(0)
	s_setprio 1
	s_barrier
	v_mfma_f32_16x16x32_bf16 v[126:129], v[130:133], v[188:191], 0
	v_mfma_f32_16x16x32_bf16 v[122:125], v[138:141], v[188:191], 0
	v_mfma_f32_16x16x32_bf16 v[110:113], v[130:133], v[196:199], 0
	v_mfma_f32_16x16x32_bf16 v[106:109], v[138:141], v[196:199], 0
	v_mfma_f32_16x16x32_bf16 v[94:97], v[130:133], v[206:209], 0
	v_mfma_f32_16x16x32_bf16 v[90:93], v[138:141], v[206:209], 0
	v_mfma_f32_16x16x32_bf16 v[78:81], v[130:133], v[214:217], 0
	v_mfma_f32_16x16x32_bf16 v[74:77], v[138:141], v[214:217], 0
	v_mfma_f32_16x16x32_bf16 v[126:129], v[134:137], v[192:195], v[126:129]
	v_mfma_f32_16x16x32_bf16 v[122:125], v[142:145], v[192:195], v[122:125]
	v_mfma_f32_16x16x32_bf16 v[110:113], v[134:137], v[200:203], v[110:113]
	v_mfma_f32_16x16x32_bf16 v[106:109], v[142:145], v[200:203], v[106:109]
	v_mfma_f32_16x16x32_bf16 v[94:97], v[134:137], v[210:213], v[94:97]
	v_mfma_f32_16x16x32_bf16 v[90:93], v[142:145], v[210:213], v[90:93]
	v_mfma_f32_16x16x32_bf16 v[78:81], v[134:137], v[218:221], v[78:81]
	v_mfma_f32_16x16x32_bf16 v[74:77], v[142:145], v[218:221], v[74:77]
	v_mfma_f32_16x16x32_bf16 v[118:121], v[164:167], v[188:191], 0
	v_mfma_f32_16x16x32_bf16 v[114:117], v[180:183], v[188:191], 0
	v_mfma_f32_16x16x32_bf16 v[102:105], v[164:167], v[196:199], 0
	v_mfma_f32_16x16x32_bf16 v[98:101], v[180:183], v[196:199], 0
	v_mfma_f32_16x16x32_bf16 v[86:89], v[164:167], v[206:209], 0
	v_mfma_f32_16x16x32_bf16 v[82:85], v[180:183], v[206:209], 0
	v_mfma_f32_16x16x32_bf16 v[70:73], v[164:167], v[214:217], 0
	v_mfma_f32_16x16x32_bf16 v[66:69], v[180:183], v[214:217], 0
	v_mfma_f32_16x16x32_bf16 v[118:121], v[176:179], v[192:195], v[118:121]
	v_mfma_f32_16x16x32_bf16 v[114:117], v[184:187], v[192:195], v[114:117]
	v_mfma_f32_16x16x32_bf16 v[102:105], v[176:179], v[200:203], v[102:105]
	v_mfma_f32_16x16x32_bf16 v[98:101], v[184:187], v[200:203], v[98:101]
	v_mfma_f32_16x16x32_bf16 v[86:89], v[176:179], v[210:213], v[86:89]
	v_mfma_f32_16x16x32_bf16 v[82:85], v[184:187], v[210:213], v[82:85]
	v_mfma_f32_16x16x32_bf16 v[70:73], v[176:179], v[218:221], v[70:73]
	v_mfma_f32_16x16x32_bf16 v[66:69], v[184:187], v[218:221], v[66:69]
	s_setprio 0
	s_barrier
	s_add_i32 s25, s82, s70
	v_lshl_add_u64 v[168:169], s[66:67], 0, v[150:151]
	s_mov_b32 m0, s25
	ds_read_b128 v[188:191], v174 offset:16384
	ds_read_b128 v[192:195], v174 offset:17408
	ds_read_b128 v[196:199], v174 offset:18432
	ds_read_b128 v[200:203], v174 offset:19456
	ds_read_b128 v[206:209], v174 offset:20480
	ds_read_b128 v[210:213], v174 offset:21504
	ds_read_b128 v[214:217], v174 offset:22528
	ds_read_b128 v[218:221], v174 offset:23552
	global_load_lds_dwordx4 v[168:169], off
	s_add_i32 m0, s25, 0x2000
	s_add_u32 s28, s66, 0x40000
	v_lshl_add_u64 v[222:223], s[66:67], 0, v[146:147]
	s_addc_u32 s29, s67, 0
	s_add_i32 s25, s83, s70
	global_load_lds_dwordx4 v[222:223], off
	v_lshl_add_u64 v[224:225], s[28:29], 0, v[150:151]
	s_mov_b32 m0, s25
	v_lshl_add_u64 v[226:227], s[68:69], 0, v[148:149]
	global_load_lds_dwordx4 v[224:225], off
	v_lshl_add_u64 v[224:225], s[28:29], 0, v[146:147]
	s_add_i32 m0, s25, 0x2000
	s_nop 0
	global_load_lds_dwordx4 v[224:225], off
	v_lshl_add_u64 v[224:225], s[68:69], 0, v[152:153]
	s_mov_b32 m0, s73
	s_nop 0
	global_load_lds_dwordx4 v[224:225], off
	s_mov_b32 m0, s74
	s_nop 0
	global_load_lds_dwordx4 v[226:227], off
	s_waitcnt vmcnt(8)
	s_waitcnt lgkmcnt(0)
	s_setprio 1
	s_barrier
	v_mfma_f32_16x16x32_bf16 v[62:65], v[130:133], v[188:191], 0
	v_mfma_f32_16x16x32_bf16 v[58:61], v[138:141], v[188:191], 0
	v_mfma_f32_16x16x32_bf16 v[46:49], v[130:133], v[196:199], 0
	v_mfma_f32_16x16x32_bf16 v[42:45], v[138:141], v[196:199], 0
	v_mfma_f32_16x16x32_bf16 v[30:33], v[130:133], v[206:209], 0
	v_mfma_f32_16x16x32_bf16 v[26:29], v[138:141], v[206:209], 0
	v_mfma_f32_16x16x32_bf16 v[14:17], v[130:133], v[214:217], 0
	v_mfma_f32_16x16x32_bf16 v[10:13], v[138:141], v[214:217], 0
	v_mfma_f32_16x16x32_bf16 v[62:65], v[134:137], v[192:195], v[62:65]
	v_mfma_f32_16x16x32_bf16 v[58:61], v[142:145], v[192:195], v[58:61]
	v_mfma_f32_16x16x32_bf16 v[46:49], v[134:137], v[200:203], v[46:49]
	v_mfma_f32_16x16x32_bf16 v[42:45], v[142:145], v[200:203], v[42:45]
	v_mfma_f32_16x16x32_bf16 v[30:33], v[134:137], v[210:213], v[30:33]
	v_mfma_f32_16x16x32_bf16 v[26:29], v[142:145], v[210:213], v[26:29]
	v_mfma_f32_16x16x32_bf16 v[14:17], v[134:137], v[218:221], v[14:17]
	v_mfma_f32_16x16x32_bf16 v[10:13], v[142:145], v[218:221], v[10:13]
	v_mfma_f32_16x16x32_bf16 v[54:57], v[164:167], v[188:191], 0
	v_mfma_f32_16x16x32_bf16 v[50:53], v[180:183], v[188:191], 0
	v_mfma_f32_16x16x32_bf16 v[38:41], v[164:167], v[196:199], 0
	v_mfma_f32_16x16x32_bf16 v[34:37], v[180:183], v[196:199], 0
	v_mfma_f32_16x16x32_bf16 v[22:25], v[164:167], v[206:209], 0
	v_mfma_f32_16x16x32_bf16 v[18:21], v[180:183], v[206:209], 0
	v_mfma_f32_16x16x32_bf16 v[6:9], v[164:167], v[214:217], 0
	v_mfma_f32_16x16x32_bf16 v[2:5], v[180:183], v[214:217], 0
	v_mfma_f32_16x16x32_bf16 v[54:57], v[176:179], v[192:195], v[54:57]
	v_mfma_f32_16x16x32_bf16 v[50:53], v[184:187], v[192:195], v[50:53]
	v_mfma_f32_16x16x32_bf16 v[38:41], v[176:179], v[200:203], v[38:41]
	v_mfma_f32_16x16x32_bf16 v[34:37], v[184:187], v[200:203], v[34:37]
	v_mfma_f32_16x16x32_bf16 v[22:25], v[176:179], v[210:213], v[22:25]
	v_mfma_f32_16x16x32_bf16 v[18:21], v[184:187], v[210:213], v[18:21]
	v_mfma_f32_16x16x32_bf16 v[6:9], v[176:179], v[218:221], v[6:9]
	v_mfma_f32_16x16x32_bf16 v[2:5], v[184:187], v[218:221], v[2:5]
	s_setprio 0
	s_barrier
	s_add_i32 s25, 0, 0x18000
	s_add_i32 s30, 0, 0x1c000
	v_add_u32_e32 v142, s25, v171
	v_add_u32_e32 v175, s30, v171
	ds_read_b128 v[130:133], v142
	ds_read_b128 v[134:137], v142 offset:1024
	ds_read_b128 v[138:141], v142 offset:2048
	ds_read_b128 v[142:145], v142 offset:3072
	ds_read_b128 v[164:167], v175
	ds_read_b128 v[176:179], v175 offset:1024
	ds_read_b128 v[180:183], v175 offset:2048
	ds_read_b128 v[184:187], v175 offset:3072
	s_add_u32 s28, s68, 0x40000
	s_addc_u32 s29, s69, 0
	s_mov_b32 m0, s75
	v_lshl_add_u64 v[228:229], s[28:29], 0, v[152:153]
	ds_read_b128 v[188:191], v174 offset:32768
	ds_read_b128 v[192:195], v174 offset:33792
	ds_read_b128 v[196:199], v174 offset:34816
	ds_read_b128 v[200:203], v174 offset:35840
	ds_read_b128 v[206:209], v174 offset:36864
	ds_read_b128 v[210:213], v174 offset:37888
	ds_read_b128 v[214:217], v174 offset:38912
	ds_read_b128 v[218:221], v174 offset:39936
	global_load_lds_dwordx4 v[228:229], off
	v_lshl_add_u64 v[228:229], s[28:29], 0, v[148:149]
	s_mov_b32 m0, s76
	s_nop 0
	global_load_lds_dwordx4 v[228:229], off
	s_waitcnt vmcnt(8)
	s_waitcnt lgkmcnt(0)
	s_setprio 1
	s_barrier
	v_mfma_f32_16x16x32_bf16 v[126:129], v[130:133], v[188:191], v[126:129]
	v_mfma_f32_16x16x32_bf16 v[122:125], v[138:141], v[188:191], v[122:125]
	v_mfma_f32_16x16x32_bf16 v[110:113], v[130:133], v[196:199], v[110:113]
	v_mfma_f32_16x16x32_bf16 v[106:109], v[138:141], v[196:199], v[106:109]
	v_mfma_f32_16x16x32_bf16 v[94:97], v[130:133], v[206:209], v[94:97]
	v_mfma_f32_16x16x32_bf16 v[90:93], v[138:141], v[206:209], v[90:93]
	v_mfma_f32_16x16x32_bf16 v[78:81], v[130:133], v[214:217], v[78:81]
	v_mfma_f32_16x16x32_bf16 v[74:77], v[138:141], v[214:217], v[74:77]
	v_mfma_f32_16x16x32_bf16 v[126:129], v[134:137], v[192:195], v[126:129]
	v_mfma_f32_16x16x32_bf16 v[122:125], v[142:145], v[192:195], v[122:125]
	v_mfma_f32_16x16x32_bf16 v[110:113], v[134:137], v[200:203], v[110:113]
	v_mfma_f32_16x16x32_bf16 v[106:109], v[142:145], v[200:203], v[106:109]
	v_mfma_f32_16x16x32_bf16 v[94:97], v[134:137], v[210:213], v[94:97]
	v_mfma_f32_16x16x32_bf16 v[90:93], v[142:145], v[210:213], v[90:93]
	v_mfma_f32_16x16x32_bf16 v[78:81], v[134:137], v[218:221], v[78:81]
	v_mfma_f32_16x16x32_bf16 v[74:77], v[142:145], v[218:221], v[74:77]
	v_mfma_f32_16x16x32_bf16 v[118:121], v[164:167], v[188:191], v[118:121]
	v_mfma_f32_16x16x32_bf16 v[114:117], v[180:183], v[188:191], v[114:117]
	v_mfma_f32_16x16x32_bf16 v[102:105], v[164:167], v[196:199], v[102:105]
	v_mfma_f32_16x16x32_bf16 v[98:101], v[180:183], v[196:199], v[98:101]
	v_mfma_f32_16x16x32_bf16 v[86:89], v[164:167], v[206:209], v[86:89]
	v_mfma_f32_16x16x32_bf16 v[82:85], v[180:183], v[206:209], v[82:85]
	v_mfma_f32_16x16x32_bf16 v[70:73], v[164:167], v[214:217], v[70:73]
	v_mfma_f32_16x16x32_bf16 v[66:69], v[180:183], v[214:217], v[66:69]
	v_mfma_f32_16x16x32_bf16 v[118:121], v[176:179], v[192:195], v[118:121]
	v_mfma_f32_16x16x32_bf16 v[114:117], v[184:187], v[192:195], v[114:117]
	v_mfma_f32_16x16x32_bf16 v[102:105], v[176:179], v[200:203], v[102:105]
	v_mfma_f32_16x16x32_bf16 v[98:101], v[184:187], v[200:203], v[98:101]
	v_mfma_f32_16x16x32_bf16 v[86:89], v[176:179], v[210:213], v[86:89]
	v_mfma_f32_16x16x32_bf16 v[82:85], v[184:187], v[210:213], v[82:85]
	v_mfma_f32_16x16x32_bf16 v[70:73], v[176:179], v[218:221], v[70:73]
	v_mfma_f32_16x16x32_bf16 v[66:69], v[184:187], v[218:221], v[66:69]
	s_setprio 0
	s_barrier
	s_add_i32 s25, s25, s70
	v_lshl_add_u64 v[168:169], v[168:169], 0, s[36:37]
	s_mov_b32 m0, s25
	ds_read_b128 v[188:191], v174 offset:49152
	ds_read_b128 v[192:195], v174 offset:50176
	ds_read_b128 v[196:199], v174 offset:51200
	ds_read_b128 v[200:203], v174 offset:52224
	ds_read_b128 v[206:209], v174 offset:53248
	ds_read_b128 v[210:213], v174 offset:54272
	ds_read_b128 v[214:217], v174 offset:55296
	ds_read_b128 v[218:221], v174 offset:56320
	global_load_lds_dwordx4 v[168:169], off
	s_add_i32 m0, s25, 0x2000
	s_add_u32 s28, s66, 0x40080
	v_lshl_add_u64 v[168:169], v[222:223], 0, s[36:37]
	s_addc_u32 s29, s67, 0
	s_add_i32 s25, s30, s70
	global_load_lds_dwordx4 v[168:169], off
	v_lshl_add_u64 v[168:169], s[28:29], 0, v[150:151]
	s_mov_b32 m0, s25
	s_nop 0
	global_load_lds_dwordx4 v[168:169], off
	v_lshl_add_u64 v[168:169], s[28:29], 0, v[146:147]
	s_add_i32 m0, s25, 0x2000
	s_nop 0
	global_load_lds_dwordx4 v[168:169], off
	v_lshl_add_u64 v[168:169], v[224:225], 0, s[36:37]
	s_mov_b32 m0, s79
	s_nop 0
	global_load_lds_dwordx4 v[168:169], off
	v_lshl_add_u64 v[168:169], v[226:227], 0, s[36:37]
	s_mov_b32 m0, s80
	s_nop 0
	global_load_lds_dwordx4 v[168:169], off
	s_waitcnt vmcnt(8)
	s_waitcnt lgkmcnt(0)
	s_setprio 1
	s_barrier
	v_mfma_f32_16x16x32_bf16 v[62:65], v[130:133], v[188:191], v[62:65]
	v_mfma_f32_16x16x32_bf16 v[58:61], v[138:141], v[188:191], v[58:61]
	v_mfma_f32_16x16x32_bf16 v[46:49], v[130:133], v[196:199], v[46:49]
	v_mfma_f32_16x16x32_bf16 v[42:45], v[138:141], v[196:199], v[42:45]
	v_mfma_f32_16x16x32_bf16 v[30:33], v[130:133], v[206:209], v[30:33]
	v_mfma_f32_16x16x32_bf16 v[26:29], v[138:141], v[206:209], v[26:29]
	v_mfma_f32_16x16x32_bf16 v[14:17], v[130:133], v[214:217], v[14:17]
	v_mfma_f32_16x16x32_bf16 v[10:13], v[138:141], v[214:217], v[10:13]
	v_mfma_f32_16x16x32_bf16 v[62:65], v[134:137], v[192:195], v[62:65]
	v_mfma_f32_16x16x32_bf16 v[58:61], v[142:145], v[192:195], v[58:61]
	v_mfma_f32_16x16x32_bf16 v[46:49], v[134:137], v[200:203], v[46:49]
	v_mfma_f32_16x16x32_bf16 v[42:45], v[142:145], v[200:203], v[42:45]
	v_mfma_f32_16x16x32_bf16 v[30:33], v[134:137], v[210:213], v[30:33]
	v_mfma_f32_16x16x32_bf16 v[26:29], v[142:145], v[210:213], v[26:29]
	v_mfma_f32_16x16x32_bf16 v[14:17], v[134:137], v[218:221], v[14:17]
	v_mfma_f32_16x16x32_bf16 v[10:13], v[142:145], v[218:221], v[10:13]
	v_mfma_f32_16x16x32_bf16 v[54:57], v[164:167], v[188:191], v[54:57]
	v_mfma_f32_16x16x32_bf16 v[50:53], v[180:183], v[188:191], v[50:53]
	v_mfma_f32_16x16x32_bf16 v[38:41], v[164:167], v[196:199], v[38:41]
	v_mfma_f32_16x16x32_bf16 v[34:37], v[180:183], v[196:199], v[34:37]
	v_mfma_f32_16x16x32_bf16 v[22:25], v[164:167], v[206:209], v[22:25]
	v_mfma_f32_16x16x32_bf16 v[18:21], v[180:183], v[206:209], v[18:21]
	v_mfma_f32_16x16x32_bf16 v[6:9], v[164:167], v[214:217], v[6:9]
	v_mfma_f32_16x16x32_bf16 v[2:5], v[180:183], v[214:217], v[2:5]
	v_mfma_f32_16x16x32_bf16 v[54:57], v[176:179], v[192:195], v[54:57]
	v_mfma_f32_16x16x32_bf16 v[50:53], v[184:187], v[192:195], v[50:53]
	v_mfma_f32_16x16x32_bf16 v[38:41], v[176:179], v[200:203], v[38:41]
	v_mfma_f32_16x16x32_bf16 v[34:37], v[184:187], v[200:203], v[34:37]
	v_mfma_f32_16x16x32_bf16 v[22:25], v[176:179], v[210:213], v[22:25]
	v_mfma_f32_16x16x32_bf16 v[18:21], v[184:187], v[210:213], v[18:21]
	v_mfma_f32_16x16x32_bf16 v[6:9], v[176:179], v[218:221], v[6:9]
	v_mfma_f32_16x16x32_bf16 v[2:5], v[184:187], v[218:221], v[2:5]
	s_setprio 0
	s_barrier
	s_add_i32 s24, s24, 2
	s_add_u32 s64, s64, 0x100
	s_addc_u32 s65, s65, 0
	s_add_u32 s18, s18, 0x100
	s_addc_u32 s19, s19, 0
	s_cmp_gt_u32 s24, 13
.LBB0_1013:
	ds_read_b128 v[130:133], v172
	ds_read_b128 v[134:137], v172 offset:1024
	ds_read_b128 v[138:141], v172 offset:2048
	ds_read_b128 v[142:145], v172 offset:3072
	ds_read_b128 v[164:167], v173
	ds_read_b128 v[176:179], v173 offset:1024
	ds_read_b128 v[180:183], v173 offset:2048
	ds_read_b128 v[184:187], v173 offset:3072
	ds_read_b128 v[188:191], v174
	ds_read_b128 v[192:195], v174 offset:1024
	ds_read_b128 v[196:199], v174 offset:2048
	ds_read_b128 v[200:203], v174 offset:3072
	ds_read_b128 v[206:209], v174 offset:4096
	ds_read_b128 v[210:213], v174 offset:5120
	ds_read_b128 v[214:217], v174 offset:6144
	ds_read_b128 v[218:221], v174 offset:7168
	s_add_u32 s25, s64, 0xfffc0080
	s_addc_u32 s28, s65, -1
	s_cmp_eq_u32 s24, 12
	s_cselect_b32 s69, s6, s28
	s_cselect_b32 s68, s14, s25
	s_cselect_b32 s67, s15, s19
	s_cselect_b32 s66, s17, s18
	s_add_i32 m0, s73, 0xc000
	v_lshl_add_u64 v[168:169], s[64:65], 0, v[156:157]
	global_load_lds_dwordx4 v[168:169], off
	v_lshl_add_u64 v[168:169], s[64:65], 0, v[158:159]
	s_add_i32 m0, s73, 0xe000
	s_nop 0
	global_load_lds_dwordx4 v[168:169], off
	s_waitcnt vmcnt(8)
	s_waitcnt lgkmcnt(0)
	s_setprio 1
	s_barrier
	v_mfma_f32_16x16x32_bf16 v[126:129], v[130:133], v[188:191], v[126:129]
	v_mfma_f32_16x16x32_bf16 v[122:125], v[138:141], v[188:191], v[122:125]
	v_mfma_f32_16x16x32_bf16 v[110:113], v[130:133], v[196:199], v[110:113]
	v_mfma_f32_16x16x32_bf16 v[106:109], v[138:141], v[196:199], v[106:109]
	v_mfma_f32_16x16x32_bf16 v[94:97], v[130:133], v[206:209], v[94:97]
	v_mfma_f32_16x16x32_bf16 v[90:93], v[138:141], v[206:209], v[90:93]
	v_mfma_f32_16x16x32_bf16 v[78:81], v[130:133], v[214:217], v[78:81]
	v_mfma_f32_16x16x32_bf16 v[74:77], v[138:141], v[214:217], v[74:77]
	v_mfma_f32_16x16x32_bf16 v[126:129], v[134:137], v[192:195], v[126:129]
	v_mfma_f32_16x16x32_bf16 v[122:125], v[142:145], v[192:195], v[122:125]
	v_mfma_f32_16x16x32_bf16 v[110:113], v[134:137], v[200:203], v[110:113]
	v_mfma_f32_16x16x32_bf16 v[106:109], v[142:145], v[200:203], v[106:109]
	v_mfma_f32_16x16x32_bf16 v[94:97], v[134:137], v[210:213], v[94:97]
	v_mfma_f32_16x16x32_bf16 v[90:93], v[142:145], v[210:213], v[90:93]
	v_mfma_f32_16x16x32_bf16 v[78:81], v[134:137], v[218:221], v[78:81]
	v_mfma_f32_16x16x32_bf16 v[74:77], v[142:145], v[218:221], v[74:77]
	v_mfma_f32_16x16x32_bf16 v[118:121], v[164:167], v[188:191], v[118:121]
	v_mfma_f32_16x16x32_bf16 v[114:117], v[180:183], v[188:191], v[114:117]
	v_mfma_f32_16x16x32_bf16 v[102:105], v[164:167], v[196:199], v[102:105]
	v_mfma_f32_16x16x32_bf16 v[98:101], v[180:183], v[196:199], v[98:101]
	v_mfma_f32_16x16x32_bf16 v[86:89], v[164:167], v[206:209], v[86:89]
	v_mfma_f32_16x16x32_bf16 v[82:85], v[180:183], v[206:209], v[82:85]
	v_mfma_f32_16x16x32_bf16 v[70:73], v[164:167], v[214:217], v[70:73]
	v_mfma_f32_16x16x32_bf16 v[66:69], v[180:183], v[214:217], v[66:69]
	v_mfma_f32_16x16x32_bf16 v[118:121], v[176:179], v[192:195], v[118:121]
	v_mfma_f32_16x16x32_bf16 v[114:117], v[184:187], v[192:195], v[114:117]
	v_mfma_f32_16x16x32_bf16 v[102:105], v[176:179], v[200:203], v[102:105]
	v_mfma_f32_16x16x32_bf16 v[98:101], v[184:187], v[200:203], v[98:101]
	v_mfma_f32_16x16x32_bf16 v[86:89], v[176:179], v[210:213], v[86:89]
	v_mfma_f32_16x16x32_bf16 v[82:85], v[184:187], v[210:213], v[82:85]
	v_mfma_f32_16x16x32_bf16 v[70:73], v[176:179], v[218:221], v[70:73]
	v_mfma_f32_16x16x32_bf16 v[66:69], v[184:187], v[218:221], v[66:69]
	s_setprio 0
	s_barrier
	s_add_i32 s25, s82, s70
	v_lshl_add_u64 v[168:169], s[66:67], 0, v[150:151]
	s_mov_b32 m0, s25
	ds_read_b128 v[188:191], v174 offset:16384
	ds_read_b128 v[192:195], v174 offset:17408
	ds_read_b128 v[196:199], v174 offset:18432
	ds_read_b128 v[200:203], v174 offset:19456
	ds_read_b128 v[206:209], v174 offset:20480
	ds_read_b128 v[210:213], v174 offset:21504
	ds_read_b128 v[214:217], v174 offset:22528
	ds_read_b128 v[218:221], v174 offset:23552
	global_load_lds_dwordx4 v[168:169], off
	s_add_i32 m0, s25, 0x2000
	s_add_u32 s28, s66, 0x40000
	v_lshl_add_u64 v[222:223], s[66:67], 0, v[146:147]
	s_addc_u32 s29, s67, 0
	s_add_i32 s25, s83, s70
	global_load_lds_dwordx4 v[222:223], off
	v_lshl_add_u64 v[224:225], s[28:29], 0, v[150:151]
	s_mov_b32 m0, s25
	v_lshl_add_u64 v[226:227], s[68:69], 0, v[148:149]
	global_load_lds_dwordx4 v[224:225], off
	v_lshl_add_u64 v[224:225], s[28:29], 0, v[146:147]
	s_add_i32 m0, s25, 0x2000
	s_nop 0
	global_load_lds_dwordx4 v[224:225], off
	v_lshl_add_u64 v[224:225], s[68:69], 0, v[152:153]
	s_mov_b32 m0, s73
	s_nop 0
	global_load_lds_dwordx4 v[224:225], off
	s_mov_b32 m0, s74
	s_nop 0
	global_load_lds_dwordx4 v[226:227], off
	s_waitcnt vmcnt(8)
	s_waitcnt lgkmcnt(0)
	s_setprio 1
	s_barrier
	v_mfma_f32_16x16x32_bf16 v[62:65], v[130:133], v[188:191], v[62:65]
	v_mfma_f32_16x16x32_bf16 v[58:61], v[138:141], v[188:191], v[58:61]
	v_mfma_f32_16x16x32_bf16 v[46:49], v[130:133], v[196:199], v[46:49]
	v_mfma_f32_16x16x32_bf16 v[42:45], v[138:141], v[196:199], v[42:45]
	v_mfma_f32_16x16x32_bf16 v[30:33], v[130:133], v[206:209], v[30:33]
	v_mfma_f32_16x16x32_bf16 v[26:29], v[138:141], v[206:209], v[26:29]
	v_mfma_f32_16x16x32_bf16 v[14:17], v[130:133], v[214:217], v[14:17]
	v_mfma_f32_16x16x32_bf16 v[10:13], v[138:141], v[214:217], v[10:13]
	v_mfma_f32_16x16x32_bf16 v[62:65], v[134:137], v[192:195], v[62:65]
	v_mfma_f32_16x16x32_bf16 v[58:61], v[142:145], v[192:195], v[58:61]
	v_mfma_f32_16x16x32_bf16 v[46:49], v[134:137], v[200:203], v[46:49]
	v_mfma_f32_16x16x32_bf16 v[42:45], v[142:145], v[200:203], v[42:45]
	v_mfma_f32_16x16x32_bf16 v[30:33], v[134:137], v[210:213], v[30:33]
	v_mfma_f32_16x16x32_bf16 v[26:29], v[142:145], v[210:213], v[26:29]
	v_mfma_f32_16x16x32_bf16 v[14:17], v[134:137], v[218:221], v[14:17]
	v_mfma_f32_16x16x32_bf16 v[10:13], v[142:145], v[218:221], v[10:13]
	v_mfma_f32_16x16x32_bf16 v[54:57], v[164:167], v[188:191], v[54:57]
	v_mfma_f32_16x16x32_bf16 v[50:53], v[180:183], v[188:191], v[50:53]
	v_mfma_f32_16x16x32_bf16 v[38:41], v[164:167], v[196:199], v[38:41]
	v_mfma_f32_16x16x32_bf16 v[34:37], v[180:183], v[196:199], v[34:37]
	v_mfma_f32_16x16x32_bf16 v[22:25], v[164:167], v[206:209], v[22:25]
	v_mfma_f32_16x16x32_bf16 v[18:21], v[180:183], v[206:209], v[18:21]
	v_mfma_f32_16x16x32_bf16 v[6:9], v[164:167], v[214:217], v[6:9]
	v_mfma_f32_16x16x32_bf16 v[2:5], v[180:183], v[214:217], v[2:5]
	v_mfma_f32_16x16x32_bf16 v[54:57], v[176:179], v[192:195], v[54:57]
	v_mfma_f32_16x16x32_bf16 v[50:53], v[184:187], v[192:195], v[50:53]
	v_mfma_f32_16x16x32_bf16 v[38:41], v[176:179], v[200:203], v[38:41]
	v_mfma_f32_16x16x32_bf16 v[34:37], v[184:187], v[200:203], v[34:37]
	v_mfma_f32_16x16x32_bf16 v[22:25], v[176:179], v[210:213], v[22:25]
	v_mfma_f32_16x16x32_bf16 v[18:21], v[184:187], v[210:213], v[18:21]
	v_mfma_f32_16x16x32_bf16 v[6:9], v[176:179], v[218:221], v[6:9]
	v_mfma_f32_16x16x32_bf16 v[2:5], v[184:187], v[218:221], v[2:5]
	s_setprio 0
	s_barrier
	s_add_i32 s25, 0, 0x18000
	s_add_i32 s30, 0, 0x1c000
	v_add_u32_e32 v142, s25, v171
	v_add_u32_e32 v175, s30, v171
	ds_read_b128 v[130:133], v142
	ds_read_b128 v[134:137], v142 offset:1024
	ds_read_b128 v[138:141], v142 offset:2048
	ds_read_b128 v[142:145], v142 offset:3072
	ds_read_b128 v[164:167], v175
	ds_read_b128 v[176:179], v175 offset:1024
	ds_read_b128 v[180:183], v175 offset:2048
	ds_read_b128 v[184:187], v175 offset:3072
	s_add_u32 s28, s68, 0x40000
	s_addc_u32 s29, s69, 0
	s_mov_b32 m0, s75
	v_lshl_add_u64 v[228:229], s[28:29], 0, v[152:153]
	ds_read_b128 v[188:191], v174 offset:32768
	ds_read_b128 v[192:195], v174 offset:33792
	ds_read_b128 v[196:199], v174 offset:34816
	ds_read_b128 v[200:203], v174 offset:35840
	ds_read_b128 v[206:209], v174 offset:36864
	ds_read_b128 v[210:213], v174 offset:37888
	ds_read_b128 v[214:217], v174 offset:38912
	ds_read_b128 v[218:221], v174 offset:39936
	global_load_lds_dwordx4 v[228:229], off
	v_lshl_add_u64 v[228:229], s[28:29], 0, v[148:149]
	s_mov_b32 m0, s76
	s_nop 0
	global_load_lds_dwordx4 v[228:229], off
	s_waitcnt vmcnt(8)
	s_waitcnt lgkmcnt(0)
	s_setprio 1
	s_barrier
	v_mfma_f32_16x16x32_bf16 v[126:129], v[130:133], v[188:191], v[126:129]
	v_mfma_f32_16x16x32_bf16 v[122:125], v[138:141], v[188:191], v[122:125]
	v_mfma_f32_16x16x32_bf16 v[110:113], v[130:133], v[196:199], v[110:113]
	v_mfma_f32_16x16x32_bf16 v[106:109], v[138:141], v[196:199], v[106:109]
	v_mfma_f32_16x16x32_bf16 v[94:97], v[130:133], v[206:209], v[94:97]
	v_mfma_f32_16x16x32_bf16 v[90:93], v[138:141], v[206:209], v[90:93]
	v_mfma_f32_16x16x32_bf16 v[78:81], v[130:133], v[214:217], v[78:81]
	v_mfma_f32_16x16x32_bf16 v[74:77], v[138:141], v[214:217], v[74:77]
	v_mfma_f32_16x16x32_bf16 v[126:129], v[134:137], v[192:195], v[126:129]
	v_mfma_f32_16x16x32_bf16 v[122:125], v[142:145], v[192:195], v[122:125]
	v_mfma_f32_16x16x32_bf16 v[110:113], v[134:137], v[200:203], v[110:113]
	v_mfma_f32_16x16x32_bf16 v[106:109], v[142:145], v[200:203], v[106:109]
	v_mfma_f32_16x16x32_bf16 v[94:97], v[134:137], v[210:213], v[94:97]
	v_mfma_f32_16x16x32_bf16 v[90:93], v[142:145], v[210:213], v[90:93]
	v_mfma_f32_16x16x32_bf16 v[78:81], v[134:137], v[218:221], v[78:81]
	v_mfma_f32_16x16x32_bf16 v[74:77], v[142:145], v[218:221], v[74:77]
	v_mfma_f32_16x16x32_bf16 v[118:121], v[164:167], v[188:191], v[118:121]
	v_mfma_f32_16x16x32_bf16 v[114:117], v[180:183], v[188:191], v[114:117]
	v_mfma_f32_16x16x32_bf16 v[102:105], v[164:167], v[196:199], v[102:105]
	v_mfma_f32_16x16x32_bf16 v[98:101], v[180:183], v[196:199], v[98:101]
	v_mfma_f32_16x16x32_bf16 v[86:89], v[164:167], v[206:209], v[86:89]
	v_mfma_f32_16x16x32_bf16 v[82:85], v[180:183], v[206:209], v[82:85]
	v_mfma_f32_16x16x32_bf16 v[70:73], v[164:167], v[214:217], v[70:73]
	v_mfma_f32_16x16x32_bf16 v[66:69], v[180:183], v[214:217], v[66:69]
	v_mfma_f32_16x16x32_bf16 v[118:121], v[176:179], v[192:195], v[118:121]
	v_mfma_f32_16x16x32_bf16 v[114:117], v[184:187], v[192:195], v[114:117]
	v_mfma_f32_16x16x32_bf16 v[102:105], v[176:179], v[200:203], v[102:105]
	v_mfma_f32_16x16x32_bf16 v[98:101], v[184:187], v[200:203], v[98:101]
	v_mfma_f32_16x16x32_bf16 v[86:89], v[176:179], v[210:213], v[86:89]
	v_mfma_f32_16x16x32_bf16 v[82:85], v[184:187], v[210:213], v[82:85]
	v_mfma_f32_16x16x32_bf16 v[70:73], v[176:179], v[218:221], v[70:73]
	v_mfma_f32_16x16x32_bf16 v[66:69], v[184:187], v[218:221], v[66:69]
	s_setprio 0
	s_barrier
	s_add_i32 s25, s25, s70
	v_lshl_add_u64 v[168:169], v[168:169], 0, s[36:37]
	s_mov_b32 m0, s25
	ds_read_b128 v[188:191], v174 offset:49152
	ds_read_b128 v[192:195], v174 offset:50176
	ds_read_b128 v[196:199], v174 offset:51200
	ds_read_b128 v[200:203], v174 offset:52224
	ds_read_b128 v[206:209], v174 offset:53248
	ds_read_b128 v[210:213], v174 offset:54272
	ds_read_b128 v[214:217], v174 offset:55296
	ds_read_b128 v[218:221], v174 offset:56320
	global_load_lds_dwordx4 v[168:169], off
	s_add_i32 m0, s25, 0x2000
	s_add_u32 s28, s66, 0x40080
	v_lshl_add_u64 v[168:169], v[222:223], 0, s[36:37]
	s_addc_u32 s29, s67, 0
	s_add_i32 s25, s30, s70
	global_load_lds_dwordx4 v[168:169], off
	v_lshl_add_u64 v[168:169], s[28:29], 0, v[150:151]
	s_mov_b32 m0, s25
	s_nop 0
	global_load_lds_dwordx4 v[168:169], off
	v_lshl_add_u64 v[168:169], s[28:29], 0, v[146:147]
	s_add_i32 m0, s25, 0x2000
	s_nop 0
	global_load_lds_dwordx4 v[168:169], off
	v_lshl_add_u64 v[168:169], v[224:225], 0, s[36:37]
	s_mov_b32 m0, s79
	s_nop 0
	global_load_lds_dwordx4 v[168:169], off
	v_lshl_add_u64 v[168:169], v[226:227], 0, s[36:37]
	s_mov_b32 m0, s80
	s_nop 0
	global_load_lds_dwordx4 v[168:169], off
	s_waitcnt vmcnt(8)
	s_waitcnt lgkmcnt(0)
	s_setprio 1
	s_barrier
	v_mfma_f32_16x16x32_bf16 v[62:65], v[130:133], v[188:191], v[62:65]
	v_mfma_f32_16x16x32_bf16 v[58:61], v[138:141], v[188:191], v[58:61]
	v_mfma_f32_16x16x32_bf16 v[46:49], v[130:133], v[196:199], v[46:49]
	v_mfma_f32_16x16x32_bf16 v[42:45], v[138:141], v[196:199], v[42:45]
	v_mfma_f32_16x16x32_bf16 v[30:33], v[130:133], v[206:209], v[30:33]
	v_mfma_f32_16x16x32_bf16 v[26:29], v[138:141], v[206:209], v[26:29]
	v_mfma_f32_16x16x32_bf16 v[14:17], v[130:133], v[214:217], v[14:17]
	v_mfma_f32_16x16x32_bf16 v[10:13], v[138:141], v[214:217], v[10:13]
	v_mfma_f32_16x16x32_bf16 v[62:65], v[134:137], v[192:195], v[62:65]
	v_mfma_f32_16x16x32_bf16 v[58:61], v[142:145], v[192:195], v[58:61]
	v_mfma_f32_16x16x32_bf16 v[46:49], v[134:137], v[200:203], v[46:49]
	v_mfma_f32_16x16x32_bf16 v[42:45], v[142:145], v[200:203], v[42:45]
	v_mfma_f32_16x16x32_bf16 v[30:33], v[134:137], v[210:213], v[30:33]
	v_mfma_f32_16x16x32_bf16 v[26:29], v[142:145], v[210:213], v[26:29]
	v_mfma_f32_16x16x32_bf16 v[14:17], v[134:137], v[218:221], v[14:17]
	v_mfma_f32_16x16x32_bf16 v[10:13], v[142:145], v[218:221], v[10:13]
	v_mfma_f32_16x16x32_bf16 v[54:57], v[164:167], v[188:191], v[54:57]
	v_mfma_f32_16x16x32_bf16 v[50:53], v[180:183], v[188:191], v[50:53]
	v_mfma_f32_16x16x32_bf16 v[38:41], v[164:167], v[196:199], v[38:41]
	v_mfma_f32_16x16x32_bf16 v[34:37], v[180:183], v[196:199], v[34:37]
	v_mfma_f32_16x16x32_bf16 v[22:25], v[164:167], v[206:209], v[22:25]
	v_mfma_f32_16x16x32_bf16 v[18:21], v[180:183], v[206:209], v[18:21]
	v_mfma_f32_16x16x32_bf16 v[6:9], v[164:167], v[214:217], v[6:9]
	v_mfma_f32_16x16x32_bf16 v[2:5], v[180:183], v[214:217], v[2:5]
	v_mfma_f32_16x16x32_bf16 v[54:57], v[176:179], v[192:195], v[54:57]
	v_mfma_f32_16x16x32_bf16 v[50:53], v[184:187], v[192:195], v[50:53]
	v_mfma_f32_16x16x32_bf16 v[38:41], v[176:179], v[200:203], v[38:41]
	v_mfma_f32_16x16x32_bf16 v[34:37], v[184:187], v[200:203], v[34:37]
	v_mfma_f32_16x16x32_bf16 v[22:25], v[176:179], v[210:213], v[22:25]
	v_mfma_f32_16x16x32_bf16 v[18:21], v[184:187], v[210:213], v[18:21]
	v_mfma_f32_16x16x32_bf16 v[6:9], v[176:179], v[218:221], v[6:9]
	v_mfma_f32_16x16x32_bf16 v[2:5], v[184:187], v[218:221], v[2:5]
	s_setprio 0
	s_barrier
	s_add_i32 s24, s24, 2
	s_add_u32 s64, s64, 0x100
	s_addc_u32 s65, s65, 0
	s_add_u32 s18, s18, 0x100
	s_addc_u32 s19, s19, 0
	s_cmp_gt_u32 s24, 13
	s_cbranch_scc0 .LBB0_1013
	s_and_b64 vcc, exec, s[38:39]
	s_cbranch_vccz .LBB0_1016
	s_barrier

.LBB0_1618:
	s_add_u32 s24, s96, s20
	s_addc_u32 s25, s97, s21
	s_and_b64 s[14:15], s[4:5], exec
	s_cselect_b32 s14, s25, s29
	s_cselect_b32 s15, s24, s28
	s_add_u32 s26, s2, s22
	s_addc_u32 s27, s3, s23
	s_and_b64 s[36:37], s[4:5], exec
	s_cselect_b32 s17, s27, s31
	s_cselect_b32 s49, s26, s30
	s_add_u32 s28, s28, 0x40080
	s_addc_u32 s29, s29, 0
	s_add_u32 s50, s30, 0x100
	s_addc_u32 s51, s31, 0
	s_mov_b32 s62, -2
	ds_read_b128 v[154:157], v150
	ds_read_b128 v[158:161], v150 offset:1024
	ds_read_b128 v[162:165], v150 offset:2048
	ds_read_b128 v[166:169], v150 offset:3072
	ds_read_b128 v[170:173], v151
	ds_read_b128 v[174:177], v151 offset:1024
	ds_read_b128 v[178:181], v151 offset:2048
	ds_read_b128 v[182:185], v151 offset:3072
	ds_read_b128 v[186:189], v152
	ds_read_b128 v[190:193], v152 offset:1024
	ds_read_b128 v[194:197], v152 offset:2048
	ds_read_b128 v[198:201], v152 offset:3072
	ds_read_b128 v[206:209], v152 offset:4096
	ds_read_b128 v[210:213], v152 offset:5120
	ds_read_b128 v[214:217], v152 offset:6144
	ds_read_b128 v[218:221], v152 offset:7168
	s_add_u32 s30, s28, 0xfffc0080
	s_addc_u32 s31, s29, -1
	s_cmp_eq_u32 s62, 12
	s_cselect_b32 s37, s14, s31
	s_cselect_b32 s36, s15, s30
	s_cselect_b32 s31, s17, s51
	s_cselect_b32 s30, s49, s50
	s_add_i32 m0, s19, 0xc000
	v_lshl_add_u64 v[146:147], s[28:29], 0, v[138:139]
	global_load_lds_dwordx4 v[146:147], off
	v_lshl_add_u64 v[146:147], s[28:29], 0, v[140:141]
	s_add_i32 m0, s19, 0xe000
	s_nop 0
	global_load_lds_dwordx4 v[146:147], off
	s_waitcnt vmcnt(8)
	s_waitcnt lgkmcnt(0)
	s_setprio 1
	s_barrier
	v_mfma_f32_16x16x32_bf16 v[126:129], v[154:157], v[186:189], 0
	v_mfma_f32_16x16x32_bf16 v[122:125], v[162:165], v[186:189], 0
	v_mfma_f32_16x16x32_bf16 v[110:113], v[154:157], v[194:197], 0
	v_mfma_f32_16x16x32_bf16 v[106:109], v[162:165], v[194:197], 0
	v_mfma_f32_16x16x32_bf16 v[94:97], v[154:157], v[206:209], 0
	v_mfma_f32_16x16x32_bf16 v[90:93], v[162:165], v[206:209], 0
	v_mfma_f32_16x16x32_bf16 v[78:81], v[154:157], v[214:217], 0
	v_mfma_f32_16x16x32_bf16 v[74:77], v[162:165], v[214:217], 0
	v_mfma_f32_16x16x32_bf16 v[126:129], v[158:161], v[190:193], v[126:129]
	v_mfma_f32_16x16x32_bf16 v[122:125], v[166:169], v[190:193], v[122:125]
	v_mfma_f32_16x16x32_bf16 v[110:113], v[158:161], v[198:201], v[110:113]
	v_mfma_f32_16x16x32_bf16 v[106:109], v[166:169], v[198:201], v[106:109]
	v_mfma_f32_16x16x32_bf16 v[94:97], v[158:161], v[210:213], v[94:97]
	v_mfma_f32_16x16x32_bf16 v[90:93], v[166:169], v[210:213], v[90:93]
	v_mfma_f32_16x16x32_bf16 v[78:81], v[158:161], v[218:221], v[78:81]
	v_mfma_f32_16x16x32_bf16 v[74:77], v[166:169], v[218:221], v[74:77]
	v_mfma_f32_16x16x32_bf16 v[118:121], v[170:173], v[186:189], 0
	v_mfma_f32_16x16x32_bf16 v[114:117], v[178:181], v[186:189], 0
	v_mfma_f32_16x16x32_bf16 v[102:105], v[170:173], v[194:197], 0
	v_mfma_f32_16x16x32_bf16 v[98:101], v[178:181], v[194:197], 0
	v_mfma_f32_16x16x32_bf16 v[86:89], v[170:173], v[206:209], 0
	v_mfma_f32_16x16x32_bf16 v[82:85], v[178:181], v[206:209], 0
	v_mfma_f32_16x16x32_bf16 v[70:73], v[170:173], v[214:217], 0
	v_mfma_f32_16x16x32_bf16 v[66:69], v[178:181], v[214:217], 0
	v_mfma_f32_16x16x32_bf16 v[118:121], v[174:177], v[190:193], v[118:121]
	v_mfma_f32_16x16x32_bf16 v[114:117], v[182:185], v[190:193], v[114:117]
	v_mfma_f32_16x16x32_bf16 v[102:105], v[174:177], v[198:201], v[102:105]
	v_mfma_f32_16x16x32_bf16 v[98:101], v[182:185], v[198:201], v[98:101]
	v_mfma_f32_16x16x32_bf16 v[86:89], v[174:177], v[210:213], v[86:89]
	v_mfma_f32_16x16x32_bf16 v[82:85], v[182:185], v[210:213], v[82:85]
	v_mfma_f32_16x16x32_bf16 v[70:73], v[174:177], v[218:221], v[70:73]
	v_mfma_f32_16x16x32_bf16 v[66:69], v[182:185], v[218:221], v[66:69]
	s_setprio 0
	s_barrier
	s_add_i32 s63, s45, s12
	v_lshl_add_u64 v[146:147], s[30:31], 0, v[134:135]
	s_mov_b32 m0, s63
	ds_read_b128 v[186:189], v152 offset:16384
	ds_read_b128 v[190:193], v152 offset:17408
	ds_read_b128 v[194:197], v152 offset:18432
	ds_read_b128 v[198:201], v152 offset:19456
	ds_read_b128 v[206:209], v152 offset:20480
	ds_read_b128 v[210:213], v152 offset:21504
	ds_read_b128 v[214:217], v152 offset:22528
	ds_read_b128 v[218:221], v152 offset:23552
	global_load_lds_dwordx4 v[146:147], off
	s_add_i32 m0, s63, 0x2000
	s_add_u32 s64, s30, 0x40000
	v_lshl_add_u64 v[202:203], s[30:31], 0, v[130:131]
	s_addc_u32 s65, s31, 0
	s_add_i32 s63, s46, s12
	global_load_lds_dwordx4 v[202:203], off
	v_lshl_add_u64 v[222:223], s[64:65], 0, v[134:135]
	s_mov_b32 m0, s63
	v_lshl_add_u64 v[224:225], s[36:37], 0, v[132:133]
	global_load_lds_dwordx4 v[222:223], off
	v_lshl_add_u64 v[222:223], s[64:65], 0, v[130:131]
	s_add_i32 m0, s63, 0x2000
	s_nop 0
	global_load_lds_dwordx4 v[222:223], off
	v_lshl_add_u64 v[222:223], s[36:37], 0, v[136:137]
	s_mov_b32 m0, s19
	s_nop 0
	global_load_lds_dwordx4 v[222:223], off
	s_mov_b32 m0, s33
	s_nop 0
	global_load_lds_dwordx4 v[224:225], off
	s_waitcnt vmcnt(8)
	s_waitcnt lgkmcnt(0)
	s_setprio 1
	s_barrier
	v_mfma_f32_16x16x32_bf16 v[62:65], v[154:157], v[186:189], 0
	v_mfma_f32_16x16x32_bf16 v[58:61], v[162:165], v[186:189], 0
	v_mfma_f32_16x16x32_bf16 v[46:49], v[154:157], v[194:197], 0
	v_mfma_f32_16x16x32_bf16 v[42:45], v[162:165], v[194:197], 0
	v_mfma_f32_16x16x32_bf16 v[30:33], v[154:157], v[206:209], 0
	v_mfma_f32_16x16x32_bf16 v[26:29], v[162:165], v[206:209], 0
	v_mfma_f32_16x16x32_bf16 v[14:17], v[154:157], v[214:217], 0
	v_mfma_f32_16x16x32_bf16 v[10:13], v[162:165], v[214:217], 0
	v_mfma_f32_16x16x32_bf16 v[62:65], v[158:161], v[190:193], v[62:65]
	v_mfma_f32_16x16x32_bf16 v[58:61], v[166:169], v[190:193], v[58:61]
	v_mfma_f32_16x16x32_bf16 v[46:49], v[158:161], v[198:201], v[46:49]
	v_mfma_f32_16x16x32_bf16 v[42:45], v[166:169], v[198:201], v[42:45]
	v_mfma_f32_16x16x32_bf16 v[30:33], v[158:161], v[210:213], v[30:33]
	v_mfma_f32_16x16x32_bf16 v[26:29], v[166:169], v[210:213], v[26:29]
	v_mfma_f32_16x16x32_bf16 v[14:17], v[158:161], v[218:221], v[14:17]
	v_mfma_f32_16x16x32_bf16 v[10:13], v[166:169], v[218:221], v[10:13]
	v_mfma_f32_16x16x32_bf16 v[54:57], v[170:173], v[186:189], 0
	v_mfma_f32_16x16x32_bf16 v[50:53], v[178:181], v[186:189], 0
	v_mfma_f32_16x16x32_bf16 v[38:41], v[170:173], v[194:197], 0
	v_mfma_f32_16x16x32_bf16 v[34:37], v[178:181], v[194:197], 0
	v_mfma_f32_16x16x32_bf16 v[22:25], v[170:173], v[206:209], 0
	v_mfma_f32_16x16x32_bf16 v[18:21], v[178:181], v[206:209], 0
	v_mfma_f32_16x16x32_bf16 v[6:9], v[170:173], v[214:217], 0
	v_mfma_f32_16x16x32_bf16 v[2:5], v[178:181], v[214:217], 0
	v_mfma_f32_16x16x32_bf16 v[54:57], v[174:177], v[190:193], v[54:57]
	v_mfma_f32_16x16x32_bf16 v[50:53], v[182:185], v[190:193], v[50:53]
	v_mfma_f32_16x16x32_bf16 v[38:41], v[174:177], v[198:201], v[38:41]
	v_mfma_f32_16x16x32_bf16 v[34:37], v[182:185], v[198:201], v[34:37]
	v_mfma_f32_16x16x32_bf16 v[22:25], v[174:177], v[210:213], v[22:25]
	v_mfma_f32_16x16x32_bf16 v[18:21], v[182:185], v[210:213], v[18:21]
	v_mfma_f32_16x16x32_bf16 v[6:9], v[174:177], v[218:221], v[6:9]
	v_mfma_f32_16x16x32_bf16 v[2:5], v[182:185], v[218:221], v[2:5]
	s_setprio 0
	s_barrier
	s_add_i32 s63, 0, 0x18000
	v_add_u32_e32 v153, s63, v149
	s_add_i32 s64, 0, 0x1c000
	ds_read_b128 v[154:157], v153
	ds_read_b128 v[158:161], v153 offset:1024
	ds_read_b128 v[162:165], v153 offset:2048
	ds_read_b128 v[166:169], v153 offset:3072
	v_add_u32_e32 v153, s64, v149
	ds_read_b128 v[170:173], v153
	ds_read_b128 v[174:177], v153 offset:1024
	ds_read_b128 v[178:181], v153 offset:2048
	ds_read_b128 v[182:185], v153 offset:3072
	s_add_u32 s36, s36, 0x40000
	s_addc_u32 s37, s37, 0
	s_mov_b32 m0, s35
	v_lshl_add_u64 v[226:227], s[36:37], 0, v[136:137]
	ds_read_b128 v[186:189], v152 offset:32768
	ds_read_b128 v[190:193], v152 offset:33792
	ds_read_b128 v[194:197], v152 offset:34816
	ds_read_b128 v[198:201], v152 offset:35840
	ds_read_b128 v[206:209], v152 offset:36864
	ds_read_b128 v[210:213], v152 offset:37888
	ds_read_b128 v[214:217], v152 offset:38912
	ds_read_b128 v[218:221], v152 offset:39936
	global_load_lds_dwordx4 v[226:227], off
	v_lshl_add_u64 v[226:227], s[36:37], 0, v[132:133]
	s_mov_b32 m0, s38
	s_nop 0
	global_load_lds_dwordx4 v[226:227], off
	s_waitcnt vmcnt(8)
	s_waitcnt lgkmcnt(0)
	s_setprio 1
	s_barrier
	v_mfma_f32_16x16x32_bf16 v[126:129], v[154:157], v[186:189], v[126:129]
	v_mfma_f32_16x16x32_bf16 v[122:125], v[162:165], v[186:189], v[122:125]
	v_mfma_f32_16x16x32_bf16 v[110:113], v[154:157], v[194:197], v[110:113]
	v_mfma_f32_16x16x32_bf16 v[106:109], v[162:165], v[194:197], v[106:109]
	v_mfma_f32_16x16x32_bf16 v[94:97], v[154:157], v[206:209], v[94:97]
	v_mfma_f32_16x16x32_bf16 v[90:93], v[162:165], v[206:209], v[90:93]
	v_mfma_f32_16x16x32_bf16 v[78:81], v[154:157], v[214:217], v[78:81]
	v_mfma_f32_16x16x32_bf16 v[74:77], v[162:165], v[214:217], v[74:77]
	v_mfma_f32_16x16x32_bf16 v[126:129], v[158:161], v[190:193], v[126:129]
	v_mfma_f32_16x16x32_bf16 v[122:125], v[166:169], v[190:193], v[122:125]
	v_mfma_f32_16x16x32_bf16 v[110:113], v[158:161], v[198:201], v[110:113]
	v_mfma_f32_16x16x32_bf16 v[106:109], v[166:169], v[198:201], v[106:109]
	v_mfma_f32_16x16x32_bf16 v[94:97], v[158:161], v[210:213], v[94:97]
	v_mfma_f32_16x16x32_bf16 v[90:93], v[166:169], v[210:213], v[90:93]
	v_mfma_f32_16x16x32_bf16 v[78:81], v[158:161], v[218:221], v[78:81]
	v_mfma_f32_16x16x32_bf16 v[74:77], v[166:169], v[218:221], v[74:77]
	v_mfma_f32_16x16x32_bf16 v[118:121], v[170:173], v[186:189], v[118:121]
	v_mfma_f32_16x16x32_bf16 v[114:117], v[178:181], v[186:189], v[114:117]
	v_mfma_f32_16x16x32_bf16 v[102:105], v[170:173], v[194:197], v[102:105]
	v_mfma_f32_16x16x32_bf16 v[98:101], v[178:181], v[194:197], v[98:101]
	v_mfma_f32_16x16x32_bf16 v[86:89], v[170:173], v[206:209], v[86:89]
	v_mfma_f32_16x16x32_bf16 v[82:85], v[178:181], v[206:209], v[82:85]
	v_mfma_f32_16x16x32_bf16 v[70:73], v[170:173], v[214:217], v[70:73]
	v_mfma_f32_16x16x32_bf16 v[66:69], v[178:181], v[214:217], v[66:69]
	v_mfma_f32_16x16x32_bf16 v[118:121], v[174:177], v[190:193], v[118:121]
	v_mfma_f32_16x16x32_bf16 v[114:117], v[182:185], v[190:193], v[114:117]
	v_mfma_f32_16x16x32_bf16 v[102:105], v[174:177], v[198:201], v[102:105]
	v_mfma_f32_16x16x32_bf16 v[98:101], v[182:185], v[198:201], v[98:101]
	v_mfma_f32_16x16x32_bf16 v[86:89], v[174:177], v[210:213], v[86:89]
	v_mfma_f32_16x16x32_bf16 v[82:85], v[182:185], v[210:213], v[82:85]
	v_mfma_f32_16x16x32_bf16 v[70:73], v[174:177], v[218:221], v[70:73]
	v_mfma_f32_16x16x32_bf16 v[66:69], v[182:185], v[218:221], v[66:69]
	s_setprio 0
	s_barrier
	s_add_i32 s36, s63, s12
	v_lshl_add_u64 v[146:147], v[146:147], 0, s[8:9]
	s_mov_b32 m0, s36
	ds_read_b128 v[186:189], v152 offset:49152
	ds_read_b128 v[190:193], v152 offset:50176
	ds_read_b128 v[194:197], v152 offset:51200
	ds_read_b128 v[198:201], v152 offset:52224
	ds_read_b128 v[206:209], v152 offset:53248
	ds_read_b128 v[210:213], v152 offset:54272
	ds_read_b128 v[214:217], v152 offset:55296
	ds_read_b128 v[218:221], v152 offset:56320
	global_load_lds_dwordx4 v[146:147], off
	s_add_i32 m0, s36, 0x2000
	s_add_u32 s30, s30, 0x40080
	v_lshl_add_u64 v[146:147], v[202:203], 0, s[8:9]
	s_addc_u32 s31, s31, 0
	s_add_i32 s36, s64, s12
	global_load_lds_dwordx4 v[146:147], off
	v_lshl_add_u64 v[146:147], s[30:31], 0, v[134:135]
	s_mov_b32 m0, s36
	s_nop 0
	global_load_lds_dwordx4 v[146:147], off
	v_lshl_add_u64 v[146:147], s[30:31], 0, v[130:131]
	s_add_i32 m0, s36, 0x2000
	s_nop 0
	global_load_lds_dwordx4 v[146:147], off
	v_lshl_add_u64 v[146:147], v[222:223], 0, s[8:9]
	s_mov_b32 m0, s42
	s_nop 0
	global_load_lds_dwordx4 v[146:147], off
	v_lshl_add_u64 v[146:147], v[224:225], 0, s[8:9]
	s_mov_b32 m0, s43
	s_nop 0
	global_load_lds_dwordx4 v[146:147], off
	s_waitcnt vmcnt(8)
	s_waitcnt lgkmcnt(0)
	s_setprio 1
	s_barrier
	v_mfma_f32_16x16x32_bf16 v[62:65], v[154:157], v[186:189], v[62:65]
	v_mfma_f32_16x16x32_bf16 v[58:61], v[162:165], v[186:189], v[58:61]
	v_mfma_f32_16x16x32_bf16 v[46:49], v[154:157], v[194:197], v[46:49]
	v_mfma_f32_16x16x32_bf16 v[42:45], v[162:165], v[194:197], v[42:45]
	v_mfma_f32_16x16x32_bf16 v[30:33], v[154:157], v[206:209], v[30:33]
	v_mfma_f32_16x16x32_bf16 v[26:29], v[162:165], v[206:209], v[26:29]
	v_mfma_f32_16x16x32_bf16 v[14:17], v[154:157], v[214:217], v[14:17]
	v_mfma_f32_16x16x32_bf16 v[10:13], v[162:165], v[214:217], v[10:13]
	v_mfma_f32_16x16x32_bf16 v[62:65], v[158:161], v[190:193], v[62:65]
	v_mfma_f32_16x16x32_bf16 v[58:61], v[166:169], v[190:193], v[58:61]
	v_mfma_f32_16x16x32_bf16 v[46:49], v[158:161], v[198:201], v[46:49]
	v_mfma_f32_16x16x32_bf16 v[42:45], v[166:169], v[198:201], v[42:45]
	v_mfma_f32_16x16x32_bf16 v[30:33], v[158:161], v[210:213], v[30:33]
	v_mfma_f32_16x16x32_bf16 v[26:29], v[166:169], v[210:213], v[26:29]
	v_mfma_f32_16x16x32_bf16 v[14:17], v[158:161], v[218:221], v[14:17]
	v_mfma_f32_16x16x32_bf16 v[10:13], v[166:169], v[218:221], v[10:13]
	v_mfma_f32_16x16x32_bf16 v[54:57], v[170:173], v[186:189], v[54:57]
	v_mfma_f32_16x16x32_bf16 v[50:53], v[178:181], v[186:189], v[50:53]
	v_mfma_f32_16x16x32_bf16 v[38:41], v[170:173], v[194:197], v[38:41]
	v_mfma_f32_16x16x32_bf16 v[34:37], v[178:181], v[194:197], v[34:37]
	v_mfma_f32_16x16x32_bf16 v[22:25], v[170:173], v[206:209], v[22:25]
	v_mfma_f32_16x16x32_bf16 v[18:21], v[178:181], v[206:209], v[18:21]
	v_mfma_f32_16x16x32_bf16 v[6:9], v[170:173], v[214:217], v[6:9]
	v_mfma_f32_16x16x32_bf16 v[2:5], v[178:181], v[214:217], v[2:5]
	v_mfma_f32_16x16x32_bf16 v[54:57], v[174:177], v[190:193], v[54:57]
	v_mfma_f32_16x16x32_bf16 v[50:53], v[182:185], v[190:193], v[50:53]
	v_mfma_f32_16x16x32_bf16 v[38:41], v[174:177], v[198:201], v[38:41]
	v_mfma_f32_16x16x32_bf16 v[34:37], v[182:185], v[198:201], v[34:37]
	v_mfma_f32_16x16x32_bf16 v[22:25], v[174:177], v[210:213], v[22:25]
	v_mfma_f32_16x16x32_bf16 v[18:21], v[182:185], v[210:213], v[18:21]
	v_mfma_f32_16x16x32_bf16 v[6:9], v[174:177], v[218:221], v[6:9]
	v_mfma_f32_16x16x32_bf16 v[2:5], v[182:185], v[218:221], v[2:5]
	s_setprio 0
	s_barrier
	s_add_i32 s62, s62, 2
	s_add_u32 s28, s28, 0x100
	s_addc_u32 s29, s29, 0
	s_add_u32 s50, s50, 0x100
	s_addc_u32 s51, s51, 0
	s_cmp_gt_u32 s62, 13
.LBB0_1619:
	ds_read_b128 v[154:157], v150
	ds_read_b128 v[158:161], v150 offset:1024
	ds_read_b128 v[162:165], v150 offset:2048
	ds_read_b128 v[166:169], v150 offset:3072
	ds_read_b128 v[170:173], v151
	ds_read_b128 v[174:177], v151 offset:1024
	ds_read_b128 v[178:181], v151 offset:2048
	ds_read_b128 v[182:185], v151 offset:3072
	ds_read_b128 v[186:189], v152
	ds_read_b128 v[190:193], v152 offset:1024
	ds_read_b128 v[194:197], v152 offset:2048
	ds_read_b128 v[198:201], v152 offset:3072
	ds_read_b128 v[206:209], v152 offset:4096
	ds_read_b128 v[210:213], v152 offset:5120
	ds_read_b128 v[214:217], v152 offset:6144
	ds_read_b128 v[218:221], v152 offset:7168
	s_add_u32 s30, s28, 0xfffc0080
	s_addc_u32 s31, s29, -1
	s_cmp_eq_u32 s62, 12
	s_cselect_b32 s37, s14, s31
	s_cselect_b32 s36, s15, s30
	s_cselect_b32 s31, s17, s51
	s_cselect_b32 s30, s49, s50
	s_add_i32 m0, s19, 0xc000
	v_lshl_add_u64 v[146:147], s[28:29], 0, v[138:139]
	global_load_lds_dwordx4 v[146:147], off
	v_lshl_add_u64 v[146:147], s[28:29], 0, v[140:141]
	s_add_i32 m0, s19, 0xe000
	s_nop 0
	global_load_lds_dwordx4 v[146:147], off
	s_waitcnt vmcnt(8)
	s_waitcnt lgkmcnt(0)
	s_setprio 1
	s_barrier
	v_mfma_f32_16x16x32_bf16 v[126:129], v[154:157], v[186:189], v[126:129]
	v_mfma_f32_16x16x32_bf16 v[122:125], v[162:165], v[186:189], v[122:125]
	v_mfma_f32_16x16x32_bf16 v[110:113], v[154:157], v[194:197], v[110:113]
	v_mfma_f32_16x16x32_bf16 v[106:109], v[162:165], v[194:197], v[106:109]
	v_mfma_f32_16x16x32_bf16 v[94:97], v[154:157], v[206:209], v[94:97]
	v_mfma_f32_16x16x32_bf16 v[90:93], v[162:165], v[206:209], v[90:93]
	v_mfma_f32_16x16x32_bf16 v[78:81], v[154:157], v[214:217], v[78:81]
	v_mfma_f32_16x16x32_bf16 v[74:77], v[162:165], v[214:217], v[74:77]
	v_mfma_f32_16x16x32_bf16 v[126:129], v[158:161], v[190:193], v[126:129]
	v_mfma_f32_16x16x32_bf16 v[122:125], v[166:169], v[190:193], v[122:125]
	v_mfma_f32_16x16x32_bf16 v[110:113], v[158:161], v[198:201], v[110:113]
	v_mfma_f32_16x16x32_bf16 v[106:109], v[166:169], v[198:201], v[106:109]
	v_mfma_f32_16x16x32_bf16 v[94:97], v[158:161], v[210:213], v[94:97]
	v_mfma_f32_16x16x32_bf16 v[90:93], v[166:169], v[210:213], v[90:93]
	v_mfma_f32_16x16x32_bf16 v[78:81], v[158:161], v[218:221], v[78:81]
	v_mfma_f32_16x16x32_bf16 v[74:77], v[166:169], v[218:221], v[74:77]
	v_mfma_f32_16x16x32_bf16 v[118:121], v[170:173], v[186:189], v[118:121]
	v_mfma_f32_16x16x32_bf16 v[114:117], v[178:181], v[186:189], v[114:117]
	v_mfma_f32_16x16x32_bf16 v[102:105], v[170:173], v[194:197], v[102:105]
	v_mfma_f32_16x16x32_bf16 v[98:101], v[178:181], v[194:197], v[98:101]
	v_mfma_f32_16x16x32_bf16 v[86:89], v[170:173], v[206:209], v[86:89]
	v_mfma_f32_16x16x32_bf16 v[82:85], v[178:181], v[206:209], v[82:85]
	v_mfma_f32_16x16x32_bf16 v[70:73], v[170:173], v[214:217], v[70:73]
	v_mfma_f32_16x16x32_bf16 v[66:69], v[178:181], v[214:217], v[66:69]
	v_mfma_f32_16x16x32_bf16 v[118:121], v[174:177], v[190:193], v[118:121]
	v_mfma_f32_16x16x32_bf16 v[114:117], v[182:185], v[190:193], v[114:117]
	v_mfma_f32_16x16x32_bf16 v[102:105], v[174:177], v[198:201], v[102:105]
	v_mfma_f32_16x16x32_bf16 v[98:101], v[182:185], v[198:201], v[98:101]
	v_mfma_f32_16x16x32_bf16 v[86:89], v[174:177], v[210:213], v[86:89]
	v_mfma_f32_16x16x32_bf16 v[82:85], v[182:185], v[210:213], v[82:85]
	v_mfma_f32_16x16x32_bf16 v[70:73], v[174:177], v[218:221], v[70:73]
	v_mfma_f32_16x16x32_bf16 v[66:69], v[182:185], v[218:221], v[66:69]
	s_setprio 0
	s_barrier
	s_add_i32 s63, s45, s12
	v_lshl_add_u64 v[146:147], s[30:31], 0, v[134:135]
	s_mov_b32 m0, s63
	ds_read_b128 v[186:189], v152 offset:16384
	ds_read_b128 v[190:193], v152 offset:17408
	ds_read_b128 v[194:197], v152 offset:18432
	ds_read_b128 v[198:201], v152 offset:19456
	ds_read_b128 v[206:209], v152 offset:20480
	ds_read_b128 v[210:213], v152 offset:21504
	ds_read_b128 v[214:217], v152 offset:22528
	ds_read_b128 v[218:221], v152 offset:23552
	global_load_lds_dwordx4 v[146:147], off
	s_add_i32 m0, s63, 0x2000
	s_add_u32 s64, s30, 0x40000
	v_lshl_add_u64 v[202:203], s[30:31], 0, v[130:131]
	s_addc_u32 s65, s31, 0
	s_add_i32 s63, s46, s12
	global_load_lds_dwordx4 v[202:203], off
	v_lshl_add_u64 v[222:223], s[64:65], 0, v[134:135]
	s_mov_b32 m0, s63
	v_lshl_add_u64 v[224:225], s[36:37], 0, v[132:133]
	global_load_lds_dwordx4 v[222:223], off
	v_lshl_add_u64 v[222:223], s[64:65], 0, v[130:131]
	s_add_i32 m0, s63, 0x2000
	s_nop 0
	global_load_lds_dwordx4 v[222:223], off
	v_lshl_add_u64 v[222:223], s[36:37], 0, v[136:137]
	s_mov_b32 m0, s19
	s_nop 0
	global_load_lds_dwordx4 v[222:223], off
	s_mov_b32 m0, s33
	s_nop 0
	global_load_lds_dwordx4 v[224:225], off
	s_waitcnt vmcnt(8)
	s_waitcnt lgkmcnt(0)
	s_setprio 1
	s_barrier
	v_mfma_f32_16x16x32_bf16 v[62:65], v[154:157], v[186:189], v[62:65]
	v_mfma_f32_16x16x32_bf16 v[58:61], v[162:165], v[186:189], v[58:61]
	v_mfma_f32_16x16x32_bf16 v[46:49], v[154:157], v[194:197], v[46:49]
	v_mfma_f32_16x16x32_bf16 v[42:45], v[162:165], v[194:197], v[42:45]
	v_mfma_f32_16x16x32_bf16 v[30:33], v[154:157], v[206:209], v[30:33]
	v_mfma_f32_16x16x32_bf16 v[26:29], v[162:165], v[206:209], v[26:29]
	v_mfma_f32_16x16x32_bf16 v[14:17], v[154:157], v[214:217], v[14:17]
	v_mfma_f32_16x16x32_bf16 v[10:13], v[162:165], v[214:217], v[10:13]
	v_mfma_f32_16x16x32_bf16 v[62:65], v[158:161], v[190:193], v[62:65]
	v_mfma_f32_16x16x32_bf16 v[58:61], v[166:169], v[190:193], v[58:61]
	v_mfma_f32_16x16x32_bf16 v[46:49], v[158:161], v[198:201], v[46:49]
	v_mfma_f32_16x16x32_bf16 v[42:45], v[166:169], v[198:201], v[42:45]
	v_mfma_f32_16x16x32_bf16 v[30:33], v[158:161], v[210:213], v[30:33]
	v_mfma_f32_16x16x32_bf16 v[26:29], v[166:169], v[210:213], v[26:29]
	v_mfma_f32_16x16x32_bf16 v[14:17], v[158:161], v[218:221], v[14:17]
	v_mfma_f32_16x16x32_bf16 v[10:13], v[166:169], v[218:221], v[10:13]
	v_mfma_f32_16x16x32_bf16 v[54:57], v[170:173], v[186:189], v[54:57]
	v_mfma_f32_16x16x32_bf16 v[50:53], v[178:181], v[186:189], v[50:53]
	v_mfma_f32_16x16x32_bf16 v[38:41], v[170:173], v[194:197], v[38:41]
	v_mfma_f32_16x16x32_bf16 v[34:37], v[178:181], v[194:197], v[34:37]
	v_mfma_f32_16x16x32_bf16 v[22:25], v[170:173], v[206:209], v[22:25]
	v_mfma_f32_16x16x32_bf16 v[18:21], v[178:181], v[206:209], v[18:21]
	v_mfma_f32_16x16x32_bf16 v[6:9], v[170:173], v[214:217], v[6:9]
	v_mfma_f32_16x16x32_bf16 v[2:5], v[178:181], v[214:217], v[2:5]
	v_mfma_f32_16x16x32_bf16 v[54:57], v[174:177], v[190:193], v[54:57]
	v_mfma_f32_16x16x32_bf16 v[50:53], v[182:185], v[190:193], v[50:53]
	v_mfma_f32_16x16x32_bf16 v[38:41], v[174:177], v[198:201], v[38:41]
	v_mfma_f32_16x16x32_bf16 v[34:37], v[182:185], v[198:201], v[34:37]
	v_mfma_f32_16x16x32_bf16 v[22:25], v[174:177], v[210:213], v[22:25]
	v_mfma_f32_16x16x32_bf16 v[18:21], v[182:185], v[210:213], v[18:21]
	v_mfma_f32_16x16x32_bf16 v[6:9], v[174:177], v[218:221], v[6:9]
	v_mfma_f32_16x16x32_bf16 v[2:5], v[182:185], v[218:221], v[2:5]
	s_setprio 0
	s_barrier
	s_add_i32 s63, 0, 0x18000
	v_add_u32_e32 v153, s63, v149
	s_add_i32 s64, 0, 0x1c000
	ds_read_b128 v[154:157], v153
	ds_read_b128 v[158:161], v153 offset:1024
	ds_read_b128 v[162:165], v153 offset:2048
	ds_read_b128 v[166:169], v153 offset:3072
	v_add_u32_e32 v153, s64, v149
	ds_read_b128 v[170:173], v153
	ds_read_b128 v[174:177], v153 offset:1024
	ds_read_b128 v[178:181], v153 offset:2048
	ds_read_b128 v[182:185], v153 offset:3072
	s_add_u32 s36, s36, 0x40000
	s_addc_u32 s37, s37, 0
	s_mov_b32 m0, s35
	v_lshl_add_u64 v[226:227], s[36:37], 0, v[136:137]
	ds_read_b128 v[186:189], v152 offset:32768
	ds_read_b128 v[190:193], v152 offset:33792
	ds_read_b128 v[194:197], v152 offset:34816
	ds_read_b128 v[198:201], v152 offset:35840
	ds_read_b128 v[206:209], v152 offset:36864
	ds_read_b128 v[210:213], v152 offset:37888
	ds_read_b128 v[214:217], v152 offset:38912
	ds_read_b128 v[218:221], v152 offset:39936
	global_load_lds_dwordx4 v[226:227], off
	v_lshl_add_u64 v[226:227], s[36:37], 0, v[132:133]
	s_mov_b32 m0, s38
	s_nop 0
	global_load_lds_dwordx4 v[226:227], off
	s_waitcnt vmcnt(8)
	s_waitcnt lgkmcnt(0)
	s_setprio 1
	s_barrier
	v_mfma_f32_16x16x32_bf16 v[126:129], v[154:157], v[186:189], v[126:129]
	v_mfma_f32_16x16x32_bf16 v[122:125], v[162:165], v[186:189], v[122:125]
	v_mfma_f32_16x16x32_bf16 v[110:113], v[154:157], v[194:197], v[110:113]
	v_mfma_f32_16x16x32_bf16 v[106:109], v[162:165], v[194:197], v[106:109]
	v_mfma_f32_16x16x32_bf16 v[94:97], v[154:157], v[206:209], v[94:97]
	v_mfma_f32_16x16x32_bf16 v[90:93], v[162:165], v[206:209], v[90:93]
	v_mfma_f32_16x16x32_bf16 v[78:81], v[154:157], v[214:217], v[78:81]
	v_mfma_f32_16x16x32_bf16 v[74:77], v[162:165], v[214:217], v[74:77]
	v_mfma_f32_16x16x32_bf16 v[126:129], v[158:161], v[190:193], v[126:129]
	v_mfma_f32_16x16x32_bf16 v[122:125], v[166:169], v[190:193], v[122:125]
	v_mfma_f32_16x16x32_bf16 v[110:113], v[158:161], v[198:201], v[110:113]
	v_mfma_f32_16x16x32_bf16 v[106:109], v[166:169], v[198:201], v[106:109]
	v_mfma_f32_16x16x32_bf16 v[94:97], v[158:161], v[210:213], v[94:97]
	v_mfma_f32_16x16x32_bf16 v[90:93], v[166:169], v[210:213], v[90:93]
	v_mfma_f32_16x16x32_bf16 v[78:81], v[158:161], v[218:221], v[78:81]
	v_mfma_f32_16x16x32_bf16 v[74:77], v[166:169], v[218:221], v[74:77]
	v_mfma_f32_16x16x32_bf16 v[118:121], v[170:173], v[186:189], v[118:121]
	v_mfma_f32_16x16x32_bf16 v[114:117], v[178:181], v[186:189], v[114:117]
	v_mfma_f32_16x16x32_bf16 v[102:105], v[170:173], v[194:197], v[102:105]
	v_mfma_f32_16x16x32_bf16 v[98:101], v[178:181], v[194:197], v[98:101]
	v_mfma_f32_16x16x32_bf16 v[86:89], v[170:173], v[206:209], v[86:89]
	v_mfma_f32_16x16x32_bf16 v[82:85], v[178:181], v[206:209], v[82:85]
	v_mfma_f32_16x16x32_bf16 v[70:73], v[170:173], v[214:217], v[70:73]
	v_mfma_f32_16x16x32_bf16 v[66:69], v[178:181], v[214:217], v[66:69]
	v_mfma_f32_16x16x32_bf16 v[118:121], v[174:177], v[190:193], v[118:121]
	v_mfma_f32_16x16x32_bf16 v[114:117], v[182:185], v[190:193], v[114:117]
	v_mfma_f32_16x16x32_bf16 v[102:105], v[174:177], v[198:201], v[102:105]
	v_mfma_f32_16x16x32_bf16 v[98:101], v[182:185], v[198:201], v[98:101]
	v_mfma_f32_16x16x32_bf16 v[86:89], v[174:177], v[210:213], v[86:89]
	v_mfma_f32_16x16x32_bf16 v[82:85], v[182:185], v[210:213], v[82:85]
	v_mfma_f32_16x16x32_bf16 v[70:73], v[174:177], v[218:221], v[70:73]
	v_mfma_f32_16x16x32_bf16 v[66:69], v[182:185], v[218:221], v[66:69]
	s_setprio 0
	s_barrier
	s_add_i32 s36, s63, s12
	v_lshl_add_u64 v[146:147], v[146:147], 0, s[8:9]
	s_mov_b32 m0, s36
	ds_read_b128 v[186:189], v152 offset:49152
	ds_read_b128 v[190:193], v152 offset:50176
	ds_read_b128 v[194:197], v152 offset:51200
	ds_read_b128 v[198:201], v152 offset:52224
	ds_read_b128 v[206:209], v152 offset:53248
	ds_read_b128 v[210:213], v152 offset:54272
	ds_read_b128 v[214:217], v152 offset:55296
	ds_read_b128 v[218:221], v152 offset:56320
	global_load_lds_dwordx4 v[146:147], off
	s_add_i32 m0, s36, 0x2000
	s_add_u32 s30, s30, 0x40080
	v_lshl_add_u64 v[146:147], v[202:203], 0, s[8:9]
	s_addc_u32 s31, s31, 0
	s_add_i32 s36, s64, s12
	global_load_lds_dwordx4 v[146:147], off
	v_lshl_add_u64 v[146:147], s[30:31], 0, v[134:135]
	s_mov_b32 m0, s36
	s_nop 0
	global_load_lds_dwordx4 v[146:147], off
	v_lshl_add_u64 v[146:147], s[30:31], 0, v[130:131]
	s_add_i32 m0, s36, 0x2000
	s_nop 0
	global_load_lds_dwordx4 v[146:147], off
	v_lshl_add_u64 v[146:147], v[222:223], 0, s[8:9]
	s_mov_b32 m0, s42
	s_nop 0
	global_load_lds_dwordx4 v[146:147], off
	v_lshl_add_u64 v[146:147], v[224:225], 0, s[8:9]
	s_mov_b32 m0, s43
	s_nop 0
	global_load_lds_dwordx4 v[146:147], off
	s_waitcnt vmcnt(8)
	s_waitcnt lgkmcnt(0)
	s_setprio 1
	s_barrier
	v_mfma_f32_16x16x32_bf16 v[62:65], v[154:157], v[186:189], v[62:65]
	v_mfma_f32_16x16x32_bf16 v[58:61], v[162:165], v[186:189], v[58:61]
	v_mfma_f32_16x16x32_bf16 v[46:49], v[154:157], v[194:197], v[46:49]
	v_mfma_f32_16x16x32_bf16 v[42:45], v[162:165], v[194:197], v[42:45]
	v_mfma_f32_16x16x32_bf16 v[30:33], v[154:157], v[206:209], v[30:33]
	v_mfma_f32_16x16x32_bf16 v[26:29], v[162:165], v[206:209], v[26:29]
	v_mfma_f32_16x16x32_bf16 v[14:17], v[154:157], v[214:217], v[14:17]
	v_mfma_f32_16x16x32_bf16 v[10:13], v[162:165], v[214:217], v[10:13]
	v_mfma_f32_16x16x32_bf16 v[62:65], v[158:161], v[190:193], v[62:65]
	v_mfma_f32_16x16x32_bf16 v[58:61], v[166:169], v[190:193], v[58:61]
	v_mfma_f32_16x16x32_bf16 v[46:49], v[158:161], v[198:201], v[46:49]
	v_mfma_f32_16x16x32_bf16 v[42:45], v[166:169], v[198:201], v[42:45]
	v_mfma_f32_16x16x32_bf16 v[30:33], v[158:161], v[210:213], v[30:33]
	v_mfma_f32_16x16x32_bf16 v[26:29], v[166:169], v[210:213], v[26:29]
	v_mfma_f32_16x16x32_bf16 v[14:17], v[158:161], v[218:221], v[14:17]
	v_mfma_f32_16x16x32_bf16 v[10:13], v[166:169], v[218:221], v[10:13]
	v_mfma_f32_16x16x32_bf16 v[54:57], v[170:173], v[186:189], v[54:57]
	v_mfma_f32_16x16x32_bf16 v[50:53], v[178:181], v[186:189], v[50:53]
	v_mfma_f32_16x16x32_bf16 v[38:41], v[170:173], v[194:197], v[38:41]
	v_mfma_f32_16x16x32_bf16 v[34:37], v[178:181], v[194:197], v[34:37]
	v_mfma_f32_16x16x32_bf16 v[22:25], v[170:173], v[206:209], v[22:25]
	v_mfma_f32_16x16x32_bf16 v[18:21], v[178:181], v[206:209], v[18:21]
	v_mfma_f32_16x16x32_bf16 v[6:9], v[170:173], v[214:217], v[6:9]
	v_mfma_f32_16x16x32_bf16 v[2:5], v[178:181], v[214:217], v[2:5]
	v_mfma_f32_16x16x32_bf16 v[54:57], v[174:177], v[190:193], v[54:57]
	v_mfma_f32_16x16x32_bf16 v[50:53], v[182:185], v[190:193], v[50:53]
	v_mfma_f32_16x16x32_bf16 v[38:41], v[174:177], v[198:201], v[38:41]
	v_mfma_f32_16x16x32_bf16 v[34:37], v[182:185], v[198:201], v[34:37]
	v_mfma_f32_16x16x32_bf16 v[22:25], v[174:177], v[210:213], v[22:25]
	v_mfma_f32_16x16x32_bf16 v[18:21], v[182:185], v[210:213], v[18:21]
	v_mfma_f32_16x16x32_bf16 v[6:9], v[174:177], v[218:221], v[6:9]
	v_mfma_f32_16x16x32_bf16 v[2:5], v[182:185], v[218:221], v[2:5]
	s_setprio 0
	s_barrier
	s_add_i32 s62, s62, 2
	s_add_u32 s28, s28, 0x100
	s_addc_u32 s29, s29, 0
	s_add_u32 s50, s50, 0x100
	s_addc_u32 s51, s51, 0
	s_cmp_gt_u32 s62, 13
	s_cbranch_scc0 .LBB0_1619
	s_and_b64 vcc, exec, s[10:11]
	s_cbranch_vccz .LBB0_1622
	s_barrier

.LBB0_1707:
	v_readlane_b32 s46, v249, 32
	v_readlane_b32 s47, v249, 33
	s_add_u32 s46, s46, s42
	s_addc_u32 s47, s47, s43
	s_and_b64 s[48:49], s[44:45], exec
	s_cselect_b32 s34, s47, s51
	s_cselect_b32 s66, s46, s50
	s_add_u32 s48, s35, s40
	s_addc_u32 s49, s70, s41
	s_and_b64 s[64:65], s[44:45], exec
	s_cselect_b32 s67, s49, s63
	s_cselect_b32 s68, s48, s62
	s_add_i32 s69, s7, -2
	s_add_u32 s50, s50, 0x100080
	s_addc_u32 s51, s51, 0
	s_add_u32 s91, s62, 0x100
	s_addc_u32 s92, s63, 0
	s_mov_b32 s62, 0
	s_waitcnt vmcnt(0)
	ds_read_b128 v[130:133], v168
	ds_read_b128 v[134:137], v168 offset:1024
	ds_read_b128 v[138:141], v168 offset:2048
	ds_read_b128 v[142:145], v168 offset:3072
	ds_read_b128 v[162:165], v169
	ds_read_b128 v[172:175], v169 offset:1024
	ds_read_b128 v[176:179], v169 offset:2048
	ds_read_b128 v[180:183], v169 offset:3072
	ds_read_b128 v[184:187], v170
	ds_read_b128 v[188:191], v170 offset:1024
	ds_read_b128 v[192:195], v170 offset:2048
	ds_read_b128 v[196:199], v170 offset:3072
	ds_read_b128 v[200:203], v170 offset:4096
	ds_read_b128 v[206:209], v170 offset:5120
	ds_read_b128 v[210:213], v170 offset:6144
	ds_read_b128 v[214:217], v170 offset:7168
	s_add_i32 s93, s62, 2
	s_add_u32 s63, s50, 0xfff00080
	s_addc_u32 s64, s51, -1
	s_cmp_eq_u32 s69, s62
	s_cselect_b32 s62, s68, s91
	s_cselect_b32 s65, s34, s64
	s_cselect_b32 s64, s66, s63
	s_cselect_b32 s63, s67, s92
	s_add_i32 m0, s12, 0xc000
	v_lshl_add_u64 v[218:219], s[50:51], 0, v[156:157]
	global_load_lds_dwordx4 v[218:219], off
	v_lshl_add_u64 v[218:219], s[50:51], 0, v[158:159]
	s_add_i32 m0, s12, 0xe000
	s_nop 0
	global_load_lds_dwordx4 v[218:219], off
	s_waitcnt vmcnt(8)
	s_waitcnt lgkmcnt(0)
	s_setprio 1
	s_barrier
	v_mfma_f32_16x16x32_bf16 v[126:129], v[130:133], v[184:187], 0
	v_mfma_f32_16x16x32_bf16 v[122:125], v[138:141], v[184:187], 0
	v_mfma_f32_16x16x32_bf16 v[110:113], v[130:133], v[192:195], 0
	v_mfma_f32_16x16x32_bf16 v[106:109], v[138:141], v[192:195], 0
	v_mfma_f32_16x16x32_bf16 v[98:101], v[130:133], v[200:203], 0
	v_mfma_f32_16x16x32_bf16 v[90:93], v[138:141], v[200:203], 0
	v_mfma_f32_16x16x32_bf16 v[82:85], v[130:133], v[210:213], 0
	v_mfma_f32_16x16x32_bf16 v[74:77], v[138:141], v[210:213], 0
	v_mfma_f32_16x16x32_bf16 v[126:129], v[134:137], v[188:191], v[126:129]
	v_mfma_f32_16x16x32_bf16 v[122:125], v[142:145], v[188:191], v[122:125]
	v_mfma_f32_16x16x32_bf16 v[110:113], v[134:137], v[196:199], v[110:113]
	v_mfma_f32_16x16x32_bf16 v[106:109], v[142:145], v[196:199], v[106:109]
	v_mfma_f32_16x16x32_bf16 v[98:101], v[134:137], v[206:209], v[98:101]
	v_mfma_f32_16x16x32_bf16 v[90:93], v[142:145], v[206:209], v[90:93]
	v_mfma_f32_16x16x32_bf16 v[82:85], v[134:137], v[214:217], v[82:85]
	v_mfma_f32_16x16x32_bf16 v[74:77], v[142:145], v[214:217], v[74:77]
	v_mfma_f32_16x16x32_bf16 v[118:121], v[162:165], v[184:187], 0
	v_mfma_f32_16x16x32_bf16 v[114:117], v[176:179], v[184:187], 0
	v_mfma_f32_16x16x32_bf16 v[102:105], v[162:165], v[192:195], 0
	v_mfma_f32_16x16x32_bf16 v[94:97], v[176:179], v[192:195], 0
	v_mfma_f32_16x16x32_bf16 v[86:89], v[162:165], v[200:203], 0
	v_mfma_f32_16x16x32_bf16 v[78:81], v[176:179], v[200:203], 0
	v_mfma_f32_16x16x32_bf16 v[70:73], v[162:165], v[210:213], 0
	v_mfma_f32_16x16x32_bf16 v[66:69], v[176:179], v[210:213], 0
	v_mfma_f32_16x16x32_bf16 v[118:121], v[172:175], v[188:191], v[118:121]
	v_mfma_f32_16x16x32_bf16 v[114:117], v[180:183], v[188:191], v[114:117]
	v_mfma_f32_16x16x32_bf16 v[102:105], v[172:175], v[196:199], v[102:105]
	v_mfma_f32_16x16x32_bf16 v[94:97], v[180:183], v[196:199], v[94:97]
	v_mfma_f32_16x16x32_bf16 v[86:89], v[172:175], v[206:209], v[86:89]
	v_mfma_f32_16x16x32_bf16 v[78:81], v[180:183], v[206:209], v[78:81]
	v_mfma_f32_16x16x32_bf16 v[70:73], v[172:175], v[214:217], v[70:73]
	v_mfma_f32_16x16x32_bf16 v[66:69], v[180:183], v[214:217], v[66:69]
	s_setprio 0
	s_barrier
	s_add_i32 s94, s31, s2
	v_lshl_add_u64 v[218:219], s[62:63], 0, v[148:149]
	s_mov_b32 m0, s94
	ds_read_b128 v[184:187], v170 offset:16384
	ds_read_b128 v[188:191], v170 offset:17408
	ds_read_b128 v[192:195], v170 offset:18432
	ds_read_b128 v[196:199], v170 offset:19456
	ds_read_b128 v[200:203], v170 offset:20480
	ds_read_b128 v[206:209], v170 offset:21504
	ds_read_b128 v[210:213], v170 offset:22528
	ds_read_b128 v[214:217], v170 offset:23552
	global_load_lds_dwordx4 v[218:219], off
	s_add_i32 m0, s94, 0x2000
	s_add_u32 s94, s62, 0x100000
	v_lshl_add_u64 v[220:221], s[62:63], 0, v[152:153]
	s_addc_u32 s95, s63, 0
	s_add_i32 s96, s82, s2
	global_load_lds_dwordx4 v[220:221], off
	v_lshl_add_u64 v[222:223], s[94:95], 0, v[148:149]
	s_mov_b32 m0, s96
	v_lshl_add_u64 v[224:225], s[64:65], 0, v[150:151]
	global_load_lds_dwordx4 v[222:223], off
	v_lshl_add_u64 v[222:223], s[94:95], 0, v[152:153]
	s_add_i32 m0, s96, 0x2000
	s_nop 0
	global_load_lds_dwordx4 v[222:223], off
	v_lshl_add_u64 v[222:223], s[64:65], 0, v[146:147]
	s_mov_b32 m0, s12
	s_nop 0
	global_load_lds_dwordx4 v[222:223], off
	s_mov_b32 m0, s13
	s_nop 0
	global_load_lds_dwordx4 v[224:225], off
	s_waitcnt vmcnt(8)
	s_waitcnt lgkmcnt(0)
	s_setprio 1
	s_barrier
	v_mfma_f32_16x16x32_bf16 v[62:65], v[130:133], v[184:187], 0
	v_mfma_f32_16x16x32_bf16 v[58:61], v[138:141], v[184:187], 0
	v_mfma_f32_16x16x32_bf16 v[50:53], v[130:133], v[192:195], 0
	v_mfma_f32_16x16x32_bf16 v[42:45], v[138:141], v[192:195], 0
	v_mfma_f32_16x16x32_bf16 v[34:37], v[130:133], v[200:203], 0
	v_mfma_f32_16x16x32_bf16 v[26:29], v[138:141], v[200:203], 0
	v_mfma_f32_16x16x32_bf16 v[18:21], v[130:133], v[210:213], 0
	v_mfma_f32_16x16x32_bf16 v[10:13], v[138:141], v[210:213], 0
	v_mfma_f32_16x16x32_bf16 v[62:65], v[134:137], v[188:191], v[62:65]
	v_mfma_f32_16x16x32_bf16 v[58:61], v[142:145], v[188:191], v[58:61]
	v_mfma_f32_16x16x32_bf16 v[50:53], v[134:137], v[196:199], v[50:53]
	v_mfma_f32_16x16x32_bf16 v[42:45], v[142:145], v[196:199], v[42:45]
	v_mfma_f32_16x16x32_bf16 v[34:37], v[134:137], v[206:209], v[34:37]
	v_mfma_f32_16x16x32_bf16 v[26:29], v[142:145], v[206:209], v[26:29]
	v_mfma_f32_16x16x32_bf16 v[18:21], v[134:137], v[214:217], v[18:21]
	v_mfma_f32_16x16x32_bf16 v[10:13], v[142:145], v[214:217], v[10:13]
	v_mfma_f32_16x16x32_bf16 v[54:57], v[162:165], v[184:187], 0
	v_mfma_f32_16x16x32_bf16 v[46:49], v[176:179], v[184:187], 0
	v_mfma_f32_16x16x32_bf16 v[38:41], v[162:165], v[192:195], 0
	v_mfma_f32_16x16x32_bf16 v[30:33], v[176:179], v[192:195], 0
	v_mfma_f32_16x16x32_bf16 v[22:25], v[162:165], v[200:203], 0
	v_mfma_f32_16x16x32_bf16 v[14:17], v[176:179], v[200:203], 0
	v_mfma_f32_16x16x32_bf16 v[6:9], v[162:165], v[210:213], 0
	v_mfma_f32_16x16x32_bf16 v[2:5], v[176:179], v[210:213], 0
	v_mfma_f32_16x16x32_bf16 v[54:57], v[172:175], v[188:191], v[54:57]
	v_mfma_f32_16x16x32_bf16 v[46:49], v[180:183], v[188:191], v[46:49]
	v_mfma_f32_16x16x32_bf16 v[38:41], v[172:175], v[196:199], v[38:41]
	v_mfma_f32_16x16x32_bf16 v[30:33], v[180:183], v[196:199], v[30:33]
	v_mfma_f32_16x16x32_bf16 v[22:25], v[172:175], v[206:209], v[22:25]
	v_mfma_f32_16x16x32_bf16 v[14:17], v[180:183], v[206:209], v[14:17]
	v_mfma_f32_16x16x32_bf16 v[6:9], v[172:175], v[214:217], v[6:9]
	v_mfma_f32_16x16x32_bf16 v[2:5], v[180:183], v[214:217], v[2:5]
	s_setprio 0
	s_barrier
	s_add_i32 s94, 0, 0x18000
	s_add_i32 s95, 0, 0x1c000
	v_add_u32_e32 v142, s94, v167
	v_add_u32_e32 v154, s95, v167
	ds_read_b128 v[130:133], v142
	ds_read_b128 v[134:137], v142 offset:1024
	ds_read_b128 v[138:141], v142 offset:2048
	ds_read_b128 v[142:145], v142 offset:3072
	ds_read_b128 v[162:165], v154
	ds_read_b128 v[172:175], v154 offset:1024
	ds_read_b128 v[176:179], v154 offset:2048
	ds_read_b128 v[180:183], v154 offset:3072
	s_add_u32 s64, s64, 0x100000
	s_addc_u32 s65, s65, 0
	s_mov_b32 m0, s18
	v_lshl_add_u64 v[226:227], s[64:65], 0, v[146:147]
	ds_read_b128 v[184:187], v170 offset:32768
	ds_read_b128 v[188:191], v170 offset:33792
	ds_read_b128 v[192:195], v170 offset:34816
	ds_read_b128 v[196:199], v170 offset:35840
	ds_read_b128 v[200:203], v170 offset:36864
	ds_read_b128 v[206:209], v170 offset:37888
	ds_read_b128 v[210:213], v170 offset:38912
	ds_read_b128 v[214:217], v170 offset:39936
	global_load_lds_dwordx4 v[226:227], off
	v_lshl_add_u64 v[226:227], s[64:65], 0, v[150:151]
	s_mov_b32 m0, s19
	s_nop 0
	global_load_lds_dwordx4 v[226:227], off
	s_waitcnt vmcnt(8)
	s_waitcnt lgkmcnt(0)
	s_setprio 1
	s_barrier
	v_mfma_f32_16x16x32_bf16 v[126:129], v[130:133], v[184:187], v[126:129]
	v_mfma_f32_16x16x32_bf16 v[122:125], v[138:141], v[184:187], v[122:125]
	v_mfma_f32_16x16x32_bf16 v[110:113], v[130:133], v[192:195], v[110:113]
	v_mfma_f32_16x16x32_bf16 v[106:109], v[138:141], v[192:195], v[106:109]
	v_mfma_f32_16x16x32_bf16 v[98:101], v[130:133], v[200:203], v[98:101]
	v_mfma_f32_16x16x32_bf16 v[90:93], v[138:141], v[200:203], v[90:93]
	v_mfma_f32_16x16x32_bf16 v[82:85], v[130:133], v[210:213], v[82:85]
	v_mfma_f32_16x16x32_bf16 v[74:77], v[138:141], v[210:213], v[74:77]
	v_mfma_f32_16x16x32_bf16 v[126:129], v[134:137], v[188:191], v[126:129]
	v_mfma_f32_16x16x32_bf16 v[122:125], v[142:145], v[188:191], v[122:125]
	v_mfma_f32_16x16x32_bf16 v[110:113], v[134:137], v[196:199], v[110:113]
	v_mfma_f32_16x16x32_bf16 v[106:109], v[142:145], v[196:199], v[106:109]
	v_mfma_f32_16x16x32_bf16 v[98:101], v[134:137], v[206:209], v[98:101]
	v_mfma_f32_16x16x32_bf16 v[90:93], v[142:145], v[206:209], v[90:93]
	v_mfma_f32_16x16x32_bf16 v[82:85], v[134:137], v[214:217], v[82:85]
	v_mfma_f32_16x16x32_bf16 v[74:77], v[142:145], v[214:217], v[74:77]
	v_mfma_f32_16x16x32_bf16 v[118:121], v[162:165], v[184:187], v[118:121]
	v_mfma_f32_16x16x32_bf16 v[114:117], v[176:179], v[184:187], v[114:117]
	v_mfma_f32_16x16x32_bf16 v[102:105], v[162:165], v[192:195], v[102:105]
	v_mfma_f32_16x16x32_bf16 v[94:97], v[176:179], v[192:195], v[94:97]
	v_mfma_f32_16x16x32_bf16 v[86:89], v[162:165], v[200:203], v[86:89]
	v_mfma_f32_16x16x32_bf16 v[78:81], v[176:179], v[200:203], v[78:81]
	v_mfma_f32_16x16x32_bf16 v[70:73], v[162:165], v[210:213], v[70:73]
	v_mfma_f32_16x16x32_bf16 v[66:69], v[176:179], v[210:213], v[66:69]
	v_mfma_f32_16x16x32_bf16 v[118:121], v[172:175], v[188:191], v[118:121]
	v_mfma_f32_16x16x32_bf16 v[114:117], v[180:183], v[188:191], v[114:117]
	v_mfma_f32_16x16x32_bf16 v[102:105], v[172:175], v[196:199], v[102:105]
	v_mfma_f32_16x16x32_bf16 v[94:97], v[180:183], v[196:199], v[94:97]
	v_mfma_f32_16x16x32_bf16 v[86:89], v[172:175], v[206:209], v[86:89]
	v_mfma_f32_16x16x32_bf16 v[78:81], v[180:183], v[206:209], v[78:81]
	v_mfma_f32_16x16x32_bf16 v[70:73], v[172:175], v[214:217], v[70:73]
	v_mfma_f32_16x16x32_bf16 v[66:69], v[180:183], v[214:217], v[66:69]
	s_setprio 0
	s_barrier
	s_add_i32 s64, s94, s2
	v_lshl_add_u64 v[218:219], v[218:219], 0, s[16:17]
	s_mov_b32 m0, s64
	ds_read_b128 v[184:187], v170 offset:49152
	ds_read_b128 v[188:191], v170 offset:50176
	ds_read_b128 v[192:195], v170 offset:51200
	ds_read_b128 v[196:199], v170 offset:52224
	ds_read_b128 v[200:203], v170 offset:53248
	ds_read_b128 v[206:209], v170 offset:54272
	ds_read_b128 v[210:213], v170 offset:55296
	ds_read_b128 v[214:217], v170 offset:56320
	global_load_lds_dwordx4 v[218:219], off
	s_add_i32 m0, s64, 0x2000
	s_add_u32 s62, s62, 0x100080
	v_lshl_add_u64 v[218:219], v[220:221], 0, s[16:17]
	s_addc_u32 s63, s63, 0
	s_add_i32 s64, s95, s2
	global_load_lds_dwordx4 v[218:219], off
	v_lshl_add_u64 v[218:219], s[62:63], 0, v[148:149]
	s_mov_b32 m0, s64
	s_nop 0
	global_load_lds_dwordx4 v[218:219], off
	v_lshl_add_u64 v[218:219], s[62:63], 0, v[152:153]
	s_add_i32 m0, s64, 0x2000
	s_nop 0
	global_load_lds_dwordx4 v[218:219], off
	v_lshl_add_u64 v[218:219], v[222:223], 0, s[16:17]
	s_mov_b32 m0, s74
	s_nop 0
	global_load_lds_dwordx4 v[218:219], off
	v_lshl_add_u64 v[218:219], v[224:225], 0, s[16:17]
	s_mov_b32 m0, s75
	s_nop 0
	global_load_lds_dwordx4 v[218:219], off
	s_waitcnt vmcnt(8)
	s_waitcnt lgkmcnt(0)
	s_setprio 1
	s_barrier
	v_mfma_f32_16x16x32_bf16 v[62:65], v[130:133], v[184:187], v[62:65]
	v_mfma_f32_16x16x32_bf16 v[58:61], v[138:141], v[184:187], v[58:61]
	v_mfma_f32_16x16x32_bf16 v[50:53], v[130:133], v[192:195], v[50:53]
	v_mfma_f32_16x16x32_bf16 v[42:45], v[138:141], v[192:195], v[42:45]
	v_mfma_f32_16x16x32_bf16 v[34:37], v[130:133], v[200:203], v[34:37]
	v_mfma_f32_16x16x32_bf16 v[26:29], v[138:141], v[200:203], v[26:29]
	v_mfma_f32_16x16x32_bf16 v[18:21], v[130:133], v[210:213], v[18:21]
	v_mfma_f32_16x16x32_bf16 v[10:13], v[138:141], v[210:213], v[10:13]
	v_mfma_f32_16x16x32_bf16 v[62:65], v[134:137], v[188:191], v[62:65]
	v_mfma_f32_16x16x32_bf16 v[58:61], v[142:145], v[188:191], v[58:61]
	v_mfma_f32_16x16x32_bf16 v[50:53], v[134:137], v[196:199], v[50:53]
	v_mfma_f32_16x16x32_bf16 v[42:45], v[142:145], v[196:199], v[42:45]
	v_mfma_f32_16x16x32_bf16 v[34:37], v[134:137], v[206:209], v[34:37]
	v_mfma_f32_16x16x32_bf16 v[26:29], v[142:145], v[206:209], v[26:29]
	v_mfma_f32_16x16x32_bf16 v[18:21], v[134:137], v[214:217], v[18:21]
	v_mfma_f32_16x16x32_bf16 v[10:13], v[142:145], v[214:217], v[10:13]
	v_mfma_f32_16x16x32_bf16 v[54:57], v[162:165], v[184:187], v[54:57]
	v_mfma_f32_16x16x32_bf16 v[46:49], v[176:179], v[184:187], v[46:49]
	v_mfma_f32_16x16x32_bf16 v[38:41], v[162:165], v[192:195], v[38:41]
	v_mfma_f32_16x16x32_bf16 v[30:33], v[176:179], v[192:195], v[30:33]
	v_mfma_f32_16x16x32_bf16 v[22:25], v[162:165], v[200:203], v[22:25]
	v_mfma_f32_16x16x32_bf16 v[14:17], v[176:179], v[200:203], v[14:17]
	v_mfma_f32_16x16x32_bf16 v[6:9], v[162:165], v[210:213], v[6:9]
	v_mfma_f32_16x16x32_bf16 v[2:5], v[176:179], v[210:213], v[2:5]
	v_mfma_f32_16x16x32_bf16 v[54:57], v[172:175], v[188:191], v[54:57]
	v_mfma_f32_16x16x32_bf16 v[46:49], v[180:183], v[188:191], v[46:49]
	v_mfma_f32_16x16x32_bf16 v[38:41], v[172:175], v[196:199], v[38:41]
	v_mfma_f32_16x16x32_bf16 v[30:33], v[180:183], v[196:199], v[30:33]
	v_mfma_f32_16x16x32_bf16 v[22:25], v[172:175], v[206:209], v[22:25]
	v_mfma_f32_16x16x32_bf16 v[14:17], v[180:183], v[206:209], v[14:17]
	v_mfma_f32_16x16x32_bf16 v[6:9], v[172:175], v[214:217], v[6:9]
	v_mfma_f32_16x16x32_bf16 v[2:5], v[180:183], v[214:217], v[2:5]
	s_setprio 0
	s_barrier
	s_add_u32 s50, s50, 0x100
	s_addc_u32 s51, s51, 0
	s_add_u32 s91, s91, 0x100
	s_addc_u32 s92, s92, 0
	s_cmp_ge_i32 s93, s7
	s_mov_b32 s62, s93
.LBB0_1708:
	ds_read_b128 v[130:133], v168
	ds_read_b128 v[134:137], v168 offset:1024
	ds_read_b128 v[138:141], v168 offset:2048
	ds_read_b128 v[142:145], v168 offset:3072
	ds_read_b128 v[162:165], v169
	ds_read_b128 v[172:175], v169 offset:1024
	ds_read_b128 v[176:179], v169 offset:2048
	ds_read_b128 v[180:183], v169 offset:3072
	ds_read_b128 v[184:187], v170
	ds_read_b128 v[188:191], v170 offset:1024
	ds_read_b128 v[192:195], v170 offset:2048
	ds_read_b128 v[196:199], v170 offset:3072
	ds_read_b128 v[200:203], v170 offset:4096
	ds_read_b128 v[206:209], v170 offset:5120
	ds_read_b128 v[210:213], v170 offset:6144
	ds_read_b128 v[214:217], v170 offset:7168
	s_add_i32 s93, s62, 2
	s_add_u32 s63, s50, 0xfff00080
	s_addc_u32 s64, s51, -1
	s_cmp_eq_u32 s69, s62
	s_cselect_b32 s62, s68, s91
	s_cselect_b32 s65, s34, s64
	s_cselect_b32 s64, s66, s63
	s_cselect_b32 s63, s67, s92
	s_add_i32 m0, s12, 0xc000
	v_lshl_add_u64 v[218:219], s[50:51], 0, v[156:157]
	global_load_lds_dwordx4 v[218:219], off
	v_lshl_add_u64 v[218:219], s[50:51], 0, v[158:159]
	s_add_i32 m0, s12, 0xe000
	s_nop 0
	global_load_lds_dwordx4 v[218:219], off
	s_waitcnt vmcnt(8)
	s_waitcnt lgkmcnt(0)
	s_setprio 1
	s_barrier
	v_mfma_f32_16x16x32_bf16 v[126:129], v[130:133], v[184:187], v[126:129]
	v_mfma_f32_16x16x32_bf16 v[122:125], v[138:141], v[184:187], v[122:125]
	v_mfma_f32_16x16x32_bf16 v[110:113], v[130:133], v[192:195], v[110:113]
	v_mfma_f32_16x16x32_bf16 v[106:109], v[138:141], v[192:195], v[106:109]
	v_mfma_f32_16x16x32_bf16 v[98:101], v[130:133], v[200:203], v[98:101]
	v_mfma_f32_16x16x32_bf16 v[90:93], v[138:141], v[200:203], v[90:93]
	v_mfma_f32_16x16x32_bf16 v[82:85], v[130:133], v[210:213], v[82:85]
	v_mfma_f32_16x16x32_bf16 v[74:77], v[138:141], v[210:213], v[74:77]
	v_mfma_f32_16x16x32_bf16 v[126:129], v[134:137], v[188:191], v[126:129]
	v_mfma_f32_16x16x32_bf16 v[122:125], v[142:145], v[188:191], v[122:125]
	v_mfma_f32_16x16x32_bf16 v[110:113], v[134:137], v[196:199], v[110:113]
	v_mfma_f32_16x16x32_bf16 v[106:109], v[142:145], v[196:199], v[106:109]
	v_mfma_f32_16x16x32_bf16 v[98:101], v[134:137], v[206:209], v[98:101]
	v_mfma_f32_16x16x32_bf16 v[90:93], v[142:145], v[206:209], v[90:93]
	v_mfma_f32_16x16x32_bf16 v[82:85], v[134:137], v[214:217], v[82:85]
	v_mfma_f32_16x16x32_bf16 v[74:77], v[142:145], v[214:217], v[74:77]
	v_mfma_f32_16x16x32_bf16 v[118:121], v[162:165], v[184:187], v[118:121]
	v_mfma_f32_16x16x32_bf16 v[114:117], v[176:179], v[184:187], v[114:117]
	v_mfma_f32_16x16x32_bf16 v[102:105], v[162:165], v[192:195], v[102:105]
	v_mfma_f32_16x16x32_bf16 v[94:97], v[176:179], v[192:195], v[94:97]
	v_mfma_f32_16x16x32_bf16 v[86:89], v[162:165], v[200:203], v[86:89]
	v_mfma_f32_16x16x32_bf16 v[78:81], v[176:179], v[200:203], v[78:81]
	v_mfma_f32_16x16x32_bf16 v[70:73], v[162:165], v[210:213], v[70:73]
	v_mfma_f32_16x16x32_bf16 v[66:69], v[176:179], v[210:213], v[66:69]
	v_mfma_f32_16x16x32_bf16 v[118:121], v[172:175], v[188:191], v[118:121]
	v_mfma_f32_16x16x32_bf16 v[114:117], v[180:183], v[188:191], v[114:117]
	v_mfma_f32_16x16x32_bf16 v[102:105], v[172:175], v[196:199], v[102:105]
	v_mfma_f32_16x16x32_bf16 v[94:97], v[180:183], v[196:199], v[94:97]
	v_mfma_f32_16x16x32_bf16 v[86:89], v[172:175], v[206:209], v[86:89]
	v_mfma_f32_16x16x32_bf16 v[78:81], v[180:183], v[206:209], v[78:81]
	v_mfma_f32_16x16x32_bf16 v[70:73], v[172:175], v[214:217], v[70:73]
	v_mfma_f32_16x16x32_bf16 v[66:69], v[180:183], v[214:217], v[66:69]
	s_setprio 0
	s_barrier
	s_add_i32 s94, s31, s2
	v_lshl_add_u64 v[218:219], s[62:63], 0, v[148:149]
	s_mov_b32 m0, s94
	ds_read_b128 v[184:187], v170 offset:16384
	ds_read_b128 v[188:191], v170 offset:17408
	ds_read_b128 v[192:195], v170 offset:18432
	ds_read_b128 v[196:199], v170 offset:19456
	ds_read_b128 v[200:203], v170 offset:20480
	ds_read_b128 v[206:209], v170 offset:21504
	ds_read_b128 v[210:213], v170 offset:22528
	ds_read_b128 v[214:217], v170 offset:23552
	global_load_lds_dwordx4 v[218:219], off
	s_add_i32 m0, s94, 0x2000
	s_add_u32 s94, s62, 0x100000
	v_lshl_add_u64 v[220:221], s[62:63], 0, v[152:153]
	s_addc_u32 s95, s63, 0
	s_add_i32 s96, s82, s2
	global_load_lds_dwordx4 v[220:221], off
	v_lshl_add_u64 v[222:223], s[94:95], 0, v[148:149]
	s_mov_b32 m0, s96
	v_lshl_add_u64 v[224:225], s[64:65], 0, v[150:151]
	global_load_lds_dwordx4 v[222:223], off
	v_lshl_add_u64 v[222:223], s[94:95], 0, v[152:153]
	s_add_i32 m0, s96, 0x2000
	s_nop 0
	global_load_lds_dwordx4 v[222:223], off
	v_lshl_add_u64 v[222:223], s[64:65], 0, v[146:147]
	s_mov_b32 m0, s12
	s_nop 0
	global_load_lds_dwordx4 v[222:223], off
	s_mov_b32 m0, s13
	s_nop 0
	global_load_lds_dwordx4 v[224:225], off
	s_waitcnt vmcnt(8)
	s_waitcnt lgkmcnt(0)
	s_setprio 1
	s_barrier
	v_mfma_f32_16x16x32_bf16 v[62:65], v[130:133], v[184:187], v[62:65]
	v_mfma_f32_16x16x32_bf16 v[58:61], v[138:141], v[184:187], v[58:61]
	v_mfma_f32_16x16x32_bf16 v[50:53], v[130:133], v[192:195], v[50:53]
	v_mfma_f32_16x16x32_bf16 v[42:45], v[138:141], v[192:195], v[42:45]
	v_mfma_f32_16x16x32_bf16 v[34:37], v[130:133], v[200:203], v[34:37]
	v_mfma_f32_16x16x32_bf16 v[26:29], v[138:141], v[200:203], v[26:29]
	v_mfma_f32_16x16x32_bf16 v[18:21], v[130:133], v[210:213], v[18:21]
	v_mfma_f32_16x16x32_bf16 v[10:13], v[138:141], v[210:213], v[10:13]
	v_mfma_f32_16x16x32_bf16 v[62:65], v[134:137], v[188:191], v[62:65]
	v_mfma_f32_16x16x32_bf16 v[58:61], v[142:145], v[188:191], v[58:61]
	v_mfma_f32_16x16x32_bf16 v[50:53], v[134:137], v[196:199], v[50:53]
	v_mfma_f32_16x16x32_bf16 v[42:45], v[142:145], v[196:199], v[42:45]
	v_mfma_f32_16x16x32_bf16 v[34:37], v[134:137], v[206:209], v[34:37]
	v_mfma_f32_16x16x32_bf16 v[26:29], v[142:145], v[206:209], v[26:29]
	v_mfma_f32_16x16x32_bf16 v[18:21], v[134:137], v[214:217], v[18:21]
	v_mfma_f32_16x16x32_bf16 v[10:13], v[142:145], v[214:217], v[10:13]
	v_mfma_f32_16x16x32_bf16 v[54:57], v[162:165], v[184:187], v[54:57]
	v_mfma_f32_16x16x32_bf16 v[46:49], v[176:179], v[184:187], v[46:49]
	v_mfma_f32_16x16x32_bf16 v[38:41], v[162:165], v[192:195], v[38:41]
	v_mfma_f32_16x16x32_bf16 v[30:33], v[176:179], v[192:195], v[30:33]
	v_mfma_f32_16x16x32_bf16 v[22:25], v[162:165], v[200:203], v[22:25]
	v_mfma_f32_16x16x32_bf16 v[14:17], v[176:179], v[200:203], v[14:17]
	v_mfma_f32_16x16x32_bf16 v[6:9], v[162:165], v[210:213], v[6:9]
	v_mfma_f32_16x16x32_bf16 v[2:5], v[176:179], v[210:213], v[2:5]
	v_mfma_f32_16x16x32_bf16 v[54:57], v[172:175], v[188:191], v[54:57]
	v_mfma_f32_16x16x32_bf16 v[46:49], v[180:183], v[188:191], v[46:49]
	v_mfma_f32_16x16x32_bf16 v[38:41], v[172:175], v[196:199], v[38:41]
	v_mfma_f32_16x16x32_bf16 v[30:33], v[180:183], v[196:199], v[30:33]
	v_mfma_f32_16x16x32_bf16 v[22:25], v[172:175], v[206:209], v[22:25]
	v_mfma_f32_16x16x32_bf16 v[14:17], v[180:183], v[206:209], v[14:17]
	v_mfma_f32_16x16x32_bf16 v[6:9], v[172:175], v[214:217], v[6:9]
	v_mfma_f32_16x16x32_bf16 v[2:5], v[180:183], v[214:217], v[2:5]
	s_setprio 0
	s_barrier
	s_add_i32 s94, 0, 0x18000
	s_add_i32 s95, 0, 0x1c000
	v_add_u32_e32 v142, s94, v167
	v_add_u32_e32 v154, s95, v167
	ds_read_b128 v[130:133], v142
	ds_read_b128 v[134:137], v142 offset:1024
	ds_read_b128 v[138:141], v142 offset:2048
	ds_read_b128 v[142:145], v142 offset:3072
	ds_read_b128 v[162:165], v154
	ds_read_b128 v[172:175], v154 offset:1024
	ds_read_b128 v[176:179], v154 offset:2048
	ds_read_b128 v[180:183], v154 offset:3072
	s_add_u32 s64, s64, 0x100000
	s_addc_u32 s65, s65, 0
	s_mov_b32 m0, s18
	v_lshl_add_u64 v[226:227], s[64:65], 0, v[146:147]
	ds_read_b128 v[184:187], v170 offset:32768
	ds_read_b128 v[188:191], v170 offset:33792
	ds_read_b128 v[192:195], v170 offset:34816
	ds_read_b128 v[196:199], v170 offset:35840
	ds_read_b128 v[200:203], v170 offset:36864
	ds_read_b128 v[206:209], v170 offset:37888
	ds_read_b128 v[210:213], v170 offset:38912
	ds_read_b128 v[214:217], v170 offset:39936
	global_load_lds_dwordx4 v[226:227], off
	v_lshl_add_u64 v[226:227], s[64:65], 0, v[150:151]
	s_mov_b32 m0, s19
	s_nop 0
	global_load_lds_dwordx4 v[226:227], off
	s_waitcnt vmcnt(8)
	s_waitcnt lgkmcnt(0)
	s_setprio 1
	s_barrier
	v_mfma_f32_16x16x32_bf16 v[126:129], v[130:133], v[184:187], v[126:129]
	v_mfma_f32_16x16x32_bf16 v[122:125], v[138:141], v[184:187], v[122:125]
	v_mfma_f32_16x16x32_bf16 v[110:113], v[130:133], v[192:195], v[110:113]
	v_mfma_f32_16x16x32_bf16 v[106:109], v[138:141], v[192:195], v[106:109]
	v_mfma_f32_16x16x32_bf16 v[98:101], v[130:133], v[200:203], v[98:101]
	v_mfma_f32_16x16x32_bf16 v[90:93], v[138:141], v[200:203], v[90:93]
	v_mfma_f32_16x16x32_bf16 v[82:85], v[130:133], v[210:213], v[82:85]
	v_mfma_f32_16x16x32_bf16 v[74:77], v[138:141], v[210:213], v[74:77]
	v_mfma_f32_16x16x32_bf16 v[126:129], v[134:137], v[188:191], v[126:129]
	v_mfma_f32_16x16x32_bf16 v[122:125], v[142:145], v[188:191], v[122:125]
	v_mfma_f32_16x16x32_bf16 v[110:113], v[134:137], v[196:199], v[110:113]
	v_mfma_f32_16x16x32_bf16 v[106:109], v[142:145], v[196:199], v[106:109]
	v_mfma_f32_16x16x32_bf16 v[98:101], v[134:137], v[206:209], v[98:101]
	v_mfma_f32_16x16x32_bf16 v[90:93], v[142:145], v[206:209], v[90:93]
	v_mfma_f32_16x16x32_bf16 v[82:85], v[134:137], v[214:217], v[82:85]
	v_mfma_f32_16x16x32_bf16 v[74:77], v[142:145], v[214:217], v[74:77]
	v_mfma_f32_16x16x32_bf16 v[118:121], v[162:165], v[184:187], v[118:121]
	v_mfma_f32_16x16x32_bf16 v[114:117], v[176:179], v[184:187], v[114:117]
	v_mfma_f32_16x16x32_bf16 v[102:105], v[162:165], v[192:195], v[102:105]
	v_mfma_f32_16x16x32_bf16 v[94:97], v[176:179], v[192:195], v[94:97]
	v_mfma_f32_16x16x32_bf16 v[86:89], v[162:165], v[200:203], v[86:89]
	v_mfma_f32_16x16x32_bf16 v[78:81], v[176:179], v[200:203], v[78:81]
	v_mfma_f32_16x16x32_bf16 v[70:73], v[162:165], v[210:213], v[70:73]
	v_mfma_f32_16x16x32_bf16 v[66:69], v[176:179], v[210:213], v[66:69]
	v_mfma_f32_16x16x32_bf16 v[118:121], v[172:175], v[188:191], v[118:121]
	v_mfma_f32_16x16x32_bf16 v[114:117], v[180:183], v[188:191], v[114:117]
	v_mfma_f32_16x16x32_bf16 v[102:105], v[172:175], v[196:199], v[102:105]
	v_mfma_f32_16x16x32_bf16 v[94:97], v[180:183], v[196:199], v[94:97]
	v_mfma_f32_16x16x32_bf16 v[86:89], v[172:175], v[206:209], v[86:89]
	v_mfma_f32_16x16x32_bf16 v[78:81], v[180:183], v[206:209], v[78:81]
	v_mfma_f32_16x16x32_bf16 v[70:73], v[172:175], v[214:217], v[70:73]
	v_mfma_f32_16x16x32_bf16 v[66:69], v[180:183], v[214:217], v[66:69]
	s_setprio 0
	s_barrier
	s_add_i32 s64, s94, s2
	v_lshl_add_u64 v[218:219], v[218:219], 0, s[16:17]
	s_mov_b32 m0, s64
	ds_read_b128 v[184:187], v170 offset:49152
	ds_read_b128 v[188:191], v170 offset:50176
	ds_read_b128 v[192:195], v170 offset:51200
	ds_read_b128 v[196:199], v170 offset:52224
	ds_read_b128 v[200:203], v170 offset:53248
	ds_read_b128 v[206:209], v170 offset:54272
	ds_read_b128 v[210:213], v170 offset:55296
	ds_read_b128 v[214:217], v170 offset:56320
	global_load_lds_dwordx4 v[218:219], off
	s_add_i32 m0, s64, 0x2000
	s_add_u32 s62, s62, 0x100080
	v_lshl_add_u64 v[218:219], v[220:221], 0, s[16:17]
	s_addc_u32 s63, s63, 0
	s_add_i32 s64, s95, s2
	global_load_lds_dwordx4 v[218:219], off
	v_lshl_add_u64 v[218:219], s[62:63], 0, v[148:149]
	s_mov_b32 m0, s64
	s_nop 0
	global_load_lds_dwordx4 v[218:219], off
	v_lshl_add_u64 v[218:219], s[62:63], 0, v[152:153]
	s_add_i32 m0, s64, 0x2000
	s_nop 0
	global_load_lds_dwordx4 v[218:219], off
	v_lshl_add_u64 v[218:219], v[222:223], 0, s[16:17]
	s_mov_b32 m0, s74
	s_nop 0
	global_load_lds_dwordx4 v[218:219], off
	v_lshl_add_u64 v[218:219], v[224:225], 0, s[16:17]
	s_mov_b32 m0, s75
	s_nop 0
	global_load_lds_dwordx4 v[218:219], off
	s_waitcnt vmcnt(8)
	s_waitcnt lgkmcnt(0)
	s_setprio 1
	s_barrier
	v_mfma_f32_16x16x32_bf16 v[62:65], v[130:133], v[184:187], v[62:65]
	v_mfma_f32_16x16x32_bf16 v[58:61], v[138:141], v[184:187], v[58:61]
	v_mfma_f32_16x16x32_bf16 v[50:53], v[130:133], v[192:195], v[50:53]
	v_mfma_f32_16x16x32_bf16 v[42:45], v[138:141], v[192:195], v[42:45]
	v_mfma_f32_16x16x32_bf16 v[34:37], v[130:133], v[200:203], v[34:37]
	v_mfma_f32_16x16x32_bf16 v[26:29], v[138:141], v[200:203], v[26:29]
	v_mfma_f32_16x16x32_bf16 v[18:21], v[130:133], v[210:213], v[18:21]
	v_mfma_f32_16x16x32_bf16 v[10:13], v[138:141], v[210:213], v[10:13]
	v_mfma_f32_16x16x32_bf16 v[62:65], v[134:137], v[188:191], v[62:65]
	v_mfma_f32_16x16x32_bf16 v[58:61], v[142:145], v[188:191], v[58:61]
	v_mfma_f32_16x16x32_bf16 v[50:53], v[134:137], v[196:199], v[50:53]
	v_mfma_f32_16x16x32_bf16 v[42:45], v[142:145], v[196:199], v[42:45]
	v_mfma_f32_16x16x32_bf16 v[34:37], v[134:137], v[206:209], v[34:37]
	v_mfma_f32_16x16x32_bf16 v[26:29], v[142:145], v[206:209], v[26:29]
	v_mfma_f32_16x16x32_bf16 v[18:21], v[134:137], v[214:217], v[18:21]
	v_mfma_f32_16x16x32_bf16 v[10:13], v[142:145], v[214:217], v[10:13]
	v_mfma_f32_16x16x32_bf16 v[54:57], v[162:165], v[184:187], v[54:57]
	v_mfma_f32_16x16x32_bf16 v[46:49], v[176:179], v[184:187], v[46:49]
	v_mfma_f32_16x16x32_bf16 v[38:41], v[162:165], v[192:195], v[38:41]
	v_mfma_f32_16x16x32_bf16 v[30:33], v[176:179], v[192:195], v[30:33]
	v_mfma_f32_16x16x32_bf16 v[22:25], v[162:165], v[200:203], v[22:25]
	v_mfma_f32_16x16x32_bf16 v[14:17], v[176:179], v[200:203], v[14:17]
	v_mfma_f32_16x16x32_bf16 v[6:9], v[162:165], v[210:213], v[6:9]
	v_mfma_f32_16x16x32_bf16 v[2:5], v[176:179], v[210:213], v[2:5]
	v_mfma_f32_16x16x32_bf16 v[54:57], v[172:175], v[188:191], v[54:57]
	v_mfma_f32_16x16x32_bf16 v[46:49], v[180:183], v[188:191], v[46:49]
	v_mfma_f32_16x16x32_bf16 v[38:41], v[172:175], v[196:199], v[38:41]
	v_mfma_f32_16x16x32_bf16 v[30:33], v[180:183], v[196:199], v[30:33]
	v_mfma_f32_16x16x32_bf16 v[22:25], v[172:175], v[206:209], v[22:25]
	v_mfma_f32_16x16x32_bf16 v[14:17], v[180:183], v[206:209], v[14:17]
	v_mfma_f32_16x16x32_bf16 v[6:9], v[172:175], v[214:217], v[6:9]
	v_mfma_f32_16x16x32_bf16 v[2:5], v[180:183], v[214:217], v[2:5]
	s_setprio 0
	s_barrier
	s_add_u32 s50, s50, 0x100
	s_addc_u32 s51, s51, 0
	s_add_u32 s91, s91, 0x100
	s_addc_u32 s92, s92, 0
	s_cmp_ge_i32 s93, s7
	s_mov_b32 s62, s93
	s_cbranch_scc0 .LBB0_1708
	s_and_b64 vcc, exec, s[20:21]
	s_cbranch_vccz .LBB0_1711
	s_barrier
